# code placement: the 8 GEMM main-loop heads aligned to 64 bytes (.p2align 6), MFMA segments re-padded to 8-byte alignment per loop
# baseline (speedup 1.0000x reference)
.Lm4bp_31:
	s_waitcnt lgkmcnt(0)
	s_mov_b32 s100, 0
	s_barrier
	v_mfma_f32_16x16x32_bf16 v[60:63], v[128:131], v[162:165], 0
	v_mfma_f32_16x16x32_bf16 v[56:59], v[136:139], v[162:165], 0
	v_mfma_f32_16x16x32_bf16 v[48:51], v[128:131], v[170:173], 0
	v_mfma_f32_16x16x32_bf16 v[40:43], v[136:139], v[170:173], 0
	v_mfma_f32_16x16x32_bf16 v[32:35], v[128:131], v[178:181], 0
	v_mfma_f32_16x16x32_bf16 v[24:27], v[136:139], v[178:181], 0
	v_mfma_f32_16x16x32_bf16 v[16:19], v[128:131], v[194:197], 0
	v_mfma_f32_16x16x32_bf16 v[8:11], v[136:139], v[194:197], 0
	v_mfma_f32_16x16x32_bf16 v[60:63], v[132:135], v[166:169], v[60:63]
	v_mfma_f32_16x16x32_bf16 v[56:59], v[146:149], v[166:169], v[56:59]
	v_mfma_f32_16x16x32_bf16 v[48:51], v[132:135], v[174:177], v[48:51]
	v_mfma_f32_16x16x32_bf16 v[40:43], v[146:149], v[174:177], v[40:43]
	v_mfma_f32_16x16x32_bf16 v[32:35], v[132:135], v[182:185], v[32:35]
	v_mfma_f32_16x16x32_bf16 v[24:27], v[146:149], v[182:185], v[24:27]
	v_mfma_f32_16x16x32_bf16 v[16:19], v[132:135], v[210:213], v[16:19]
	v_mfma_f32_16x16x32_bf16 v[8:11], v[146:149], v[210:213], v[8:11]
	v_mfma_f32_16x16x32_bf16 v[52:55], v[214:217], v[162:165], 0
	v_mfma_f32_16x16x32_bf16 v[44:47], v[222:225], v[162:165], 0
	v_mfma_f32_16x16x32_bf16 v[36:39], v[214:217], v[170:173], 0
	v_mfma_f32_16x16x32_bf16 v[28:31], v[222:225], v[170:173], 0
	v_mfma_f32_16x16x32_bf16 v[20:23], v[214:217], v[178:181], 0
	v_mfma_f32_16x16x32_bf16 v[12:15], v[222:225], v[178:181], 0
	v_mfma_f32_16x16x32_bf16 v[4:7], v[214:217], v[194:197], 0
	v_mfma_f32_16x16x32_bf16 v[0:3], v[222:225], v[194:197], 0
	v_mfma_f32_16x16x32_bf16 v[52:55], v[218:221], v[166:169], v[52:55]
	v_mfma_f32_16x16x32_bf16 v[44:47], v[226:229], v[166:169], v[44:47]
	v_mfma_f32_16x16x32_bf16 v[36:39], v[218:221], v[174:177], v[36:39]
	v_mfma_f32_16x16x32_bf16 v[28:31], v[226:229], v[174:177], v[28:31]
	v_mfma_f32_16x16x32_bf16 v[20:23], v[218:221], v[182:185], v[20:23]
	v_mfma_f32_16x16x32_bf16 v[12:15], v[226:229], v[182:185], v[12:15]
	v_mfma_f32_16x16x32_bf16 v[4:7], v[218:221], v[210:213], v[4:7]
	v_mfma_f32_16x16x32_bf16 v[0:3], v[226:229], v[210:213], v[0:3]
	s_barrier
	s_add_i32 s6, 0, 0x18000
	v_add_u32_e32 v146, s6, v206
	ds_read_b128 v[128:131], v146
	ds_read_b128 v[132:135], v146 offset:1024
	ds_read_b128 v[136:139], v146 offset:2048
	ds_read_b128 v[146:149], v146 offset:3072
	s_add_u32 s50, s52, 0xb0000
	s_addc_u32 s51, s53, 0
	s_mov_b32 m0, s68
	v_lshl_add_u64 v[214:215], s[50:51], 0, v[154:155]
	ds_read_b128 v[162:165], v208 offset:32768
	ds_read_b128 v[166:169], v208 offset:33792
	ds_read_b128 v[170:173], v208 offset:34816
	ds_read_b128 v[174:177], v208 offset:35840
	ds_read_b128 v[178:181], v208 offset:36864
	ds_read_b128 v[182:185], v208 offset:37888
	ds_read_b128 v[194:197], v208 offset:38912
	ds_read_b128 v[210:213], v208 offset:39936
	global_load_lds_dwordx4 v[214:215], off
	v_lshl_add_u64 v[214:215], s[50:51], 0, v[152:153]
	s_mov_b32 m0, s69
	s_nop 0
	global_load_lds_dwordx4 v[214:215], off
	s_add_i32 s19, 0, 0x1c000
	v_add_u32_e32 v192, s19, v206
	ds_read_b128 v[214:217], v192
	ds_read_b128 v[218:221], v192 offset:1024
	ds_read_b128 v[222:225], v192 offset:2048
	ds_read_b128 v[226:229], v192 offset:3072
	s_waitcnt vmcnt(8)
	s_waitcnt lgkmcnt(0)
	s_barrier
	v_mfma_f32_16x16x32_bf16 v[124:127], v[128:131], v[162:165], v[124:127]
	v_mfma_f32_16x16x32_bf16 v[120:123], v[136:139], v[162:165], v[120:123]
	v_mfma_f32_16x16x32_bf16 v[108:111], v[128:131], v[170:173], v[108:111]
	v_mfma_f32_16x16x32_bf16 v[104:107], v[136:139], v[170:173], v[104:107]
	v_mfma_f32_16x16x32_bf16 v[96:99], v[128:131], v[178:181], v[96:99]
	v_mfma_f32_16x16x32_bf16 v[88:91], v[136:139], v[178:181], v[88:91]
	v_mfma_f32_16x16x32_bf16 v[84:87], v[128:131], v[194:197], v[84:87]
	v_mfma_f32_16x16x32_bf16 v[80:83], v[136:139], v[194:197], v[80:83]
	v_mfma_f32_16x16x32_bf16 v[124:127], v[132:135], v[166:169], v[124:127]
	v_mfma_f32_16x16x32_bf16 v[120:123], v[146:149], v[166:169], v[120:123]
	v_mfma_f32_16x16x32_bf16 v[108:111], v[132:135], v[174:177], v[108:111]
	v_mfma_f32_16x16x32_bf16 v[104:107], v[146:149], v[174:177], v[104:107]
	v_mfma_f32_16x16x32_bf16 v[96:99], v[132:135], v[182:185], v[96:99]
	v_mfma_f32_16x16x32_bf16 v[88:91], v[146:149], v[182:185], v[88:91]
	v_mfma_f32_16x16x32_bf16 v[84:87], v[132:135], v[210:213], v[84:87]
	v_mfma_f32_16x16x32_bf16 v[80:83], v[146:149], v[210:213], v[80:83]
	v_mfma_f32_16x16x32_bf16 v[116:119], v[214:217], v[162:165], v[116:119]
	v_mfma_f32_16x16x32_bf16 v[112:115], v[222:225], v[162:165], v[112:115]
	v_mfma_f32_16x16x32_bf16 v[100:103], v[214:217], v[170:173], v[100:103]
	v_mfma_f32_16x16x32_bf16 v[92:95], v[222:225], v[170:173], v[92:95]
	v_mfma_f32_16x16x32_bf16 v[76:79], v[214:217], v[178:181], v[76:79]
	v_mfma_f32_16x16x32_bf16 v[72:75], v[222:225], v[178:181], v[72:75]
	v_mfma_f32_16x16x32_bf16 v[68:71], v[214:217], v[194:197], v[68:71]
	v_mfma_f32_16x16x32_bf16 v[64:67], v[222:225], v[194:197], v[64:67]
	v_mfma_f32_16x16x32_bf16 v[116:119], v[218:221], v[166:169], v[116:119]
	v_mfma_f32_16x16x32_bf16 v[112:115], v[226:229], v[166:169], v[112:115]
	v_mfma_f32_16x16x32_bf16 v[100:103], v[218:221], v[174:177], v[100:103]
	v_mfma_f32_16x16x32_bf16 v[92:95], v[226:229], v[174:177], v[92:95]
	v_mfma_f32_16x16x32_bf16 v[76:79], v[218:221], v[182:185], v[76:79]
	v_mfma_f32_16x16x32_bf16 v[72:75], v[226:229], v[182:185], v[72:75]
	v_mfma_f32_16x16x32_bf16 v[68:71], v[218:221], v[210:213], v[68:71]
	v_mfma_f32_16x16x32_bf16 v[64:67], v[226:229], v[210:213], v[64:67]
	s_barrier
	s_add_i32 s6, s6, s57
	v_lshl_add_u64 v[230:231], v[230:231], 0, s[36:37]
	s_mov_b32 m0, s6
	s_nop 0
	global_load_lds_dwordx4 v[230:231], off
	v_lshl_add_u64 v[230:231], v[232:233], 0, s[36:37]
	s_add_i32 m0, s6, 0x2000
	s_nop 0
	global_load_lds_dwordx4 v[230:231], off
	s_mov_b32 m0, s70
	v_lshl_add_u64 v[230:231], v[234:235], 0, s[36:37]
	ds_read_b128 v[162:165], v208 offset:49152
	ds_read_b128 v[166:169], v208 offset:50176
	ds_read_b128 v[170:173], v208 offset:51200
	ds_read_b128 v[174:177], v208 offset:52224
	ds_read_b128 v[178:181], v208 offset:53248
	ds_read_b128 v[182:185], v208 offset:54272
	ds_read_b128 v[194:197], v208 offset:55296
	ds_read_b128 v[210:213], v208 offset:56320
	global_load_lds_dwordx4 v[230:231], off
	v_lshl_add_u64 v[230:231], v[236:237], 0, s[36:37]
	s_mov_b32 m0, s71
	s_nop 0
	global_load_lds_dwordx4 v[230:231], off
	s_add_u32 s48, s48, 0xb0080
	s_addc_u32 s49, s49, 0
	s_add_i32 s6, s19, s57
	v_lshl_add_u64 v[250:251], s[48:49], 0, v[140:141]
	s_mov_b32 m0, s6
	s_nop 0
	global_load_lds_dwordx4 v[250:251], off
	v_lshl_add_u64 v[250:251], s[48:49], 0, v[150:151]
	s_add_i32 m0, s6, 0x2000
	s_nop 0
	global_load_lds_dwordx4 v[250:251], off
	s_add_i32 s12, s12, 2
	s_add_u32 s10, s10, 0x100
	s_addc_u32 s11, s11, 0
	s_cmp_gt_u32 s12, 41
	s_mov_b64 s[50:51], s[46:47]
	s_waitcnt vmcnt(8)
	s_waitcnt lgkmcnt(0)
	s_barrier
	v_mfma_f32_16x16x32_bf16 v[60:63], v[128:131], v[162:165], v[60:63]
	v_mfma_f32_16x16x32_bf16 v[56:59], v[136:139], v[162:165], v[56:59]
	v_mfma_f32_16x16x32_bf16 v[48:51], v[128:131], v[170:173], v[48:51]
	v_mfma_f32_16x16x32_bf16 v[40:43], v[136:139], v[170:173], v[40:43]
	v_mfma_f32_16x16x32_bf16 v[32:35], v[128:131], v[178:181], v[32:35]
	v_mfma_f32_16x16x32_bf16 v[24:27], v[136:139], v[178:181], v[24:27]
	v_mfma_f32_16x16x32_bf16 v[16:19], v[128:131], v[194:197], v[16:19]
	v_mfma_f32_16x16x32_bf16 v[8:11], v[136:139], v[194:197], v[8:11]
	v_mfma_f32_16x16x32_bf16 v[60:63], v[132:135], v[166:169], v[60:63]
	v_mfma_f32_16x16x32_bf16 v[56:59], v[146:149], v[166:169], v[56:59]
	v_mfma_f32_16x16x32_bf16 v[48:51], v[132:135], v[174:177], v[48:51]
	v_mfma_f32_16x16x32_bf16 v[40:43], v[146:149], v[174:177], v[40:43]
	v_mfma_f32_16x16x32_bf16 v[32:35], v[132:135], v[182:185], v[32:35]
	v_mfma_f32_16x16x32_bf16 v[24:27], v[146:149], v[182:185], v[24:27]
	v_mfma_f32_16x16x32_bf16 v[16:19], v[132:135], v[210:213], v[16:19]
	v_mfma_f32_16x16x32_bf16 v[8:11], v[146:149], v[210:213], v[8:11]
	v_mfma_f32_16x16x32_bf16 v[52:55], v[214:217], v[162:165], v[52:55]
	v_mfma_f32_16x16x32_bf16 v[44:47], v[222:225], v[162:165], v[44:47]
	v_mfma_f32_16x16x32_bf16 v[36:39], v[214:217], v[170:173], v[36:39]
	v_mfma_f32_16x16x32_bf16 v[28:31], v[222:225], v[170:173], v[28:31]
	v_mfma_f32_16x16x32_bf16 v[20:23], v[214:217], v[178:181], v[20:23]
	v_mfma_f32_16x16x32_bf16 v[12:15], v[222:225], v[178:181], v[12:15]
	v_mfma_f32_16x16x32_bf16 v[4:7], v[214:217], v[194:197], v[4:7]
	v_mfma_f32_16x16x32_bf16 v[0:3], v[222:225], v[194:197], v[0:3]
	v_mfma_f32_16x16x32_bf16 v[52:55], v[218:221], v[166:169], v[52:55]
	v_mfma_f32_16x16x32_bf16 v[44:47], v[226:229], v[166:169], v[44:47]
	v_mfma_f32_16x16x32_bf16 v[36:39], v[218:221], v[174:177], v[36:39]
	v_mfma_f32_16x16x32_bf16 v[28:31], v[226:229], v[174:177], v[28:31]
	v_mfma_f32_16x16x32_bf16 v[20:23], v[218:221], v[182:185], v[20:23]
	v_mfma_f32_16x16x32_bf16 v[12:15], v[226:229], v[182:185], v[12:15]
	v_mfma_f32_16x16x32_bf16 v[4:7], v[218:221], v[210:213], v[4:7]
	v_mfma_f32_16x16x32_bf16 v[0:3], v[226:229], v[210:213], v[0:3]
	s_barrier
	.p2align	6
.LBB0_31:
	s_add_u32 s46, s50, 0x100
	s_addc_u32 s47, s51, 0
	s_add_i32 s6, 0, 0x10000
	v_add_u32_e32 v146, s6, v206
	ds_read_b128 v[128:131], v146
	ds_read_b128 v[132:135], v146 offset:1024
	ds_read_b128 v[136:139], v146 offset:2048
	ds_read_b128 v[146:149], v146 offset:3072
	s_cmp_eq_u32 s12, 40
	s_cselect_b32 s53, s31, s47
	s_cselect_b32 s52, s30, s46
	s_cselect_b32 s49, s35, s11
	s_cselect_b32 s48, s34, s10
	v_lshl_add_u64 v[214:215], s[50:51], 0, v[158:159]
	s_add_i32 m0, s58, 0xc000
	ds_read_b128 v[162:165], v208
	ds_read_b128 v[166:169], v208 offset:1024
	ds_read_b128 v[170:173], v208 offset:2048
	ds_read_b128 v[174:177], v208 offset:3072
	ds_read_b128 v[178:181], v208 offset:4096
	ds_read_b128 v[182:185], v208 offset:5120
	ds_read_b128 v[194:197], v208 offset:6144
	ds_read_b128 v[210:213], v208 offset:7168
	global_load_lds_dwordx4 v[214:215], off
	v_lshl_add_u64 v[214:215], s[50:51], 0, v[160:161]
	s_add_i32 m0, s58, 0xe000
	s_nop 0
	global_load_lds_dwordx4 v[214:215], off
	s_add_i32 s19, 0, 0x14000
	v_add_u32_e32 v192, s19, v206
	ds_read_b128 v[214:217], v192
	ds_read_b128 v[218:221], v192 offset:1024
	ds_read_b128 v[222:225], v192 offset:2048
	ds_read_b128 v[226:229], v192 offset:3072
	s_waitcnt vmcnt(8)
	s_waitcnt lgkmcnt(0)
	s_barrier
	v_mfma_f32_16x16x32_bf16 v[124:127], v[128:131], v[162:165], v[124:127]
	v_mfma_f32_16x16x32_bf16 v[120:123], v[136:139], v[162:165], v[120:123]
	v_mfma_f32_16x16x32_bf16 v[108:111], v[128:131], v[170:173], v[108:111]
	v_mfma_f32_16x16x32_bf16 v[104:107], v[136:139], v[170:173], v[104:107]
	v_mfma_f32_16x16x32_bf16 v[96:99], v[128:131], v[178:181], v[96:99]
	v_mfma_f32_16x16x32_bf16 v[88:91], v[136:139], v[178:181], v[88:91]
	v_mfma_f32_16x16x32_bf16 v[84:87], v[128:131], v[194:197], v[84:87]
	v_mfma_f32_16x16x32_bf16 v[80:83], v[136:139], v[194:197], v[80:83]
	v_mfma_f32_16x16x32_bf16 v[124:127], v[132:135], v[166:169], v[124:127]
	v_mfma_f32_16x16x32_bf16 v[120:123], v[146:149], v[166:169], v[120:123]
	v_mfma_f32_16x16x32_bf16 v[108:111], v[132:135], v[174:177], v[108:111]
	v_mfma_f32_16x16x32_bf16 v[104:107], v[146:149], v[174:177], v[104:107]
	v_mfma_f32_16x16x32_bf16 v[96:99], v[132:135], v[182:185], v[96:99]
	v_mfma_f32_16x16x32_bf16 v[88:91], v[146:149], v[182:185], v[88:91]
	v_mfma_f32_16x16x32_bf16 v[84:87], v[132:135], v[210:213], v[84:87]
	v_mfma_f32_16x16x32_bf16 v[80:83], v[146:149], v[210:213], v[80:83]
	v_mfma_f32_16x16x32_bf16 v[116:119], v[214:217], v[162:165], v[116:119]
	v_mfma_f32_16x16x32_bf16 v[112:115], v[222:225], v[162:165], v[112:115]
	v_mfma_f32_16x16x32_bf16 v[100:103], v[214:217], v[170:173], v[100:103]
	v_mfma_f32_16x16x32_bf16 v[92:95], v[222:225], v[170:173], v[92:95]
	v_mfma_f32_16x16x32_bf16 v[76:79], v[214:217], v[178:181], v[76:79]
	v_mfma_f32_16x16x32_bf16 v[72:75], v[222:225], v[178:181], v[72:75]
	v_mfma_f32_16x16x32_bf16 v[68:71], v[214:217], v[194:197], v[68:71]
	v_mfma_f32_16x16x32_bf16 v[64:67], v[222:225], v[194:197], v[64:67]
	v_mfma_f32_16x16x32_bf16 v[116:119], v[218:221], v[166:169], v[116:119]
	v_mfma_f32_16x16x32_bf16 v[112:115], v[226:229], v[166:169], v[112:115]
	v_mfma_f32_16x16x32_bf16 v[100:103], v[218:221], v[174:177], v[100:103]
	v_mfma_f32_16x16x32_bf16 v[92:95], v[226:229], v[174:177], v[92:95]
	v_mfma_f32_16x16x32_bf16 v[76:79], v[218:221], v[182:185], v[76:79]
	v_mfma_f32_16x16x32_bf16 v[72:75], v[226:229], v[182:185], v[72:75]
	v_mfma_f32_16x16x32_bf16 v[68:71], v[218:221], v[210:213], v[68:71]
	v_mfma_f32_16x16x32_bf16 v[64:67], v[226:229], v[210:213], v[64:67]
	s_barrier
	s_add_i32 s6, s6, s57
	v_lshl_add_u64 v[230:231], s[48:49], 0, v[140:141]
	s_mov_b32 m0, s6
	s_nop 0
	global_load_lds_dwordx4 v[230:231], off
	v_lshl_add_u64 v[232:233], s[48:49], 0, v[150:151]
	s_add_i32 m0, s6, 0x2000
	s_nop 0
	global_load_lds_dwordx4 v[232:233], off
	s_mov_b32 m0, s58
	v_lshl_add_u64 v[234:235], s[52:53], 0, v[154:155]
	ds_read_b128 v[162:165], v208 offset:16384
	ds_read_b128 v[166:169], v208 offset:17408
	ds_read_b128 v[170:173], v208 offset:18432
	ds_read_b128 v[174:177], v208 offset:19456
	ds_read_b128 v[178:181], v208 offset:20480
	ds_read_b128 v[182:185], v208 offset:21504
	ds_read_b128 v[194:197], v208 offset:22528
	ds_read_b128 v[210:213], v208 offset:23552
	global_load_lds_dwordx4 v[234:235], off
	v_lshl_add_u64 v[236:237], s[52:53], 0, v[152:153]
	s_mov_b32 m0, s59
	s_nop 0
	global_load_lds_dwordx4 v[236:237], off
	s_add_u32 s50, s48, 0xb0000
	s_addc_u32 s51, s49, 0
	s_add_i32 s6, s19, s57
	v_lshl_add_u64 v[250:251], s[50:51], 0, v[140:141]
	s_mov_b32 m0, s6
	s_nop 0
	global_load_lds_dwordx4 v[250:251], off
	v_lshl_add_u64 v[250:251], s[50:51], 0, v[150:151]
	s_add_i32 m0, s6, 0x2000
	s_nop 0
	global_load_lds_dwordx4 v[250:251], off
	s_waitcnt vmcnt(8)
	s_waitcnt lgkmcnt(0)
	s_barrier
	v_mfma_f32_16x16x32_bf16 v[60:63], v[128:131], v[162:165], v[60:63]
	v_mfma_f32_16x16x32_bf16 v[56:59], v[136:139], v[162:165], v[56:59]
	v_mfma_f32_16x16x32_bf16 v[48:51], v[128:131], v[170:173], v[48:51]
	v_mfma_f32_16x16x32_bf16 v[40:43], v[136:139], v[170:173], v[40:43]
	v_mfma_f32_16x16x32_bf16 v[32:35], v[128:131], v[178:181], v[32:35]
	v_mfma_f32_16x16x32_bf16 v[24:27], v[136:139], v[178:181], v[24:27]
	v_mfma_f32_16x16x32_bf16 v[16:19], v[128:131], v[194:197], v[16:19]
	v_mfma_f32_16x16x32_bf16 v[8:11], v[136:139], v[194:197], v[8:11]
	v_mfma_f32_16x16x32_bf16 v[60:63], v[132:135], v[166:169], v[60:63]
	v_mfma_f32_16x16x32_bf16 v[56:59], v[146:149], v[166:169], v[56:59]
	v_mfma_f32_16x16x32_bf16 v[48:51], v[132:135], v[174:177], v[48:51]
	v_mfma_f32_16x16x32_bf16 v[40:43], v[146:149], v[174:177], v[40:43]
	v_mfma_f32_16x16x32_bf16 v[32:35], v[132:135], v[182:185], v[32:35]
	v_mfma_f32_16x16x32_bf16 v[24:27], v[146:149], v[182:185], v[24:27]
	v_mfma_f32_16x16x32_bf16 v[16:19], v[132:135], v[210:213], v[16:19]
	v_mfma_f32_16x16x32_bf16 v[8:11], v[146:149], v[210:213], v[8:11]
	v_mfma_f32_16x16x32_bf16 v[52:55], v[214:217], v[162:165], v[52:55]
	v_mfma_f32_16x16x32_bf16 v[44:47], v[222:225], v[162:165], v[44:47]
	v_mfma_f32_16x16x32_bf16 v[36:39], v[214:217], v[170:173], v[36:39]
	v_mfma_f32_16x16x32_bf16 v[28:31], v[222:225], v[170:173], v[28:31]
	v_mfma_f32_16x16x32_bf16 v[20:23], v[214:217], v[178:181], v[20:23]
	v_mfma_f32_16x16x32_bf16 v[12:15], v[222:225], v[178:181], v[12:15]
	v_mfma_f32_16x16x32_bf16 v[4:7], v[214:217], v[194:197], v[4:7]
	v_mfma_f32_16x16x32_bf16 v[0:3], v[222:225], v[194:197], v[0:3]
	v_mfma_f32_16x16x32_bf16 v[52:55], v[218:221], v[166:169], v[52:55]
	v_mfma_f32_16x16x32_bf16 v[44:47], v[226:229], v[166:169], v[44:47]
	v_mfma_f32_16x16x32_bf16 v[36:39], v[218:221], v[174:177], v[36:39]
	v_mfma_f32_16x16x32_bf16 v[28:31], v[226:229], v[174:177], v[28:31]
	v_mfma_f32_16x16x32_bf16 v[20:23], v[218:221], v[182:185], v[20:23]
	v_mfma_f32_16x16x32_bf16 v[12:15], v[226:229], v[182:185], v[12:15]
	v_mfma_f32_16x16x32_bf16 v[4:7], v[218:221], v[210:213], v[4:7]
	v_mfma_f32_16x16x32_bf16 v[0:3], v[226:229], v[210:213], v[0:3]
	s_barrier
	s_add_i32 s6, 0, 0x18000
	v_add_u32_e32 v146, s6, v206
	ds_read_b128 v[128:131], v146
	ds_read_b128 v[132:135], v146 offset:1024
	ds_read_b128 v[136:139], v146 offset:2048
	ds_read_b128 v[146:149], v146 offset:3072
	s_add_u32 s50, s52, 0xb0000
	s_addc_u32 s51, s53, 0
	s_mov_b32 m0, s68
	v_lshl_add_u64 v[214:215], s[50:51], 0, v[154:155]
	ds_read_b128 v[162:165], v208 offset:32768
	ds_read_b128 v[166:169], v208 offset:33792
	ds_read_b128 v[170:173], v208 offset:34816
	ds_read_b128 v[174:177], v208 offset:35840
	ds_read_b128 v[178:181], v208 offset:36864
	ds_read_b128 v[182:185], v208 offset:37888
	ds_read_b128 v[194:197], v208 offset:38912
	ds_read_b128 v[210:213], v208 offset:39936
	global_load_lds_dwordx4 v[214:215], off
	v_lshl_add_u64 v[214:215], s[50:51], 0, v[152:153]
	s_mov_b32 m0, s69
	s_nop 0
	global_load_lds_dwordx4 v[214:215], off
	s_add_i32 s19, 0, 0x1c000
	v_add_u32_e32 v192, s19, v206
	ds_read_b128 v[214:217], v192
	ds_read_b128 v[218:221], v192 offset:1024
	ds_read_b128 v[222:225], v192 offset:2048
	ds_read_b128 v[226:229], v192 offset:3072
	s_waitcnt vmcnt(8)
	s_waitcnt lgkmcnt(0)
	s_barrier
	v_mfma_f32_16x16x32_bf16 v[124:127], v[128:131], v[162:165], v[124:127]
	v_mfma_f32_16x16x32_bf16 v[120:123], v[136:139], v[162:165], v[120:123]
	v_mfma_f32_16x16x32_bf16 v[108:111], v[128:131], v[170:173], v[108:111]
	v_mfma_f32_16x16x32_bf16 v[104:107], v[136:139], v[170:173], v[104:107]
	v_mfma_f32_16x16x32_bf16 v[96:99], v[128:131], v[178:181], v[96:99]
	v_mfma_f32_16x16x32_bf16 v[88:91], v[136:139], v[178:181], v[88:91]
	v_mfma_f32_16x16x32_bf16 v[84:87], v[128:131], v[194:197], v[84:87]
	v_mfma_f32_16x16x32_bf16 v[80:83], v[136:139], v[194:197], v[80:83]
	v_mfma_f32_16x16x32_bf16 v[124:127], v[132:135], v[166:169], v[124:127]
	v_mfma_f32_16x16x32_bf16 v[120:123], v[146:149], v[166:169], v[120:123]
	v_mfma_f32_16x16x32_bf16 v[108:111], v[132:135], v[174:177], v[108:111]
	v_mfma_f32_16x16x32_bf16 v[104:107], v[146:149], v[174:177], v[104:107]
	v_mfma_f32_16x16x32_bf16 v[96:99], v[132:135], v[182:185], v[96:99]
	v_mfma_f32_16x16x32_bf16 v[88:91], v[146:149], v[182:185], v[88:91]
	v_mfma_f32_16x16x32_bf16 v[84:87], v[132:135], v[210:213], v[84:87]
	v_mfma_f32_16x16x32_bf16 v[80:83], v[146:149], v[210:213], v[80:83]
	v_mfma_f32_16x16x32_bf16 v[116:119], v[214:217], v[162:165], v[116:119]
	v_mfma_f32_16x16x32_bf16 v[112:115], v[222:225], v[162:165], v[112:115]
	v_mfma_f32_16x16x32_bf16 v[100:103], v[214:217], v[170:173], v[100:103]
	v_mfma_f32_16x16x32_bf16 v[92:95], v[222:225], v[170:173], v[92:95]
	v_mfma_f32_16x16x32_bf16 v[76:79], v[214:217], v[178:181], v[76:79]
	v_mfma_f32_16x16x32_bf16 v[72:75], v[222:225], v[178:181], v[72:75]
	v_mfma_f32_16x16x32_bf16 v[68:71], v[214:217], v[194:197], v[68:71]
	v_mfma_f32_16x16x32_bf16 v[64:67], v[222:225], v[194:197], v[64:67]
	v_mfma_f32_16x16x32_bf16 v[116:119], v[218:221], v[166:169], v[116:119]
	v_mfma_f32_16x16x32_bf16 v[112:115], v[226:229], v[166:169], v[112:115]
	v_mfma_f32_16x16x32_bf16 v[100:103], v[218:221], v[174:177], v[100:103]
	v_mfma_f32_16x16x32_bf16 v[92:95], v[226:229], v[174:177], v[92:95]
	v_mfma_f32_16x16x32_bf16 v[76:79], v[218:221], v[182:185], v[76:79]
	v_mfma_f32_16x16x32_bf16 v[72:75], v[226:229], v[182:185], v[72:75]
	v_mfma_f32_16x16x32_bf16 v[68:71], v[218:221], v[210:213], v[68:71]
	v_mfma_f32_16x16x32_bf16 v[64:67], v[226:229], v[210:213], v[64:67]
	s_barrier
	s_add_i32 s6, s6, s57
	v_lshl_add_u64 v[230:231], v[230:231], 0, s[36:37]
	s_mov_b32 m0, s6
	s_nop 0
	global_load_lds_dwordx4 v[230:231], off
	v_lshl_add_u64 v[230:231], v[232:233], 0, s[36:37]
	s_add_i32 m0, s6, 0x2000
	s_nop 0
	global_load_lds_dwordx4 v[230:231], off
	s_mov_b32 m0, s70
	v_lshl_add_u64 v[230:231], v[234:235], 0, s[36:37]
	ds_read_b128 v[162:165], v208 offset:49152
	ds_read_b128 v[166:169], v208 offset:50176
	ds_read_b128 v[170:173], v208 offset:51200
	ds_read_b128 v[174:177], v208 offset:52224
	ds_read_b128 v[178:181], v208 offset:53248
	ds_read_b128 v[182:185], v208 offset:54272
	ds_read_b128 v[194:197], v208 offset:55296
	ds_read_b128 v[210:213], v208 offset:56320
	global_load_lds_dwordx4 v[230:231], off
	v_lshl_add_u64 v[230:231], v[236:237], 0, s[36:37]
	s_mov_b32 m0, s71
	s_nop 0
	global_load_lds_dwordx4 v[230:231], off
	s_add_u32 s48, s48, 0xb0080
	s_addc_u32 s49, s49, 0
	s_add_i32 s6, s19, s57
	v_lshl_add_u64 v[250:251], s[48:49], 0, v[140:141]
	s_mov_b32 m0, s6
	s_nop 0
	global_load_lds_dwordx4 v[250:251], off
	v_lshl_add_u64 v[250:251], s[48:49], 0, v[150:151]
	s_add_i32 m0, s6, 0x2000
	s_nop 0
	global_load_lds_dwordx4 v[250:251], off
	s_add_i32 s12, s12, 2
	s_add_u32 s10, s10, 0x100
	s_addc_u32 s11, s11, 0
	s_cmp_gt_u32 s12, 41
	s_mov_b64 s[50:51], s[46:47]
	s_waitcnt vmcnt(8)
	s_waitcnt lgkmcnt(0)
	s_barrier
	v_mfma_f32_16x16x32_bf16 v[60:63], v[128:131], v[162:165], v[60:63]
	v_mfma_f32_16x16x32_bf16 v[56:59], v[136:139], v[162:165], v[56:59]
	v_mfma_f32_16x16x32_bf16 v[48:51], v[128:131], v[170:173], v[48:51]
	v_mfma_f32_16x16x32_bf16 v[40:43], v[136:139], v[170:173], v[40:43]
	v_mfma_f32_16x16x32_bf16 v[32:35], v[128:131], v[178:181], v[32:35]
	v_mfma_f32_16x16x32_bf16 v[24:27], v[136:139], v[178:181], v[24:27]
	v_mfma_f32_16x16x32_bf16 v[16:19], v[128:131], v[194:197], v[16:19]
	v_mfma_f32_16x16x32_bf16 v[8:11], v[136:139], v[194:197], v[8:11]
	v_mfma_f32_16x16x32_bf16 v[60:63], v[132:135], v[166:169], v[60:63]
	v_mfma_f32_16x16x32_bf16 v[56:59], v[146:149], v[166:169], v[56:59]
	v_mfma_f32_16x16x32_bf16 v[48:51], v[132:135], v[174:177], v[48:51]
	v_mfma_f32_16x16x32_bf16 v[40:43], v[146:149], v[174:177], v[40:43]
	v_mfma_f32_16x16x32_bf16 v[32:35], v[132:135], v[182:185], v[32:35]
	v_mfma_f32_16x16x32_bf16 v[24:27], v[146:149], v[182:185], v[24:27]
	v_mfma_f32_16x16x32_bf16 v[16:19], v[132:135], v[210:213], v[16:19]
	v_mfma_f32_16x16x32_bf16 v[8:11], v[146:149], v[210:213], v[8:11]
	v_mfma_f32_16x16x32_bf16 v[52:55], v[214:217], v[162:165], v[52:55]
	v_mfma_f32_16x16x32_bf16 v[44:47], v[222:225], v[162:165], v[44:47]
	v_mfma_f32_16x16x32_bf16 v[36:39], v[214:217], v[170:173], v[36:39]
	v_mfma_f32_16x16x32_bf16 v[28:31], v[222:225], v[170:173], v[28:31]
	v_mfma_f32_16x16x32_bf16 v[20:23], v[214:217], v[178:181], v[20:23]
	v_mfma_f32_16x16x32_bf16 v[12:15], v[222:225], v[178:181], v[12:15]
	v_mfma_f32_16x16x32_bf16 v[4:7], v[214:217], v[194:197], v[4:7]
	v_mfma_f32_16x16x32_bf16 v[0:3], v[222:225], v[194:197], v[0:3]
	v_mfma_f32_16x16x32_bf16 v[52:55], v[218:221], v[166:169], v[52:55]
	v_mfma_f32_16x16x32_bf16 v[44:47], v[226:229], v[166:169], v[44:47]
	v_mfma_f32_16x16x32_bf16 v[36:39], v[218:221], v[174:177], v[36:39]
	v_mfma_f32_16x16x32_bf16 v[28:31], v[226:229], v[174:177], v[28:31]
	v_mfma_f32_16x16x32_bf16 v[20:23], v[218:221], v[182:185], v[20:23]
	v_mfma_f32_16x16x32_bf16 v[12:15], v[226:229], v[182:185], v[12:15]
	v_mfma_f32_16x16x32_bf16 v[4:7], v[218:221], v[210:213], v[4:7]
	v_mfma_f32_16x16x32_bf16 v[0:3], v[226:229], v[210:213], v[0:3]
	s_barrier
	s_cbranch_scc0 .LBB0_31
	s_mov_b32 s100, 1
	s_ashr_i32 s39, s38, 31
	v_lshl_or_b32 v128, s81, 8, v207
	s_lshl_b64 s[10:11], s[38:39], 8
	v_ashrrev_i32_e32 v129, 31, v128
	v_lshl_add_u64 v[168:169], s[10:11], 0, v[156:157]
	v_lshlrev_b64 v[170:171], 1, v[128:129]
	v_lshl_add_u64 v[174:175], s[4:5], 0, v[170:171]
	v_lshlrev_b64 v[172:173], 11, v[168:169]
	v_lshl_add_u64 v[128:129], v[174:175], 0, v[172:173]
	global_load_dwordx4 v[146:149], v[128:129], off
	global_load_dwordx4 v[182:185], v[128:129], off offset:256
	v_or_b32_e32 v166, 16, v168
	v_mov_b32_e32 v167, v169
	v_lshlrev_b64 v[176:177], 11, v[166:167]
	v_lshl_add_u64 v[128:129], v[174:175], 0, v[176:177]
	global_load_dwordx4 v[194:197], v[128:129], off
	global_load_dwordx4 v[210:213], v[128:129], off offset:256
	v_or_b32_e32 v164, 32, v168
	v_mov_b32_e32 v165, v169
	v_or_b32_e32 v162, 48, v168
	v_mov_b32_e32 v163, v169
	v_lshlrev_b64 v[180:181], 11, v[164:165]
	v_lshlrev_b64 v[178:179], 11, v[162:163]
	v_lshl_add_u64 v[128:129], v[174:175], 0, v[180:181]
	v_lshl_add_u64 v[130:131], v[174:175], 0, v[178:179]
	global_load_dwordx4 v[214:217], v[128:129], off
	global_load_dwordx4 v[136:139], v[128:129], off offset:256
	global_load_dwordx4 v[132:135], v[130:131], off
	s_nop 0
	global_load_dwordx4 v[128:131], v[130:131], off offset:256
	s_mov_b64 s[10:11], 0x90
	v_lshl_add_u64 v[172:173], s[28:29], 0, v[172:173]
	v_lshl_add_u64 v[172:173], v[172:173], 0, v[170:171]
	s_waitcnt vmcnt(0)
	v_lshlrev_b32_e32 v218, 16, v146
	v_and_b32_e32 v219, 0xffff0000, v146
	v_lshlrev_b32_e32 v220, 16, v148
	v_and_b32_e32 v221, 0xffff0000, v148
	v_lshlrev_b32_e32 v146, 16, v147
	v_and_b32_e32 v147, 0xffff0000, v147
	v_lshlrev_b32_e32 v222, 16, v182
	v_and_b32_e32 v223, 0xffff0000, v182
	v_lshlrev_b32_e32 v224, 16, v184
	v_and_b32_e32 v225, 0xffff0000, v184
	v_lshlrev_b32_e32 v182, 16, v183
	v_and_b32_e32 v183, 0xffff0000, v183
	v_pk_fma_f32 v[124:125], v[124:125], 0.5, v[218:219] op_sel_hi:[1,0,1]
	v_pk_fma_f32 v[120:121], v[120:121], 0.5, v[220:221] op_sel_hi:[1,0,1]
	v_pk_fma_f32 v[126:127], v[126:127], 0.5, v[146:147] op_sel_hi:[1,0,1]
	v_pk_fma_f32 v[116:117], v[116:117], 0.5, v[222:223] op_sel_hi:[1,0,1]
	v_pk_fma_f32 v[146:147], v[112:113], 0.5, v[224:225] op_sel_hi:[1,0,1]
	v_pk_fma_f32 v[118:119], v[118:119], 0.5, v[182:183] op_sel_hi:[1,0,1]
	v_pk_mul_f32 v[220:221], v[124:125], v[124:125]
	v_pk_mul_f32 v[222:223], v[126:127], v[126:127]
	v_cvt_pk_bf16_f32 v112, v124, v125
	v_cvt_pk_bf16_f32 v113, v126, v127
	v_pk_mul_f32 v[124:125], v[116:117], v[116:117]
	v_pk_mul_f32 v[126:127], v[118:119], v[118:119]
	v_pk_mul_f32 v[228:229], v[146:147], v[146:147]
	v_cvt_pk_bf16_f32 v116, v116, v117
	v_cvt_pk_bf16_f32 v117, v118, v119
	v_cvt_pk_bf16_f32 v118, v146, v147
	v_add_f32_e32 v146, v220, v221
	v_add_f32_e32 v146, v222, v146
	v_lshlrev_b32_e32 v148, 16, v149
	v_and_b32_e32 v149, 0xffff0000, v149
	v_pk_mul_f32 v[224:225], v[120:121], v[120:121]
	v_add_f32_e32 v146, v223, v146
	v_pk_fma_f32 v[122:123], v[122:123], 0.5, v[148:149] op_sel_hi:[1,0,1]
	v_add_f32_e32 v146, v224, v146
	v_pk_mul_f32 v[226:227], v[122:123], v[122:123]
	v_add_f32_e32 v146, v225, v146
	v_add_f32_e32 v146, v226, v146
	v_add_f32_e32 v146, v227, v146
	v_add_f32_e32 v124, v124, v146
	v_add_f32_e32 v124, v125, v124
	v_add_f32_e32 v124, v126, v124
	v_lshlrev_b32_e32 v184, 16, v185
	v_and_b32_e32 v185, 0xffff0000, v185
	v_add_f32_e32 v124, v127, v124
	v_pk_fma_f32 v[148:149], v[114:115], 0.5, v[184:185] op_sel_hi:[1,0,1]
	v_add_f32_e32 v124, v228, v124
	v_pk_mul_f32 v[230:231], v[148:149], v[148:149]
	v_add_f32_e32 v124, v229, v124
	v_add_f32_e32 v124, v230, v124
	v_add_f32_e32 v209, v231, v124
	v_lshlrev_b32_e32 v124, 16, v212
	v_and_b32_e32 v125, 0xffff0000, v212
	v_pk_fma_f32 v[124:125], v[92:93], 0.5, v[124:125] op_sel_hi:[1,0,1]
	v_lshlrev_b32_e32 v92, 16, v211
	v_and_b32_e32 v93, 0xffff0000, v211
	v_pk_fma_f32 v[102:103], v[102:103], 0.5, v[92:93] op_sel_hi:[1,0,1]
	v_lshlrev_b32_e32 v92, 16, v213
	v_and_b32_e32 v93, 0xffff0000, v213
	v_pk_fma_f32 v[126:127], v[94:95], 0.5, v[92:93] op_sel_hi:[1,0,1]
	v_lshlrev_b32_e32 v92, 16, v214
	v_and_b32_e32 v93, 0xffff0000, v214
	v_pk_fma_f32 v[92:93], v[96:97], 0.5, v[92:93] op_sel_hi:[1,0,1]
	v_lshlrev_b32_e32 v96, 16, v217
	v_and_b32_e32 v97, 0xffff0000, v217
	v_lshlrev_b32_e32 v94, 16, v216
	v_and_b32_e32 v95, 0xffff0000, v216
	v_pk_fma_f32 v[90:91], v[90:91], 0.5, v[96:97] op_sel_hi:[1,0,1]
	v_lshlrev_b32_e32 v96, 16, v136
	v_and_b32_e32 v97, 0xffff0000, v136
	v_lshlrev_b32_e32 v182, 16, v194
	v_and_b32_e32 v183, 0xffff0000, v194
	v_pk_fma_f32 v[88:89], v[88:89], 0.5, v[94:95] op_sel_hi:[1,0,1]
	v_lshlrev_b32_e32 v94, 16, v215
	v_and_b32_e32 v95, 0xffff0000, v215
	v_pk_fma_f32 v[96:97], v[76:77], 0.5, v[96:97] op_sel_hi:[1,0,1]
	v_lshl_add_u64 v[76:77], v[168:169], 0, s[36:37]
	v_lshlrev_b32_e32 v184, 16, v196
	v_and_b32_e32 v185, 0xffff0000, v196
	v_cvt_pk_bf16_f32 v114, v120, v121
	v_pk_fma_f32 v[120:121], v[108:109], 0.5, v[182:183] op_sel_hi:[1,0,1]
	v_pk_fma_f32 v[94:95], v[98:99], 0.5, v[94:95] op_sel_hi:[1,0,1]
	v_lshlrev_b64 v[182:183], 11, v[76:77]
	v_lshlrev_b32_e32 v98, 16, v138
	v_and_b32_e32 v99, 0xffff0000, v138
	v_pk_fma_f32 v[108:109], v[104:105], 0.5, v[184:185] op_sel_hi:[1,0,1]
	v_lshl_add_u64 v[184:185], v[174:175], 0, v[182:183]
	v_pk_fma_f32 v[98:99], v[72:73], 0.5, v[98:99] op_sel_hi:[1,0,1]
	v_lshlrev_b32_e32 v72, 16, v137
	v_and_b32_e32 v73, 0xffff0000, v137
	v_lshlrev_b32_e32 v218, 16, v210
	v_and_b32_e32 v219, 0xffff0000, v210
	global_load_dwordx4 v[210:213], v[184:185], off
	v_pk_fma_f32 v[136:137], v[78:79], 0.5, v[72:73] op_sel_hi:[1,0,1]
	v_lshlrev_b32_e32 v72, 16, v139
	v_and_b32_e32 v73, 0xffff0000, v139
	v_pk_fma_f32 v[138:139], v[74:75], 0.5, v[72:73] op_sel_hi:[1,0,1]
	v_lshlrev_b32_e32 v72, 16, v132
	v_and_b32_e32 v73, 0xffff0000, v132
	v_pk_fma_f32 v[74:75], v[84:85], 0.5, v[72:73] op_sel_hi:[1,0,1]
	v_lshlrev_b32_e32 v72, 16, v134
	v_and_b32_e32 v73, 0xffff0000, v134
	v_pk_fma_f32 v[78:79], v[80:81], 0.5, v[72:73] op_sel_hi:[1,0,1]
	v_lshlrev_b32_e32 v72, 16, v133
	v_and_b32_e32 v73, 0xffff0000, v133
	v_pk_fma_f32 v[100:101], v[100:101], 0.5, v[218:219] op_sel_hi:[1,0,1]
	global_load_dwordx4 v[218:221], v[184:185], off offset:256
	v_pk_fma_f32 v[80:81], v[86:87], 0.5, v[72:73] op_sel_hi:[1,0,1]
	v_lshlrev_b32_e32 v72, 16, v135
	v_and_b32_e32 v73, 0xffff0000, v135
	v_pk_fma_f32 v[82:83], v[82:83], 0.5, v[72:73] op_sel_hi:[1,0,1]
	v_lshl_add_u64 v[72:73], v[168:169], 0, s[10:11]
	v_lshlrev_b64 v[132:133], 11, v[72:73]
	v_lshl_add_u64 v[134:135], v[174:175], 0, v[132:133]
	v_lshlrev_b32_e32 v84, 16, v128
	v_and_b32_e32 v85, 0xffff0000, v128
	global_load_dwordx4 v[226:229], v[134:135], off
	global_load_dwordx4 v[234:237], v[134:135], off offset:256
	v_pk_fma_f32 v[84:85], v[68:69], 0.5, v[84:85] op_sel_hi:[1,0,1]
	v_lshlrev_b32_e32 v68, 16, v130
	v_and_b32_e32 v69, 0xffff0000, v130
	v_pk_fma_f32 v[86:87], v[64:65], 0.5, v[68:69] op_sel_hi:[1,0,1]
	v_lshlrev_b32_e32 v64, 16, v129
	v_and_b32_e32 v65, 0xffff0000, v129
	s_mov_b64 s[10:11], 0xa0
	v_pk_fma_f32 v[128:129], v[70:71], 0.5, v[64:65] op_sel_hi:[1,0,1]
	v_lshl_add_u64 v[70:71], v[168:169], 0, s[10:11]
	s_mov_b64 s[10:11], 0xb0
	v_lshlrev_b32_e32 v64, 16, v131
	v_and_b32_e32 v65, 0xffff0000, v131
	v_lshlrev_b64 v[134:135], 11, v[70:71]
	v_lshl_add_u64 v[68:69], v[168:169], 0, s[10:11]
	v_pk_fma_f32 v[130:131], v[66:67], 0.5, v[64:65] op_sel_hi:[1,0,1]
	v_lshl_add_u64 v[64:65], v[174:175], 0, v[134:135]
	v_lshlrev_b64 v[184:185], 11, v[68:69]
	global_load_dwordx4 v[238:241], v[64:65], off
	global_load_dwordx4 v[242:245], v[64:65], off offset:256
	v_lshl_add_u64 v[64:65], v[174:175], 0, v[184:185]
	global_load_dwordx4 v[246:249], v[64:65], off
	s_nop 0
	global_load_dwordx4 v[64:67], v[64:65], off offset:256
	v_lshlrev_b32_e32 v194, 16, v195
	v_and_b32_e32 v195, 0xffff0000, v195
	v_lshlrev_b32_e32 v196, 16, v197
	v_and_b32_e32 v197, 0xffff0000, v197
	v_cvt_pk_bf16_f32 v115, v122, v123
	v_cvt_pk_bf16_f32 v119, v148, v149
	v_pk_fma_f32 v[122:123], v[110:111], 0.5, v[194:195] op_sel_hi:[1,0,1]
	v_pk_fma_f32 v[110:111], v[106:107], 0.5, v[196:197] op_sel_hi:[1,0,1]
	global_store_dwordx4 v[172:173], v[112:115], off
	global_store_dwordx4 v[172:173], v[116:119], off offset:256
	v_cvt_pk_bf16_f32 v104, v120, v121
	v_lshl_add_u64 v[112:113], s[28:29], 0, v[176:177]
	v_cvt_pk_bf16_f32 v105, v122, v123
	v_cvt_pk_bf16_f32 v106, v108, v109
	v_cvt_pk_bf16_f32 v107, v110, v111
	v_lshl_add_u64 v[112:113], v[112:113], 0, v[170:171]
	v_cvt_pk_bf16_f32 v146, v100, v101
	v_cvt_pk_bf16_f32 v147, v102, v103
	v_cvt_pk_bf16_f32 v148, v124, v125
	v_cvt_pk_bf16_f32 v149, v126, v127
	global_store_dwordx4 v[112:113], v[104:107], off
	global_store_dwordx4 v[112:113], v[146:149], off offset:256
	v_cvt_pk_bf16_f32 v194, v92, v93
	v_lshl_add_u64 v[104:105], s[28:29], 0, v[180:181]
	v_cvt_pk_bf16_f32 v195, v94, v95
	v_cvt_pk_bf16_f32 v196, v88, v89
	v_cvt_pk_bf16_f32 v197, v90, v91
	v_lshl_add_u64 v[104:105], v[104:105], 0, v[170:171]
	v_cvt_pk_bf16_f32 v214, v96, v97
	v_cvt_pk_bf16_f32 v215, v136, v137
	v_cvt_pk_bf16_f32 v216, v98, v99
	v_cvt_pk_bf16_f32 v217, v138, v139
	global_store_dwordx4 v[104:105], v[194:197], off
	global_store_dwordx4 v[104:105], v[214:217], off offset:256
	v_lshl_add_u64 v[104:105], s[28:29], 0, v[178:179]
	v_cvt_pk_bf16_f32 v222, v74, v75
	v_cvt_pk_bf16_f32 v223, v80, v81
	v_cvt_pk_bf16_f32 v224, v78, v79
	v_cvt_pk_bf16_f32 v225, v82, v83
	v_lshl_add_u64 v[104:105], v[104:105], 0, v[170:171]
	v_cvt_pk_bf16_f32 v230, v84, v85
	v_cvt_pk_bf16_f32 v231, v128, v129
	v_cvt_pk_bf16_f32 v232, v86, v87
	v_cvt_pk_bf16_f32 v233, v130, v131
	global_store_dwordx4 v[104:105], v[222:225], off
	global_store_dwordx4 v[104:105], v[230:233], off offset:256
	s_waitcnt vmcnt(8)
	v_lshlrev_b32_e32 v104, 16, v210
	v_and_b32_e32 v105, 0xffff0000, v210
	v_pk_fma_f32 v[60:61], v[60:61], 0.5, v[104:105] op_sel_hi:[1,0,1]
	v_lshlrev_b32_e32 v104, 16, v212
	v_and_b32_e32 v105, 0xffff0000, v212
	v_pk_fma_f32 v[56:57], v[56:57], 0.5, v[104:105] op_sel_hi:[1,0,1]
	v_lshlrev_b32_e32 v104, 16, v211
	v_and_b32_e32 v105, 0xffff0000, v211
	v_pk_fma_f32 v[62:63], v[62:63], 0.5, v[104:105] op_sel_hi:[1,0,1]
	v_lshlrev_b32_e32 v104, 16, v213
	v_and_b32_e32 v105, 0xffff0000, v213
	v_pk_fma_f32 v[58:59], v[58:59], 0.5, v[104:105] op_sel_hi:[1,0,1]
	v_lshlrev_b32_e32 v104, 16, v218
	v_and_b32_e32 v105, 0xffff0000, v218
	v_pk_fma_f32 v[52:53], v[52:53], 0.5, v[104:105] op_sel_hi:[1,0,1]
	v_lshlrev_b32_e32 v104, 16, v220
	v_and_b32_e32 v105, 0xffff0000, v220
	v_pk_fma_f32 v[104:105], v[44:45], 0.5, v[104:105] op_sel_hi:[1,0,1]
	v_lshlrev_b32_e32 v44, 16, v219
	v_and_b32_e32 v45, 0xffff0000, v219
	v_pk_fma_f32 v[54:55], v[54:55], 0.5, v[44:45] op_sel_hi:[1,0,1]
	v_lshlrev_b32_e32 v44, 16, v221
	v_and_b32_e32 v45, 0xffff0000, v221
	v_pk_fma_f32 v[106:107], v[46:47], 0.5, v[44:45] op_sel_hi:[1,0,1]
	v_lshlrev_b32_e32 v44, 16, v226
	v_and_b32_e32 v45, 0xffff0000, v226
	v_pk_fma_f32 v[44:45], v[48:49], 0.5, v[44:45] op_sel_hi:[1,0,1]
	v_lshlrev_b32_e32 v48, 16, v229
	v_and_b32_e32 v49, 0xffff0000, v229
	v_pk_fma_f32 v[42:43], v[42:43], 0.5, v[48:49] op_sel_hi:[1,0,1]
	v_lshlrev_b32_e32 v48, 16, v234
	v_and_b32_e32 v49, 0xffff0000, v234
	v_pk_fma_f32 v[36:37], v[36:37], 0.5, v[48:49] op_sel_hi:[1,0,1]
	v_lshlrev_b32_e32 v48, 16, v236
	v_and_b32_e32 v49, 0xffff0000, v236
	v_lshlrev_b32_e32 v46, 16, v228
	v_and_b32_e32 v47, 0xffff0000, v228
	v_pk_fma_f32 v[48:49], v[28:29], 0.5, v[48:49] op_sel_hi:[1,0,1]
	v_lshlrev_b32_e32 v28, 16, v235
	v_and_b32_e32 v29, 0xffff0000, v235
	v_pk_fma_f32 v[40:41], v[40:41], 0.5, v[46:47] op_sel_hi:[1,0,1]
	v_lshlrev_b32_e32 v46, 16, v227
	v_and_b32_e32 v47, 0xffff0000, v227
	v_pk_fma_f32 v[38:39], v[38:39], 0.5, v[28:29] op_sel_hi:[1,0,1]
	v_lshlrev_b32_e32 v28, 16, v237
	v_and_b32_e32 v29, 0xffff0000, v237
	v_pk_fma_f32 v[46:47], v[50:51], 0.5, v[46:47] op_sel_hi:[1,0,1]
	v_pk_fma_f32 v[50:51], v[30:31], 0.5, v[28:29] op_sel_hi:[1,0,1]
	v_lshlrev_b32_e32 v28, 16, v238
	v_and_b32_e32 v29, 0xffff0000, v238
	v_lshlrev_b32_e32 v180, 16, v64
	v_and_b32_e32 v181, 0xffff0000, v64
	v_pk_fma_f32 v[28:29], v[32:33], 0.5, v[28:29] op_sel_hi:[1,0,1]
	v_lshlrev_b32_e32 v32, 16, v241
	v_and_b32_e32 v33, 0xffff0000, v241
	v_pk_fma_f32 v[4:5], v[4:5], 0.5, v[180:181] op_sel_hi:[1,0,1]
	v_lshlrev_b32_e32 v180, 16, v66
	v_and_b32_e32 v181, 0xffff0000, v66
	v_pk_fma_f32 v[26:27], v[26:27], 0.5, v[32:33] op_sel_hi:[1,0,1]
	v_lshlrev_b32_e32 v32, 16, v242
	v_and_b32_e32 v33, 0xffff0000, v242
	v_pk_fma_f32 v[0:1], v[0:1], 0.5, v[180:181] op_sel_hi:[1,0,1]
	v_lshl_add_u64 v[180:181], s[28:29], 0, v[182:183]
	v_cvt_pk_bf16_f32 v112, v60, v61
	v_cvt_pk_bf16_f32 v113, v62, v63
	v_cvt_pk_bf16_f32 v114, v56, v57
	v_cvt_pk_bf16_f32 v115, v58, v59
	v_pk_fma_f32 v[20:21], v[20:21], 0.5, v[32:33] op_sel_hi:[1,0,1]
	v_lshlrev_b32_e32 v32, 16, v244
	v_and_b32_e32 v33, 0xffff0000, v244
	v_lshl_add_u64 v[180:181], v[180:181], 0, v[170:171]
	v_cvt_pk_bf16_f32 v116, v52, v53
	v_cvt_pk_bf16_f32 v117, v54, v55
	v_cvt_pk_bf16_f32 v118, v104, v105
	v_cvt_pk_bf16_f32 v119, v106, v107
	v_lshlrev_b32_e32 v30, 16, v240
	v_and_b32_e32 v31, 0xffff0000, v240
	v_pk_fma_f32 v[32:33], v[12:13], 0.5, v[32:33] op_sel_hi:[1,0,1]
	v_lshlrev_b32_e32 v12, 16, v243
	v_and_b32_e32 v13, 0xffff0000, v243
	global_store_dwordx4 v[180:181], v[112:115], off
	global_store_dwordx4 v[180:181], v[116:119], off offset:256
	v_cvt_pk_bf16_f32 v146, v44, v45
	v_lshl_add_u64 v[112:113], s[28:29], 0, v[132:133]
	v_cvt_pk_bf16_f32 v147, v46, v47
	v_cvt_pk_bf16_f32 v148, v40, v41
	v_cvt_pk_bf16_f32 v149, v42, v43
	v_pk_fma_f32 v[24:25], v[24:25], 0.5, v[30:31] op_sel_hi:[1,0,1]
	v_lshlrev_b32_e32 v30, 16, v239
	v_and_b32_e32 v31, 0xffff0000, v239
	v_pk_fma_f32 v[22:23], v[22:23], 0.5, v[12:13] op_sel_hi:[1,0,1]
	v_lshlrev_b32_e32 v12, 16, v245
	v_and_b32_e32 v13, 0xffff0000, v245
	v_lshl_add_u64 v[112:113], v[112:113], 0, v[170:171]
	v_cvt_pk_bf16_f32 v172, v36, v37
	v_cvt_pk_bf16_f32 v173, v38, v39
	v_cvt_pk_bf16_f32 v174, v48, v49
	v_cvt_pk_bf16_f32 v175, v50, v51
	v_pk_fma_f32 v[30:31], v[34:35], 0.5, v[30:31] op_sel_hi:[1,0,1]
	v_pk_fma_f32 v[34:35], v[14:15], 0.5, v[12:13] op_sel_hi:[1,0,1]
	v_lshlrev_b32_e32 v12, 16, v246
	v_and_b32_e32 v13, 0xffff0000, v246
	v_lshlrev_b32_e32 v14, 16, v248
	v_and_b32_e32 v15, 0xffff0000, v248
	global_store_dwordx4 v[112:113], v[146:149], off
	global_store_dwordx4 v[112:113], v[172:175], off offset:256
	v_lshl_add_u64 v[112:113], s[28:29], 0, v[134:135]
	v_cvt_pk_bf16_f32 v176, v28, v29
	v_cvt_pk_bf16_f32 v177, v30, v31
	v_cvt_pk_bf16_f32 v178, v24, v25
	v_cvt_pk_bf16_f32 v179, v26, v27
	v_pk_fma_f32 v[12:13], v[16:17], 0.5, v[12:13] op_sel_hi:[1,0,1]
	v_pk_fma_f32 v[8:9], v[8:9], 0.5, v[14:15] op_sel_hi:[1,0,1]
	v_lshlrev_b32_e32 v14, 16, v247
	v_and_b32_e32 v15, 0xffff0000, v247
	v_lshlrev_b32_e32 v16, 16, v249
	v_and_b32_e32 v17, 0xffff0000, v249
	v_lshlrev_b32_e32 v64, 16, v65
	v_and_b32_e32 v65, 0xffff0000, v65
	v_lshl_add_u64 v[112:113], v[112:113], 0, v[170:171]
	v_cvt_pk_bf16_f32 v194, v20, v21
	v_cvt_pk_bf16_f32 v195, v22, v23
	v_cvt_pk_bf16_f32 v196, v32, v33
	v_cvt_pk_bf16_f32 v197, v34, v35
	v_pk_fma_f32 v[14:15], v[18:19], 0.5, v[14:15] op_sel_hi:[1,0,1]
	v_pk_fma_f32 v[10:11], v[10:11], 0.5, v[16:17] op_sel_hi:[1,0,1]
	v_pk_fma_f32 v[6:7], v[6:7], 0.5, v[64:65] op_sel_hi:[1,0,1]
	v_lshlrev_b32_e32 v64, 16, v67
	v_and_b32_e32 v65, 0xffff0000, v67
	global_store_dwordx4 v[112:113], v[176:179], off
	global_store_dwordx4 v[112:113], v[194:197], off offset:256
	v_lshl_add_u64 v[112:113], s[28:29], 0, v[184:185]
	v_cvt_pk_bf16_f32 v16, v12, v13
	v_cvt_pk_bf16_f32 v17, v14, v15
	v_cvt_pk_bf16_f32 v18, v8, v9
	v_cvt_pk_bf16_f32 v19, v10, v11
	v_pk_fma_f32 v[2:3], v[2:3], 0.5, v[64:65] op_sel_hi:[1,0,1]
	v_lshl_add_u64 v[112:113], v[112:113], 0, v[170:171]
	v_cvt_pk_bf16_f32 v64, v4, v5
	v_cvt_pk_bf16_f32 v65, v6, v7
	v_cvt_pk_bf16_f32 v66, v0, v1
	v_cvt_pk_bf16_f32 v67, v2, v3
	global_store_dwordx4 v[112:113], v[16:19], off
	global_store_dwordx4 v[112:113], v[64:67], off offset:256
	s_lshl_b32 s10, s81, 2
	v_and_b32_e32 v17, 64, v188
	v_xor_b32_e32 v16, 16, v188
	v_add_u32_e32 v17, 64, v17
	v_cmp_lt_i32_e32 vcc, v16, v17
	v_xor_b32_e32 v18, 32, v188
	s_ashr_i32 s11, s10, 31
	v_cndmask_b32_e32 v16, v188, v16, vcc
	v_lshlrev_b32_e32 v16, 2, v16
	v_mov_b32_e32 v132, v209
	v_cmp_lt_i32_e32 vcc, v18, v17
	s_lshl_b64 s[10:11], s[10:11], 2
	s_add_u32 s38, s73, s10
	v_cndmask_b32_e32 v17, v188, v18, vcc
	v_lshlrev_b32_e32 v17, 2, v17
	s_addc_u32 s39, s74, s11
	v_pk_mul_f32 v[18:19], v[120:121], v[120:121]
	v_pk_mul_f32 v[64:65], v[122:123], v[122:123]
	v_add_f32_e32 v18, v18, v19
	v_add_f32_e32 v18, v64, v18
	v_pk_mul_f32 v[66:67], v[108:109], v[108:109]
	v_add_f32_e32 v18, v65, v18
	v_add_f32_e32 v18, v66, v18
	v_pk_mul_f32 v[108:109], v[110:111], v[110:111]
	v_add_f32_e32 v18, v67, v18
	v_add_f32_e32 v18, v108, v18
	v_pk_mul_f32 v[100:101], v[100:101], v[100:101]
	v_add_f32_e32 v18, v109, v18
	v_add_f32_e32 v18, v100, v18
	v_pk_mul_f32 v[102:103], v[102:103], v[102:103]
	v_add_f32_e32 v18, v101, v18
	v_add_f32_e32 v18, v102, v18
	v_pk_mul_f32 v[110:111], v[124:125], v[124:125]
	v_add_f32_e32 v18, v103, v18
	v_add_f32_e32 v18, v110, v18
	v_pk_mul_f32 v[112:113], v[126:127], v[126:127]
	v_add_f32_e32 v18, v111, v18
	v_add_f32_e32 v18, v112, v18
	v_add_f32_e32 v18, v113, v18
	v_mov_b32_e32 v133, v18
	v_pk_mul_f32 v[18:19], v[92:93], v[92:93]
	v_pk_mul_f32 v[64:65], v[94:95], v[94:95]
	v_add_f32_e32 v18, v18, v19
	v_add_f32_e32 v18, v64, v18
	v_pk_mul_f32 v[66:67], v[88:89], v[88:89]
	v_add_f32_e32 v18, v65, v18
	v_add_f32_e32 v18, v66, v18
	v_pk_mul_f32 v[88:89], v[90:91], v[90:91]
	v_add_f32_e32 v18, v67, v18
	v_add_f32_e32 v18, v88, v18
	v_pk_mul_f32 v[90:91], v[96:97], v[96:97]
	v_add_f32_e32 v18, v89, v18
	v_add_f32_e32 v18, v90, v18
	v_pk_mul_f32 v[92:93], v[136:137], v[136:137]
	v_add_f32_e32 v18, v91, v18
	v_add_f32_e32 v18, v92, v18
	v_pk_mul_f32 v[94:95], v[98:99], v[98:99]
	v_add_f32_e32 v18, v93, v18
	v_add_f32_e32 v18, v94, v18
	v_pk_mul_f32 v[96:97], v[138:139], v[138:139]
	v_add_f32_e32 v18, v95, v18
	v_add_f32_e32 v18, v96, v18
	v_add_f32_e32 v18, v97, v18
	v_mov_b32_e32 v134, v18
	v_pk_mul_f32 v[18:19], v[74:75], v[74:75]
	v_pk_mul_f32 v[210:211], v[60:61], v[60:61]
	v_pk_mul_f32 v[64:65], v[80:81], v[80:81]
	v_pk_mul_f32 v[60:61], v[62:63], v[62:63]
	v_add_f32_e32 v18, v18, v19
	v_add_f32_e32 v210, v210, v211
	v_add_f32_e32 v18, v64, v18
	v_add_f32_e32 v210, v60, v210
	v_pk_mul_f32 v[66:67], v[78:79], v[78:79]
	v_pk_mul_f32 v[56:57], v[56:57], v[56:57]
	v_add_f32_e32 v18, v65, v18
	v_add_f32_e32 v210, v61, v210
	v_add_f32_e32 v18, v66, v18
	v_add_f32_e32 v210, v56, v210
	v_pk_mul_f32 v[74:75], v[82:83], v[82:83]
	v_pk_mul_f32 v[58:59], v[58:59], v[58:59]
	v_add_f32_e32 v18, v67, v18
	v_add_f32_e32 v210, v57, v210
	v_add_f32_e32 v18, v74, v18
	v_add_f32_e32 v210, v58, v210
	v_pk_mul_f32 v[78:79], v[84:85], v[84:85]
	v_pk_mul_f32 v[52:53], v[52:53], v[52:53]
	v_add_f32_e32 v18, v75, v18
	v_add_f32_e32 v210, v59, v210
	v_add_f32_e32 v18, v78, v18
	v_add_f32_e32 v210, v52, v210
	v_pk_mul_f32 v[80:81], v[128:129], v[128:129]
	v_pk_mul_f32 v[54:55], v[54:55], v[54:55]
	v_add_f32_e32 v18, v79, v18
	v_add_f32_e32 v210, v53, v210
	v_add_f32_e32 v18, v80, v18
	v_add_f32_e32 v210, v54, v210
	v_pk_mul_f32 v[82:83], v[86:87], v[86:87]
	v_pk_mul_f32 v[62:63], v[104:105], v[104:105]
	v_add_f32_e32 v18, v81, v18
	v_add_f32_e32 v210, v55, v210
	v_add_f32_e32 v18, v82, v18
	v_add_f32_e32 v210, v62, v210
	v_pk_mul_f32 v[84:85], v[130:131], v[130:131]
	v_pk_mul_f32 v[212:213], v[106:107], v[106:107]
	v_add_f32_e32 v18, v83, v18
	v_add_f32_e32 v210, v63, v210
	v_add_f32_e32 v18, v84, v18
	v_add_f32_e32 v210, v212, v210
	v_add_f32_e32 v18, v85, v18
	v_add_f32_e32 v210, v213, v210
	v_mov_b32_e32 v135, v18
	v_mov_b32_e32 v146, v210
	v_pk_mul_f32 v[18:19], v[44:45], v[44:45]
	v_pk_mul_f32 v[210:211], v[28:29], v[28:29]
	v_pk_mul_f32 v[44:45], v[46:47], v[46:47]
	v_pk_mul_f32 v[28:29], v[30:31], v[30:31]
	v_add_f32_e32 v18, v18, v19
	v_add_f32_e32 v210, v210, v211
	v_add_f32_e32 v18, v44, v18
	v_add_f32_e32 v210, v28, v210
	v_pk_mul_f32 v[40:41], v[40:41], v[40:41]
	v_pk_mul_f32 v[24:25], v[24:25], v[24:25]
	v_add_f32_e32 v18, v45, v18
	v_add_f32_e32 v210, v29, v210
	v_add_f32_e32 v18, v40, v18
	v_add_f32_e32 v210, v24, v210
	v_pk_mul_f32 v[42:43], v[42:43], v[42:43]
	v_pk_mul_f32 v[26:27], v[26:27], v[26:27]
	v_add_f32_e32 v18, v41, v18
	v_add_f32_e32 v210, v25, v210
	v_add_f32_e32 v18, v42, v18
	v_add_f32_e32 v210, v26, v210
	v_pk_mul_f32 v[36:37], v[36:37], v[36:37]
	v_pk_mul_f32 v[20:21], v[20:21], v[20:21]
	v_add_f32_e32 v18, v43, v18
	v_add_f32_e32 v210, v27, v210
	v_add_f32_e32 v18, v36, v18
	v_add_f32_e32 v210, v20, v210
	v_pk_mul_f32 v[38:39], v[38:39], v[38:39]
	v_pk_mul_f32 v[22:23], v[22:23], v[22:23]
	v_add_f32_e32 v18, v37, v18
	v_add_f32_e32 v210, v21, v210
	v_add_f32_e32 v18, v38, v18
	v_add_f32_e32 v210, v22, v210
	v_pk_mul_f32 v[46:47], v[48:49], v[48:49]
	v_pk_mul_f32 v[30:31], v[32:33], v[32:33]
	v_add_f32_e32 v18, v39, v18
	v_add_f32_e32 v210, v23, v210
	v_add_f32_e32 v18, v46, v18
	v_add_f32_e32 v210, v30, v210
	v_pk_mul_f32 v[48:49], v[50:51], v[50:51]
	v_pk_mul_f32 v[32:33], v[34:35], v[34:35]
	v_add_f32_e32 v18, v47, v18
	v_add_f32_e32 v210, v31, v210
	v_add_f32_e32 v18, v48, v18
	v_add_f32_e32 v210, v32, v210
	v_add_f32_e32 v18, v49, v18
	v_add_f32_e32 v210, v33, v210
	v_mov_b32_e32 v147, v18
	v_mov_b32_e32 v148, v210
	v_pk_mul_f32 v[12:13], v[12:13], v[12:13]
	v_pk_mul_f32 v[14:15], v[14:15], v[14:15]
	v_add_f32_e32 v12, v12, v13
	v_add_f32_e32 v12, v14, v12
	v_pk_mul_f32 v[8:9], v[8:9], v[8:9]
	v_add_f32_e32 v12, v15, v12
	v_add_f32_e32 v8, v8, v12
	v_pk_mul_f32 v[10:11], v[10:11], v[10:11]
	v_add_f32_e32 v8, v9, v8
	v_add_f32_e32 v8, v10, v8
	v_pk_mul_f32 v[4:5], v[4:5], v[4:5]
	v_add_f32_e32 v8, v11, v8
	v_add_f32_e32 v4, v4, v8
	v_pk_mul_f32 v[6:7], v[6:7], v[6:7]
	v_add_f32_e32 v4, v5, v4
	v_add_f32_e32 v4, v6, v4
	v_pk_mul_f32 v[0:1], v[0:1], v[0:1]
	v_add_f32_e32 v4, v7, v4
	v_add_f32_e32 v0, v0, v4
	v_pk_mul_f32 v[2:3], v[2:3], v[2:3]
	v_add_f32_e32 v0, v1, v0
	v_add_f32_e32 v0, v2, v0
	v_add_f32_e32 v0, v3, v0
	v_mov_b32_e32 v149, v0
	ds_bpermute_b32 v172, v16, v132
	ds_bpermute_b32 v173, v16, v133
	ds_bpermute_b32 v174, v16, v134
	ds_bpermute_b32 v175, v16, v135
	ds_bpermute_b32 v180, v16, v146
	ds_bpermute_b32 v181, v16, v147
	ds_bpermute_b32 v182, v16, v148
	ds_bpermute_b32 v183, v16, v149
	s_waitcnt lgkmcnt(0)
	v_add_f32_e32 v132, v132, v172
	v_add_f32_e32 v133, v133, v173
	v_add_f32_e32 v134, v134, v174
	v_add_f32_e32 v135, v135, v175
	v_add_f32_e32 v146, v146, v180
	v_add_f32_e32 v147, v147, v181
	v_add_f32_e32 v148, v148, v182
	v_add_f32_e32 v149, v149, v183
	ds_bpermute_b32 v172, v17, v132
	ds_bpermute_b32 v173, v17, v133
	ds_bpermute_b32 v174, v17, v134
	ds_bpermute_b32 v175, v17, v135
	ds_bpermute_b32 v180, v17, v146
	ds_bpermute_b32 v181, v17, v147
	ds_bpermute_b32 v182, v17, v148
	ds_bpermute_b32 v183, v17, v149
	s_and_saveexec_b64 s[46:47], s[42:43]
	s_cbranch_execz .LBB0_19
	s_waitcnt lgkmcnt(0)
	v_add_f32_e32 v132, v132, v172
	v_lshlrev_b64 v[18:19], 6, v[168:169]
	v_lshl_add_u64 v[18:19], s[38:39], 0, v[18:19]
	global_store_dword v[18:19], v132, off
	v_add_f32_e32 v133, v133, v173
	v_lshlrev_b64 v[18:19], 6, v[166:167]
	v_lshl_add_u64 v[18:19], s[38:39], 0, v[18:19]
	global_store_dword v[18:19], v133, off
	v_add_f32_e32 v134, v134, v174
	v_lshlrev_b64 v[18:19], 6, v[164:165]
	v_lshl_add_u64 v[18:19], s[38:39], 0, v[18:19]
	global_store_dword v[18:19], v134, off
	v_add_f32_e32 v135, v135, v175
	v_lshlrev_b64 v[18:19], 6, v[162:163]
	v_lshl_add_u64 v[18:19], s[38:39], 0, v[18:19]
	global_store_dword v[18:19], v135, off
	v_add_f32_e32 v146, v146, v180
	v_lshlrev_b64 v[18:19], 6, v[76:77]
	v_lshl_add_u64 v[18:19], s[38:39], 0, v[18:19]
	global_store_dword v[18:19], v146, off
	v_add_f32_e32 v147, v147, v181
	v_lshlrev_b64 v[18:19], 6, v[72:73]
	v_lshl_add_u64 v[18:19], s[38:39], 0, v[18:19]
	global_store_dword v[18:19], v147, off
	v_add_f32_e32 v148, v148, v182
	v_lshlrev_b64 v[18:19], 6, v[70:71]
	v_lshl_add_u64 v[18:19], s[38:39], 0, v[18:19]
	global_store_dword v[18:19], v148, off
	v_add_f32_e32 v149, v149, v183
	v_lshlrev_b64 v[18:19], 6, v[68:69]
	v_lshl_add_u64 v[18:19], s[38:39], 0, v[18:19]
	global_store_dword v[18:19], v149, off
	s_branch .LBB0_19

.Lm4bp_77:
	s_waitcnt lgkmcnt(0)
	s_mov_b32 s100, 0
	s_barrier
	s_nop 0
	v_mfma_f32_16x16x32_bf16 v[60:63], v[158:161], v[174:177], 0
	v_mfma_f32_16x16x32_bf16 v[56:59], v[166:169], v[174:177], 0
	v_mfma_f32_16x16x32_bf16 v[52:55], v[158:161], v[182:185], 0
	v_mfma_f32_16x16x32_bf16 v[48:51], v[166:169], v[182:185], 0
	v_mfma_f32_16x16x32_bf16 v[44:47], v[158:161], v[210:213], 0
	v_mfma_f32_16x16x32_bf16 v[40:43], v[166:169], v[210:213], 0
	v_mfma_f32_16x16x32_bf16 v[36:39], v[158:161], v[218:221], 0
	v_mfma_f32_16x16x32_bf16 v[32:35], v[166:169], v[218:221], 0
	v_mfma_f32_16x16x32_bf16 v[60:63], v[162:165], v[178:181], v[60:63]
	v_mfma_f32_16x16x32_bf16 v[56:59], v[170:173], v[178:181], v[56:59]
	v_mfma_f32_16x16x32_bf16 v[52:55], v[162:165], v[206:209], v[52:55]
	v_mfma_f32_16x16x32_bf16 v[48:51], v[170:173], v[206:209], v[48:51]
	v_mfma_f32_16x16x32_bf16 v[44:47], v[162:165], v[214:217], v[44:47]
	v_mfma_f32_16x16x32_bf16 v[40:43], v[170:173], v[214:217], v[40:43]
	v_mfma_f32_16x16x32_bf16 v[36:39], v[162:165], v[222:225], v[36:39]
	v_mfma_f32_16x16x32_bf16 v[32:35], v[170:173], v[222:225], v[32:35]
	v_mfma_f32_16x16x32_bf16 v[28:31], v[226:229], v[174:177], 0
	v_mfma_f32_16x16x32_bf16 v[24:27], v[234:237], v[174:177], 0
	v_mfma_f32_16x16x32_bf16 v[20:23], v[226:229], v[182:185], 0
	v_mfma_f32_16x16x32_bf16 v[16:19], v[234:237], v[182:185], 0
	v_mfma_f32_16x16x32_bf16 v[12:15], v[226:229], v[210:213], 0
	v_mfma_f32_16x16x32_bf16 v[8:11], v[234:237], v[210:213], 0
	v_mfma_f32_16x16x32_bf16 v[4:7], v[226:229], v[218:221], 0
	v_mfma_f32_16x16x32_bf16 v[0:3], v[234:237], v[218:221], 0
	v_mfma_f32_16x16x32_bf16 v[28:31], v[230:233], v[178:181], v[28:31]
	v_mfma_f32_16x16x32_bf16 v[24:27], v[238:241], v[178:181], v[24:27]
	v_mfma_f32_16x16x32_bf16 v[20:23], v[230:233], v[206:209], v[20:23]
	v_mfma_f32_16x16x32_bf16 v[16:19], v[238:241], v[206:209], v[16:19]
	v_mfma_f32_16x16x32_bf16 v[12:15], v[230:233], v[214:217], v[12:15]
	v_mfma_f32_16x16x32_bf16 v[8:11], v[238:241], v[214:217], v[8:11]
	v_mfma_f32_16x16x32_bf16 v[4:7], v[230:233], v[222:225], v[4:7]
	v_mfma_f32_16x16x32_bf16 v[0:3], v[238:241], v[222:225], v[0:3]
	s_barrier
	s_add_i32 s6, 0, 0x18000
	v_add_u32_e32 v170, s6, v154
	ds_read_b128 v[158:161], v170
	ds_read_b128 v[162:165], v170 offset:1024
	ds_read_b128 v[166:169], v170 offset:2048
	ds_read_b128 v[170:173], v170 offset:3072
	s_add_u32 s54, s54, 0x40000
	s_addc_u32 s55, s55, 0
	s_mov_b32 m0, s70
	v_lshl_add_u64 v[226:227], s[54:55], 0, v[128:129]
	ds_read_b128 v[174:177], v157 offset:32768
	ds_read_b128 v[178:181], v157 offset:33792
	ds_read_b128 v[182:185], v157 offset:34816
	ds_read_b128 v[206:209], v157 offset:35840
	ds_read_b128 v[210:213], v157 offset:36864
	ds_read_b128 v[214:217], v157 offset:37888
	ds_read_b128 v[218:221], v157 offset:38912
	ds_read_b128 v[222:225], v157 offset:39936
	global_load_lds_dwordx4 v[226:227], off
	v_lshl_add_u64 v[226:227], s[54:55], 0, v[130:131]
	s_mov_b32 m0, s71
	s_nop 0
	global_load_lds_dwordx4 v[226:227], off
	s_add_i32 s19, 0, 0x1c000
	v_add_u32_e32 v192, s19, v154
	ds_read_b128 v[226:229], v192
	ds_read_b128 v[230:233], v192 offset:1024
	ds_read_b128 v[234:237], v192 offset:2048
	ds_read_b128 v[238:241], v192 offset:3072
	s_waitcnt vmcnt(8)
	s_waitcnt lgkmcnt(0)
	s_barrier
	v_mfma_f32_16x16x32_bf16 v[124:127], v[158:161], v[174:177], v[124:127]
	v_mfma_f32_16x16x32_bf16 v[120:123], v[166:169], v[174:177], v[120:123]
	v_mfma_f32_16x16x32_bf16 v[116:119], v[158:161], v[182:185], v[116:119]
	v_mfma_f32_16x16x32_bf16 v[112:115], v[166:169], v[182:185], v[112:115]
	v_mfma_f32_16x16x32_bf16 v[108:111], v[158:161], v[210:213], v[108:111]
	v_mfma_f32_16x16x32_bf16 v[104:107], v[166:169], v[210:213], v[104:107]
	v_mfma_f32_16x16x32_bf16 v[100:103], v[158:161], v[218:221], v[100:103]
	v_mfma_f32_16x16x32_bf16 v[96:99], v[166:169], v[218:221], v[96:99]
	v_mfma_f32_16x16x32_bf16 v[124:127], v[162:165], v[178:181], v[124:127]
	v_mfma_f32_16x16x32_bf16 v[120:123], v[170:173], v[178:181], v[120:123]
	v_mfma_f32_16x16x32_bf16 v[116:119], v[162:165], v[206:209], v[116:119]
	v_mfma_f32_16x16x32_bf16 v[112:115], v[170:173], v[206:209], v[112:115]
	v_mfma_f32_16x16x32_bf16 v[108:111], v[162:165], v[214:217], v[108:111]
	v_mfma_f32_16x16x32_bf16 v[104:107], v[170:173], v[214:217], v[104:107]
	v_mfma_f32_16x16x32_bf16 v[100:103], v[162:165], v[222:225], v[100:103]
	v_mfma_f32_16x16x32_bf16 v[96:99], v[170:173], v[222:225], v[96:99]
	v_mfma_f32_16x16x32_bf16 v[92:95], v[226:229], v[174:177], v[92:95]
	v_mfma_f32_16x16x32_bf16 v[88:91], v[234:237], v[174:177], v[88:91]
	v_mfma_f32_16x16x32_bf16 v[84:87], v[226:229], v[182:185], v[84:87]
	v_mfma_f32_16x16x32_bf16 v[80:83], v[234:237], v[182:185], v[80:83]
	v_mfma_f32_16x16x32_bf16 v[76:79], v[226:229], v[210:213], v[76:79]
	v_mfma_f32_16x16x32_bf16 v[72:75], v[234:237], v[210:213], v[72:75]
	v_mfma_f32_16x16x32_bf16 v[68:71], v[226:229], v[218:221], v[68:71]
	v_mfma_f32_16x16x32_bf16 v[64:67], v[234:237], v[218:221], v[64:67]
	v_mfma_f32_16x16x32_bf16 v[92:95], v[230:233], v[178:181], v[92:95]
	v_mfma_f32_16x16x32_bf16 v[88:91], v[238:241], v[178:181], v[88:91]
	v_mfma_f32_16x16x32_bf16 v[84:87], v[230:233], v[206:209], v[84:87]
	v_mfma_f32_16x16x32_bf16 v[80:83], v[238:241], v[206:209], v[80:83]
	v_mfma_f32_16x16x32_bf16 v[76:79], v[230:233], v[214:217], v[76:79]
	v_mfma_f32_16x16x32_bf16 v[72:75], v[238:241], v[214:217], v[72:75]
	v_mfma_f32_16x16x32_bf16 v[68:71], v[230:233], v[222:225], v[68:71]
	v_mfma_f32_16x16x32_bf16 v[64:67], v[238:241], v[222:225], v[64:67]
	s_barrier
	s_add_i32 s6, s6, s59
	v_lshl_add_u64 v[146:147], v[146:147], 0, s[36:37]
	s_mov_b32 m0, s6
	s_nop 0
	global_load_lds_dwordx4 v[146:147], off
	v_lshl_add_u64 v[146:147], v[148:149], 0, s[36:37]
	s_add_i32 m0, s6, 0x2000
	s_nop 0
	global_load_lds_dwordx4 v[146:147], off
	s_mov_b32 m0, s72
	v_lshl_add_u64 v[146:147], v[194:195], 0, s[36:37]
	ds_read_b128 v[174:177], v157 offset:49152
	ds_read_b128 v[178:181], v157 offset:50176
	ds_read_b128 v[182:185], v157 offset:51200
	ds_read_b128 v[206:209], v157 offset:52224
	ds_read_b128 v[210:213], v157 offset:53248
	ds_read_b128 v[214:217], v157 offset:54272
	ds_read_b128 v[218:221], v157 offset:55296
	ds_read_b128 v[222:225], v157 offset:56320
	global_load_lds_dwordx4 v[146:147], off
	v_lshl_add_u64 v[146:147], v[196:197], 0, s[36:37]
	s_mov_b32 m0, s73
	s_nop 0
	global_load_lds_dwordx4 v[146:147], off
	s_add_u32 s52, s52, 0x40080
	s_addc_u32 s53, s53, 0
	s_add_i32 s6, s19, s59
	v_lshl_add_u64 v[146:147], s[52:53], 0, v[140:141]
	s_mov_b32 m0, s6
	s_nop 0
	global_load_lds_dwordx4 v[146:147], off
	v_lshl_add_u64 v[146:147], s[52:53], 0, v[132:133]
	s_add_i32 m0, s6, 0x2000
	s_nop 0
	global_load_lds_dwordx4 v[146:147], off
	s_add_i32 s81, s81, 2
	s_add_u32 s50, s50, 0x100
	s_addc_u32 s51, s51, 0
	s_cmp_gt_u32 s81, 13
	s_nop 0
	s_waitcnt vmcnt(8)
	s_waitcnt lgkmcnt(0)
	s_barrier
	v_mfma_f32_16x16x32_bf16 v[60:63], v[158:161], v[174:177], v[60:63]
	v_mfma_f32_16x16x32_bf16 v[56:59], v[166:169], v[174:177], v[56:59]
	v_mfma_f32_16x16x32_bf16 v[52:55], v[158:161], v[182:185], v[52:55]
	v_mfma_f32_16x16x32_bf16 v[48:51], v[166:169], v[182:185], v[48:51]
	v_mfma_f32_16x16x32_bf16 v[44:47], v[158:161], v[210:213], v[44:47]
	v_mfma_f32_16x16x32_bf16 v[40:43], v[166:169], v[210:213], v[40:43]
	v_mfma_f32_16x16x32_bf16 v[36:39], v[158:161], v[218:221], v[36:39]
	v_mfma_f32_16x16x32_bf16 v[32:35], v[166:169], v[218:221], v[32:35]
	v_mfma_f32_16x16x32_bf16 v[60:63], v[162:165], v[178:181], v[60:63]
	v_mfma_f32_16x16x32_bf16 v[56:59], v[170:173], v[178:181], v[56:59]
	v_mfma_f32_16x16x32_bf16 v[52:55], v[162:165], v[206:209], v[52:55]
	v_mfma_f32_16x16x32_bf16 v[48:51], v[170:173], v[206:209], v[48:51]
	v_mfma_f32_16x16x32_bf16 v[44:47], v[162:165], v[214:217], v[44:47]
	v_mfma_f32_16x16x32_bf16 v[40:43], v[170:173], v[214:217], v[40:43]
	v_mfma_f32_16x16x32_bf16 v[36:39], v[162:165], v[222:225], v[36:39]
	v_mfma_f32_16x16x32_bf16 v[32:35], v[170:173], v[222:225], v[32:35]
	v_mfma_f32_16x16x32_bf16 v[28:31], v[226:229], v[174:177], v[28:31]
	v_mfma_f32_16x16x32_bf16 v[24:27], v[234:237], v[174:177], v[24:27]
	v_mfma_f32_16x16x32_bf16 v[20:23], v[226:229], v[182:185], v[20:23]
	v_mfma_f32_16x16x32_bf16 v[16:19], v[234:237], v[182:185], v[16:19]
	v_mfma_f32_16x16x32_bf16 v[12:15], v[226:229], v[210:213], v[12:15]
	v_mfma_f32_16x16x32_bf16 v[8:11], v[234:237], v[210:213], v[8:11]
	v_mfma_f32_16x16x32_bf16 v[4:7], v[226:229], v[218:221], v[4:7]
	v_mfma_f32_16x16x32_bf16 v[0:3], v[234:237], v[218:221], v[0:3]
	v_mfma_f32_16x16x32_bf16 v[28:31], v[230:233], v[178:181], v[28:31]
	v_mfma_f32_16x16x32_bf16 v[24:27], v[238:241], v[178:181], v[24:27]
	v_mfma_f32_16x16x32_bf16 v[20:23], v[230:233], v[206:209], v[20:23]
	v_mfma_f32_16x16x32_bf16 v[16:19], v[238:241], v[206:209], v[16:19]
	v_mfma_f32_16x16x32_bf16 v[12:15], v[230:233], v[214:217], v[12:15]
	v_mfma_f32_16x16x32_bf16 v[8:11], v[238:241], v[214:217], v[8:11]
	v_mfma_f32_16x16x32_bf16 v[4:7], v[230:233], v[222:225], v[4:7]
	v_mfma_f32_16x16x32_bf16 v[0:3], v[238:241], v[222:225], v[0:3]
	s_barrier
	.p2align	6
.LBB0_77:
	s_add_u32 s6, s26, s50
	s_addc_u32 s19, s27, s51
	s_add_u32 s6, s6, 0x100
	s_addc_u32 s19, s19, 0
	s_add_u32 s23, s10, s50
	s_addc_u32 s52, s11, s51
	s_add_i32 s82, 0, 0x10000
	v_add_u32_e32 v146, s82, v154
	ds_read_b128 v[158:161], v146
	ds_read_b128 v[162:165], v146 offset:1024
	ds_read_b128 v[166:169], v146 offset:2048
	ds_read_b128 v[170:173], v146 offset:3072
	s_cmpk_eq_i32 s50, 0x700
	s_cselect_b32 s55, s12, s19
	s_cselect_b32 s54, s31, s6
	s_cselect_b32 s53, s35, s52
	s_cselect_b32 s52, s39, s23
	v_lshl_add_u64 v[146:147], v[150:151], 0, s[50:51]
	s_add_i32 m0, s68, 0xc000
	ds_read_b128 v[174:177], v157
	ds_read_b128 v[178:181], v157 offset:1024
	ds_read_b128 v[182:185], v157 offset:2048
	ds_read_b128 v[206:209], v157 offset:3072
	ds_read_b128 v[210:213], v157 offset:4096
	ds_read_b128 v[214:217], v157 offset:5120
	ds_read_b128 v[218:221], v157 offset:6144
	ds_read_b128 v[222:225], v157 offset:7168
	global_load_lds_dwordx4 v[146:147], off
	v_lshl_add_u64 v[146:147], v[152:153], 0, s[50:51]
	s_add_i32 m0, s68, 0xe000
	s_nop 0
	global_load_lds_dwordx4 v[146:147], off
	s_add_i32 s6, 0, 0x14000
	v_add_u32_e32 v146, s6, v154
	ds_read_b128 v[226:229], v146
	ds_read_b128 v[230:233], v146 offset:1024
	ds_read_b128 v[234:237], v146 offset:2048
	ds_read_b128 v[238:241], v146 offset:3072
	s_waitcnt vmcnt(8)
	s_waitcnt lgkmcnt(0)
	s_barrier
	v_mfma_f32_16x16x32_bf16 v[124:127], v[158:161], v[174:177], v[124:127]
	v_mfma_f32_16x16x32_bf16 v[120:123], v[166:169], v[174:177], v[120:123]
	v_mfma_f32_16x16x32_bf16 v[116:119], v[158:161], v[182:185], v[116:119]
	v_mfma_f32_16x16x32_bf16 v[112:115], v[166:169], v[182:185], v[112:115]
	v_mfma_f32_16x16x32_bf16 v[108:111], v[158:161], v[210:213], v[108:111]
	v_mfma_f32_16x16x32_bf16 v[104:107], v[166:169], v[210:213], v[104:107]
	v_mfma_f32_16x16x32_bf16 v[100:103], v[158:161], v[218:221], v[100:103]
	v_mfma_f32_16x16x32_bf16 v[96:99], v[166:169], v[218:221], v[96:99]
	v_mfma_f32_16x16x32_bf16 v[124:127], v[162:165], v[178:181], v[124:127]
	v_mfma_f32_16x16x32_bf16 v[120:123], v[170:173], v[178:181], v[120:123]
	v_mfma_f32_16x16x32_bf16 v[116:119], v[162:165], v[206:209], v[116:119]
	v_mfma_f32_16x16x32_bf16 v[112:115], v[170:173], v[206:209], v[112:115]
	v_mfma_f32_16x16x32_bf16 v[108:111], v[162:165], v[214:217], v[108:111]
	v_mfma_f32_16x16x32_bf16 v[104:107], v[170:173], v[214:217], v[104:107]
	v_mfma_f32_16x16x32_bf16 v[100:103], v[162:165], v[222:225], v[100:103]
	v_mfma_f32_16x16x32_bf16 v[96:99], v[170:173], v[222:225], v[96:99]
	v_mfma_f32_16x16x32_bf16 v[92:95], v[226:229], v[174:177], v[92:95]
	v_mfma_f32_16x16x32_bf16 v[88:91], v[234:237], v[174:177], v[88:91]
	v_mfma_f32_16x16x32_bf16 v[84:87], v[226:229], v[182:185], v[84:87]
	v_mfma_f32_16x16x32_bf16 v[80:83], v[234:237], v[182:185], v[80:83]
	v_mfma_f32_16x16x32_bf16 v[76:79], v[226:229], v[210:213], v[76:79]
	v_mfma_f32_16x16x32_bf16 v[72:75], v[234:237], v[210:213], v[72:75]
	v_mfma_f32_16x16x32_bf16 v[68:71], v[226:229], v[218:221], v[68:71]
	v_mfma_f32_16x16x32_bf16 v[64:67], v[234:237], v[218:221], v[64:67]
	v_mfma_f32_16x16x32_bf16 v[92:95], v[230:233], v[178:181], v[92:95]
	v_mfma_f32_16x16x32_bf16 v[88:91], v[238:241], v[178:181], v[88:91]
	v_mfma_f32_16x16x32_bf16 v[84:87], v[230:233], v[206:209], v[84:87]
	v_mfma_f32_16x16x32_bf16 v[80:83], v[238:241], v[206:209], v[80:83]
	v_mfma_f32_16x16x32_bf16 v[76:79], v[230:233], v[214:217], v[76:79]
	v_mfma_f32_16x16x32_bf16 v[72:75], v[238:241], v[214:217], v[72:75]
	v_mfma_f32_16x16x32_bf16 v[68:71], v[230:233], v[222:225], v[68:71]
	v_mfma_f32_16x16x32_bf16 v[64:67], v[238:241], v[222:225], v[64:67]
	s_barrier
	s_add_i32 s19, s82, s59
	v_lshl_add_u64 v[146:147], s[52:53], 0, v[140:141]
	s_mov_b32 m0, s19
	v_lshl_add_u64 v[148:149], s[52:53], 0, v[132:133]
	global_load_lds_dwordx4 v[146:147], off
	s_add_i32 m0, s19, 0x2000
	s_nop 0
	global_load_lds_dwordx4 v[148:149], off
	s_mov_b32 m0, s68
	v_lshl_add_u64 v[194:195], s[54:55], 0, v[128:129]
	ds_read_b128 v[174:177], v157 offset:16384
	ds_read_b128 v[178:181], v157 offset:17408
	ds_read_b128 v[182:185], v157 offset:18432
	ds_read_b128 v[206:209], v157 offset:19456
	ds_read_b128 v[210:213], v157 offset:20480
	ds_read_b128 v[214:217], v157 offset:21504
	ds_read_b128 v[218:221], v157 offset:22528
	ds_read_b128 v[222:225], v157 offset:23552
	global_load_lds_dwordx4 v[194:195], off
	v_lshl_add_u64 v[196:197], s[54:55], 0, v[130:131]
	s_mov_b32 m0, s69
	s_nop 0
	global_load_lds_dwordx4 v[196:197], off
	s_add_u32 s82, s52, 0x40000
	s_addc_u32 s83, s53, 0
	s_add_i32 s6, s6, s59
	v_lshl_add_u64 v[250:251], s[82:83], 0, v[140:141]
	s_mov_b32 m0, s6
	s_nop 0
	global_load_lds_dwordx4 v[250:251], off
	v_lshl_add_u64 v[250:251], s[82:83], 0, v[132:133]
	s_add_i32 m0, s6, 0x2000
	s_nop 0
	global_load_lds_dwordx4 v[250:251], off
	s_nop 0
	s_waitcnt vmcnt(8)
	s_waitcnt lgkmcnt(0)
	s_barrier
	v_mfma_f32_16x16x32_bf16 v[60:63], v[158:161], v[174:177], v[60:63]
	v_mfma_f32_16x16x32_bf16 v[56:59], v[166:169], v[174:177], v[56:59]
	v_mfma_f32_16x16x32_bf16 v[52:55], v[158:161], v[182:185], v[52:55]
	v_mfma_f32_16x16x32_bf16 v[48:51], v[166:169], v[182:185], v[48:51]
	v_mfma_f32_16x16x32_bf16 v[44:47], v[158:161], v[210:213], v[44:47]
	v_mfma_f32_16x16x32_bf16 v[40:43], v[166:169], v[210:213], v[40:43]
	v_mfma_f32_16x16x32_bf16 v[36:39], v[158:161], v[218:221], v[36:39]
	v_mfma_f32_16x16x32_bf16 v[32:35], v[166:169], v[218:221], v[32:35]
	v_mfma_f32_16x16x32_bf16 v[60:63], v[162:165], v[178:181], v[60:63]
	v_mfma_f32_16x16x32_bf16 v[56:59], v[170:173], v[178:181], v[56:59]
	v_mfma_f32_16x16x32_bf16 v[52:55], v[162:165], v[206:209], v[52:55]
	v_mfma_f32_16x16x32_bf16 v[48:51], v[170:173], v[206:209], v[48:51]
	v_mfma_f32_16x16x32_bf16 v[44:47], v[162:165], v[214:217], v[44:47]
	v_mfma_f32_16x16x32_bf16 v[40:43], v[170:173], v[214:217], v[40:43]
	v_mfma_f32_16x16x32_bf16 v[36:39], v[162:165], v[222:225], v[36:39]
	v_mfma_f32_16x16x32_bf16 v[32:35], v[170:173], v[222:225], v[32:35]
	v_mfma_f32_16x16x32_bf16 v[28:31], v[226:229], v[174:177], v[28:31]
	v_mfma_f32_16x16x32_bf16 v[24:27], v[234:237], v[174:177], v[24:27]
	v_mfma_f32_16x16x32_bf16 v[20:23], v[226:229], v[182:185], v[20:23]
	v_mfma_f32_16x16x32_bf16 v[16:19], v[234:237], v[182:185], v[16:19]
	v_mfma_f32_16x16x32_bf16 v[12:15], v[226:229], v[210:213], v[12:15]
	v_mfma_f32_16x16x32_bf16 v[8:11], v[234:237], v[210:213], v[8:11]
	v_mfma_f32_16x16x32_bf16 v[4:7], v[226:229], v[218:221], v[4:7]
	v_mfma_f32_16x16x32_bf16 v[0:3], v[234:237], v[218:221], v[0:3]
	v_mfma_f32_16x16x32_bf16 v[28:31], v[230:233], v[178:181], v[28:31]
	v_mfma_f32_16x16x32_bf16 v[24:27], v[238:241], v[178:181], v[24:27]
	v_mfma_f32_16x16x32_bf16 v[20:23], v[230:233], v[206:209], v[20:23]
	v_mfma_f32_16x16x32_bf16 v[16:19], v[238:241], v[206:209], v[16:19]
	v_mfma_f32_16x16x32_bf16 v[12:15], v[230:233], v[214:217], v[12:15]
	v_mfma_f32_16x16x32_bf16 v[8:11], v[238:241], v[214:217], v[8:11]
	v_mfma_f32_16x16x32_bf16 v[4:7], v[230:233], v[222:225], v[4:7]
	v_mfma_f32_16x16x32_bf16 v[0:3], v[238:241], v[222:225], v[0:3]
	s_barrier
	s_add_i32 s6, 0, 0x18000
	v_add_u32_e32 v170, s6, v154
	ds_read_b128 v[158:161], v170
	ds_read_b128 v[162:165], v170 offset:1024
	ds_read_b128 v[166:169], v170 offset:2048
	ds_read_b128 v[170:173], v170 offset:3072
	s_add_u32 s54, s54, 0x40000
	s_addc_u32 s55, s55, 0
	s_mov_b32 m0, s70
	v_lshl_add_u64 v[226:227], s[54:55], 0, v[128:129]
	ds_read_b128 v[174:177], v157 offset:32768
	ds_read_b128 v[178:181], v157 offset:33792
	ds_read_b128 v[182:185], v157 offset:34816
	ds_read_b128 v[206:209], v157 offset:35840
	ds_read_b128 v[210:213], v157 offset:36864
	ds_read_b128 v[214:217], v157 offset:37888
	ds_read_b128 v[218:221], v157 offset:38912
	ds_read_b128 v[222:225], v157 offset:39936
	global_load_lds_dwordx4 v[226:227], off
	v_lshl_add_u64 v[226:227], s[54:55], 0, v[130:131]
	s_mov_b32 m0, s71
	s_nop 0
	global_load_lds_dwordx4 v[226:227], off
	s_add_i32 s19, 0, 0x1c000
	v_add_u32_e32 v192, s19, v154
	ds_read_b128 v[226:229], v192
	ds_read_b128 v[230:233], v192 offset:1024
	ds_read_b128 v[234:237], v192 offset:2048
	ds_read_b128 v[238:241], v192 offset:3072
	s_waitcnt vmcnt(8)
	s_waitcnt lgkmcnt(0)
	s_barrier
	v_mfma_f32_16x16x32_bf16 v[124:127], v[158:161], v[174:177], v[124:127]
	v_mfma_f32_16x16x32_bf16 v[120:123], v[166:169], v[174:177], v[120:123]
	v_mfma_f32_16x16x32_bf16 v[116:119], v[158:161], v[182:185], v[116:119]
	v_mfma_f32_16x16x32_bf16 v[112:115], v[166:169], v[182:185], v[112:115]
	v_mfma_f32_16x16x32_bf16 v[108:111], v[158:161], v[210:213], v[108:111]
	v_mfma_f32_16x16x32_bf16 v[104:107], v[166:169], v[210:213], v[104:107]
	v_mfma_f32_16x16x32_bf16 v[100:103], v[158:161], v[218:221], v[100:103]
	v_mfma_f32_16x16x32_bf16 v[96:99], v[166:169], v[218:221], v[96:99]
	v_mfma_f32_16x16x32_bf16 v[124:127], v[162:165], v[178:181], v[124:127]
	v_mfma_f32_16x16x32_bf16 v[120:123], v[170:173], v[178:181], v[120:123]
	v_mfma_f32_16x16x32_bf16 v[116:119], v[162:165], v[206:209], v[116:119]
	v_mfma_f32_16x16x32_bf16 v[112:115], v[170:173], v[206:209], v[112:115]
	v_mfma_f32_16x16x32_bf16 v[108:111], v[162:165], v[214:217], v[108:111]
	v_mfma_f32_16x16x32_bf16 v[104:107], v[170:173], v[214:217], v[104:107]
	v_mfma_f32_16x16x32_bf16 v[100:103], v[162:165], v[222:225], v[100:103]
	v_mfma_f32_16x16x32_bf16 v[96:99], v[170:173], v[222:225], v[96:99]
	v_mfma_f32_16x16x32_bf16 v[92:95], v[226:229], v[174:177], v[92:95]
	v_mfma_f32_16x16x32_bf16 v[88:91], v[234:237], v[174:177], v[88:91]
	v_mfma_f32_16x16x32_bf16 v[84:87], v[226:229], v[182:185], v[84:87]
	v_mfma_f32_16x16x32_bf16 v[80:83], v[234:237], v[182:185], v[80:83]
	v_mfma_f32_16x16x32_bf16 v[76:79], v[226:229], v[210:213], v[76:79]
	v_mfma_f32_16x16x32_bf16 v[72:75], v[234:237], v[210:213], v[72:75]
	v_mfma_f32_16x16x32_bf16 v[68:71], v[226:229], v[218:221], v[68:71]
	v_mfma_f32_16x16x32_bf16 v[64:67], v[234:237], v[218:221], v[64:67]
	v_mfma_f32_16x16x32_bf16 v[92:95], v[230:233], v[178:181], v[92:95]
	v_mfma_f32_16x16x32_bf16 v[88:91], v[238:241], v[178:181], v[88:91]
	v_mfma_f32_16x16x32_bf16 v[84:87], v[230:233], v[206:209], v[84:87]
	v_mfma_f32_16x16x32_bf16 v[80:83], v[238:241], v[206:209], v[80:83]
	v_mfma_f32_16x16x32_bf16 v[76:79], v[230:233], v[214:217], v[76:79]
	v_mfma_f32_16x16x32_bf16 v[72:75], v[238:241], v[214:217], v[72:75]
	v_mfma_f32_16x16x32_bf16 v[68:71], v[230:233], v[222:225], v[68:71]
	v_mfma_f32_16x16x32_bf16 v[64:67], v[238:241], v[222:225], v[64:67]
	s_barrier
	s_add_i32 s6, s6, s59
	v_lshl_add_u64 v[146:147], v[146:147], 0, s[36:37]
	s_mov_b32 m0, s6
	s_nop 0
	global_load_lds_dwordx4 v[146:147], off
	v_lshl_add_u64 v[146:147], v[148:149], 0, s[36:37]
	s_add_i32 m0, s6, 0x2000
	s_nop 0
	global_load_lds_dwordx4 v[146:147], off
	s_mov_b32 m0, s72
	v_lshl_add_u64 v[146:147], v[194:195], 0, s[36:37]
	ds_read_b128 v[174:177], v157 offset:49152
	ds_read_b128 v[178:181], v157 offset:50176
	ds_read_b128 v[182:185], v157 offset:51200
	ds_read_b128 v[206:209], v157 offset:52224
	ds_read_b128 v[210:213], v157 offset:53248
	ds_read_b128 v[214:217], v157 offset:54272
	ds_read_b128 v[218:221], v157 offset:55296
	ds_read_b128 v[222:225], v157 offset:56320
	global_load_lds_dwordx4 v[146:147], off
	v_lshl_add_u64 v[146:147], v[196:197], 0, s[36:37]
	s_mov_b32 m0, s73
	s_nop 0
	global_load_lds_dwordx4 v[146:147], off
	s_add_u32 s52, s52, 0x40080
	s_addc_u32 s53, s53, 0
	s_add_i32 s6, s19, s59
	v_lshl_add_u64 v[146:147], s[52:53], 0, v[140:141]
	s_mov_b32 m0, s6
	s_nop 0
	global_load_lds_dwordx4 v[146:147], off
	v_lshl_add_u64 v[146:147], s[52:53], 0, v[132:133]
	s_add_i32 m0, s6, 0x2000
	s_nop 0
	global_load_lds_dwordx4 v[146:147], off
	s_add_i32 s81, s81, 2
	s_add_u32 s50, s50, 0x100
	s_addc_u32 s51, s51, 0
	s_cmp_gt_u32 s81, 13
	s_nop 0
	s_waitcnt vmcnt(8)
	s_waitcnt lgkmcnt(0)
	s_barrier
	v_mfma_f32_16x16x32_bf16 v[60:63], v[158:161], v[174:177], v[60:63]
	v_mfma_f32_16x16x32_bf16 v[56:59], v[166:169], v[174:177], v[56:59]
	v_mfma_f32_16x16x32_bf16 v[52:55], v[158:161], v[182:185], v[52:55]
	v_mfma_f32_16x16x32_bf16 v[48:51], v[166:169], v[182:185], v[48:51]
	v_mfma_f32_16x16x32_bf16 v[44:47], v[158:161], v[210:213], v[44:47]
	v_mfma_f32_16x16x32_bf16 v[40:43], v[166:169], v[210:213], v[40:43]
	v_mfma_f32_16x16x32_bf16 v[36:39], v[158:161], v[218:221], v[36:39]
	v_mfma_f32_16x16x32_bf16 v[32:35], v[166:169], v[218:221], v[32:35]
	v_mfma_f32_16x16x32_bf16 v[60:63], v[162:165], v[178:181], v[60:63]
	v_mfma_f32_16x16x32_bf16 v[56:59], v[170:173], v[178:181], v[56:59]
	v_mfma_f32_16x16x32_bf16 v[52:55], v[162:165], v[206:209], v[52:55]
	v_mfma_f32_16x16x32_bf16 v[48:51], v[170:173], v[206:209], v[48:51]
	v_mfma_f32_16x16x32_bf16 v[44:47], v[162:165], v[214:217], v[44:47]
	v_mfma_f32_16x16x32_bf16 v[40:43], v[170:173], v[214:217], v[40:43]
	v_mfma_f32_16x16x32_bf16 v[36:39], v[162:165], v[222:225], v[36:39]
	v_mfma_f32_16x16x32_bf16 v[32:35], v[170:173], v[222:225], v[32:35]
	v_mfma_f32_16x16x32_bf16 v[28:31], v[226:229], v[174:177], v[28:31]
	v_mfma_f32_16x16x32_bf16 v[24:27], v[234:237], v[174:177], v[24:27]
	v_mfma_f32_16x16x32_bf16 v[20:23], v[226:229], v[182:185], v[20:23]
	v_mfma_f32_16x16x32_bf16 v[16:19], v[234:237], v[182:185], v[16:19]
	v_mfma_f32_16x16x32_bf16 v[12:15], v[226:229], v[210:213], v[12:15]
	v_mfma_f32_16x16x32_bf16 v[8:11], v[234:237], v[210:213], v[8:11]
	v_mfma_f32_16x16x32_bf16 v[4:7], v[226:229], v[218:221], v[4:7]
	v_mfma_f32_16x16x32_bf16 v[0:3], v[234:237], v[218:221], v[0:3]
	v_mfma_f32_16x16x32_bf16 v[28:31], v[230:233], v[178:181], v[28:31]
	v_mfma_f32_16x16x32_bf16 v[24:27], v[238:241], v[178:181], v[24:27]
	v_mfma_f32_16x16x32_bf16 v[20:23], v[230:233], v[206:209], v[20:23]
	v_mfma_f32_16x16x32_bf16 v[16:19], v[238:241], v[206:209], v[16:19]
	v_mfma_f32_16x16x32_bf16 v[12:15], v[230:233], v[214:217], v[12:15]
	v_mfma_f32_16x16x32_bf16 v[8:11], v[238:241], v[214:217], v[8:11]
	v_mfma_f32_16x16x32_bf16 v[4:7], v[230:233], v[222:225], v[4:7]
	v_mfma_f32_16x16x32_bf16 v[0:3], v[238:241], v[222:225], v[0:3]
	s_barrier
	s_cbranch_scc0 .LBB0_77
	s_mov_b32 s100, 1
	v_lshl_add_u32 v158, s75, 10, v155
	ds_read2_b32 v[146:147], v158 offset1:16
	ds_read2_b32 v[208:209], v158 offset0:32 offset1:48
	ds_read2_b32 v[210:211], v158 offset0:128 offset1:144
	ds_read2_b32 v[212:213], v158 offset0:160 offset1:176
	s_add_u32 s50, s10, 0xffffff00
	s_addc_u32 s51, s11, -1
	s_ashr_i32 s31, s30, 31
	s_lshl_b64 s[10:11], s[30:31], 8
	s_waitcnt lgkmcnt(0)
	v_mul_f32_e32 v184, 0xbfb8aa3b, v146
	v_mul_f32_e32 v206, v146, v146
	v_pk_mul_f32 v[168:169], v[124:125], v[184:185] op_sel_hi:[1,0]
	v_pk_mul_f32 v[170:171], v[126:127], v[184:185] op_sel_hi:[1,0]
	v_pk_mul_f32 v[172:173], v[120:121], v[184:185] op_sel_hi:[1,0]
	v_pk_mul_f32 v[174:175], v[122:123], v[184:185] op_sel_hi:[1,0]
	v_exp_f32_e32 v168, v168
	v_exp_f32_e32 v169, v169
	v_exp_f32_e32 v170, v170
	v_exp_f32_e32 v171, v171
	v_exp_f32_e32 v172, v172
	v_exp_f32_e32 v173, v173
	v_exp_f32_e32 v174, v174
	v_exp_f32_e32 v175, v175
	v_pk_mul_f32 v[176:177], v[124:125], v[92:93]
	v_pk_mul_f32 v[178:179], v[126:127], v[94:95]
	v_pk_mul_f32 v[180:181], v[120:121], v[88:89]
	v_pk_mul_f32 v[182:183], v[122:123], v[90:91]
	v_pk_add_f32 v[168:169], v[168:169], 1.0 op_sel_hi:[1,0]
	v_pk_add_f32 v[170:171], v[170:171], 1.0 op_sel_hi:[1,0]
	v_pk_add_f32 v[172:173], v[172:173], 1.0 op_sel_hi:[1,0]
	v_pk_add_f32 v[174:175], v[174:175], 1.0 op_sel_hi:[1,0]
	v_rcp_f32_e32 v168, v168
	v_rcp_f32_e32 v169, v169
	v_rcp_f32_e32 v170, v170
	v_rcp_f32_e32 v171, v171
	v_rcp_f32_e32 v172, v172
	v_rcp_f32_e32 v173, v173
	v_rcp_f32_e32 v174, v174
	v_rcp_f32_e32 v175, v175
	v_pk_mul_f32 v[176:177], v[176:177], v[206:207] op_sel_hi:[1,0]
	v_pk_mul_f32 v[178:179], v[178:179], v[206:207] op_sel_hi:[1,0]
	v_pk_mul_f32 v[180:181], v[180:181], v[206:207] op_sel_hi:[1,0]
	v_pk_mul_f32 v[182:183], v[182:183], v[206:207] op_sel_hi:[1,0]
	v_pk_mul_f32 v[176:177], v[176:177], v[168:169]
	v_pk_mul_f32 v[178:179], v[178:179], v[170:171]
	v_pk_mul_f32 v[180:181], v[180:181], v[172:173]
	v_pk_mul_f32 v[182:183], v[182:183], v[174:175]
	v_cvt_pk_bf16_f32 v160, v176, v177
	v_cvt_pk_bf16_f32 v161, v178, v179
	v_cvt_pk_bf16_f32 v162, v180, v181
	v_cvt_pk_bf16_f32 v163, v182, v183
	v_lshl_add_u64 v[152:153], v[134:135], 0, s[10:11]
	s_movk_i32 s6, 0x1600
	v_lshl_or_b32 v150, s74, 7, v156
	v_ashrrev_i32_e32 v151, 31, v150
	s_nop 1
	v_mov_b64_e32 v[148:149], s[28:29]
	v_mad_u64_u32 v[148:149], s[10:11], v152, s6, v[148:149]
	v_mov_b32_e32 v146, v149
	v_mad_u64_u32 v[152:153], s[10:11], v153, s6, v[146:147]
	v_mov_b32_e32 v149, v152
	v_mov_b32_e32 v146, v147
	v_lshl_add_u64 v[150:151], v[150:151], 1, v[148:149]
	global_store_dwordx4 v[150:151], v[160:163], off
	v_mul_f32_e32 v184, 0xbfb8aa3b, v146
	v_mul_f32_e32 v206, v146, v146
	v_pk_mul_f32 v[168:169], v[116:117], v[184:185] op_sel_hi:[1,0]
	v_pk_mul_f32 v[170:171], v[118:119], v[184:185] op_sel_hi:[1,0]
	v_pk_mul_f32 v[172:173], v[112:113], v[184:185] op_sel_hi:[1,0]
	v_pk_mul_f32 v[174:175], v[114:115], v[184:185] op_sel_hi:[1,0]
	v_exp_f32_e32 v168, v168
	v_exp_f32_e32 v169, v169
	v_exp_f32_e32 v170, v170
	v_exp_f32_e32 v171, v171
	v_exp_f32_e32 v172, v172
	v_exp_f32_e32 v173, v173
	v_exp_f32_e32 v174, v174
	v_exp_f32_e32 v175, v175
	v_pk_mul_f32 v[176:177], v[116:117], v[84:85]
	v_pk_mul_f32 v[178:179], v[118:119], v[86:87]
	v_pk_mul_f32 v[180:181], v[112:113], v[80:81]
	v_pk_mul_f32 v[182:183], v[114:115], v[82:83]
	v_pk_add_f32 v[168:169], v[168:169], 1.0 op_sel_hi:[1,0]
	v_pk_add_f32 v[170:171], v[170:171], 1.0 op_sel_hi:[1,0]
	v_pk_add_f32 v[172:173], v[172:173], 1.0 op_sel_hi:[1,0]
	v_pk_add_f32 v[174:175], v[174:175], 1.0 op_sel_hi:[1,0]
	v_rcp_f32_e32 v168, v168
	v_rcp_f32_e32 v169, v169
	v_rcp_f32_e32 v170, v170
	v_rcp_f32_e32 v171, v171
	v_rcp_f32_e32 v172, v172
	v_rcp_f32_e32 v173, v173
	v_rcp_f32_e32 v174, v174
	v_rcp_f32_e32 v175, v175
	v_pk_mul_f32 v[176:177], v[176:177], v[206:207] op_sel_hi:[1,0]
	v_pk_mul_f32 v[178:179], v[178:179], v[206:207] op_sel_hi:[1,0]
	v_pk_mul_f32 v[180:181], v[180:181], v[206:207] op_sel_hi:[1,0]
	v_pk_mul_f32 v[182:183], v[182:183], v[206:207] op_sel_hi:[1,0]
	v_pk_mul_f32 v[176:177], v[176:177], v[168:169]
	v_pk_mul_f32 v[178:179], v[178:179], v[170:171]
	v_pk_mul_f32 v[180:181], v[180:181], v[172:173]
	v_pk_mul_f32 v[182:183], v[182:183], v[174:175]
	v_cvt_pk_bf16_f32 v160, v176, v177
	v_cvt_pk_bf16_f32 v161, v178, v179
	v_cvt_pk_bf16_f32 v162, v180, v181
	v_cvt_pk_bf16_f32 v163, v182, v183
	s_mov_b32 s6, 0x16000
	s_nop 1
	v_add_co_u32_e32 v146, vcc, s6, v150
	s_nop 0
	v_addc_co_u32_e32 v147, vcc, 0, v151, vcc
	global_store_dwordx4 v[146:147], v[160:163], off
	v_mov_b32_e32 v146, v208
	v_mov_b32_e32 v147, v209
	s_mov_b32 s6, 0x2c000
	s_waitcnt lgkmcnt(0)
	v_mul_f32_e32 v184, 0xbfb8aa3b, v146
	v_mul_f32_e32 v206, v146, v146
	v_pk_mul_f32 v[168:169], v[108:109], v[184:185] op_sel_hi:[1,0]
	v_pk_mul_f32 v[170:171], v[110:111], v[184:185] op_sel_hi:[1,0]
	v_pk_mul_f32 v[172:173], v[104:105], v[184:185] op_sel_hi:[1,0]
	v_pk_mul_f32 v[174:175], v[106:107], v[184:185] op_sel_hi:[1,0]
	v_exp_f32_e32 v168, v168
	v_exp_f32_e32 v169, v169
	v_exp_f32_e32 v170, v170
	v_exp_f32_e32 v171, v171
	v_exp_f32_e32 v172, v172
	v_exp_f32_e32 v173, v173
	v_exp_f32_e32 v174, v174
	v_exp_f32_e32 v175, v175
	v_pk_mul_f32 v[176:177], v[108:109], v[76:77]
	v_pk_mul_f32 v[178:179], v[110:111], v[78:79]
	v_pk_mul_f32 v[180:181], v[104:105], v[72:73]
	v_pk_mul_f32 v[182:183], v[106:107], v[74:75]
	v_pk_add_f32 v[168:169], v[168:169], 1.0 op_sel_hi:[1,0]
	v_pk_add_f32 v[170:171], v[170:171], 1.0 op_sel_hi:[1,0]
	v_pk_add_f32 v[172:173], v[172:173], 1.0 op_sel_hi:[1,0]
	v_pk_add_f32 v[174:175], v[174:175], 1.0 op_sel_hi:[1,0]
	v_rcp_f32_e32 v168, v168
	v_rcp_f32_e32 v169, v169
	v_rcp_f32_e32 v170, v170
	v_rcp_f32_e32 v171, v171
	v_rcp_f32_e32 v172, v172
	v_rcp_f32_e32 v173, v173
	v_rcp_f32_e32 v174, v174
	v_rcp_f32_e32 v175, v175
	v_pk_mul_f32 v[176:177], v[176:177], v[206:207] op_sel_hi:[1,0]
	v_pk_mul_f32 v[178:179], v[178:179], v[206:207] op_sel_hi:[1,0]
	v_pk_mul_f32 v[180:181], v[180:181], v[206:207] op_sel_hi:[1,0]
	v_pk_mul_f32 v[182:183], v[182:183], v[206:207] op_sel_hi:[1,0]
	v_pk_mul_f32 v[176:177], v[176:177], v[168:169]
	v_pk_mul_f32 v[178:179], v[178:179], v[170:171]
	v_pk_mul_f32 v[180:181], v[180:181], v[172:173]
	v_pk_mul_f32 v[182:183], v[182:183], v[174:175]
	v_cvt_pk_bf16_f32 v160, v176, v177
	v_cvt_pk_bf16_f32 v161, v178, v179
	v_cvt_pk_bf16_f32 v162, v180, v181
	v_cvt_pk_bf16_f32 v163, v182, v183
	s_nop 1
	v_mov_b32_e32 v146, v147
	v_add_co_u32_e32 v148, vcc, s6, v150
	v_addc_co_u32_e32 v149, vcc, 0, v151, vcc
	global_store_dwordx4 v[148:149], v[160:163], off
	v_mul_f32_e32 v184, 0xbfb8aa3b, v146
	v_mul_f32_e32 v206, v146, v146
	v_pk_mul_f32 v[168:169], v[100:101], v[184:185] op_sel_hi:[1,0]
	v_pk_mul_f32 v[170:171], v[102:103], v[184:185] op_sel_hi:[1,0]
	v_pk_mul_f32 v[172:173], v[96:97], v[184:185] op_sel_hi:[1,0]
	v_pk_mul_f32 v[174:175], v[98:99], v[184:185] op_sel_hi:[1,0]
	v_exp_f32_e32 v168, v168
	v_exp_f32_e32 v169, v169
	v_exp_f32_e32 v170, v170
	v_exp_f32_e32 v171, v171
	v_exp_f32_e32 v172, v172
	v_exp_f32_e32 v173, v173
	v_exp_f32_e32 v174, v174
	v_exp_f32_e32 v175, v175
	v_pk_mul_f32 v[176:177], v[100:101], v[68:69]
	v_pk_mul_f32 v[178:179], v[102:103], v[70:71]
	v_pk_mul_f32 v[180:181], v[96:97], v[64:65]
	v_pk_mul_f32 v[182:183], v[98:99], v[66:67]
	v_pk_add_f32 v[168:169], v[168:169], 1.0 op_sel_hi:[1,0]
	v_pk_add_f32 v[170:171], v[170:171], 1.0 op_sel_hi:[1,0]
	v_pk_add_f32 v[172:173], v[172:173], 1.0 op_sel_hi:[1,0]
	v_pk_add_f32 v[174:175], v[174:175], 1.0 op_sel_hi:[1,0]
	v_rcp_f32_e32 v168, v168
	v_rcp_f32_e32 v169, v169
	v_rcp_f32_e32 v170, v170
	v_rcp_f32_e32 v171, v171
	v_rcp_f32_e32 v172, v172
	v_rcp_f32_e32 v173, v173
	v_rcp_f32_e32 v174, v174
	v_rcp_f32_e32 v175, v175
	v_pk_mul_f32 v[176:177], v[176:177], v[206:207] op_sel_hi:[1,0]
	v_pk_mul_f32 v[178:179], v[178:179], v[206:207] op_sel_hi:[1,0]
	v_pk_mul_f32 v[180:181], v[180:181], v[206:207] op_sel_hi:[1,0]
	v_pk_mul_f32 v[182:183], v[182:183], v[206:207] op_sel_hi:[1,0]
	v_pk_mul_f32 v[176:177], v[176:177], v[168:169]
	v_pk_mul_f32 v[178:179], v[178:179], v[170:171]
	v_pk_mul_f32 v[180:181], v[180:181], v[172:173]
	v_pk_mul_f32 v[182:183], v[182:183], v[174:175]
	v_cvt_pk_bf16_f32 v160, v176, v177
	v_cvt_pk_bf16_f32 v161, v178, v179
	v_cvt_pk_bf16_f32 v162, v180, v181
	v_cvt_pk_bf16_f32 v163, v182, v183
	s_mov_b32 s6, 0x42000
	s_nop 1
	v_add_co_u32_e32 v146, vcc, s6, v150
	s_nop 0
	v_addc_co_u32_e32 v147, vcc, 0, v151, vcc
	global_store_dwordx4 v[146:147], v[160:163], off
	v_mov_b32_e32 v146, v210
	v_mov_b32_e32 v147, v211
	s_mov_b32 s6, 0xb0000
	s_waitcnt lgkmcnt(0)
	v_mul_f32_e32 v184, 0xbfb8aa3b, v146
	v_mul_f32_e32 v206, v146, v146
	v_pk_mul_f32 v[168:169], v[60:61], v[184:185] op_sel_hi:[1,0]
	v_pk_mul_f32 v[170:171], v[62:63], v[184:185] op_sel_hi:[1,0]
	v_pk_mul_f32 v[172:173], v[56:57], v[184:185] op_sel_hi:[1,0]
	v_pk_mul_f32 v[174:175], v[58:59], v[184:185] op_sel_hi:[1,0]
	v_exp_f32_e32 v168, v168
	v_exp_f32_e32 v169, v169
	v_exp_f32_e32 v170, v170
	v_exp_f32_e32 v171, v171
	v_exp_f32_e32 v172, v172
	v_exp_f32_e32 v173, v173
	v_exp_f32_e32 v174, v174
	v_exp_f32_e32 v175, v175
	v_pk_mul_f32 v[176:177], v[60:61], v[28:29]
	v_pk_mul_f32 v[178:179], v[62:63], v[30:31]
	v_pk_mul_f32 v[180:181], v[56:57], v[24:25]
	v_pk_mul_f32 v[182:183], v[58:59], v[26:27]
	v_pk_add_f32 v[168:169], v[168:169], 1.0 op_sel_hi:[1,0]
	v_pk_add_f32 v[170:171], v[170:171], 1.0 op_sel_hi:[1,0]
	v_pk_add_f32 v[172:173], v[172:173], 1.0 op_sel_hi:[1,0]
	v_pk_add_f32 v[174:175], v[174:175], 1.0 op_sel_hi:[1,0]
	v_rcp_f32_e32 v168, v168
	v_rcp_f32_e32 v169, v169
	v_rcp_f32_e32 v170, v170
	v_rcp_f32_e32 v171, v171
	v_rcp_f32_e32 v172, v172
	v_rcp_f32_e32 v173, v173
	v_rcp_f32_e32 v174, v174
	v_rcp_f32_e32 v175, v175
	v_pk_mul_f32 v[176:177], v[176:177], v[206:207] op_sel_hi:[1,0]
	v_pk_mul_f32 v[178:179], v[178:179], v[206:207] op_sel_hi:[1,0]
	v_pk_mul_f32 v[180:181], v[180:181], v[206:207] op_sel_hi:[1,0]
	v_pk_mul_f32 v[182:183], v[182:183], v[206:207] op_sel_hi:[1,0]
	v_pk_mul_f32 v[176:177], v[176:177], v[168:169]
	v_pk_mul_f32 v[178:179], v[178:179], v[170:171]
	v_pk_mul_f32 v[180:181], v[180:181], v[172:173]
	v_pk_mul_f32 v[182:183], v[182:183], v[174:175]
	v_cvt_pk_bf16_f32 v160, v176, v177
	v_cvt_pk_bf16_f32 v161, v178, v179
	v_cvt_pk_bf16_f32 v162, v180, v181
	v_cvt_pk_bf16_f32 v163, v182, v183
	s_nop 1
	v_mov_b32_e32 v146, v147
	v_add_co_u32_e32 v148, vcc, s6, v150
	v_addc_co_u32_e32 v149, vcc, 0, v151, vcc
	global_store_dwordx4 v[148:149], v[160:163], off
	v_mul_f32_e32 v184, 0xbfb8aa3b, v146
	v_mul_f32_e32 v206, v146, v146
	v_pk_mul_f32 v[168:169], v[52:53], v[184:185] op_sel_hi:[1,0]
	v_pk_mul_f32 v[170:171], v[54:55], v[184:185] op_sel_hi:[1,0]
	v_pk_mul_f32 v[172:173], v[48:49], v[184:185] op_sel_hi:[1,0]
	v_pk_mul_f32 v[174:175], v[50:51], v[184:185] op_sel_hi:[1,0]
	v_exp_f32_e32 v168, v168
	v_exp_f32_e32 v169, v169
	v_exp_f32_e32 v170, v170
	v_exp_f32_e32 v171, v171
	v_exp_f32_e32 v172, v172
	v_exp_f32_e32 v173, v173
	v_exp_f32_e32 v174, v174
	v_exp_f32_e32 v175, v175
	v_pk_mul_f32 v[176:177], v[52:53], v[20:21]
	v_pk_mul_f32 v[178:179], v[54:55], v[22:23]
	v_pk_mul_f32 v[180:181], v[48:49], v[16:17]
	v_pk_mul_f32 v[182:183], v[50:51], v[18:19]
	v_pk_add_f32 v[168:169], v[168:169], 1.0 op_sel_hi:[1,0]
	v_pk_add_f32 v[170:171], v[170:171], 1.0 op_sel_hi:[1,0]
	v_pk_add_f32 v[172:173], v[172:173], 1.0 op_sel_hi:[1,0]
	v_pk_add_f32 v[174:175], v[174:175], 1.0 op_sel_hi:[1,0]
	v_rcp_f32_e32 v168, v168
	v_rcp_f32_e32 v169, v169
	v_rcp_f32_e32 v170, v170
	v_rcp_f32_e32 v171, v171
	v_rcp_f32_e32 v172, v172
	v_rcp_f32_e32 v173, v173
	v_rcp_f32_e32 v174, v174
	v_rcp_f32_e32 v175, v175
	v_pk_mul_f32 v[176:177], v[176:177], v[206:207] op_sel_hi:[1,0]
	v_pk_mul_f32 v[178:179], v[178:179], v[206:207] op_sel_hi:[1,0]
	v_pk_mul_f32 v[180:181], v[180:181], v[206:207] op_sel_hi:[1,0]
	v_pk_mul_f32 v[182:183], v[182:183], v[206:207] op_sel_hi:[1,0]
	v_pk_mul_f32 v[176:177], v[176:177], v[168:169]
	v_pk_mul_f32 v[178:179], v[178:179], v[170:171]
	v_pk_mul_f32 v[180:181], v[180:181], v[172:173]
	v_pk_mul_f32 v[182:183], v[182:183], v[174:175]
	v_cvt_pk_bf16_f32 v160, v176, v177
	v_cvt_pk_bf16_f32 v161, v178, v179
	v_cvt_pk_bf16_f32 v162, v180, v181
	v_cvt_pk_bf16_f32 v163, v182, v183
	s_mov_b32 s6, 0xc6000
	s_nop 1
	v_add_co_u32_e32 v146, vcc, s6, v150
	s_nop 0
	v_addc_co_u32_e32 v147, vcc, 0, v151, vcc
	global_store_dwordx4 v[146:147], v[160:163], off
	v_mov_b32_e32 v146, v212
	v_mov_b32_e32 v147, v213
	s_mov_b32 s6, 0xdc000
	s_waitcnt lgkmcnt(0)
	v_mul_f32_e32 v184, 0xbfb8aa3b, v146
	v_mul_f32_e32 v206, v146, v146
	v_pk_mul_f32 v[168:169], v[44:45], v[184:185] op_sel_hi:[1,0]
	v_pk_mul_f32 v[170:171], v[46:47], v[184:185] op_sel_hi:[1,0]
	v_pk_mul_f32 v[172:173], v[40:41], v[184:185] op_sel_hi:[1,0]
	v_pk_mul_f32 v[174:175], v[42:43], v[184:185] op_sel_hi:[1,0]
	v_exp_f32_e32 v168, v168
	v_exp_f32_e32 v169, v169
	v_exp_f32_e32 v170, v170
	v_exp_f32_e32 v171, v171
	v_exp_f32_e32 v172, v172
	v_exp_f32_e32 v173, v173
	v_exp_f32_e32 v174, v174
	v_exp_f32_e32 v175, v175
	v_pk_mul_f32 v[176:177], v[44:45], v[12:13]
	v_pk_mul_f32 v[178:179], v[46:47], v[14:15]
	v_pk_mul_f32 v[180:181], v[40:41], v[8:9]
	v_pk_mul_f32 v[182:183], v[42:43], v[10:11]
	v_pk_add_f32 v[168:169], v[168:169], 1.0 op_sel_hi:[1,0]
	v_pk_add_f32 v[170:171], v[170:171], 1.0 op_sel_hi:[1,0]
	v_pk_add_f32 v[172:173], v[172:173], 1.0 op_sel_hi:[1,0]
	v_pk_add_f32 v[174:175], v[174:175], 1.0 op_sel_hi:[1,0]
	v_rcp_f32_e32 v168, v168
	v_rcp_f32_e32 v169, v169
	v_rcp_f32_e32 v170, v170
	v_rcp_f32_e32 v171, v171
	v_rcp_f32_e32 v172, v172
	v_rcp_f32_e32 v173, v173
	v_rcp_f32_e32 v174, v174
	v_rcp_f32_e32 v175, v175
	v_pk_mul_f32 v[176:177], v[176:177], v[206:207] op_sel_hi:[1,0]
	v_pk_mul_f32 v[178:179], v[178:179], v[206:207] op_sel_hi:[1,0]
	v_pk_mul_f32 v[180:181], v[180:181], v[206:207] op_sel_hi:[1,0]
	v_pk_mul_f32 v[182:183], v[182:183], v[206:207] op_sel_hi:[1,0]
	v_pk_mul_f32 v[176:177], v[176:177], v[168:169]
	v_pk_mul_f32 v[178:179], v[178:179], v[170:171]
	v_pk_mul_f32 v[180:181], v[180:181], v[172:173]
	v_pk_mul_f32 v[182:183], v[182:183], v[174:175]
	v_cvt_pk_bf16_f32 v158, v176, v177
	v_cvt_pk_bf16_f32 v159, v178, v179
	v_cvt_pk_bf16_f32 v160, v180, v181
	v_cvt_pk_bf16_f32 v161, v182, v183
	s_nop 1
	v_mov_b32_e32 v146, v147
	v_add_co_u32_e32 v148, vcc, s6, v150
	v_addc_co_u32_e32 v149, vcc, 0, v151, vcc
	global_store_dwordx4 v[148:149], v[158:161], off
	v_mul_f32_e32 v184, 0xbfb8aa3b, v146
	v_mul_f32_e32 v206, v146, v146
	v_pk_mul_f32 v[168:169], v[36:37], v[184:185] op_sel_hi:[1,0]
	v_pk_mul_f32 v[170:171], v[38:39], v[184:185] op_sel_hi:[1,0]
	v_pk_mul_f32 v[172:173], v[32:33], v[184:185] op_sel_hi:[1,0]
	v_pk_mul_f32 v[174:175], v[34:35], v[184:185] op_sel_hi:[1,0]
	v_exp_f32_e32 v168, v168
	v_exp_f32_e32 v169, v169
	v_exp_f32_e32 v170, v170
	v_exp_f32_e32 v171, v171
	v_exp_f32_e32 v172, v172
	v_exp_f32_e32 v173, v173
	v_exp_f32_e32 v174, v174
	v_exp_f32_e32 v175, v175
	v_pk_mul_f32 v[176:177], v[36:37], v[4:5]
	v_pk_mul_f32 v[178:179], v[38:39], v[6:7]
	v_pk_mul_f32 v[180:181], v[32:33], v[0:1]
	v_pk_mul_f32 v[182:183], v[34:35], v[2:3]
	v_pk_add_f32 v[168:169], v[168:169], 1.0 op_sel_hi:[1,0]
	v_pk_add_f32 v[170:171], v[170:171], 1.0 op_sel_hi:[1,0]
	v_pk_add_f32 v[172:173], v[172:173], 1.0 op_sel_hi:[1,0]
	v_pk_add_f32 v[174:175], v[174:175], 1.0 op_sel_hi:[1,0]
	v_rcp_f32_e32 v168, v168
	v_rcp_f32_e32 v169, v169
	v_rcp_f32_e32 v170, v170
	v_rcp_f32_e32 v171, v171
	v_rcp_f32_e32 v172, v172
	v_rcp_f32_e32 v173, v173
	v_rcp_f32_e32 v174, v174
	v_rcp_f32_e32 v175, v175
	v_pk_mul_f32 v[176:177], v[176:177], v[206:207] op_sel_hi:[1,0]
	v_pk_mul_f32 v[178:179], v[178:179], v[206:207] op_sel_hi:[1,0]
	v_pk_mul_f32 v[180:181], v[180:181], v[206:207] op_sel_hi:[1,0]
	v_pk_mul_f32 v[182:183], v[182:183], v[206:207] op_sel_hi:[1,0]
	v_pk_mul_f32 v[176:177], v[176:177], v[168:169]
	v_pk_mul_f32 v[178:179], v[178:179], v[170:171]
	v_pk_mul_f32 v[180:181], v[180:181], v[172:173]
	v_pk_mul_f32 v[182:183], v[182:183], v[174:175]
	v_cvt_pk_bf16_f32 v158, v176, v177
	v_cvt_pk_bf16_f32 v159, v178, v179
	v_cvt_pk_bf16_f32 v160, v180, v181
	v_cvt_pk_bf16_f32 v161, v182, v183
	s_nop 1
	v_add_co_u32_e32 v146, vcc, 0xf2000, v150
	s_nop 0
	v_addc_co_u32_e32 v147, vcc, 0, v151, vcc
	s_andn2_b64 vcc, exec, s[44:45]
	global_store_dwordx4 v[146:147], v[158:161], off
	s_cbranch_vccz .LBB0_73
	s_mov_b64 s[46:47], s[50:51]
	s_andn2_b64 vcc, exec, s[42:43]
	s_mov_b64 s[50:51], s[46:47]
	s_cbranch_vccnz .LBB0_74

.Lm4bp_103:
	s_waitcnt lgkmcnt(0)
	s_mov_b32 s100, 0
	s_barrier
	s_nop 0
	v_mfma_f32_16x16x32_bf16 v[60:63], v[128:131], v[162:165], 0
	v_mfma_f32_16x16x32_bf16 v[56:59], v[136:139], v[162:165], 0
	v_mfma_f32_16x16x32_bf16 v[48:51], v[128:131], v[170:173], 0
	v_mfma_f32_16x16x32_bf16 v[40:43], v[136:139], v[170:173], 0
	v_mfma_f32_16x16x32_bf16 v[32:35], v[128:131], v[178:181], 0
	v_mfma_f32_16x16x32_bf16 v[24:27], v[136:139], v[178:181], 0
	v_mfma_f32_16x16x32_bf16 v[16:19], v[128:131], v[194:197], 0
	v_mfma_f32_16x16x32_bf16 v[8:11], v[136:139], v[194:197], 0
	v_mfma_f32_16x16x32_bf16 v[60:63], v[132:135], v[166:169], v[60:63]
	v_mfma_f32_16x16x32_bf16 v[56:59], v[146:149], v[166:169], v[56:59]
	v_mfma_f32_16x16x32_bf16 v[48:51], v[132:135], v[174:177], v[48:51]
	v_mfma_f32_16x16x32_bf16 v[40:43], v[146:149], v[174:177], v[40:43]
	v_mfma_f32_16x16x32_bf16 v[32:35], v[132:135], v[182:185], v[32:35]
	v_mfma_f32_16x16x32_bf16 v[24:27], v[146:149], v[182:185], v[24:27]
	v_mfma_f32_16x16x32_bf16 v[16:19], v[132:135], v[210:213], v[16:19]
	v_mfma_f32_16x16x32_bf16 v[8:11], v[146:149], v[210:213], v[8:11]
	v_mfma_f32_16x16x32_bf16 v[52:55], v[214:217], v[162:165], 0
	v_mfma_f32_16x16x32_bf16 v[44:47], v[222:225], v[162:165], 0
	v_mfma_f32_16x16x32_bf16 v[36:39], v[214:217], v[170:173], 0
	v_mfma_f32_16x16x32_bf16 v[28:31], v[222:225], v[170:173], 0
	v_mfma_f32_16x16x32_bf16 v[20:23], v[214:217], v[178:181], 0
	v_mfma_f32_16x16x32_bf16 v[12:15], v[222:225], v[178:181], 0
	v_mfma_f32_16x16x32_bf16 v[4:7], v[214:217], v[194:197], 0
	v_mfma_f32_16x16x32_bf16 v[0:3], v[222:225], v[194:197], 0
	v_mfma_f32_16x16x32_bf16 v[52:55], v[218:221], v[166:169], v[52:55]
	v_mfma_f32_16x16x32_bf16 v[44:47], v[226:229], v[166:169], v[44:47]
	v_mfma_f32_16x16x32_bf16 v[36:39], v[218:221], v[174:177], v[36:39]
	v_mfma_f32_16x16x32_bf16 v[28:31], v[226:229], v[174:177], v[28:31]
	v_mfma_f32_16x16x32_bf16 v[20:23], v[218:221], v[182:185], v[20:23]
	v_mfma_f32_16x16x32_bf16 v[12:15], v[226:229], v[182:185], v[12:15]
	v_mfma_f32_16x16x32_bf16 v[4:7], v[218:221], v[210:213], v[4:7]
	v_mfma_f32_16x16x32_bf16 v[0:3], v[226:229], v[210:213], v[0:3]
	s_barrier
	s_add_i32 s6, 0, 0x18000
	v_add_u32_e32 v146, s6, v206
	ds_read_b128 v[128:131], v146
	ds_read_b128 v[132:135], v146 offset:1024
	ds_read_b128 v[136:139], v146 offset:2048
	ds_read_b128 v[146:149], v146 offset:3072
	s_add_u32 s68, s68, 0x40000
	s_addc_u32 s69, s69, 0
	s_mov_b32 m0, s74
	v_lshl_add_u64 v[214:215], s[68:69], 0, v[154:155]
	ds_read_b128 v[162:165], v208 offset:32768
	ds_read_b128 v[166:169], v208 offset:33792
	ds_read_b128 v[170:173], v208 offset:34816
	ds_read_b128 v[174:177], v208 offset:35840
	ds_read_b128 v[178:181], v208 offset:36864
	ds_read_b128 v[182:185], v208 offset:37888
	ds_read_b128 v[194:197], v208 offset:38912
	ds_read_b128 v[210:213], v208 offset:39936
	global_load_lds_dwordx4 v[214:215], off
	v_lshl_add_u64 v[214:215], s[68:69], 0, v[152:153]
	s_mov_b32 m0, s75
	s_nop 0
	global_load_lds_dwordx4 v[214:215], off
	s_add_i32 s19, 0, 0x1c000
	v_add_u32_e32 v209, s19, v206
	ds_read_b128 v[214:217], v209
	ds_read_b128 v[218:221], v209 offset:1024
	ds_read_b128 v[222:225], v209 offset:2048
	ds_read_b128 v[226:229], v209 offset:3072
	s_waitcnt vmcnt(8)
	s_waitcnt lgkmcnt(0)
	s_barrier
	v_mfma_f32_16x16x32_bf16 v[124:127], v[128:131], v[162:165], v[124:127]
	v_mfma_f32_16x16x32_bf16 v[120:123], v[136:139], v[162:165], v[120:123]
	v_mfma_f32_16x16x32_bf16 v[108:111], v[128:131], v[170:173], v[108:111]
	v_mfma_f32_16x16x32_bf16 v[104:107], v[136:139], v[170:173], v[104:107]
	v_mfma_f32_16x16x32_bf16 v[96:99], v[128:131], v[178:181], v[96:99]
	v_mfma_f32_16x16x32_bf16 v[88:91], v[136:139], v[178:181], v[88:91]
	v_mfma_f32_16x16x32_bf16 v[84:87], v[128:131], v[194:197], v[84:87]
	v_mfma_f32_16x16x32_bf16 v[80:83], v[136:139], v[194:197], v[80:83]
	v_mfma_f32_16x16x32_bf16 v[124:127], v[132:135], v[166:169], v[124:127]
	v_mfma_f32_16x16x32_bf16 v[120:123], v[146:149], v[166:169], v[120:123]
	v_mfma_f32_16x16x32_bf16 v[108:111], v[132:135], v[174:177], v[108:111]
	v_mfma_f32_16x16x32_bf16 v[104:107], v[146:149], v[174:177], v[104:107]
	v_mfma_f32_16x16x32_bf16 v[96:99], v[132:135], v[182:185], v[96:99]
	v_mfma_f32_16x16x32_bf16 v[88:91], v[146:149], v[182:185], v[88:91]
	v_mfma_f32_16x16x32_bf16 v[84:87], v[132:135], v[210:213], v[84:87]
	v_mfma_f32_16x16x32_bf16 v[80:83], v[146:149], v[210:213], v[80:83]
	v_mfma_f32_16x16x32_bf16 v[116:119], v[214:217], v[162:165], v[116:119]
	v_mfma_f32_16x16x32_bf16 v[112:115], v[222:225], v[162:165], v[112:115]
	v_mfma_f32_16x16x32_bf16 v[100:103], v[214:217], v[170:173], v[100:103]
	v_mfma_f32_16x16x32_bf16 v[92:95], v[222:225], v[170:173], v[92:95]
	v_mfma_f32_16x16x32_bf16 v[76:79], v[214:217], v[178:181], v[76:79]
	v_mfma_f32_16x16x32_bf16 v[72:75], v[222:225], v[178:181], v[72:75]
	v_mfma_f32_16x16x32_bf16 v[68:71], v[214:217], v[194:197], v[68:71]
	v_mfma_f32_16x16x32_bf16 v[64:67], v[222:225], v[194:197], v[64:67]
	v_mfma_f32_16x16x32_bf16 v[116:119], v[218:221], v[166:169], v[116:119]
	v_mfma_f32_16x16x32_bf16 v[112:115], v[226:229], v[166:169], v[112:115]
	v_mfma_f32_16x16x32_bf16 v[100:103], v[218:221], v[174:177], v[100:103]
	v_mfma_f32_16x16x32_bf16 v[92:95], v[226:229], v[174:177], v[92:95]
	v_mfma_f32_16x16x32_bf16 v[76:79], v[218:221], v[182:185], v[76:79]
	v_mfma_f32_16x16x32_bf16 v[72:75], v[226:229], v[182:185], v[72:75]
	v_mfma_f32_16x16x32_bf16 v[68:71], v[218:221], v[210:213], v[68:71]
	v_mfma_f32_16x16x32_bf16 v[64:67], v[226:229], v[210:213], v[64:67]
	s_barrier
	s_add_i32 s6, s6, s71
	v_lshl_add_u64 v[192:193], v[192:193], 0, s[36:37]
	s_mov_b32 m0, s6
	s_nop 0
	global_load_lds_dwordx4 v[192:193], off
	v_lshl_add_u64 v[192:193], v[230:231], 0, s[36:37]
	s_add_i32 m0, s6, 0x2000
	s_nop 0
	global_load_lds_dwordx4 v[192:193], off
	s_mov_b32 m0, s80
	v_lshl_add_u64 v[192:193], v[232:233], 0, s[36:37]
	ds_read_b128 v[162:165], v208 offset:49152
	ds_read_b128 v[166:169], v208 offset:50176
	ds_read_b128 v[170:173], v208 offset:51200
	ds_read_b128 v[174:177], v208 offset:52224
	ds_read_b128 v[178:181], v208 offset:53248
	ds_read_b128 v[182:185], v208 offset:54272
	ds_read_b128 v[194:197], v208 offset:55296
	ds_read_b128 v[210:213], v208 offset:56320
	global_load_lds_dwordx4 v[192:193], off
	v_lshl_add_u64 v[192:193], v[234:235], 0, s[36:37]
	s_mov_b32 m0, s81
	s_nop 0
	global_load_lds_dwordx4 v[192:193], off
	s_add_u32 s58, s58, 0x40080
	s_addc_u32 s59, s59, 0
	s_add_i32 s6, s19, s71
	v_lshl_add_u64 v[250:251], s[58:59], 0, v[140:141]
	s_mov_b32 m0, s6
	s_nop 0
	global_load_lds_dwordx4 v[250:251], off
	v_lshl_add_u64 v[250:251], s[58:59], 0, v[150:151]
	s_add_i32 m0, s6, 0x2000
	s_nop 0
	global_load_lds_dwordx4 v[250:251], off
	s_add_i32 s12, s12, 2
	s_add_u32 s54, s54, 0x100
	s_addc_u32 s55, s55, 0
	s_add_u32 s10, s10, 0x100
	s_addc_u32 s11, s11, 0
	s_cmp_gt_u32 s12, 13
	s_waitcnt vmcnt(8)
	s_waitcnt lgkmcnt(0)
	s_barrier
	v_mfma_f32_16x16x32_bf16 v[60:63], v[128:131], v[162:165], v[60:63]
	v_mfma_f32_16x16x32_bf16 v[56:59], v[136:139], v[162:165], v[56:59]
	v_mfma_f32_16x16x32_bf16 v[48:51], v[128:131], v[170:173], v[48:51]
	v_mfma_f32_16x16x32_bf16 v[40:43], v[136:139], v[170:173], v[40:43]
	v_mfma_f32_16x16x32_bf16 v[32:35], v[128:131], v[178:181], v[32:35]
	v_mfma_f32_16x16x32_bf16 v[24:27], v[136:139], v[178:181], v[24:27]
	v_mfma_f32_16x16x32_bf16 v[16:19], v[128:131], v[194:197], v[16:19]
	v_mfma_f32_16x16x32_bf16 v[8:11], v[136:139], v[194:197], v[8:11]
	v_mfma_f32_16x16x32_bf16 v[60:63], v[132:135], v[166:169], v[60:63]
	v_mfma_f32_16x16x32_bf16 v[56:59], v[146:149], v[166:169], v[56:59]
	v_mfma_f32_16x16x32_bf16 v[48:51], v[132:135], v[174:177], v[48:51]
	v_mfma_f32_16x16x32_bf16 v[40:43], v[146:149], v[174:177], v[40:43]
	v_mfma_f32_16x16x32_bf16 v[32:35], v[132:135], v[182:185], v[32:35]
	v_mfma_f32_16x16x32_bf16 v[24:27], v[146:149], v[182:185], v[24:27]
	v_mfma_f32_16x16x32_bf16 v[16:19], v[132:135], v[210:213], v[16:19]
	v_mfma_f32_16x16x32_bf16 v[8:11], v[146:149], v[210:213], v[8:11]
	v_mfma_f32_16x16x32_bf16 v[52:55], v[214:217], v[162:165], v[52:55]
	v_mfma_f32_16x16x32_bf16 v[44:47], v[222:225], v[162:165], v[44:47]
	v_mfma_f32_16x16x32_bf16 v[36:39], v[214:217], v[170:173], v[36:39]
	v_mfma_f32_16x16x32_bf16 v[28:31], v[222:225], v[170:173], v[28:31]
	v_mfma_f32_16x16x32_bf16 v[20:23], v[214:217], v[178:181], v[20:23]
	v_mfma_f32_16x16x32_bf16 v[12:15], v[222:225], v[178:181], v[12:15]
	v_mfma_f32_16x16x32_bf16 v[4:7], v[214:217], v[194:197], v[4:7]
	v_mfma_f32_16x16x32_bf16 v[0:3], v[222:225], v[194:197], v[0:3]
	v_mfma_f32_16x16x32_bf16 v[52:55], v[218:221], v[166:169], v[52:55]
	v_mfma_f32_16x16x32_bf16 v[44:47], v[226:229], v[166:169], v[44:47]
	v_mfma_f32_16x16x32_bf16 v[36:39], v[218:221], v[174:177], v[36:39]
	v_mfma_f32_16x16x32_bf16 v[28:31], v[226:229], v[174:177], v[28:31]
	v_mfma_f32_16x16x32_bf16 v[20:23], v[218:221], v[182:185], v[20:23]
	v_mfma_f32_16x16x32_bf16 v[12:15], v[226:229], v[182:185], v[12:15]
	v_mfma_f32_16x16x32_bf16 v[4:7], v[218:221], v[210:213], v[4:7]
	v_mfma_f32_16x16x32_bf16 v[0:3], v[226:229], v[210:213], v[0:3]
	s_barrier
	.p2align	6
.LBB0_103:
	s_add_u32 s6, s54, 0xfffc0080
	s_addc_u32 s19, s55, -1
	s_add_i32 s23, 0, 0x10000
	v_add_u32_e32 v146, s23, v206
	ds_read_b128 v[128:131], v146
	ds_read_b128 v[132:135], v146 offset:1024
	ds_read_b128 v[136:139], v146 offset:2048
	ds_read_b128 v[146:149], v146 offset:3072
	s_cmp_eq_u32 s12, 12
	s_cselect_b32 s69, s47, s19
	s_cselect_b32 s68, s46, s6
	s_cselect_b32 s59, s49, s11
	s_cselect_b32 s58, s48, s10
	v_lshl_add_u64 v[192:193], s[54:55], 0, v[158:159]
	s_add_i32 m0, s72, 0xc000
	ds_read_b128 v[162:165], v208
	ds_read_b128 v[166:169], v208 offset:1024
	ds_read_b128 v[170:173], v208 offset:2048
	ds_read_b128 v[174:177], v208 offset:3072
	ds_read_b128 v[178:181], v208 offset:4096
	ds_read_b128 v[182:185], v208 offset:5120
	ds_read_b128 v[194:197], v208 offset:6144
	ds_read_b128 v[210:213], v208 offset:7168
	global_load_lds_dwordx4 v[192:193], off
	v_lshl_add_u64 v[192:193], s[54:55], 0, v[160:161]
	s_add_i32 m0, s72, 0xe000
	s_nop 0
	global_load_lds_dwordx4 v[192:193], off
	s_add_i32 s6, 0, 0x14000
	v_add_u32_e32 v192, s6, v206
	ds_read_b128 v[214:217], v192
	ds_read_b128 v[218:221], v192 offset:1024
	ds_read_b128 v[222:225], v192 offset:2048
	ds_read_b128 v[226:229], v192 offset:3072
	s_waitcnt vmcnt(8)
	s_waitcnt lgkmcnt(0)
	s_barrier
	v_mfma_f32_16x16x32_bf16 v[124:127], v[128:131], v[162:165], v[124:127]
	v_mfma_f32_16x16x32_bf16 v[120:123], v[136:139], v[162:165], v[120:123]
	v_mfma_f32_16x16x32_bf16 v[108:111], v[128:131], v[170:173], v[108:111]
	v_mfma_f32_16x16x32_bf16 v[104:107], v[136:139], v[170:173], v[104:107]
	v_mfma_f32_16x16x32_bf16 v[96:99], v[128:131], v[178:181], v[96:99]
	v_mfma_f32_16x16x32_bf16 v[88:91], v[136:139], v[178:181], v[88:91]
	v_mfma_f32_16x16x32_bf16 v[84:87], v[128:131], v[194:197], v[84:87]
	v_mfma_f32_16x16x32_bf16 v[80:83], v[136:139], v[194:197], v[80:83]
	v_mfma_f32_16x16x32_bf16 v[124:127], v[132:135], v[166:169], v[124:127]
	v_mfma_f32_16x16x32_bf16 v[120:123], v[146:149], v[166:169], v[120:123]
	v_mfma_f32_16x16x32_bf16 v[108:111], v[132:135], v[174:177], v[108:111]
	v_mfma_f32_16x16x32_bf16 v[104:107], v[146:149], v[174:177], v[104:107]
	v_mfma_f32_16x16x32_bf16 v[96:99], v[132:135], v[182:185], v[96:99]
	v_mfma_f32_16x16x32_bf16 v[88:91], v[146:149], v[182:185], v[88:91]
	v_mfma_f32_16x16x32_bf16 v[84:87], v[132:135], v[210:213], v[84:87]
	v_mfma_f32_16x16x32_bf16 v[80:83], v[146:149], v[210:213], v[80:83]
	v_mfma_f32_16x16x32_bf16 v[116:119], v[214:217], v[162:165], v[116:119]
	v_mfma_f32_16x16x32_bf16 v[112:115], v[222:225], v[162:165], v[112:115]
	v_mfma_f32_16x16x32_bf16 v[100:103], v[214:217], v[170:173], v[100:103]
	v_mfma_f32_16x16x32_bf16 v[92:95], v[222:225], v[170:173], v[92:95]
	v_mfma_f32_16x16x32_bf16 v[76:79], v[214:217], v[178:181], v[76:79]
	v_mfma_f32_16x16x32_bf16 v[72:75], v[222:225], v[178:181], v[72:75]
	v_mfma_f32_16x16x32_bf16 v[68:71], v[214:217], v[194:197], v[68:71]
	v_mfma_f32_16x16x32_bf16 v[64:67], v[222:225], v[194:197], v[64:67]
	v_mfma_f32_16x16x32_bf16 v[116:119], v[218:221], v[166:169], v[116:119]
	v_mfma_f32_16x16x32_bf16 v[112:115], v[226:229], v[166:169], v[112:115]
	v_mfma_f32_16x16x32_bf16 v[100:103], v[218:221], v[174:177], v[100:103]
	v_mfma_f32_16x16x32_bf16 v[92:95], v[226:229], v[174:177], v[92:95]
	v_mfma_f32_16x16x32_bf16 v[76:79], v[218:221], v[182:185], v[76:79]
	v_mfma_f32_16x16x32_bf16 v[72:75], v[226:229], v[182:185], v[72:75]
	v_mfma_f32_16x16x32_bf16 v[68:71], v[218:221], v[210:213], v[68:71]
	v_mfma_f32_16x16x32_bf16 v[64:67], v[226:229], v[210:213], v[64:67]
	s_barrier
	s_add_i32 s19, s23, s71
	v_lshl_add_u64 v[192:193], s[58:59], 0, v[140:141]
	s_mov_b32 m0, s19
	v_lshl_add_u64 v[230:231], s[58:59], 0, v[150:151]
	global_load_lds_dwordx4 v[192:193], off
	s_add_i32 m0, s19, 0x2000
	s_nop 0
	global_load_lds_dwordx4 v[230:231], off
	s_mov_b32 m0, s72
	v_lshl_add_u64 v[232:233], s[68:69], 0, v[154:155]
	ds_read_b128 v[162:165], v208 offset:16384
	ds_read_b128 v[166:169], v208 offset:17408
	ds_read_b128 v[170:173], v208 offset:18432
	ds_read_b128 v[174:177], v208 offset:19456
	ds_read_b128 v[178:181], v208 offset:20480
	ds_read_b128 v[182:185], v208 offset:21504
	ds_read_b128 v[194:197], v208 offset:22528
	ds_read_b128 v[210:213], v208 offset:23552
	global_load_lds_dwordx4 v[232:233], off
	v_lshl_add_u64 v[234:235], s[68:69], 0, v[152:153]
	s_mov_b32 m0, s73
	s_nop 0
	global_load_lds_dwordx4 v[234:235], off
	s_add_u32 s86, s58, 0x40000
	s_addc_u32 s87, s59, 0
	s_add_i32 s6, s6, s71
	v_lshl_add_u64 v[250:251], s[86:87], 0, v[140:141]
	s_mov_b32 m0, s6
	s_nop 0
	global_load_lds_dwordx4 v[250:251], off
	v_lshl_add_u64 v[250:251], s[86:87], 0, v[150:151]
	s_add_i32 m0, s6, 0x2000
	s_nop 0
	global_load_lds_dwordx4 v[250:251], off
	s_nop 0
	s_waitcnt vmcnt(8)
	s_waitcnt lgkmcnt(0)
	s_barrier
	v_mfma_f32_16x16x32_bf16 v[60:63], v[128:131], v[162:165], v[60:63]
	v_mfma_f32_16x16x32_bf16 v[56:59], v[136:139], v[162:165], v[56:59]
	v_mfma_f32_16x16x32_bf16 v[48:51], v[128:131], v[170:173], v[48:51]
	v_mfma_f32_16x16x32_bf16 v[40:43], v[136:139], v[170:173], v[40:43]
	v_mfma_f32_16x16x32_bf16 v[32:35], v[128:131], v[178:181], v[32:35]
	v_mfma_f32_16x16x32_bf16 v[24:27], v[136:139], v[178:181], v[24:27]
	v_mfma_f32_16x16x32_bf16 v[16:19], v[128:131], v[194:197], v[16:19]
	v_mfma_f32_16x16x32_bf16 v[8:11], v[136:139], v[194:197], v[8:11]
	v_mfma_f32_16x16x32_bf16 v[60:63], v[132:135], v[166:169], v[60:63]
	v_mfma_f32_16x16x32_bf16 v[56:59], v[146:149], v[166:169], v[56:59]
	v_mfma_f32_16x16x32_bf16 v[48:51], v[132:135], v[174:177], v[48:51]
	v_mfma_f32_16x16x32_bf16 v[40:43], v[146:149], v[174:177], v[40:43]
	v_mfma_f32_16x16x32_bf16 v[32:35], v[132:135], v[182:185], v[32:35]
	v_mfma_f32_16x16x32_bf16 v[24:27], v[146:149], v[182:185], v[24:27]
	v_mfma_f32_16x16x32_bf16 v[16:19], v[132:135], v[210:213], v[16:19]
	v_mfma_f32_16x16x32_bf16 v[8:11], v[146:149], v[210:213], v[8:11]
	v_mfma_f32_16x16x32_bf16 v[52:55], v[214:217], v[162:165], v[52:55]
	v_mfma_f32_16x16x32_bf16 v[44:47], v[222:225], v[162:165], v[44:47]
	v_mfma_f32_16x16x32_bf16 v[36:39], v[214:217], v[170:173], v[36:39]
	v_mfma_f32_16x16x32_bf16 v[28:31], v[222:225], v[170:173], v[28:31]
	v_mfma_f32_16x16x32_bf16 v[20:23], v[214:217], v[178:181], v[20:23]
	v_mfma_f32_16x16x32_bf16 v[12:15], v[222:225], v[178:181], v[12:15]
	v_mfma_f32_16x16x32_bf16 v[4:7], v[214:217], v[194:197], v[4:7]
	v_mfma_f32_16x16x32_bf16 v[0:3], v[222:225], v[194:197], v[0:3]
	v_mfma_f32_16x16x32_bf16 v[52:55], v[218:221], v[166:169], v[52:55]
	v_mfma_f32_16x16x32_bf16 v[44:47], v[226:229], v[166:169], v[44:47]
	v_mfma_f32_16x16x32_bf16 v[36:39], v[218:221], v[174:177], v[36:39]
	v_mfma_f32_16x16x32_bf16 v[28:31], v[226:229], v[174:177], v[28:31]
	v_mfma_f32_16x16x32_bf16 v[20:23], v[218:221], v[182:185], v[20:23]
	v_mfma_f32_16x16x32_bf16 v[12:15], v[226:229], v[182:185], v[12:15]
	v_mfma_f32_16x16x32_bf16 v[4:7], v[218:221], v[210:213], v[4:7]
	v_mfma_f32_16x16x32_bf16 v[0:3], v[226:229], v[210:213], v[0:3]
	s_barrier
	s_add_i32 s6, 0, 0x18000
	v_add_u32_e32 v146, s6, v206
	ds_read_b128 v[128:131], v146
	ds_read_b128 v[132:135], v146 offset:1024
	ds_read_b128 v[136:139], v146 offset:2048
	ds_read_b128 v[146:149], v146 offset:3072
	s_add_u32 s68, s68, 0x40000
	s_addc_u32 s69, s69, 0
	s_mov_b32 m0, s74
	v_lshl_add_u64 v[214:215], s[68:69], 0, v[154:155]
	ds_read_b128 v[162:165], v208 offset:32768
	ds_read_b128 v[166:169], v208 offset:33792
	ds_read_b128 v[170:173], v208 offset:34816
	ds_read_b128 v[174:177], v208 offset:35840
	ds_read_b128 v[178:181], v208 offset:36864
	ds_read_b128 v[182:185], v208 offset:37888
	ds_read_b128 v[194:197], v208 offset:38912
	ds_read_b128 v[210:213], v208 offset:39936
	global_load_lds_dwordx4 v[214:215], off
	v_lshl_add_u64 v[214:215], s[68:69], 0, v[152:153]
	s_mov_b32 m0, s75
	s_nop 0
	global_load_lds_dwordx4 v[214:215], off
	s_add_i32 s19, 0, 0x1c000
	v_add_u32_e32 v209, s19, v206
	ds_read_b128 v[214:217], v209
	ds_read_b128 v[218:221], v209 offset:1024
	ds_read_b128 v[222:225], v209 offset:2048
	ds_read_b128 v[226:229], v209 offset:3072
	s_waitcnt vmcnt(8)
	s_waitcnt lgkmcnt(0)
	s_barrier
	v_mfma_f32_16x16x32_bf16 v[124:127], v[128:131], v[162:165], v[124:127]
	v_mfma_f32_16x16x32_bf16 v[120:123], v[136:139], v[162:165], v[120:123]
	v_mfma_f32_16x16x32_bf16 v[108:111], v[128:131], v[170:173], v[108:111]
	v_mfma_f32_16x16x32_bf16 v[104:107], v[136:139], v[170:173], v[104:107]
	v_mfma_f32_16x16x32_bf16 v[96:99], v[128:131], v[178:181], v[96:99]
	v_mfma_f32_16x16x32_bf16 v[88:91], v[136:139], v[178:181], v[88:91]
	v_mfma_f32_16x16x32_bf16 v[84:87], v[128:131], v[194:197], v[84:87]
	v_mfma_f32_16x16x32_bf16 v[80:83], v[136:139], v[194:197], v[80:83]
	v_mfma_f32_16x16x32_bf16 v[124:127], v[132:135], v[166:169], v[124:127]
	v_mfma_f32_16x16x32_bf16 v[120:123], v[146:149], v[166:169], v[120:123]
	v_mfma_f32_16x16x32_bf16 v[108:111], v[132:135], v[174:177], v[108:111]
	v_mfma_f32_16x16x32_bf16 v[104:107], v[146:149], v[174:177], v[104:107]
	v_mfma_f32_16x16x32_bf16 v[96:99], v[132:135], v[182:185], v[96:99]
	v_mfma_f32_16x16x32_bf16 v[88:91], v[146:149], v[182:185], v[88:91]
	v_mfma_f32_16x16x32_bf16 v[84:87], v[132:135], v[210:213], v[84:87]
	v_mfma_f32_16x16x32_bf16 v[80:83], v[146:149], v[210:213], v[80:83]
	v_mfma_f32_16x16x32_bf16 v[116:119], v[214:217], v[162:165], v[116:119]
	v_mfma_f32_16x16x32_bf16 v[112:115], v[222:225], v[162:165], v[112:115]
	v_mfma_f32_16x16x32_bf16 v[100:103], v[214:217], v[170:173], v[100:103]
	v_mfma_f32_16x16x32_bf16 v[92:95], v[222:225], v[170:173], v[92:95]
	v_mfma_f32_16x16x32_bf16 v[76:79], v[214:217], v[178:181], v[76:79]
	v_mfma_f32_16x16x32_bf16 v[72:75], v[222:225], v[178:181], v[72:75]
	v_mfma_f32_16x16x32_bf16 v[68:71], v[214:217], v[194:197], v[68:71]
	v_mfma_f32_16x16x32_bf16 v[64:67], v[222:225], v[194:197], v[64:67]
	v_mfma_f32_16x16x32_bf16 v[116:119], v[218:221], v[166:169], v[116:119]
	v_mfma_f32_16x16x32_bf16 v[112:115], v[226:229], v[166:169], v[112:115]
	v_mfma_f32_16x16x32_bf16 v[100:103], v[218:221], v[174:177], v[100:103]
	v_mfma_f32_16x16x32_bf16 v[92:95], v[226:229], v[174:177], v[92:95]
	v_mfma_f32_16x16x32_bf16 v[76:79], v[218:221], v[182:185], v[76:79]
	v_mfma_f32_16x16x32_bf16 v[72:75], v[226:229], v[182:185], v[72:75]
	v_mfma_f32_16x16x32_bf16 v[68:71], v[218:221], v[210:213], v[68:71]
	v_mfma_f32_16x16x32_bf16 v[64:67], v[226:229], v[210:213], v[64:67]
	s_barrier
	s_add_i32 s6, s6, s71
	v_lshl_add_u64 v[192:193], v[192:193], 0, s[36:37]
	s_mov_b32 m0, s6
	s_nop 0
	global_load_lds_dwordx4 v[192:193], off
	v_lshl_add_u64 v[192:193], v[230:231], 0, s[36:37]
	s_add_i32 m0, s6, 0x2000
	s_nop 0
	global_load_lds_dwordx4 v[192:193], off
	s_mov_b32 m0, s80
	v_lshl_add_u64 v[192:193], v[232:233], 0, s[36:37]
	ds_read_b128 v[162:165], v208 offset:49152
	ds_read_b128 v[166:169], v208 offset:50176
	ds_read_b128 v[170:173], v208 offset:51200
	ds_read_b128 v[174:177], v208 offset:52224
	ds_read_b128 v[178:181], v208 offset:53248
	ds_read_b128 v[182:185], v208 offset:54272
	ds_read_b128 v[194:197], v208 offset:55296
	ds_read_b128 v[210:213], v208 offset:56320
	global_load_lds_dwordx4 v[192:193], off
	v_lshl_add_u64 v[192:193], v[234:235], 0, s[36:37]
	s_mov_b32 m0, s81
	s_nop 0
	global_load_lds_dwordx4 v[192:193], off
	s_add_u32 s58, s58, 0x40080
	s_addc_u32 s59, s59, 0
	s_add_i32 s6, s19, s71
	v_lshl_add_u64 v[250:251], s[58:59], 0, v[140:141]
	s_mov_b32 m0, s6
	s_nop 0
	global_load_lds_dwordx4 v[250:251], off
	v_lshl_add_u64 v[250:251], s[58:59], 0, v[150:151]
	s_add_i32 m0, s6, 0x2000
	s_nop 0
	global_load_lds_dwordx4 v[250:251], off
	s_add_i32 s12, s12, 2
	s_add_u32 s54, s54, 0x100
	s_addc_u32 s55, s55, 0
	s_add_u32 s10, s10, 0x100
	s_addc_u32 s11, s11, 0
	s_cmp_gt_u32 s12, 13
	s_waitcnt vmcnt(8)
	s_waitcnt lgkmcnt(0)
	s_barrier
	v_mfma_f32_16x16x32_bf16 v[60:63], v[128:131], v[162:165], v[60:63]
	v_mfma_f32_16x16x32_bf16 v[56:59], v[136:139], v[162:165], v[56:59]
	v_mfma_f32_16x16x32_bf16 v[48:51], v[128:131], v[170:173], v[48:51]
	v_mfma_f32_16x16x32_bf16 v[40:43], v[136:139], v[170:173], v[40:43]
	v_mfma_f32_16x16x32_bf16 v[32:35], v[128:131], v[178:181], v[32:35]
	v_mfma_f32_16x16x32_bf16 v[24:27], v[136:139], v[178:181], v[24:27]
	v_mfma_f32_16x16x32_bf16 v[16:19], v[128:131], v[194:197], v[16:19]
	v_mfma_f32_16x16x32_bf16 v[8:11], v[136:139], v[194:197], v[8:11]
	v_mfma_f32_16x16x32_bf16 v[60:63], v[132:135], v[166:169], v[60:63]
	v_mfma_f32_16x16x32_bf16 v[56:59], v[146:149], v[166:169], v[56:59]
	v_mfma_f32_16x16x32_bf16 v[48:51], v[132:135], v[174:177], v[48:51]
	v_mfma_f32_16x16x32_bf16 v[40:43], v[146:149], v[174:177], v[40:43]
	v_mfma_f32_16x16x32_bf16 v[32:35], v[132:135], v[182:185], v[32:35]
	v_mfma_f32_16x16x32_bf16 v[24:27], v[146:149], v[182:185], v[24:27]
	v_mfma_f32_16x16x32_bf16 v[16:19], v[132:135], v[210:213], v[16:19]
	v_mfma_f32_16x16x32_bf16 v[8:11], v[146:149], v[210:213], v[8:11]
	v_mfma_f32_16x16x32_bf16 v[52:55], v[214:217], v[162:165], v[52:55]
	v_mfma_f32_16x16x32_bf16 v[44:47], v[222:225], v[162:165], v[44:47]
	v_mfma_f32_16x16x32_bf16 v[36:39], v[214:217], v[170:173], v[36:39]
	v_mfma_f32_16x16x32_bf16 v[28:31], v[222:225], v[170:173], v[28:31]
	v_mfma_f32_16x16x32_bf16 v[20:23], v[214:217], v[178:181], v[20:23]
	v_mfma_f32_16x16x32_bf16 v[12:15], v[222:225], v[178:181], v[12:15]
	v_mfma_f32_16x16x32_bf16 v[4:7], v[214:217], v[194:197], v[4:7]
	v_mfma_f32_16x16x32_bf16 v[0:3], v[222:225], v[194:197], v[0:3]
	v_mfma_f32_16x16x32_bf16 v[52:55], v[218:221], v[166:169], v[52:55]
	v_mfma_f32_16x16x32_bf16 v[44:47], v[226:229], v[166:169], v[44:47]
	v_mfma_f32_16x16x32_bf16 v[36:39], v[218:221], v[174:177], v[36:39]
	v_mfma_f32_16x16x32_bf16 v[28:31], v[226:229], v[174:177], v[28:31]
	v_mfma_f32_16x16x32_bf16 v[20:23], v[218:221], v[182:185], v[20:23]
	v_mfma_f32_16x16x32_bf16 v[12:15], v[226:229], v[182:185], v[12:15]
	v_mfma_f32_16x16x32_bf16 v[4:7], v[218:221], v[210:213], v[4:7]
	v_mfma_f32_16x16x32_bf16 v[0:3], v[226:229], v[210:213], v[0:3]
	s_barrier
	s_cbranch_scc0 .LBB0_103
	s_mov_b32 s100, 1
	s_ashr_i32 s51, s50, 31
	s_ashr_i32 s53, s52, 31
	s_lshl_b64 s[10:11], s[50:51], 13
	s_lshl_b64 s[50:51], s[52:53], 8
	s_add_u32 s10, s50, s10
	v_lshl_or_b32 v128, s85, 8, v207
	s_addc_u32 s11, s51, s11
	v_ashrrev_i32_e32 v129, 31, v128
	v_lshl_add_u64 v[168:169], s[10:11], 0, v[156:157]
	v_lshlrev_b64 v[170:171], 1, v[128:129]
	v_lshl_add_u64 v[174:175], s[26:27], 0, v[170:171]
	v_lshlrev_b64 v[172:173], 11, v[168:169]
	v_or_b32_e32 v166, 16, v168
	v_mov_b32_e32 v167, v169
	v_lshl_add_u64 v[128:129], v[174:175], 0, v[172:173]
	v_lshlrev_b64 v[176:177], 11, v[166:167]
	global_load_dwordx4 v[146:149], v[128:129], off
	global_load_dwordx4 v[182:185], v[128:129], off offset:256
	v_lshl_add_u64 v[128:129], v[174:175], 0, v[176:177]
	global_load_dwordx4 v[194:197], v[128:129], off
	global_load_dwordx4 v[210:213], v[128:129], off offset:256
	v_or_b32_e32 v164, 32, v168
	v_mov_b32_e32 v165, v169
	v_or_b32_e32 v162, 48, v168
	v_mov_b32_e32 v163, v169
	v_lshlrev_b64 v[180:181], 11, v[164:165]
	v_lshlrev_b64 v[178:179], 11, v[162:163]
	v_lshl_add_u64 v[128:129], v[174:175], 0, v[180:181]
	v_lshl_add_u64 v[130:131], v[174:175], 0, v[178:179]
	global_load_dwordx4 v[214:217], v[128:129], off
	global_load_dwordx4 v[136:139], v[128:129], off offset:256
	global_load_dwordx4 v[132:135], v[130:131], off
	s_nop 0
	global_load_dwordx4 v[128:131], v[130:131], off offset:256
	s_mov_b64 s[10:11], 0x90
	v_lshl_add_u64 v[172:173], s[28:29], 0, v[172:173]
	v_lshl_add_u64 v[172:173], v[172:173], 0, v[170:171]
	s_waitcnt vmcnt(0)
	v_lshlrev_b32_e32 v192, 16, v146
	v_and_b32_e32 v193, 0xffff0000, v146
	v_lshlrev_b32_e32 v218, 16, v148
	v_and_b32_e32 v219, 0xffff0000, v148
	v_lshlrev_b32_e32 v146, 16, v147
	v_and_b32_e32 v147, 0xffff0000, v147
	v_lshlrev_b32_e32 v148, 16, v149
	v_and_b32_e32 v149, 0xffff0000, v149
	v_lshlrev_b32_e32 v220, 16, v182
	v_and_b32_e32 v221, 0xffff0000, v182
	v_lshlrev_b32_e32 v222, 16, v184
	v_and_b32_e32 v223, 0xffff0000, v184
	v_lshlrev_b32_e32 v182, 16, v183
	v_and_b32_e32 v183, 0xffff0000, v183
	v_lshlrev_b32_e32 v184, 16, v185
	v_and_b32_e32 v185, 0xffff0000, v185
	v_pk_add_f32 v[124:125], v[124:125], v[192:193]
	v_pk_add_f32 v[126:127], v[126:127], v[146:147]
	v_pk_add_f32 v[122:123], v[122:123], v[148:149]
	v_pk_add_f32 v[116:117], v[116:117], v[220:221]
	v_pk_add_f32 v[146:147], v[112:113], v[222:223]
	v_pk_add_f32 v[118:119], v[118:119], v[182:183]
	v_pk_add_f32 v[148:149], v[114:115], v[184:185]
	v_lshlrev_b32_e32 v182, 16, v194
	v_and_b32_e32 v183, 0xffff0000, v194
	v_lshlrev_b32_e32 v184, 16, v196
	v_and_b32_e32 v185, 0xffff0000, v196
	v_lshlrev_b32_e32 v192, 16, v195
	v_and_b32_e32 v193, 0xffff0000, v195
	v_lshlrev_b32_e32 v194, 16, v197
	v_and_b32_e32 v195, 0xffff0000, v197
	v_pk_mul_f32 v[196:197], v[124:125], v[124:125]
	v_pk_add_f32 v[120:121], v[120:121], v[218:219]
	v_pk_mul_f32 v[218:219], v[126:127], v[126:127]
	v_cvt_pk_bf16_f32 v112, v124, v125
	v_cvt_pk_bf16_f32 v113, v126, v127
	v_pk_mul_f32 v[124:125], v[116:117], v[116:117]
	v_pk_mul_f32 v[126:127], v[118:119], v[118:119]
	v_pk_mul_f32 v[224:225], v[146:147], v[146:147]
	v_cvt_pk_bf16_f32 v116, v116, v117
	v_cvt_pk_bf16_f32 v117, v118, v119
	v_cvt_pk_bf16_f32 v118, v146, v147
	v_add_f32_e32 v146, v196, v197
	v_add_f32_e32 v146, v218, v146
	v_pk_mul_f32 v[220:221], v[120:121], v[120:121]
	v_add_f32_e32 v146, v219, v146
	v_add_f32_e32 v146, v220, v146
	v_pk_mul_f32 v[222:223], v[122:123], v[122:123]
	v_add_f32_e32 v146, v221, v146
	v_add_f32_e32 v146, v222, v146
	v_add_f32_e32 v146, v223, v146
	v_add_f32_e32 v124, v124, v146
	v_add_f32_e32 v124, v125, v124
	v_add_f32_e32 v124, v126, v124
	v_add_f32_e32 v124, v127, v124
	v_add_f32_e32 v124, v224, v124
	v_pk_mul_f32 v[226:227], v[148:149], v[148:149]
	v_add_f32_e32 v124, v225, v124
	v_add_f32_e32 v124, v226, v124
	v_add_f32_e32 v209, v227, v124
	v_lshlrev_b32_e32 v124, 16, v210
	v_and_b32_e32 v125, 0xffff0000, v210
	v_pk_add_f32 v[100:101], v[100:101], v[124:125]
	v_lshlrev_b32_e32 v124, 16, v212
	v_and_b32_e32 v125, 0xffff0000, v212
	v_pk_add_f32 v[124:125], v[92:93], v[124:125]
	v_lshlrev_b32_e32 v92, 16, v211
	v_and_b32_e32 v93, 0xffff0000, v211
	v_pk_add_f32 v[102:103], v[102:103], v[92:93]
	v_lshlrev_b32_e32 v92, 16, v213
	v_and_b32_e32 v93, 0xffff0000, v213
	v_pk_add_f32 v[126:127], v[94:95], v[92:93]
	v_lshlrev_b32_e32 v92, 16, v214
	v_and_b32_e32 v93, 0xffff0000, v214
	v_pk_add_f32 v[92:93], v[96:97], v[92:93]
	v_lshlrev_b32_e32 v96, 16, v217
	v_and_b32_e32 v97, 0xffff0000, v217
	v_lshlrev_b32_e32 v94, 16, v216
	v_and_b32_e32 v95, 0xffff0000, v216
	v_pk_add_f32 v[90:91], v[90:91], v[96:97]
	v_lshlrev_b32_e32 v96, 16, v136
	v_and_b32_e32 v97, 0xffff0000, v136
	v_pk_add_f32 v[88:89], v[88:89], v[94:95]
	v_lshlrev_b32_e32 v94, 16, v215
	v_and_b32_e32 v95, 0xffff0000, v215
	v_pk_add_f32 v[96:97], v[76:77], v[96:97]
	v_lshl_add_u64 v[76:77], v[168:169], 0, s[36:37]
	v_cvt_pk_bf16_f32 v114, v120, v121
	v_pk_add_f32 v[120:121], v[108:109], v[182:183]
	v_pk_add_f32 v[94:95], v[98:99], v[94:95]
	v_lshlrev_b64 v[182:183], 11, v[76:77]
	v_lshlrev_b32_e32 v98, 16, v138
	v_and_b32_e32 v99, 0xffff0000, v138
	v_pk_add_f32 v[108:109], v[104:105], v[184:185]
	v_lshl_add_u64 v[184:185], v[174:175], 0, v[182:183]
	v_pk_add_f32 v[98:99], v[72:73], v[98:99]
	v_lshlrev_b32_e32 v72, 16, v137
	v_and_b32_e32 v73, 0xffff0000, v137
	global_load_dwordx4 v[210:213], v[184:185], off
	global_load_dwordx4 v[218:221], v[184:185], off offset:256
	v_pk_add_f32 v[136:137], v[78:79], v[72:73]
	v_lshlrev_b32_e32 v72, 16, v139
	v_and_b32_e32 v73, 0xffff0000, v139
	v_pk_add_f32 v[138:139], v[74:75], v[72:73]
	v_lshlrev_b32_e32 v72, 16, v132
	v_and_b32_e32 v73, 0xffff0000, v132
	v_pk_add_f32 v[74:75], v[84:85], v[72:73]
	v_lshlrev_b32_e32 v72, 16, v134
	v_and_b32_e32 v73, 0xffff0000, v134
	v_pk_add_f32 v[78:79], v[80:81], v[72:73]
	v_lshlrev_b32_e32 v72, 16, v133
	v_and_b32_e32 v73, 0xffff0000, v133
	v_pk_add_f32 v[80:81], v[86:87], v[72:73]
	v_lshlrev_b32_e32 v72, 16, v135
	v_and_b32_e32 v73, 0xffff0000, v135
	v_pk_add_f32 v[82:83], v[82:83], v[72:73]
	v_lshl_add_u64 v[72:73], v[168:169], 0, s[10:11]
	v_lshlrev_b64 v[132:133], 11, v[72:73]
	v_lshl_add_u64 v[134:135], v[174:175], 0, v[132:133]
	v_lshlrev_b32_e32 v84, 16, v128
	v_and_b32_e32 v85, 0xffff0000, v128
	global_load_dwordx4 v[226:229], v[134:135], off
	global_load_dwordx4 v[234:237], v[134:135], off offset:256
	v_pk_add_f32 v[84:85], v[68:69], v[84:85]
	v_lshlrev_b32_e32 v68, 16, v130
	v_and_b32_e32 v69, 0xffff0000, v130
	v_pk_add_f32 v[86:87], v[64:65], v[68:69]
	v_lshlrev_b32_e32 v64, 16, v129
	v_and_b32_e32 v65, 0xffff0000, v129
	s_mov_b64 s[10:11], 0xa0
	v_pk_add_f32 v[128:129], v[70:71], v[64:65]
	v_lshl_add_u64 v[70:71], v[168:169], 0, s[10:11]
	s_mov_b64 s[10:11], 0xb0
	v_lshlrev_b32_e32 v64, 16, v131
	v_and_b32_e32 v65, 0xffff0000, v131
	v_lshlrev_b64 v[134:135], 11, v[70:71]
	v_lshl_add_u64 v[68:69], v[168:169], 0, s[10:11]
	v_pk_add_f32 v[130:131], v[66:67], v[64:65]
	v_lshl_add_u64 v[64:65], v[174:175], 0, v[134:135]
	v_lshlrev_b64 v[184:185], 11, v[68:69]
	global_load_dwordx4 v[238:241], v[64:65], off
	global_load_dwordx4 v[242:245], v[64:65], off offset:256
	v_lshl_add_u64 v[64:65], v[174:175], 0, v[184:185]
	global_load_dwordx4 v[246:249], v[64:65], off
	s_nop 0
	global_load_dwordx4 v[64:67], v[64:65], off offset:256
	v_cvt_pk_bf16_f32 v115, v122, v123
	v_cvt_pk_bf16_f32 v119, v148, v149
	v_pk_add_f32 v[110:111], v[110:111], v[192:193]
	v_pk_add_f32 v[122:123], v[106:107], v[194:195]
	global_store_dwordx4 v[172:173], v[112:115], off
	global_store_dwordx4 v[172:173], v[116:119], off offset:256
	v_cvt_pk_bf16_f32 v104, v120, v121
	v_lshl_add_u64 v[112:113], s[28:29], 0, v[176:177]
	v_cvt_pk_bf16_f32 v105, v110, v111
	v_cvt_pk_bf16_f32 v106, v108, v109
	v_cvt_pk_bf16_f32 v107, v122, v123
	v_lshl_add_u64 v[112:113], v[112:113], 0, v[170:171]
	v_cvt_pk_bf16_f32 v146, v100, v101
	v_cvt_pk_bf16_f32 v147, v102, v103
	v_cvt_pk_bf16_f32 v148, v124, v125
	v_cvt_pk_bf16_f32 v149, v126, v127
	global_store_dwordx4 v[112:113], v[104:107], off
	global_store_dwordx4 v[112:113], v[146:149], off offset:256
	v_cvt_pk_bf16_f32 v194, v92, v93
	v_lshl_add_u64 v[104:105], s[28:29], 0, v[180:181]
	v_cvt_pk_bf16_f32 v195, v94, v95
	v_cvt_pk_bf16_f32 v196, v88, v89
	v_cvt_pk_bf16_f32 v197, v90, v91
	v_lshl_add_u64 v[104:105], v[104:105], 0, v[170:171]
	v_cvt_pk_bf16_f32 v214, v96, v97
	v_cvt_pk_bf16_f32 v215, v136, v137
	v_cvt_pk_bf16_f32 v216, v98, v99
	v_cvt_pk_bf16_f32 v217, v138, v139
	global_store_dwordx4 v[104:105], v[194:197], off
	global_store_dwordx4 v[104:105], v[214:217], off offset:256
	v_lshl_add_u64 v[104:105], s[28:29], 0, v[178:179]
	v_cvt_pk_bf16_f32 v222, v74, v75
	v_cvt_pk_bf16_f32 v223, v80, v81
	v_cvt_pk_bf16_f32 v224, v78, v79
	v_cvt_pk_bf16_f32 v225, v82, v83
	v_lshl_add_u64 v[104:105], v[104:105], 0, v[170:171]
	v_cvt_pk_bf16_f32 v230, v84, v85
	v_cvt_pk_bf16_f32 v231, v128, v129
	v_cvt_pk_bf16_f32 v232, v86, v87
	v_cvt_pk_bf16_f32 v233, v130, v131
	global_store_dwordx4 v[104:105], v[222:225], off
	global_store_dwordx4 v[104:105], v[230:233], off offset:256
	s_waitcnt vmcnt(8)
	v_lshlrev_b32_e32 v104, 16, v210
	v_and_b32_e32 v105, 0xffff0000, v210
	v_pk_add_f32 v[60:61], v[60:61], v[104:105]
	v_lshlrev_b32_e32 v104, 16, v212
	v_and_b32_e32 v105, 0xffff0000, v212
	v_pk_add_f32 v[56:57], v[56:57], v[104:105]
	v_lshlrev_b32_e32 v104, 16, v211
	v_and_b32_e32 v105, 0xffff0000, v211
	v_pk_add_f32 v[62:63], v[62:63], v[104:105]
	v_lshlrev_b32_e32 v104, 16, v213
	v_and_b32_e32 v105, 0xffff0000, v213
	v_pk_add_f32 v[58:59], v[58:59], v[104:105]
	v_lshlrev_b32_e32 v104, 16, v218
	v_and_b32_e32 v105, 0xffff0000, v218
	v_pk_add_f32 v[52:53], v[52:53], v[104:105]
	v_lshlrev_b32_e32 v104, 16, v220
	v_and_b32_e32 v105, 0xffff0000, v220
	v_pk_add_f32 v[104:105], v[44:45], v[104:105]
	v_lshlrev_b32_e32 v44, 16, v219
	v_and_b32_e32 v45, 0xffff0000, v219
	v_pk_add_f32 v[54:55], v[54:55], v[44:45]
	v_lshlrev_b32_e32 v44, 16, v221
	v_and_b32_e32 v45, 0xffff0000, v221
	v_pk_add_f32 v[106:107], v[46:47], v[44:45]
	v_lshlrev_b32_e32 v44, 16, v226
	v_and_b32_e32 v45, 0xffff0000, v226
	v_pk_add_f32 v[44:45], v[48:49], v[44:45]
	v_lshlrev_b32_e32 v48, 16, v229
	v_and_b32_e32 v49, 0xffff0000, v229
	v_pk_add_f32 v[42:43], v[42:43], v[48:49]
	v_lshlrev_b32_e32 v48, 16, v234
	v_and_b32_e32 v49, 0xffff0000, v234
	v_pk_add_f32 v[36:37], v[36:37], v[48:49]
	v_lshlrev_b32_e32 v48, 16, v236
	v_and_b32_e32 v49, 0xffff0000, v236
	v_lshlrev_b32_e32 v46, 16, v228
	v_and_b32_e32 v47, 0xffff0000, v228
	v_pk_add_f32 v[48:49], v[28:29], v[48:49]
	v_lshlrev_b32_e32 v28, 16, v235
	v_and_b32_e32 v29, 0xffff0000, v235
	v_pk_add_f32 v[40:41], v[40:41], v[46:47]
	v_lshlrev_b32_e32 v46, 16, v227
	v_and_b32_e32 v47, 0xffff0000, v227
	v_pk_add_f32 v[38:39], v[38:39], v[28:29]
	v_lshlrev_b32_e32 v28, 16, v237
	v_and_b32_e32 v29, 0xffff0000, v237
	v_pk_add_f32 v[46:47], v[50:51], v[46:47]
	v_pk_add_f32 v[50:51], v[30:31], v[28:29]
	v_lshlrev_b32_e32 v28, 16, v238
	v_and_b32_e32 v29, 0xffff0000, v238
	v_lshlrev_b32_e32 v180, 16, v64
	v_and_b32_e32 v181, 0xffff0000, v64
	v_pk_add_f32 v[28:29], v[32:33], v[28:29]
	v_lshlrev_b32_e32 v32, 16, v241
	v_and_b32_e32 v33, 0xffff0000, v241
	v_pk_add_f32 v[4:5], v[4:5], v[180:181]
	v_lshlrev_b32_e32 v180, 16, v66
	v_and_b32_e32 v181, 0xffff0000, v66
	v_pk_add_f32 v[26:27], v[26:27], v[32:33]
	v_lshlrev_b32_e32 v32, 16, v242
	v_and_b32_e32 v33, 0xffff0000, v242
	v_pk_add_f32 v[0:1], v[0:1], v[180:181]
	v_lshl_add_u64 v[180:181], s[28:29], 0, v[182:183]
	v_cvt_pk_bf16_f32 v112, v60, v61
	v_cvt_pk_bf16_f32 v113, v62, v63
	v_cvt_pk_bf16_f32 v114, v56, v57
	v_cvt_pk_bf16_f32 v115, v58, v59
	v_pk_add_f32 v[20:21], v[20:21], v[32:33]
	v_lshlrev_b32_e32 v32, 16, v244
	v_and_b32_e32 v33, 0xffff0000, v244
	v_lshl_add_u64 v[180:181], v[180:181], 0, v[170:171]
	v_cvt_pk_bf16_f32 v116, v52, v53
	v_cvt_pk_bf16_f32 v117, v54, v55
	v_cvt_pk_bf16_f32 v118, v104, v105
	v_cvt_pk_bf16_f32 v119, v106, v107
	v_lshlrev_b32_e32 v30, 16, v240
	v_and_b32_e32 v31, 0xffff0000, v240
	v_pk_add_f32 v[32:33], v[12:13], v[32:33]
	v_lshlrev_b32_e32 v12, 16, v243
	v_and_b32_e32 v13, 0xffff0000, v243
	global_store_dwordx4 v[180:181], v[112:115], off
	global_store_dwordx4 v[180:181], v[116:119], off offset:256
	v_cvt_pk_bf16_f32 v146, v44, v45
	v_lshl_add_u64 v[112:113], s[28:29], 0, v[132:133]
	v_cvt_pk_bf16_f32 v147, v46, v47
	v_cvt_pk_bf16_f32 v148, v40, v41
	v_cvt_pk_bf16_f32 v149, v42, v43
	v_pk_add_f32 v[24:25], v[24:25], v[30:31]
	v_lshlrev_b32_e32 v30, 16, v239
	v_and_b32_e32 v31, 0xffff0000, v239
	v_pk_add_f32 v[22:23], v[22:23], v[12:13]
	v_lshlrev_b32_e32 v12, 16, v245
	v_and_b32_e32 v13, 0xffff0000, v245
	v_lshl_add_u64 v[112:113], v[112:113], 0, v[170:171]
	v_cvt_pk_bf16_f32 v172, v36, v37
	v_cvt_pk_bf16_f32 v173, v38, v39
	v_cvt_pk_bf16_f32 v174, v48, v49
	v_cvt_pk_bf16_f32 v175, v50, v51
	v_pk_add_f32 v[30:31], v[34:35], v[30:31]
	v_pk_add_f32 v[34:35], v[14:15], v[12:13]
	v_lshlrev_b32_e32 v12, 16, v246
	v_and_b32_e32 v13, 0xffff0000, v246
	v_lshlrev_b32_e32 v14, 16, v248
	v_and_b32_e32 v15, 0xffff0000, v248
	global_store_dwordx4 v[112:113], v[146:149], off
	global_store_dwordx4 v[112:113], v[172:175], off offset:256
	v_lshl_add_u64 v[112:113], s[28:29], 0, v[134:135]
	v_cvt_pk_bf16_f32 v176, v28, v29
	v_cvt_pk_bf16_f32 v177, v30, v31
	v_cvt_pk_bf16_f32 v178, v24, v25
	v_cvt_pk_bf16_f32 v179, v26, v27
	v_pk_add_f32 v[12:13], v[16:17], v[12:13]
	v_pk_add_f32 v[8:9], v[8:9], v[14:15]
	v_lshlrev_b32_e32 v14, 16, v247
	v_and_b32_e32 v15, 0xffff0000, v247
	v_lshlrev_b32_e32 v16, 16, v249
	v_and_b32_e32 v17, 0xffff0000, v249
	v_lshlrev_b32_e32 v64, 16, v65
	v_and_b32_e32 v65, 0xffff0000, v65
	v_lshl_add_u64 v[112:113], v[112:113], 0, v[170:171]
	v_cvt_pk_bf16_f32 v194, v20, v21
	v_cvt_pk_bf16_f32 v195, v22, v23
	v_cvt_pk_bf16_f32 v196, v32, v33
	v_cvt_pk_bf16_f32 v197, v34, v35
	v_pk_add_f32 v[14:15], v[18:19], v[14:15]
	v_pk_add_f32 v[10:11], v[10:11], v[16:17]
	v_pk_add_f32 v[6:7], v[6:7], v[64:65]
	v_lshlrev_b32_e32 v64, 16, v67
	v_and_b32_e32 v65, 0xffff0000, v67
	global_store_dwordx4 v[112:113], v[176:179], off
	global_store_dwordx4 v[112:113], v[194:197], off offset:256
	v_lshl_add_u64 v[112:113], s[28:29], 0, v[184:185]
	v_cvt_pk_bf16_f32 v16, v12, v13
	v_cvt_pk_bf16_f32 v17, v14, v15
	v_cvt_pk_bf16_f32 v18, v8, v9
	v_cvt_pk_bf16_f32 v19, v10, v11
	v_pk_add_f32 v[2:3], v[2:3], v[64:65]
	v_lshl_add_u64 v[112:113], v[112:113], 0, v[170:171]
	v_cvt_pk_bf16_f32 v64, v4, v5
	v_cvt_pk_bf16_f32 v65, v6, v7
	v_cvt_pk_bf16_f32 v66, v0, v1
	v_cvt_pk_bf16_f32 v67, v2, v3
	global_store_dwordx4 v[112:113], v[16:19], off
	global_store_dwordx4 v[112:113], v[64:67], off offset:256
	s_lshl_b32 s10, s85, 2
	v_and_b32_e32 v17, 64, v188
	v_xor_b32_e32 v16, 16, v188
	v_add_u32_e32 v17, 64, v17
	v_cmp_lt_i32_e32 vcc, v16, v17
	v_xor_b32_e32 v18, 32, v188
	s_ashr_i32 s11, s10, 31
	v_cndmask_b32_e32 v16, v188, v16, vcc
	v_lshlrev_b32_e32 v16, 2, v16
	v_mov_b32_e32 v132, v209
	v_cmp_lt_i32_e32 vcc, v18, v17
	s_lshl_b64 s[10:11], s[10:11], 2
	s_add_u32 s50, s83, s10
	v_cndmask_b32_e32 v17, v188, v18, vcc
	v_lshlrev_b32_e32 v17, 2, v17
	s_addc_u32 s51, s84, s11
	v_pk_mul_f32 v[18:19], v[120:121], v[120:121]
	v_pk_mul_f32 v[64:65], v[110:111], v[110:111]
	v_add_f32_e32 v18, v18, v19
	v_add_f32_e32 v18, v64, v18
	v_pk_mul_f32 v[66:67], v[108:109], v[108:109]
	v_add_f32_e32 v18, v65, v18
	v_add_f32_e32 v18, v66, v18
	v_pk_mul_f32 v[108:109], v[122:123], v[122:123]
	v_add_f32_e32 v18, v67, v18
	v_add_f32_e32 v18, v108, v18
	v_pk_mul_f32 v[100:101], v[100:101], v[100:101]
	v_add_f32_e32 v18, v109, v18
	v_add_f32_e32 v18, v100, v18
	v_pk_mul_f32 v[102:103], v[102:103], v[102:103]
	v_add_f32_e32 v18, v101, v18
	v_add_f32_e32 v18, v102, v18
	v_pk_mul_f32 v[110:111], v[124:125], v[124:125]
	v_add_f32_e32 v18, v103, v18
	v_add_f32_e32 v18, v110, v18
	v_pk_mul_f32 v[112:113], v[126:127], v[126:127]
	v_add_f32_e32 v18, v111, v18
	v_add_f32_e32 v18, v112, v18
	v_add_f32_e32 v18, v113, v18
	v_mov_b32_e32 v133, v18
	v_pk_mul_f32 v[18:19], v[92:93], v[92:93]
	v_pk_mul_f32 v[64:65], v[94:95], v[94:95]
	v_add_f32_e32 v18, v18, v19
	v_add_f32_e32 v18, v64, v18
	v_pk_mul_f32 v[66:67], v[88:89], v[88:89]
	v_add_f32_e32 v18, v65, v18
	v_add_f32_e32 v18, v66, v18
	v_pk_mul_f32 v[88:89], v[90:91], v[90:91]
	v_add_f32_e32 v18, v67, v18
	v_add_f32_e32 v18, v88, v18
	v_pk_mul_f32 v[90:91], v[96:97], v[96:97]
	v_add_f32_e32 v18, v89, v18
	v_add_f32_e32 v18, v90, v18
	v_pk_mul_f32 v[92:93], v[136:137], v[136:137]
	v_add_f32_e32 v18, v91, v18
	v_add_f32_e32 v18, v92, v18
	v_pk_mul_f32 v[94:95], v[98:99], v[98:99]
	v_add_f32_e32 v18, v93, v18
	v_add_f32_e32 v18, v94, v18
	v_pk_mul_f32 v[96:97], v[138:139], v[138:139]
	v_add_f32_e32 v18, v95, v18
	v_add_f32_e32 v18, v96, v18
	v_add_f32_e32 v18, v97, v18
	v_mov_b32_e32 v134, v18
	v_pk_mul_f32 v[18:19], v[74:75], v[74:75]
	v_pk_mul_f32 v[192:193], v[60:61], v[60:61]
	v_pk_mul_f32 v[64:65], v[80:81], v[80:81]
	v_pk_mul_f32 v[60:61], v[62:63], v[62:63]
	v_add_f32_e32 v18, v18, v19
	v_add_f32_e32 v192, v192, v193
	v_add_f32_e32 v18, v64, v18
	v_add_f32_e32 v192, v60, v192
	v_pk_mul_f32 v[66:67], v[78:79], v[78:79]
	v_pk_mul_f32 v[56:57], v[56:57], v[56:57]
	v_add_f32_e32 v18, v65, v18
	v_add_f32_e32 v192, v61, v192
	v_add_f32_e32 v18, v66, v18
	v_add_f32_e32 v192, v56, v192
	v_pk_mul_f32 v[74:75], v[82:83], v[82:83]
	v_pk_mul_f32 v[58:59], v[58:59], v[58:59]
	v_add_f32_e32 v18, v67, v18
	v_add_f32_e32 v192, v57, v192
	v_add_f32_e32 v18, v74, v18
	v_add_f32_e32 v192, v58, v192
	v_pk_mul_f32 v[78:79], v[84:85], v[84:85]
	v_pk_mul_f32 v[52:53], v[52:53], v[52:53]
	v_add_f32_e32 v18, v75, v18
	v_add_f32_e32 v192, v59, v192
	v_add_f32_e32 v18, v78, v18
	v_add_f32_e32 v192, v52, v192
	v_pk_mul_f32 v[80:81], v[128:129], v[128:129]
	v_pk_mul_f32 v[54:55], v[54:55], v[54:55]
	v_add_f32_e32 v18, v79, v18
	v_add_f32_e32 v192, v53, v192
	v_add_f32_e32 v18, v80, v18
	v_add_f32_e32 v192, v54, v192
	v_pk_mul_f32 v[82:83], v[86:87], v[86:87]
	v_pk_mul_f32 v[62:63], v[104:105], v[104:105]
	v_add_f32_e32 v18, v81, v18
	v_add_f32_e32 v192, v55, v192
	v_add_f32_e32 v18, v82, v18
	v_add_f32_e32 v192, v62, v192
	v_pk_mul_f32 v[84:85], v[130:131], v[130:131]
	v_pk_mul_f32 v[210:211], v[106:107], v[106:107]
	v_add_f32_e32 v18, v83, v18
	v_add_f32_e32 v192, v63, v192
	v_add_f32_e32 v18, v84, v18
	v_add_f32_e32 v192, v210, v192
	v_add_f32_e32 v18, v85, v18
	v_add_f32_e32 v192, v211, v192
	v_mov_b32_e32 v135, v18
	v_mov_b32_e32 v146, v192
	v_pk_mul_f32 v[18:19], v[44:45], v[44:45]
	v_pk_mul_f32 v[192:193], v[28:29], v[28:29]
	v_pk_mul_f32 v[44:45], v[46:47], v[46:47]
	v_pk_mul_f32 v[28:29], v[30:31], v[30:31]
	v_add_f32_e32 v18, v18, v19
	v_add_f32_e32 v192, v192, v193
	v_add_f32_e32 v18, v44, v18
	v_add_f32_e32 v192, v28, v192
	v_pk_mul_f32 v[40:41], v[40:41], v[40:41]
	v_pk_mul_f32 v[24:25], v[24:25], v[24:25]
	v_add_f32_e32 v18, v45, v18
	v_add_f32_e32 v192, v29, v192
	v_add_f32_e32 v18, v40, v18
	v_add_f32_e32 v192, v24, v192
	v_pk_mul_f32 v[42:43], v[42:43], v[42:43]
	v_pk_mul_f32 v[26:27], v[26:27], v[26:27]
	v_add_f32_e32 v18, v41, v18
	v_add_f32_e32 v192, v25, v192
	v_add_f32_e32 v18, v42, v18
	v_add_f32_e32 v192, v26, v192
	v_pk_mul_f32 v[36:37], v[36:37], v[36:37]
	v_pk_mul_f32 v[20:21], v[20:21], v[20:21]
	v_add_f32_e32 v18, v43, v18
	v_add_f32_e32 v192, v27, v192
	v_add_f32_e32 v18, v36, v18
	v_add_f32_e32 v192, v20, v192
	v_pk_mul_f32 v[38:39], v[38:39], v[38:39]
	v_pk_mul_f32 v[22:23], v[22:23], v[22:23]
	v_add_f32_e32 v18, v37, v18
	v_add_f32_e32 v192, v21, v192
	v_add_f32_e32 v18, v38, v18
	v_add_f32_e32 v192, v22, v192
	v_pk_mul_f32 v[46:47], v[48:49], v[48:49]
	v_pk_mul_f32 v[30:31], v[32:33], v[32:33]
	v_add_f32_e32 v18, v39, v18
	v_add_f32_e32 v192, v23, v192
	v_add_f32_e32 v18, v46, v18
	v_add_f32_e32 v192, v30, v192
	v_pk_mul_f32 v[48:49], v[50:51], v[50:51]
	v_pk_mul_f32 v[32:33], v[34:35], v[34:35]
	v_add_f32_e32 v18, v47, v18
	v_add_f32_e32 v192, v31, v192
	v_add_f32_e32 v18, v48, v18
	v_add_f32_e32 v192, v32, v192
	v_add_f32_e32 v18, v49, v18
	v_add_f32_e32 v192, v33, v192
	v_mov_b32_e32 v147, v18
	v_mov_b32_e32 v148, v192
	v_pk_mul_f32 v[12:13], v[12:13], v[12:13]
	v_pk_mul_f32 v[14:15], v[14:15], v[14:15]
	v_add_f32_e32 v12, v12, v13
	v_add_f32_e32 v12, v14, v12
	v_pk_mul_f32 v[8:9], v[8:9], v[8:9]
	v_add_f32_e32 v12, v15, v12
	v_add_f32_e32 v8, v8, v12
	v_pk_mul_f32 v[10:11], v[10:11], v[10:11]
	v_add_f32_e32 v8, v9, v8
	v_add_f32_e32 v8, v10, v8
	v_pk_mul_f32 v[4:5], v[4:5], v[4:5]
	v_add_f32_e32 v8, v11, v8
	v_add_f32_e32 v4, v4, v8
	v_pk_mul_f32 v[6:7], v[6:7], v[6:7]
	v_add_f32_e32 v4, v5, v4
	v_add_f32_e32 v4, v6, v4
	v_pk_mul_f32 v[0:1], v[0:1], v[0:1]
	v_add_f32_e32 v4, v7, v4
	v_add_f32_e32 v0, v0, v4
	v_pk_mul_f32 v[2:3], v[2:3], v[2:3]
	v_add_f32_e32 v0, v1, v0
	v_add_f32_e32 v0, v2, v0
	v_add_f32_e32 v0, v3, v0
	v_mov_b32_e32 v149, v0
	ds_bpermute_b32 v172, v16, v132
	ds_bpermute_b32 v173, v16, v133
	ds_bpermute_b32 v174, v16, v134
	ds_bpermute_b32 v175, v16, v135
	ds_bpermute_b32 v180, v16, v146
	ds_bpermute_b32 v181, v16, v147
	ds_bpermute_b32 v182, v16, v148
	ds_bpermute_b32 v183, v16, v149
	s_waitcnt lgkmcnt(0)
	v_add_f32_e32 v132, v132, v172
	v_add_f32_e32 v133, v133, v173
	v_add_f32_e32 v134, v134, v174
	v_add_f32_e32 v135, v135, v175
	v_add_f32_e32 v146, v146, v180
	v_add_f32_e32 v147, v147, v181
	v_add_f32_e32 v148, v148, v182
	v_add_f32_e32 v149, v149, v183
	ds_bpermute_b32 v172, v17, v132
	ds_bpermute_b32 v173, v17, v133
	ds_bpermute_b32 v174, v17, v134
	ds_bpermute_b32 v175, v17, v135
	ds_bpermute_b32 v180, v17, v146
	ds_bpermute_b32 v181, v17, v147
	ds_bpermute_b32 v182, v17, v148
	ds_bpermute_b32 v183, v17, v149
	s_and_saveexec_b64 s[52:53], s[42:43]
	s_cbranch_execz .LBB0_91
	s_waitcnt lgkmcnt(0)
	v_add_f32_e32 v132, v132, v172
	v_lshlrev_b64 v[18:19], 6, v[168:169]
	v_lshl_add_u64 v[18:19], s[50:51], 0, v[18:19]
	global_store_dword v[18:19], v132, off
	v_add_f32_e32 v133, v133, v173
	v_lshlrev_b64 v[18:19], 6, v[166:167]
	v_lshl_add_u64 v[18:19], s[50:51], 0, v[18:19]
	global_store_dword v[18:19], v133, off
	v_add_f32_e32 v134, v134, v174
	v_lshlrev_b64 v[18:19], 6, v[164:165]
	v_lshl_add_u64 v[18:19], s[50:51], 0, v[18:19]
	global_store_dword v[18:19], v134, off
	v_add_f32_e32 v135, v135, v175
	v_lshlrev_b64 v[18:19], 6, v[162:163]
	v_lshl_add_u64 v[18:19], s[50:51], 0, v[18:19]
	global_store_dword v[18:19], v135, off
	v_add_f32_e32 v146, v146, v180
	v_lshlrev_b64 v[18:19], 6, v[76:77]
	v_lshl_add_u64 v[18:19], s[50:51], 0, v[18:19]
	global_store_dword v[18:19], v146, off
	v_add_f32_e32 v147, v147, v181
	v_lshlrev_b64 v[18:19], 6, v[72:73]
	v_lshl_add_u64 v[18:19], s[50:51], 0, v[18:19]
	global_store_dword v[18:19], v147, off
	v_add_f32_e32 v148, v148, v182
	v_lshlrev_b64 v[18:19], 6, v[70:71]
	v_lshl_add_u64 v[18:19], s[50:51], 0, v[18:19]
	global_store_dword v[18:19], v148, off
	v_add_f32_e32 v149, v149, v183
	v_lshlrev_b64 v[18:19], 6, v[68:69]
	v_lshl_add_u64 v[18:19], s[50:51], 0, v[18:19]
	global_store_dword v[18:19], v149, off
	s_branch .LBB0_91

.Lm4bp_248:
	s_waitcnt lgkmcnt(0)
	s_mov_b32 s100, 0
	s_barrier
	v_mfma_f32_16x16x32_bf16 v[60:63], v[128:131], v[162:165], 0
	v_mfma_f32_16x16x32_bf16 v[56:59], v[136:139], v[162:165], 0
	v_mfma_f32_16x16x32_bf16 v[48:51], v[128:131], v[170:173], 0
	v_mfma_f32_16x16x32_bf16 v[40:43], v[136:139], v[170:173], 0
	v_mfma_f32_16x16x32_bf16 v[32:35], v[128:131], v[178:181], 0
	v_mfma_f32_16x16x32_bf16 v[24:27], v[136:139], v[178:181], 0
	v_mfma_f32_16x16x32_bf16 v[16:19], v[128:131], v[194:197], 0
	v_mfma_f32_16x16x32_bf16 v[8:11], v[136:139], v[194:197], 0
	v_mfma_f32_16x16x32_bf16 v[60:63], v[132:135], v[166:169], v[60:63]
	v_mfma_f32_16x16x32_bf16 v[56:59], v[146:149], v[166:169], v[56:59]
	v_mfma_f32_16x16x32_bf16 v[48:51], v[132:135], v[174:177], v[48:51]
	v_mfma_f32_16x16x32_bf16 v[40:43], v[146:149], v[174:177], v[40:43]
	v_mfma_f32_16x16x32_bf16 v[32:35], v[132:135], v[182:185], v[32:35]
	v_mfma_f32_16x16x32_bf16 v[24:27], v[146:149], v[182:185], v[24:27]
	v_mfma_f32_16x16x32_bf16 v[16:19], v[132:135], v[210:213], v[16:19]
	v_mfma_f32_16x16x32_bf16 v[8:11], v[146:149], v[210:213], v[8:11]
	v_mfma_f32_16x16x32_bf16 v[52:55], v[214:217], v[162:165], 0
	v_mfma_f32_16x16x32_bf16 v[44:47], v[222:225], v[162:165], 0
	v_mfma_f32_16x16x32_bf16 v[36:39], v[214:217], v[170:173], 0
	v_mfma_f32_16x16x32_bf16 v[28:31], v[222:225], v[170:173], 0
	v_mfma_f32_16x16x32_bf16 v[20:23], v[214:217], v[178:181], 0
	v_mfma_f32_16x16x32_bf16 v[12:15], v[222:225], v[178:181], 0
	v_mfma_f32_16x16x32_bf16 v[4:7], v[214:217], v[194:197], 0
	v_mfma_f32_16x16x32_bf16 v[0:3], v[222:225], v[194:197], 0
	v_mfma_f32_16x16x32_bf16 v[52:55], v[218:221], v[166:169], v[52:55]
	v_mfma_f32_16x16x32_bf16 v[44:47], v[226:229], v[166:169], v[44:47]
	v_mfma_f32_16x16x32_bf16 v[36:39], v[218:221], v[174:177], v[36:39]
	v_mfma_f32_16x16x32_bf16 v[28:31], v[226:229], v[174:177], v[28:31]
	v_mfma_f32_16x16x32_bf16 v[20:23], v[218:221], v[182:185], v[20:23]
	v_mfma_f32_16x16x32_bf16 v[12:15], v[226:229], v[182:185], v[12:15]
	v_mfma_f32_16x16x32_bf16 v[4:7], v[218:221], v[210:213], v[4:7]
	v_mfma_f32_16x16x32_bf16 v[0:3], v[226:229], v[210:213], v[0:3]
	s_barrier
	s_add_i32 s6, 0, 0x18000
	v_add_u32_e32 v146, s6, v206
	ds_read_b128 v[128:131], v146
	ds_read_b128 v[132:135], v146 offset:1024
	ds_read_b128 v[136:139], v146 offset:2048
	ds_read_b128 v[146:149], v146 offset:3072
	s_add_u32 s58, s58, 0x40000
	s_addc_u32 s59, s59, 0
	s_mov_b32 m0, s70
	v_lshl_add_u64 v[214:215], s[58:59], 0, v[154:155]
	ds_read_b128 v[162:165], v208 offset:32768
	ds_read_b128 v[166:169], v208 offset:33792
	ds_read_b128 v[170:173], v208 offset:34816
	ds_read_b128 v[174:177], v208 offset:35840
	ds_read_b128 v[178:181], v208 offset:36864
	ds_read_b128 v[182:185], v208 offset:37888
	ds_read_b128 v[194:197], v208 offset:38912
	ds_read_b128 v[210:213], v208 offset:39936
	global_load_lds_dwordx4 v[214:215], off
	v_lshl_add_u64 v[214:215], s[58:59], 0, v[152:153]
	s_mov_b32 m0, s71
	s_nop 0
	global_load_lds_dwordx4 v[214:215], off
	s_add_i32 s19, 0, 0x1c000
	v_add_u32_e32 v192, s19, v206
	ds_read_b128 v[214:217], v192
	ds_read_b128 v[218:221], v192 offset:1024
	ds_read_b128 v[222:225], v192 offset:2048
	ds_read_b128 v[226:229], v192 offset:3072
	s_waitcnt vmcnt(8)
	s_waitcnt lgkmcnt(0)
	s_barrier
	v_mfma_f32_16x16x32_bf16 v[124:127], v[128:131], v[162:165], v[124:127]
	v_mfma_f32_16x16x32_bf16 v[120:123], v[136:139], v[162:165], v[120:123]
	v_mfma_f32_16x16x32_bf16 v[108:111], v[128:131], v[170:173], v[108:111]
	v_mfma_f32_16x16x32_bf16 v[104:107], v[136:139], v[170:173], v[104:107]
	v_mfma_f32_16x16x32_bf16 v[96:99], v[128:131], v[178:181], v[96:99]
	v_mfma_f32_16x16x32_bf16 v[88:91], v[136:139], v[178:181], v[88:91]
	v_mfma_f32_16x16x32_bf16 v[84:87], v[128:131], v[194:197], v[84:87]
	v_mfma_f32_16x16x32_bf16 v[80:83], v[136:139], v[194:197], v[80:83]
	v_mfma_f32_16x16x32_bf16 v[124:127], v[132:135], v[166:169], v[124:127]
	v_mfma_f32_16x16x32_bf16 v[120:123], v[146:149], v[166:169], v[120:123]
	v_mfma_f32_16x16x32_bf16 v[108:111], v[132:135], v[174:177], v[108:111]
	v_mfma_f32_16x16x32_bf16 v[104:107], v[146:149], v[174:177], v[104:107]
	v_mfma_f32_16x16x32_bf16 v[96:99], v[132:135], v[182:185], v[96:99]
	v_mfma_f32_16x16x32_bf16 v[88:91], v[146:149], v[182:185], v[88:91]
	v_mfma_f32_16x16x32_bf16 v[84:87], v[132:135], v[210:213], v[84:87]
	v_mfma_f32_16x16x32_bf16 v[80:83], v[146:149], v[210:213], v[80:83]
	v_mfma_f32_16x16x32_bf16 v[116:119], v[214:217], v[162:165], v[116:119]
	v_mfma_f32_16x16x32_bf16 v[112:115], v[222:225], v[162:165], v[112:115]
	v_mfma_f32_16x16x32_bf16 v[100:103], v[214:217], v[170:173], v[100:103]
	v_mfma_f32_16x16x32_bf16 v[92:95], v[222:225], v[170:173], v[92:95]
	v_mfma_f32_16x16x32_bf16 v[76:79], v[214:217], v[178:181], v[76:79]
	v_mfma_f32_16x16x32_bf16 v[72:75], v[222:225], v[178:181], v[72:75]
	v_mfma_f32_16x16x32_bf16 v[68:71], v[214:217], v[194:197], v[68:71]
	v_mfma_f32_16x16x32_bf16 v[64:67], v[222:225], v[194:197], v[64:67]
	v_mfma_f32_16x16x32_bf16 v[116:119], v[218:221], v[166:169], v[116:119]
	v_mfma_f32_16x16x32_bf16 v[112:115], v[226:229], v[166:169], v[112:115]
	v_mfma_f32_16x16x32_bf16 v[100:103], v[218:221], v[174:177], v[100:103]
	v_mfma_f32_16x16x32_bf16 v[92:95], v[226:229], v[174:177], v[92:95]
	v_mfma_f32_16x16x32_bf16 v[76:79], v[218:221], v[182:185], v[76:79]
	v_mfma_f32_16x16x32_bf16 v[72:75], v[226:229], v[182:185], v[72:75]
	v_mfma_f32_16x16x32_bf16 v[68:71], v[218:221], v[210:213], v[68:71]
	v_mfma_f32_16x16x32_bf16 v[64:67], v[226:229], v[210:213], v[64:67]
	s_barrier
	s_add_i32 s6, s6, s57
	v_lshl_add_u64 v[230:231], v[230:231], 0, s[36:37]
	s_mov_b32 m0, s6
	s_nop 0
	global_load_lds_dwordx4 v[230:231], off
	v_lshl_add_u64 v[230:231], v[232:233], 0, s[36:37]
	s_add_i32 m0, s6, 0x2000
	s_nop 0
	global_load_lds_dwordx4 v[230:231], off
	s_mov_b32 m0, s72
	v_lshl_add_u64 v[230:231], v[234:235], 0, s[36:37]
	ds_read_b128 v[162:165], v208 offset:49152
	ds_read_b128 v[166:169], v208 offset:50176
	ds_read_b128 v[170:173], v208 offset:51200
	ds_read_b128 v[174:177], v208 offset:52224
	ds_read_b128 v[178:181], v208 offset:53248
	ds_read_b128 v[182:185], v208 offset:54272
	ds_read_b128 v[194:197], v208 offset:55296
	ds_read_b128 v[210:213], v208 offset:56320
	global_load_lds_dwordx4 v[230:231], off
	v_lshl_add_u64 v[230:231], v[236:237], 0, s[36:37]
	s_mov_b32 m0, s73
	s_nop 0
	global_load_lds_dwordx4 v[230:231], off
	s_add_u32 s54, s54, 0x40080
	s_addc_u32 s55, s55, 0
	s_add_i32 s6, s19, s57
	v_lshl_add_u64 v[250:251], s[54:55], 0, v[140:141]
	s_mov_b32 m0, s6
	s_nop 0
	global_load_lds_dwordx4 v[250:251], off
	v_lshl_add_u64 v[250:251], s[54:55], 0, v[150:151]
	s_add_i32 m0, s6, 0x2000
	s_nop 0
	global_load_lds_dwordx4 v[250:251], off
	s_add_i32 s82, s82, 2
	s_add_u32 s52, s52, 0x100
	s_addc_u32 s53, s53, 0
	s_add_u32 s39, s39, 0x100
	s_addc_u32 s51, s51, 0
	s_cmp_gt_u32 s82, 13
	s_waitcnt vmcnt(8)
	s_waitcnt lgkmcnt(0)
	s_barrier
	v_mfma_f32_16x16x32_bf16 v[60:63], v[128:131], v[162:165], v[60:63]
	v_mfma_f32_16x16x32_bf16 v[56:59], v[136:139], v[162:165], v[56:59]
	v_mfma_f32_16x16x32_bf16 v[48:51], v[128:131], v[170:173], v[48:51]
	v_mfma_f32_16x16x32_bf16 v[40:43], v[136:139], v[170:173], v[40:43]
	v_mfma_f32_16x16x32_bf16 v[32:35], v[128:131], v[178:181], v[32:35]
	v_mfma_f32_16x16x32_bf16 v[24:27], v[136:139], v[178:181], v[24:27]
	v_mfma_f32_16x16x32_bf16 v[16:19], v[128:131], v[194:197], v[16:19]
	v_mfma_f32_16x16x32_bf16 v[8:11], v[136:139], v[194:197], v[8:11]
	v_mfma_f32_16x16x32_bf16 v[60:63], v[132:135], v[166:169], v[60:63]
	v_mfma_f32_16x16x32_bf16 v[56:59], v[146:149], v[166:169], v[56:59]
	v_mfma_f32_16x16x32_bf16 v[48:51], v[132:135], v[174:177], v[48:51]
	v_mfma_f32_16x16x32_bf16 v[40:43], v[146:149], v[174:177], v[40:43]
	v_mfma_f32_16x16x32_bf16 v[32:35], v[132:135], v[182:185], v[32:35]
	v_mfma_f32_16x16x32_bf16 v[24:27], v[146:149], v[182:185], v[24:27]
	v_mfma_f32_16x16x32_bf16 v[16:19], v[132:135], v[210:213], v[16:19]
	v_mfma_f32_16x16x32_bf16 v[8:11], v[146:149], v[210:213], v[8:11]
	v_mfma_f32_16x16x32_bf16 v[52:55], v[214:217], v[162:165], v[52:55]
	v_mfma_f32_16x16x32_bf16 v[44:47], v[222:225], v[162:165], v[44:47]
	v_mfma_f32_16x16x32_bf16 v[36:39], v[214:217], v[170:173], v[36:39]
	v_mfma_f32_16x16x32_bf16 v[28:31], v[222:225], v[170:173], v[28:31]
	v_mfma_f32_16x16x32_bf16 v[20:23], v[214:217], v[178:181], v[20:23]
	v_mfma_f32_16x16x32_bf16 v[12:15], v[222:225], v[178:181], v[12:15]
	v_mfma_f32_16x16x32_bf16 v[4:7], v[214:217], v[194:197], v[4:7]
	v_mfma_f32_16x16x32_bf16 v[0:3], v[222:225], v[194:197], v[0:3]
	v_mfma_f32_16x16x32_bf16 v[52:55], v[218:221], v[166:169], v[52:55]
	v_mfma_f32_16x16x32_bf16 v[44:47], v[226:229], v[166:169], v[44:47]
	v_mfma_f32_16x16x32_bf16 v[36:39], v[218:221], v[174:177], v[36:39]
	v_mfma_f32_16x16x32_bf16 v[28:31], v[226:229], v[174:177], v[28:31]
	v_mfma_f32_16x16x32_bf16 v[20:23], v[218:221], v[182:185], v[20:23]
	v_mfma_f32_16x16x32_bf16 v[12:15], v[226:229], v[182:185], v[12:15]
	v_mfma_f32_16x16x32_bf16 v[4:7], v[218:221], v[210:213], v[4:7]
	v_mfma_f32_16x16x32_bf16 v[0:3], v[226:229], v[210:213], v[0:3]
	s_barrier
	.p2align	6
.LBB0_248:
	s_add_u32 s6, s52, 0xfffc0080
	s_addc_u32 s19, s53, -1
	s_add_i32 s23, 0, 0x10000
	v_add_u32_e32 v146, s23, v206
	ds_read_b128 v[128:131], v146
	ds_read_b128 v[132:135], v146 offset:1024
	ds_read_b128 v[136:139], v146 offset:2048
	ds_read_b128 v[146:149], v146 offset:3072
	s_cmp_eq_u32 s82, 12
	s_cselect_b32 s59, s10, s19
	s_cselect_b32 s58, s11, s6
	s_cselect_b32 s55, s12, s51
	s_cselect_b32 s54, s35, s39
	v_lshl_add_u64 v[214:215], s[52:53], 0, v[158:159]
	s_add_i32 m0, s68, 0xc000
	ds_read_b128 v[162:165], v208
	ds_read_b128 v[166:169], v208 offset:1024
	ds_read_b128 v[170:173], v208 offset:2048
	ds_read_b128 v[174:177], v208 offset:3072
	ds_read_b128 v[178:181], v208 offset:4096
	ds_read_b128 v[182:185], v208 offset:5120
	ds_read_b128 v[194:197], v208 offset:6144
	ds_read_b128 v[210:213], v208 offset:7168
	global_load_lds_dwordx4 v[214:215], off
	v_lshl_add_u64 v[214:215], s[52:53], 0, v[160:161]
	s_add_i32 m0, s68, 0xe000
	s_nop 0
	global_load_lds_dwordx4 v[214:215], off
	s_add_i32 s6, 0, 0x14000
	v_add_u32_e32 v192, s6, v206
	ds_read_b128 v[214:217], v192
	ds_read_b128 v[218:221], v192 offset:1024
	ds_read_b128 v[222:225], v192 offset:2048
	ds_read_b128 v[226:229], v192 offset:3072
	s_waitcnt vmcnt(8)
	s_waitcnt lgkmcnt(0)
	s_barrier
	v_mfma_f32_16x16x32_bf16 v[124:127], v[128:131], v[162:165], v[124:127]
	v_mfma_f32_16x16x32_bf16 v[120:123], v[136:139], v[162:165], v[120:123]
	v_mfma_f32_16x16x32_bf16 v[108:111], v[128:131], v[170:173], v[108:111]
	v_mfma_f32_16x16x32_bf16 v[104:107], v[136:139], v[170:173], v[104:107]
	v_mfma_f32_16x16x32_bf16 v[96:99], v[128:131], v[178:181], v[96:99]
	v_mfma_f32_16x16x32_bf16 v[88:91], v[136:139], v[178:181], v[88:91]
	v_mfma_f32_16x16x32_bf16 v[84:87], v[128:131], v[194:197], v[84:87]
	v_mfma_f32_16x16x32_bf16 v[80:83], v[136:139], v[194:197], v[80:83]
	v_mfma_f32_16x16x32_bf16 v[124:127], v[132:135], v[166:169], v[124:127]
	v_mfma_f32_16x16x32_bf16 v[120:123], v[146:149], v[166:169], v[120:123]
	v_mfma_f32_16x16x32_bf16 v[108:111], v[132:135], v[174:177], v[108:111]
	v_mfma_f32_16x16x32_bf16 v[104:107], v[146:149], v[174:177], v[104:107]
	v_mfma_f32_16x16x32_bf16 v[96:99], v[132:135], v[182:185], v[96:99]
	v_mfma_f32_16x16x32_bf16 v[88:91], v[146:149], v[182:185], v[88:91]
	v_mfma_f32_16x16x32_bf16 v[84:87], v[132:135], v[210:213], v[84:87]
	v_mfma_f32_16x16x32_bf16 v[80:83], v[146:149], v[210:213], v[80:83]
	v_mfma_f32_16x16x32_bf16 v[116:119], v[214:217], v[162:165], v[116:119]
	v_mfma_f32_16x16x32_bf16 v[112:115], v[222:225], v[162:165], v[112:115]
	v_mfma_f32_16x16x32_bf16 v[100:103], v[214:217], v[170:173], v[100:103]
	v_mfma_f32_16x16x32_bf16 v[92:95], v[222:225], v[170:173], v[92:95]
	v_mfma_f32_16x16x32_bf16 v[76:79], v[214:217], v[178:181], v[76:79]
	v_mfma_f32_16x16x32_bf16 v[72:75], v[222:225], v[178:181], v[72:75]
	v_mfma_f32_16x16x32_bf16 v[68:71], v[214:217], v[194:197], v[68:71]
	v_mfma_f32_16x16x32_bf16 v[64:67], v[222:225], v[194:197], v[64:67]
	v_mfma_f32_16x16x32_bf16 v[116:119], v[218:221], v[166:169], v[116:119]
	v_mfma_f32_16x16x32_bf16 v[112:115], v[226:229], v[166:169], v[112:115]
	v_mfma_f32_16x16x32_bf16 v[100:103], v[218:221], v[174:177], v[100:103]
	v_mfma_f32_16x16x32_bf16 v[92:95], v[226:229], v[174:177], v[92:95]
	v_mfma_f32_16x16x32_bf16 v[76:79], v[218:221], v[182:185], v[76:79]
	v_mfma_f32_16x16x32_bf16 v[72:75], v[226:229], v[182:185], v[72:75]
	v_mfma_f32_16x16x32_bf16 v[68:71], v[218:221], v[210:213], v[68:71]
	v_mfma_f32_16x16x32_bf16 v[64:67], v[226:229], v[210:213], v[64:67]
	s_barrier
	s_add_i32 s19, s23, s57
	v_lshl_add_u64 v[230:231], s[54:55], 0, v[140:141]
	s_mov_b32 m0, s19
	s_nop 0
	global_load_lds_dwordx4 v[230:231], off
	v_lshl_add_u64 v[232:233], s[54:55], 0, v[150:151]
	s_add_i32 m0, s19, 0x2000
	s_nop 0
	global_load_lds_dwordx4 v[232:233], off
	s_mov_b32 m0, s68
	v_lshl_add_u64 v[234:235], s[58:59], 0, v[154:155]
	ds_read_b128 v[162:165], v208 offset:16384
	ds_read_b128 v[166:169], v208 offset:17408
	ds_read_b128 v[170:173], v208 offset:18432
	ds_read_b128 v[174:177], v208 offset:19456
	ds_read_b128 v[178:181], v208 offset:20480
	ds_read_b128 v[182:185], v208 offset:21504
	ds_read_b128 v[194:197], v208 offset:22528
	ds_read_b128 v[210:213], v208 offset:23552
	global_load_lds_dwordx4 v[234:235], off
	v_lshl_add_u64 v[236:237], s[58:59], 0, v[152:153]
	s_mov_b32 m0, s69
	s_nop 0
	global_load_lds_dwordx4 v[236:237], off
	s_add_u32 s84, s54, 0x40000
	s_addc_u32 s85, s55, 0
	s_add_i32 s6, s6, s57
	v_lshl_add_u64 v[250:251], s[84:85], 0, v[140:141]
	s_mov_b32 m0, s6
	s_nop 0
	global_load_lds_dwordx4 v[250:251], off
	v_lshl_add_u64 v[250:251], s[84:85], 0, v[150:151]
	s_add_i32 m0, s6, 0x2000
	s_nop 0
	global_load_lds_dwordx4 v[250:251], off
	s_waitcnt vmcnt(8)
	s_waitcnt lgkmcnt(0)
	s_barrier
	v_mfma_f32_16x16x32_bf16 v[60:63], v[128:131], v[162:165], v[60:63]
	v_mfma_f32_16x16x32_bf16 v[56:59], v[136:139], v[162:165], v[56:59]
	v_mfma_f32_16x16x32_bf16 v[48:51], v[128:131], v[170:173], v[48:51]
	v_mfma_f32_16x16x32_bf16 v[40:43], v[136:139], v[170:173], v[40:43]
	v_mfma_f32_16x16x32_bf16 v[32:35], v[128:131], v[178:181], v[32:35]
	v_mfma_f32_16x16x32_bf16 v[24:27], v[136:139], v[178:181], v[24:27]
	v_mfma_f32_16x16x32_bf16 v[16:19], v[128:131], v[194:197], v[16:19]
	v_mfma_f32_16x16x32_bf16 v[8:11], v[136:139], v[194:197], v[8:11]
	v_mfma_f32_16x16x32_bf16 v[60:63], v[132:135], v[166:169], v[60:63]
	v_mfma_f32_16x16x32_bf16 v[56:59], v[146:149], v[166:169], v[56:59]
	v_mfma_f32_16x16x32_bf16 v[48:51], v[132:135], v[174:177], v[48:51]
	v_mfma_f32_16x16x32_bf16 v[40:43], v[146:149], v[174:177], v[40:43]
	v_mfma_f32_16x16x32_bf16 v[32:35], v[132:135], v[182:185], v[32:35]
	v_mfma_f32_16x16x32_bf16 v[24:27], v[146:149], v[182:185], v[24:27]
	v_mfma_f32_16x16x32_bf16 v[16:19], v[132:135], v[210:213], v[16:19]
	v_mfma_f32_16x16x32_bf16 v[8:11], v[146:149], v[210:213], v[8:11]
	v_mfma_f32_16x16x32_bf16 v[52:55], v[214:217], v[162:165], v[52:55]
	v_mfma_f32_16x16x32_bf16 v[44:47], v[222:225], v[162:165], v[44:47]
	v_mfma_f32_16x16x32_bf16 v[36:39], v[214:217], v[170:173], v[36:39]
	v_mfma_f32_16x16x32_bf16 v[28:31], v[222:225], v[170:173], v[28:31]
	v_mfma_f32_16x16x32_bf16 v[20:23], v[214:217], v[178:181], v[20:23]
	v_mfma_f32_16x16x32_bf16 v[12:15], v[222:225], v[178:181], v[12:15]
	v_mfma_f32_16x16x32_bf16 v[4:7], v[214:217], v[194:197], v[4:7]
	v_mfma_f32_16x16x32_bf16 v[0:3], v[222:225], v[194:197], v[0:3]
	v_mfma_f32_16x16x32_bf16 v[52:55], v[218:221], v[166:169], v[52:55]
	v_mfma_f32_16x16x32_bf16 v[44:47], v[226:229], v[166:169], v[44:47]
	v_mfma_f32_16x16x32_bf16 v[36:39], v[218:221], v[174:177], v[36:39]
	v_mfma_f32_16x16x32_bf16 v[28:31], v[226:229], v[174:177], v[28:31]
	v_mfma_f32_16x16x32_bf16 v[20:23], v[218:221], v[182:185], v[20:23]
	v_mfma_f32_16x16x32_bf16 v[12:15], v[226:229], v[182:185], v[12:15]
	v_mfma_f32_16x16x32_bf16 v[4:7], v[218:221], v[210:213], v[4:7]
	v_mfma_f32_16x16x32_bf16 v[0:3], v[226:229], v[210:213], v[0:3]
	s_barrier
	s_add_i32 s6, 0, 0x18000
	v_add_u32_e32 v146, s6, v206
	ds_read_b128 v[128:131], v146
	ds_read_b128 v[132:135], v146 offset:1024
	ds_read_b128 v[136:139], v146 offset:2048
	ds_read_b128 v[146:149], v146 offset:3072
	s_add_u32 s58, s58, 0x40000
	s_addc_u32 s59, s59, 0
	s_mov_b32 m0, s70
	v_lshl_add_u64 v[214:215], s[58:59], 0, v[154:155]
	ds_read_b128 v[162:165], v208 offset:32768
	ds_read_b128 v[166:169], v208 offset:33792
	ds_read_b128 v[170:173], v208 offset:34816
	ds_read_b128 v[174:177], v208 offset:35840
	ds_read_b128 v[178:181], v208 offset:36864
	ds_read_b128 v[182:185], v208 offset:37888
	ds_read_b128 v[194:197], v208 offset:38912
	ds_read_b128 v[210:213], v208 offset:39936
	global_load_lds_dwordx4 v[214:215], off
	v_lshl_add_u64 v[214:215], s[58:59], 0, v[152:153]
	s_mov_b32 m0, s71
	s_nop 0
	global_load_lds_dwordx4 v[214:215], off
	s_add_i32 s19, 0, 0x1c000
	v_add_u32_e32 v192, s19, v206
	ds_read_b128 v[214:217], v192
	ds_read_b128 v[218:221], v192 offset:1024
	ds_read_b128 v[222:225], v192 offset:2048
	ds_read_b128 v[226:229], v192 offset:3072
	s_waitcnt vmcnt(8)
	s_waitcnt lgkmcnt(0)
	s_barrier
	v_mfma_f32_16x16x32_bf16 v[124:127], v[128:131], v[162:165], v[124:127]
	v_mfma_f32_16x16x32_bf16 v[120:123], v[136:139], v[162:165], v[120:123]
	v_mfma_f32_16x16x32_bf16 v[108:111], v[128:131], v[170:173], v[108:111]
	v_mfma_f32_16x16x32_bf16 v[104:107], v[136:139], v[170:173], v[104:107]
	v_mfma_f32_16x16x32_bf16 v[96:99], v[128:131], v[178:181], v[96:99]
	v_mfma_f32_16x16x32_bf16 v[88:91], v[136:139], v[178:181], v[88:91]
	v_mfma_f32_16x16x32_bf16 v[84:87], v[128:131], v[194:197], v[84:87]
	v_mfma_f32_16x16x32_bf16 v[80:83], v[136:139], v[194:197], v[80:83]
	v_mfma_f32_16x16x32_bf16 v[124:127], v[132:135], v[166:169], v[124:127]
	v_mfma_f32_16x16x32_bf16 v[120:123], v[146:149], v[166:169], v[120:123]
	v_mfma_f32_16x16x32_bf16 v[108:111], v[132:135], v[174:177], v[108:111]
	v_mfma_f32_16x16x32_bf16 v[104:107], v[146:149], v[174:177], v[104:107]
	v_mfma_f32_16x16x32_bf16 v[96:99], v[132:135], v[182:185], v[96:99]
	v_mfma_f32_16x16x32_bf16 v[88:91], v[146:149], v[182:185], v[88:91]
	v_mfma_f32_16x16x32_bf16 v[84:87], v[132:135], v[210:213], v[84:87]
	v_mfma_f32_16x16x32_bf16 v[80:83], v[146:149], v[210:213], v[80:83]
	v_mfma_f32_16x16x32_bf16 v[116:119], v[214:217], v[162:165], v[116:119]
	v_mfma_f32_16x16x32_bf16 v[112:115], v[222:225], v[162:165], v[112:115]
	v_mfma_f32_16x16x32_bf16 v[100:103], v[214:217], v[170:173], v[100:103]
	v_mfma_f32_16x16x32_bf16 v[92:95], v[222:225], v[170:173], v[92:95]
	v_mfma_f32_16x16x32_bf16 v[76:79], v[214:217], v[178:181], v[76:79]
	v_mfma_f32_16x16x32_bf16 v[72:75], v[222:225], v[178:181], v[72:75]
	v_mfma_f32_16x16x32_bf16 v[68:71], v[214:217], v[194:197], v[68:71]
	v_mfma_f32_16x16x32_bf16 v[64:67], v[222:225], v[194:197], v[64:67]
	v_mfma_f32_16x16x32_bf16 v[116:119], v[218:221], v[166:169], v[116:119]
	v_mfma_f32_16x16x32_bf16 v[112:115], v[226:229], v[166:169], v[112:115]
	v_mfma_f32_16x16x32_bf16 v[100:103], v[218:221], v[174:177], v[100:103]
	v_mfma_f32_16x16x32_bf16 v[92:95], v[226:229], v[174:177], v[92:95]
	v_mfma_f32_16x16x32_bf16 v[76:79], v[218:221], v[182:185], v[76:79]
	v_mfma_f32_16x16x32_bf16 v[72:75], v[226:229], v[182:185], v[72:75]
	v_mfma_f32_16x16x32_bf16 v[68:71], v[218:221], v[210:213], v[68:71]
	v_mfma_f32_16x16x32_bf16 v[64:67], v[226:229], v[210:213], v[64:67]
	s_barrier
	s_add_i32 s6, s6, s57
	v_lshl_add_u64 v[230:231], v[230:231], 0, s[36:37]
	s_mov_b32 m0, s6
	s_nop 0
	global_load_lds_dwordx4 v[230:231], off
	v_lshl_add_u64 v[230:231], v[232:233], 0, s[36:37]
	s_add_i32 m0, s6, 0x2000
	s_nop 0
	global_load_lds_dwordx4 v[230:231], off
	s_mov_b32 m0, s72
	v_lshl_add_u64 v[230:231], v[234:235], 0, s[36:37]
	ds_read_b128 v[162:165], v208 offset:49152
	ds_read_b128 v[166:169], v208 offset:50176
	ds_read_b128 v[170:173], v208 offset:51200
	ds_read_b128 v[174:177], v208 offset:52224
	ds_read_b128 v[178:181], v208 offset:53248
	ds_read_b128 v[182:185], v208 offset:54272
	ds_read_b128 v[194:197], v208 offset:55296
	ds_read_b128 v[210:213], v208 offset:56320
	global_load_lds_dwordx4 v[230:231], off
	v_lshl_add_u64 v[230:231], v[236:237], 0, s[36:37]
	s_mov_b32 m0, s73
	s_nop 0
	global_load_lds_dwordx4 v[230:231], off
	s_add_u32 s54, s54, 0x40080
	s_addc_u32 s55, s55, 0
	s_add_i32 s6, s19, s57
	v_lshl_add_u64 v[250:251], s[54:55], 0, v[140:141]
	s_mov_b32 m0, s6
	s_nop 0
	global_load_lds_dwordx4 v[250:251], off
	v_lshl_add_u64 v[250:251], s[54:55], 0, v[150:151]
	s_add_i32 m0, s6, 0x2000
	s_nop 0
	global_load_lds_dwordx4 v[250:251], off
	s_add_i32 s82, s82, 2
	s_add_u32 s52, s52, 0x100
	s_addc_u32 s53, s53, 0
	s_add_u32 s39, s39, 0x100
	s_addc_u32 s51, s51, 0
	s_cmp_gt_u32 s82, 13
	s_waitcnt vmcnt(8)
	s_waitcnt lgkmcnt(0)
	s_barrier
	v_mfma_f32_16x16x32_bf16 v[60:63], v[128:131], v[162:165], v[60:63]
	v_mfma_f32_16x16x32_bf16 v[56:59], v[136:139], v[162:165], v[56:59]
	v_mfma_f32_16x16x32_bf16 v[48:51], v[128:131], v[170:173], v[48:51]
	v_mfma_f32_16x16x32_bf16 v[40:43], v[136:139], v[170:173], v[40:43]
	v_mfma_f32_16x16x32_bf16 v[32:35], v[128:131], v[178:181], v[32:35]
	v_mfma_f32_16x16x32_bf16 v[24:27], v[136:139], v[178:181], v[24:27]
	v_mfma_f32_16x16x32_bf16 v[16:19], v[128:131], v[194:197], v[16:19]
	v_mfma_f32_16x16x32_bf16 v[8:11], v[136:139], v[194:197], v[8:11]
	v_mfma_f32_16x16x32_bf16 v[60:63], v[132:135], v[166:169], v[60:63]
	v_mfma_f32_16x16x32_bf16 v[56:59], v[146:149], v[166:169], v[56:59]
	v_mfma_f32_16x16x32_bf16 v[48:51], v[132:135], v[174:177], v[48:51]
	v_mfma_f32_16x16x32_bf16 v[40:43], v[146:149], v[174:177], v[40:43]
	v_mfma_f32_16x16x32_bf16 v[32:35], v[132:135], v[182:185], v[32:35]
	v_mfma_f32_16x16x32_bf16 v[24:27], v[146:149], v[182:185], v[24:27]
	v_mfma_f32_16x16x32_bf16 v[16:19], v[132:135], v[210:213], v[16:19]
	v_mfma_f32_16x16x32_bf16 v[8:11], v[146:149], v[210:213], v[8:11]
	v_mfma_f32_16x16x32_bf16 v[52:55], v[214:217], v[162:165], v[52:55]
	v_mfma_f32_16x16x32_bf16 v[44:47], v[222:225], v[162:165], v[44:47]
	v_mfma_f32_16x16x32_bf16 v[36:39], v[214:217], v[170:173], v[36:39]
	v_mfma_f32_16x16x32_bf16 v[28:31], v[222:225], v[170:173], v[28:31]
	v_mfma_f32_16x16x32_bf16 v[20:23], v[214:217], v[178:181], v[20:23]
	v_mfma_f32_16x16x32_bf16 v[12:15], v[222:225], v[178:181], v[12:15]
	v_mfma_f32_16x16x32_bf16 v[4:7], v[214:217], v[194:197], v[4:7]
	v_mfma_f32_16x16x32_bf16 v[0:3], v[222:225], v[194:197], v[0:3]
	v_mfma_f32_16x16x32_bf16 v[52:55], v[218:221], v[166:169], v[52:55]
	v_mfma_f32_16x16x32_bf16 v[44:47], v[226:229], v[166:169], v[44:47]
	v_mfma_f32_16x16x32_bf16 v[36:39], v[218:221], v[174:177], v[36:39]
	v_mfma_f32_16x16x32_bf16 v[28:31], v[226:229], v[174:177], v[28:31]
	v_mfma_f32_16x16x32_bf16 v[20:23], v[218:221], v[182:185], v[20:23]
	v_mfma_f32_16x16x32_bf16 v[12:15], v[226:229], v[182:185], v[12:15]
	v_mfma_f32_16x16x32_bf16 v[4:7], v[218:221], v[210:213], v[4:7]
	v_mfma_f32_16x16x32_bf16 v[0:3], v[226:229], v[210:213], v[0:3]
	s_barrier
	s_cbranch_scc0 .LBB0_248
	s_mov_b32 s100, 1
	s_ashr_i32 s51, s50, 31
	v_lshl_or_b32 v128, s81, 8, v207
	s_lshl_b64 s[10:11], s[50:51], 8
	v_ashrrev_i32_e32 v129, 31, v128
	v_lshl_add_u64 v[168:169], s[10:11], 0, v[156:157]
	v_lshlrev_b64 v[170:171], 1, v[128:129]
	v_lshl_add_u64 v[174:175], s[28:29], 0, v[170:171]
	v_lshlrev_b64 v[172:173], 11, v[168:169]
	v_lshl_add_u64 v[128:129], v[174:175], 0, v[172:173]
	global_load_dwordx4 v[146:149], v[128:129], off
	global_load_dwordx4 v[182:185], v[128:129], off offset:256
	v_or_b32_e32 v166, 16, v168
	v_mov_b32_e32 v167, v169
	v_lshlrev_b64 v[176:177], 11, v[166:167]
	v_lshl_add_u64 v[128:129], v[174:175], 0, v[176:177]
	global_load_dwordx4 v[194:197], v[128:129], off
	global_load_dwordx4 v[210:213], v[128:129], off offset:256
	v_or_b32_e32 v164, 32, v168
	v_mov_b32_e32 v165, v169
	v_or_b32_e32 v162, 48, v168
	v_mov_b32_e32 v163, v169
	v_lshlrev_b64 v[180:181], 11, v[164:165]
	v_lshlrev_b64 v[178:179], 11, v[162:163]
	v_lshl_add_u64 v[128:129], v[174:175], 0, v[180:181]
	v_lshl_add_u64 v[130:131], v[174:175], 0, v[178:179]
	global_load_dwordx4 v[214:217], v[128:129], off
	global_load_dwordx4 v[136:139], v[128:129], off offset:256
	global_load_dwordx4 v[132:135], v[130:131], off
	s_nop 0
	global_load_dwordx4 v[128:131], v[130:131], off offset:256
	s_mov_b64 s[10:11], 0x90
	v_lshl_add_u64 v[172:173], s[30:31], 0, v[172:173]
	v_lshl_add_u64 v[172:173], v[172:173], 0, v[170:171]
	s_waitcnt vmcnt(0)
	v_lshlrev_b32_e32 v218, 16, v146
	v_and_b32_e32 v219, 0xffff0000, v146
	v_lshlrev_b32_e32 v220, 16, v148
	v_and_b32_e32 v221, 0xffff0000, v148
	v_lshlrev_b32_e32 v146, 16, v147
	v_and_b32_e32 v147, 0xffff0000, v147
	v_lshlrev_b32_e32 v222, 16, v182
	v_and_b32_e32 v223, 0xffff0000, v182
	v_lshlrev_b32_e32 v224, 16, v184
	v_and_b32_e32 v225, 0xffff0000, v184
	v_lshlrev_b32_e32 v182, 16, v183
	v_and_b32_e32 v183, 0xffff0000, v183
	v_pk_add_f32 v[124:125], v[124:125], v[218:219]
	v_pk_add_f32 v[120:121], v[120:121], v[220:221]
	v_pk_add_f32 v[126:127], v[126:127], v[146:147]
	v_pk_add_f32 v[116:117], v[116:117], v[222:223]
	v_pk_add_f32 v[146:147], v[112:113], v[224:225]
	v_pk_add_f32 v[118:119], v[118:119], v[182:183]
	v_pk_mul_f32 v[220:221], v[124:125], v[124:125]
	v_pk_mul_f32 v[222:223], v[126:127], v[126:127]
	v_cvt_pk_bf16_f32 v112, v124, v125
	v_cvt_pk_bf16_f32 v113, v126, v127
	v_pk_mul_f32 v[124:125], v[116:117], v[116:117]
	v_pk_mul_f32 v[126:127], v[118:119], v[118:119]
	v_pk_mul_f32 v[228:229], v[146:147], v[146:147]
	v_cvt_pk_bf16_f32 v116, v116, v117
	v_cvt_pk_bf16_f32 v117, v118, v119
	v_cvt_pk_bf16_f32 v118, v146, v147
	v_add_f32_e32 v146, v220, v221
	v_add_f32_e32 v146, v222, v146
	v_lshlrev_b32_e32 v148, 16, v149
	v_and_b32_e32 v149, 0xffff0000, v149
	v_pk_mul_f32 v[224:225], v[120:121], v[120:121]
	v_add_f32_e32 v146, v223, v146
	v_pk_add_f32 v[122:123], v[122:123], v[148:149]
	v_add_f32_e32 v146, v224, v146
	v_pk_mul_f32 v[226:227], v[122:123], v[122:123]
	v_add_f32_e32 v146, v225, v146
	v_add_f32_e32 v146, v226, v146
	v_add_f32_e32 v146, v227, v146
	v_add_f32_e32 v124, v124, v146
	v_add_f32_e32 v124, v125, v124
	v_add_f32_e32 v124, v126, v124
	v_lshlrev_b32_e32 v184, 16, v185
	v_and_b32_e32 v185, 0xffff0000, v185
	v_add_f32_e32 v124, v127, v124
	v_pk_add_f32 v[148:149], v[114:115], v[184:185]
	v_add_f32_e32 v124, v228, v124
	v_pk_mul_f32 v[230:231], v[148:149], v[148:149]
	v_add_f32_e32 v124, v229, v124
	v_add_f32_e32 v124, v230, v124
	v_add_f32_e32 v209, v231, v124
	v_lshlrev_b32_e32 v124, 16, v212
	v_and_b32_e32 v125, 0xffff0000, v212
	v_pk_add_f32 v[124:125], v[92:93], v[124:125]
	v_lshlrev_b32_e32 v92, 16, v211
	v_and_b32_e32 v93, 0xffff0000, v211
	v_pk_add_f32 v[102:103], v[102:103], v[92:93]
	v_lshlrev_b32_e32 v92, 16, v213
	v_and_b32_e32 v93, 0xffff0000, v213
	v_pk_add_f32 v[126:127], v[94:95], v[92:93]
	v_lshlrev_b32_e32 v92, 16, v214
	v_and_b32_e32 v93, 0xffff0000, v214
	v_pk_add_f32 v[92:93], v[96:97], v[92:93]
	v_lshlrev_b32_e32 v96, 16, v217
	v_and_b32_e32 v97, 0xffff0000, v217
	v_lshlrev_b32_e32 v94, 16, v216
	v_and_b32_e32 v95, 0xffff0000, v216
	v_pk_add_f32 v[90:91], v[90:91], v[96:97]
	v_lshlrev_b32_e32 v96, 16, v136
	v_and_b32_e32 v97, 0xffff0000, v136
	v_lshlrev_b32_e32 v182, 16, v194
	v_and_b32_e32 v183, 0xffff0000, v194
	v_pk_add_f32 v[88:89], v[88:89], v[94:95]
	v_lshlrev_b32_e32 v94, 16, v215
	v_and_b32_e32 v95, 0xffff0000, v215
	v_pk_add_f32 v[96:97], v[76:77], v[96:97]
	v_lshl_add_u64 v[76:77], v[168:169], 0, s[36:37]
	v_lshlrev_b32_e32 v184, 16, v196
	v_and_b32_e32 v185, 0xffff0000, v196
	v_cvt_pk_bf16_f32 v114, v120, v121
	v_pk_add_f32 v[120:121], v[108:109], v[182:183]
	v_pk_add_f32 v[94:95], v[98:99], v[94:95]
	v_lshlrev_b64 v[182:183], 11, v[76:77]
	v_lshlrev_b32_e32 v98, 16, v138
	v_and_b32_e32 v99, 0xffff0000, v138
	v_pk_add_f32 v[108:109], v[104:105], v[184:185]
	v_lshl_add_u64 v[184:185], v[174:175], 0, v[182:183]
	v_pk_add_f32 v[98:99], v[72:73], v[98:99]
	v_lshlrev_b32_e32 v72, 16, v137
	v_and_b32_e32 v73, 0xffff0000, v137
	v_lshlrev_b32_e32 v218, 16, v210
	v_and_b32_e32 v219, 0xffff0000, v210
	global_load_dwordx4 v[210:213], v[184:185], off
	v_pk_add_f32 v[136:137], v[78:79], v[72:73]
	v_lshlrev_b32_e32 v72, 16, v139
	v_and_b32_e32 v73, 0xffff0000, v139
	v_pk_add_f32 v[138:139], v[74:75], v[72:73]
	v_lshlrev_b32_e32 v72, 16, v132
	v_and_b32_e32 v73, 0xffff0000, v132
	v_pk_add_f32 v[74:75], v[84:85], v[72:73]
	v_lshlrev_b32_e32 v72, 16, v134
	v_and_b32_e32 v73, 0xffff0000, v134
	v_pk_add_f32 v[78:79], v[80:81], v[72:73]
	v_lshlrev_b32_e32 v72, 16, v133
	v_and_b32_e32 v73, 0xffff0000, v133
	v_pk_add_f32 v[100:101], v[100:101], v[218:219]
	global_load_dwordx4 v[218:221], v[184:185], off offset:256
	v_pk_add_f32 v[80:81], v[86:87], v[72:73]
	v_lshlrev_b32_e32 v72, 16, v135
	v_and_b32_e32 v73, 0xffff0000, v135
	v_pk_add_f32 v[82:83], v[82:83], v[72:73]
	v_lshl_add_u64 v[72:73], v[168:169], 0, s[10:11]
	v_lshlrev_b64 v[132:133], 11, v[72:73]
	v_lshl_add_u64 v[134:135], v[174:175], 0, v[132:133]
	v_lshlrev_b32_e32 v84, 16, v128
	v_and_b32_e32 v85, 0xffff0000, v128
	global_load_dwordx4 v[226:229], v[134:135], off
	global_load_dwordx4 v[234:237], v[134:135], off offset:256
	v_pk_add_f32 v[84:85], v[68:69], v[84:85]
	v_lshlrev_b32_e32 v68, 16, v130
	v_and_b32_e32 v69, 0xffff0000, v130
	v_pk_add_f32 v[86:87], v[64:65], v[68:69]
	v_lshlrev_b32_e32 v64, 16, v129
	v_and_b32_e32 v65, 0xffff0000, v129
	s_mov_b64 s[10:11], 0xa0
	v_pk_add_f32 v[128:129], v[70:71], v[64:65]
	v_lshl_add_u64 v[70:71], v[168:169], 0, s[10:11]
	s_mov_b64 s[10:11], 0xb0
	v_lshlrev_b32_e32 v64, 16, v131
	v_and_b32_e32 v65, 0xffff0000, v131
	v_lshlrev_b64 v[134:135], 11, v[70:71]
	v_lshl_add_u64 v[68:69], v[168:169], 0, s[10:11]
	v_pk_add_f32 v[130:131], v[66:67], v[64:65]
	v_lshl_add_u64 v[64:65], v[174:175], 0, v[134:135]
	v_lshlrev_b64 v[184:185], 11, v[68:69]
	global_load_dwordx4 v[238:241], v[64:65], off
	global_load_dwordx4 v[242:245], v[64:65], off offset:256
	v_lshl_add_u64 v[64:65], v[174:175], 0, v[184:185]
	global_load_dwordx4 v[246:249], v[64:65], off
	s_nop 0
	global_load_dwordx4 v[64:67], v[64:65], off offset:256
	v_lshlrev_b32_e32 v194, 16, v195
	v_and_b32_e32 v195, 0xffff0000, v195
	v_lshlrev_b32_e32 v196, 16, v197
	v_and_b32_e32 v197, 0xffff0000, v197
	v_cvt_pk_bf16_f32 v115, v122, v123
	v_cvt_pk_bf16_f32 v119, v148, v149
	v_pk_add_f32 v[122:123], v[110:111], v[194:195]
	v_pk_add_f32 v[110:111], v[106:107], v[196:197]
	global_store_dwordx4 v[172:173], v[112:115], off
	global_store_dwordx4 v[172:173], v[116:119], off offset:256
	v_cvt_pk_bf16_f32 v104, v120, v121
	v_lshl_add_u64 v[112:113], s[30:31], 0, v[176:177]
	v_cvt_pk_bf16_f32 v105, v122, v123
	v_cvt_pk_bf16_f32 v106, v108, v109
	v_cvt_pk_bf16_f32 v107, v110, v111
	v_lshl_add_u64 v[112:113], v[112:113], 0, v[170:171]
	v_cvt_pk_bf16_f32 v146, v100, v101
	v_cvt_pk_bf16_f32 v147, v102, v103
	v_cvt_pk_bf16_f32 v148, v124, v125
	v_cvt_pk_bf16_f32 v149, v126, v127
	global_store_dwordx4 v[112:113], v[104:107], off
	global_store_dwordx4 v[112:113], v[146:149], off offset:256
	v_cvt_pk_bf16_f32 v194, v92, v93
	v_lshl_add_u64 v[104:105], s[30:31], 0, v[180:181]
	v_cvt_pk_bf16_f32 v195, v94, v95
	v_cvt_pk_bf16_f32 v196, v88, v89
	v_cvt_pk_bf16_f32 v197, v90, v91
	v_lshl_add_u64 v[104:105], v[104:105], 0, v[170:171]
	v_cvt_pk_bf16_f32 v214, v96, v97
	v_cvt_pk_bf16_f32 v215, v136, v137
	v_cvt_pk_bf16_f32 v216, v98, v99
	v_cvt_pk_bf16_f32 v217, v138, v139
	global_store_dwordx4 v[104:105], v[194:197], off
	global_store_dwordx4 v[104:105], v[214:217], off offset:256
	v_lshl_add_u64 v[104:105], s[30:31], 0, v[178:179]
	v_cvt_pk_bf16_f32 v222, v74, v75
	v_cvt_pk_bf16_f32 v223, v80, v81
	v_cvt_pk_bf16_f32 v224, v78, v79
	v_cvt_pk_bf16_f32 v225, v82, v83
	v_lshl_add_u64 v[104:105], v[104:105], 0, v[170:171]
	v_cvt_pk_bf16_f32 v230, v84, v85
	v_cvt_pk_bf16_f32 v231, v128, v129
	v_cvt_pk_bf16_f32 v232, v86, v87
	v_cvt_pk_bf16_f32 v233, v130, v131
	global_store_dwordx4 v[104:105], v[222:225], off
	global_store_dwordx4 v[104:105], v[230:233], off offset:256
	s_waitcnt vmcnt(8)
	v_lshlrev_b32_e32 v104, 16, v210
	v_and_b32_e32 v105, 0xffff0000, v210
	v_pk_add_f32 v[60:61], v[60:61], v[104:105]
	v_lshlrev_b32_e32 v104, 16, v212
	v_and_b32_e32 v105, 0xffff0000, v212
	v_pk_add_f32 v[56:57], v[56:57], v[104:105]
	v_lshlrev_b32_e32 v104, 16, v211
	v_and_b32_e32 v105, 0xffff0000, v211
	v_pk_add_f32 v[62:63], v[62:63], v[104:105]
	v_lshlrev_b32_e32 v104, 16, v213
	v_and_b32_e32 v105, 0xffff0000, v213
	v_pk_add_f32 v[58:59], v[58:59], v[104:105]
	v_lshlrev_b32_e32 v104, 16, v218
	v_and_b32_e32 v105, 0xffff0000, v218
	v_pk_add_f32 v[52:53], v[52:53], v[104:105]
	v_lshlrev_b32_e32 v104, 16, v220
	v_and_b32_e32 v105, 0xffff0000, v220
	v_pk_add_f32 v[104:105], v[44:45], v[104:105]
	v_lshlrev_b32_e32 v44, 16, v219
	v_and_b32_e32 v45, 0xffff0000, v219
	v_pk_add_f32 v[54:55], v[54:55], v[44:45]
	v_lshlrev_b32_e32 v44, 16, v221
	v_and_b32_e32 v45, 0xffff0000, v221
	v_pk_add_f32 v[106:107], v[46:47], v[44:45]
	v_lshlrev_b32_e32 v44, 16, v226
	v_and_b32_e32 v45, 0xffff0000, v226
	v_pk_add_f32 v[44:45], v[48:49], v[44:45]
	v_lshlrev_b32_e32 v48, 16, v229
	v_and_b32_e32 v49, 0xffff0000, v229
	v_pk_add_f32 v[42:43], v[42:43], v[48:49]
	v_lshlrev_b32_e32 v48, 16, v234
	v_and_b32_e32 v49, 0xffff0000, v234
	v_pk_add_f32 v[36:37], v[36:37], v[48:49]
	v_lshlrev_b32_e32 v48, 16, v236
	v_and_b32_e32 v49, 0xffff0000, v236
	v_lshlrev_b32_e32 v46, 16, v228
	v_and_b32_e32 v47, 0xffff0000, v228
	v_pk_add_f32 v[48:49], v[28:29], v[48:49]
	v_lshlrev_b32_e32 v28, 16, v235
	v_and_b32_e32 v29, 0xffff0000, v235
	v_pk_add_f32 v[40:41], v[40:41], v[46:47]
	v_lshlrev_b32_e32 v46, 16, v227
	v_and_b32_e32 v47, 0xffff0000, v227
	v_pk_add_f32 v[38:39], v[38:39], v[28:29]
	v_lshlrev_b32_e32 v28, 16, v237
	v_and_b32_e32 v29, 0xffff0000, v237
	v_pk_add_f32 v[46:47], v[50:51], v[46:47]
	v_pk_add_f32 v[50:51], v[30:31], v[28:29]
	v_lshlrev_b32_e32 v28, 16, v238
	v_and_b32_e32 v29, 0xffff0000, v238
	v_lshlrev_b32_e32 v180, 16, v64
	v_and_b32_e32 v181, 0xffff0000, v64
	v_pk_add_f32 v[28:29], v[32:33], v[28:29]
	v_lshlrev_b32_e32 v32, 16, v241
	v_and_b32_e32 v33, 0xffff0000, v241
	v_pk_add_f32 v[4:5], v[4:5], v[180:181]
	v_lshlrev_b32_e32 v180, 16, v66
	v_and_b32_e32 v181, 0xffff0000, v66
	v_pk_add_f32 v[26:27], v[26:27], v[32:33]
	v_lshlrev_b32_e32 v32, 16, v242
	v_and_b32_e32 v33, 0xffff0000, v242
	v_pk_add_f32 v[0:1], v[0:1], v[180:181]
	v_lshl_add_u64 v[180:181], s[30:31], 0, v[182:183]
	v_cvt_pk_bf16_f32 v112, v60, v61
	v_cvt_pk_bf16_f32 v113, v62, v63
	v_cvt_pk_bf16_f32 v114, v56, v57
	v_cvt_pk_bf16_f32 v115, v58, v59
	v_pk_add_f32 v[20:21], v[20:21], v[32:33]
	v_lshlrev_b32_e32 v32, 16, v244
	v_and_b32_e32 v33, 0xffff0000, v244
	v_lshl_add_u64 v[180:181], v[180:181], 0, v[170:171]
	v_cvt_pk_bf16_f32 v116, v52, v53
	v_cvt_pk_bf16_f32 v117, v54, v55
	v_cvt_pk_bf16_f32 v118, v104, v105
	v_cvt_pk_bf16_f32 v119, v106, v107
	v_lshlrev_b32_e32 v30, 16, v240
	v_and_b32_e32 v31, 0xffff0000, v240
	v_pk_add_f32 v[32:33], v[12:13], v[32:33]
	v_lshlrev_b32_e32 v12, 16, v243
	v_and_b32_e32 v13, 0xffff0000, v243
	global_store_dwordx4 v[180:181], v[112:115], off
	global_store_dwordx4 v[180:181], v[116:119], off offset:256
	v_cvt_pk_bf16_f32 v146, v44, v45
	v_lshl_add_u64 v[112:113], s[30:31], 0, v[132:133]
	v_cvt_pk_bf16_f32 v147, v46, v47
	v_cvt_pk_bf16_f32 v148, v40, v41
	v_cvt_pk_bf16_f32 v149, v42, v43
	v_pk_add_f32 v[24:25], v[24:25], v[30:31]
	v_lshlrev_b32_e32 v30, 16, v239
	v_and_b32_e32 v31, 0xffff0000, v239
	v_pk_add_f32 v[22:23], v[22:23], v[12:13]
	v_lshlrev_b32_e32 v12, 16, v245
	v_and_b32_e32 v13, 0xffff0000, v245
	v_lshl_add_u64 v[112:113], v[112:113], 0, v[170:171]
	v_cvt_pk_bf16_f32 v172, v36, v37
	v_cvt_pk_bf16_f32 v173, v38, v39
	v_cvt_pk_bf16_f32 v174, v48, v49
	v_cvt_pk_bf16_f32 v175, v50, v51
	v_pk_add_f32 v[30:31], v[34:35], v[30:31]
	v_pk_add_f32 v[34:35], v[14:15], v[12:13]
	v_lshlrev_b32_e32 v12, 16, v246
	v_and_b32_e32 v13, 0xffff0000, v246
	v_lshlrev_b32_e32 v14, 16, v248
	v_and_b32_e32 v15, 0xffff0000, v248
	global_store_dwordx4 v[112:113], v[146:149], off
	global_store_dwordx4 v[112:113], v[172:175], off offset:256
	v_lshl_add_u64 v[112:113], s[30:31], 0, v[134:135]
	v_cvt_pk_bf16_f32 v176, v28, v29
	v_cvt_pk_bf16_f32 v177, v30, v31
	v_cvt_pk_bf16_f32 v178, v24, v25
	v_cvt_pk_bf16_f32 v179, v26, v27
	v_pk_add_f32 v[12:13], v[16:17], v[12:13]
	v_pk_add_f32 v[8:9], v[8:9], v[14:15]
	v_lshlrev_b32_e32 v14, 16, v247
	v_and_b32_e32 v15, 0xffff0000, v247
	v_lshlrev_b32_e32 v16, 16, v249
	v_and_b32_e32 v17, 0xffff0000, v249
	v_lshlrev_b32_e32 v64, 16, v65
	v_and_b32_e32 v65, 0xffff0000, v65
	v_lshl_add_u64 v[112:113], v[112:113], 0, v[170:171]
	v_cvt_pk_bf16_f32 v194, v20, v21
	v_cvt_pk_bf16_f32 v195, v22, v23
	v_cvt_pk_bf16_f32 v196, v32, v33
	v_cvt_pk_bf16_f32 v197, v34, v35
	v_pk_add_f32 v[14:15], v[18:19], v[14:15]
	v_pk_add_f32 v[10:11], v[10:11], v[16:17]
	v_pk_add_f32 v[6:7], v[6:7], v[64:65]
	v_lshlrev_b32_e32 v64, 16, v67
	v_and_b32_e32 v65, 0xffff0000, v67
	global_store_dwordx4 v[112:113], v[176:179], off
	global_store_dwordx4 v[112:113], v[194:197], off offset:256
	v_lshl_add_u64 v[112:113], s[30:31], 0, v[184:185]
	v_cvt_pk_bf16_f32 v16, v12, v13
	v_cvt_pk_bf16_f32 v17, v14, v15
	v_cvt_pk_bf16_f32 v18, v8, v9
	v_cvt_pk_bf16_f32 v19, v10, v11
	v_pk_add_f32 v[2:3], v[2:3], v[64:65]
	v_lshl_add_u64 v[112:113], v[112:113], 0, v[170:171]
	v_cvt_pk_bf16_f32 v64, v4, v5
	v_cvt_pk_bf16_f32 v65, v6, v7
	v_cvt_pk_bf16_f32 v66, v0, v1
	v_cvt_pk_bf16_f32 v67, v2, v3
	global_store_dwordx4 v[112:113], v[16:19], off
	global_store_dwordx4 v[112:113], v[64:67], off offset:256
	s_lshl_b32 s10, s81, 2
	v_and_b32_e32 v17, 64, v188
	v_xor_b32_e32 v16, 16, v188
	v_add_u32_e32 v17, 64, v17
	v_cmp_lt_i32_e32 vcc, v16, v17
	v_xor_b32_e32 v18, 32, v188
	s_ashr_i32 s11, s10, 31
	v_cndmask_b32_e32 v16, v188, v16, vcc
	v_lshlrev_b32_e32 v16, 2, v16
	v_mov_b32_e32 v132, v209
	v_cmp_lt_i32_e32 vcc, v18, v17
	s_lshl_b64 s[10:11], s[10:11], 2
	s_add_u32 s50, s75, s10
	v_cndmask_b32_e32 v17, v188, v18, vcc
	v_lshlrev_b32_e32 v17, 2, v17
	s_addc_u32 s51, s80, s11
	v_pk_mul_f32 v[18:19], v[120:121], v[120:121]
	v_pk_mul_f32 v[64:65], v[122:123], v[122:123]
	v_add_f32_e32 v18, v18, v19
	v_add_f32_e32 v18, v64, v18
	v_pk_mul_f32 v[66:67], v[108:109], v[108:109]
	v_add_f32_e32 v18, v65, v18
	v_add_f32_e32 v18, v66, v18
	v_pk_mul_f32 v[108:109], v[110:111], v[110:111]
	v_add_f32_e32 v18, v67, v18
	v_add_f32_e32 v18, v108, v18
	v_pk_mul_f32 v[100:101], v[100:101], v[100:101]
	v_add_f32_e32 v18, v109, v18
	v_add_f32_e32 v18, v100, v18
	v_pk_mul_f32 v[102:103], v[102:103], v[102:103]
	v_add_f32_e32 v18, v101, v18
	v_add_f32_e32 v18, v102, v18
	v_pk_mul_f32 v[110:111], v[124:125], v[124:125]
	v_add_f32_e32 v18, v103, v18
	v_add_f32_e32 v18, v110, v18
	v_pk_mul_f32 v[112:113], v[126:127], v[126:127]
	v_add_f32_e32 v18, v111, v18
	v_add_f32_e32 v18, v112, v18
	v_add_f32_e32 v18, v113, v18
	v_mov_b32_e32 v133, v18
	v_pk_mul_f32 v[18:19], v[92:93], v[92:93]
	v_pk_mul_f32 v[64:65], v[94:95], v[94:95]
	v_add_f32_e32 v18, v18, v19
	v_add_f32_e32 v18, v64, v18
	v_pk_mul_f32 v[66:67], v[88:89], v[88:89]
	v_add_f32_e32 v18, v65, v18
	v_add_f32_e32 v18, v66, v18
	v_pk_mul_f32 v[88:89], v[90:91], v[90:91]
	v_add_f32_e32 v18, v67, v18
	v_add_f32_e32 v18, v88, v18
	v_pk_mul_f32 v[90:91], v[96:97], v[96:97]
	v_add_f32_e32 v18, v89, v18
	v_add_f32_e32 v18, v90, v18
	v_pk_mul_f32 v[92:93], v[136:137], v[136:137]
	v_add_f32_e32 v18, v91, v18
	v_add_f32_e32 v18, v92, v18
	v_pk_mul_f32 v[94:95], v[98:99], v[98:99]
	v_add_f32_e32 v18, v93, v18
	v_add_f32_e32 v18, v94, v18
	v_pk_mul_f32 v[96:97], v[138:139], v[138:139]
	v_add_f32_e32 v18, v95, v18
	v_add_f32_e32 v18, v96, v18
	v_add_f32_e32 v18, v97, v18
	v_mov_b32_e32 v134, v18
	v_pk_mul_f32 v[18:19], v[74:75], v[74:75]
	v_pk_mul_f32 v[210:211], v[60:61], v[60:61]
	v_pk_mul_f32 v[64:65], v[80:81], v[80:81]
	v_pk_mul_f32 v[60:61], v[62:63], v[62:63]
	v_add_f32_e32 v18, v18, v19
	v_add_f32_e32 v210, v210, v211
	v_add_f32_e32 v18, v64, v18
	v_add_f32_e32 v210, v60, v210
	v_pk_mul_f32 v[66:67], v[78:79], v[78:79]
	v_pk_mul_f32 v[56:57], v[56:57], v[56:57]
	v_add_f32_e32 v18, v65, v18
	v_add_f32_e32 v210, v61, v210
	v_add_f32_e32 v18, v66, v18
	v_add_f32_e32 v210, v56, v210
	v_pk_mul_f32 v[74:75], v[82:83], v[82:83]
	v_pk_mul_f32 v[58:59], v[58:59], v[58:59]
	v_add_f32_e32 v18, v67, v18
	v_add_f32_e32 v210, v57, v210
	v_add_f32_e32 v18, v74, v18
	v_add_f32_e32 v210, v58, v210
	v_pk_mul_f32 v[78:79], v[84:85], v[84:85]
	v_pk_mul_f32 v[52:53], v[52:53], v[52:53]
	v_add_f32_e32 v18, v75, v18
	v_add_f32_e32 v210, v59, v210
	v_add_f32_e32 v18, v78, v18
	v_add_f32_e32 v210, v52, v210
	v_pk_mul_f32 v[80:81], v[128:129], v[128:129]
	v_pk_mul_f32 v[54:55], v[54:55], v[54:55]
	v_add_f32_e32 v18, v79, v18
	v_add_f32_e32 v210, v53, v210
	v_add_f32_e32 v18, v80, v18
	v_add_f32_e32 v210, v54, v210
	v_pk_mul_f32 v[82:83], v[86:87], v[86:87]
	v_pk_mul_f32 v[62:63], v[104:105], v[104:105]
	v_add_f32_e32 v18, v81, v18
	v_add_f32_e32 v210, v55, v210
	v_add_f32_e32 v18, v82, v18
	v_add_f32_e32 v210, v62, v210
	v_pk_mul_f32 v[84:85], v[130:131], v[130:131]
	v_pk_mul_f32 v[212:213], v[106:107], v[106:107]
	v_add_f32_e32 v18, v83, v18
	v_add_f32_e32 v210, v63, v210
	v_add_f32_e32 v18, v84, v18
	v_add_f32_e32 v210, v212, v210
	v_add_f32_e32 v18, v85, v18
	v_add_f32_e32 v210, v213, v210
	v_mov_b32_e32 v135, v18
	v_mov_b32_e32 v146, v210
	v_pk_mul_f32 v[18:19], v[44:45], v[44:45]
	v_pk_mul_f32 v[210:211], v[28:29], v[28:29]
	v_pk_mul_f32 v[44:45], v[46:47], v[46:47]
	v_pk_mul_f32 v[28:29], v[30:31], v[30:31]
	v_add_f32_e32 v18, v18, v19
	v_add_f32_e32 v210, v210, v211
	v_add_f32_e32 v18, v44, v18
	v_add_f32_e32 v210, v28, v210
	v_pk_mul_f32 v[40:41], v[40:41], v[40:41]
	v_pk_mul_f32 v[24:25], v[24:25], v[24:25]
	v_add_f32_e32 v18, v45, v18
	v_add_f32_e32 v210, v29, v210
	v_add_f32_e32 v18, v40, v18
	v_add_f32_e32 v210, v24, v210
	v_pk_mul_f32 v[42:43], v[42:43], v[42:43]
	v_pk_mul_f32 v[26:27], v[26:27], v[26:27]
	v_add_f32_e32 v18, v41, v18
	v_add_f32_e32 v210, v25, v210
	v_add_f32_e32 v18, v42, v18
	v_add_f32_e32 v210, v26, v210
	v_pk_mul_f32 v[36:37], v[36:37], v[36:37]
	v_pk_mul_f32 v[20:21], v[20:21], v[20:21]
	v_add_f32_e32 v18, v43, v18
	v_add_f32_e32 v210, v27, v210
	v_add_f32_e32 v18, v36, v18
	v_add_f32_e32 v210, v20, v210
	v_pk_mul_f32 v[38:39], v[38:39], v[38:39]
	v_pk_mul_f32 v[22:23], v[22:23], v[22:23]
	v_add_f32_e32 v18, v37, v18
	v_add_f32_e32 v210, v21, v210
	v_add_f32_e32 v18, v38, v18
	v_add_f32_e32 v210, v22, v210
	v_pk_mul_f32 v[46:47], v[48:49], v[48:49]
	v_pk_mul_f32 v[30:31], v[32:33], v[32:33]
	v_add_f32_e32 v18, v39, v18
	v_add_f32_e32 v210, v23, v210
	v_add_f32_e32 v18, v46, v18
	v_add_f32_e32 v210, v30, v210
	v_pk_mul_f32 v[48:49], v[50:51], v[50:51]
	v_pk_mul_f32 v[32:33], v[34:35], v[34:35]
	v_add_f32_e32 v18, v47, v18
	v_add_f32_e32 v210, v31, v210
	v_add_f32_e32 v18, v48, v18
	v_add_f32_e32 v210, v32, v210
	v_add_f32_e32 v18, v49, v18
	v_add_f32_e32 v210, v33, v210
	v_mov_b32_e32 v147, v18
	v_mov_b32_e32 v148, v210
	v_pk_mul_f32 v[12:13], v[12:13], v[12:13]
	v_pk_mul_f32 v[14:15], v[14:15], v[14:15]
	v_add_f32_e32 v12, v12, v13
	v_add_f32_e32 v12, v14, v12
	v_pk_mul_f32 v[8:9], v[8:9], v[8:9]
	v_add_f32_e32 v12, v15, v12
	v_add_f32_e32 v8, v8, v12
	v_pk_mul_f32 v[10:11], v[10:11], v[10:11]
	v_add_f32_e32 v8, v9, v8
	v_add_f32_e32 v8, v10, v8
	v_pk_mul_f32 v[4:5], v[4:5], v[4:5]
	v_add_f32_e32 v8, v11, v8
	v_add_f32_e32 v4, v4, v8
	v_pk_mul_f32 v[6:7], v[6:7], v[6:7]
	v_add_f32_e32 v4, v5, v4
	v_add_f32_e32 v4, v6, v4
	v_pk_mul_f32 v[0:1], v[0:1], v[0:1]
	v_add_f32_e32 v4, v7, v4
	v_add_f32_e32 v0, v0, v4
	v_pk_mul_f32 v[2:3], v[2:3], v[2:3]
	v_add_f32_e32 v0, v1, v0
	v_add_f32_e32 v0, v2, v0
	v_add_f32_e32 v0, v3, v0
	v_mov_b32_e32 v149, v0
	ds_bpermute_b32 v172, v16, v132
	ds_bpermute_b32 v173, v16, v133
	ds_bpermute_b32 v174, v16, v134
	ds_bpermute_b32 v175, v16, v135
	ds_bpermute_b32 v180, v16, v146
	ds_bpermute_b32 v181, v16, v147
	ds_bpermute_b32 v182, v16, v148
	ds_bpermute_b32 v183, v16, v149
	s_waitcnt lgkmcnt(0)
	v_add_f32_e32 v132, v132, v172
	v_add_f32_e32 v133, v133, v173
	v_add_f32_e32 v134, v134, v174
	v_add_f32_e32 v135, v135, v175
	v_add_f32_e32 v146, v146, v180
	v_add_f32_e32 v147, v147, v181
	v_add_f32_e32 v148, v148, v182
	v_add_f32_e32 v149, v149, v183
	ds_bpermute_b32 v172, v17, v132
	ds_bpermute_b32 v173, v17, v133
	ds_bpermute_b32 v174, v17, v134
	ds_bpermute_b32 v175, v17, v135
	ds_bpermute_b32 v180, v17, v146
	ds_bpermute_b32 v181, v17, v147
	ds_bpermute_b32 v182, v17, v148
	ds_bpermute_b32 v183, v17, v149
	s_and_saveexec_b64 s[52:53], s[42:43]
	s_cbranch_execz .LBB0_240
	s_waitcnt lgkmcnt(0)
	v_add_f32_e32 v132, v132, v172
	v_lshlrev_b64 v[18:19], 6, v[168:169]
	v_lshl_add_u64 v[18:19], s[50:51], 0, v[18:19]
	global_store_dword v[18:19], v132, off
	v_add_f32_e32 v133, v133, v173
	v_lshlrev_b64 v[18:19], 6, v[166:167]
	v_lshl_add_u64 v[18:19], s[50:51], 0, v[18:19]
	global_store_dword v[18:19], v133, off
	v_add_f32_e32 v134, v134, v174
	v_lshlrev_b64 v[18:19], 6, v[164:165]
	v_lshl_add_u64 v[18:19], s[50:51], 0, v[18:19]
	global_store_dword v[18:19], v134, off
	v_add_f32_e32 v135, v135, v175
	v_lshlrev_b64 v[18:19], 6, v[162:163]
	v_lshl_add_u64 v[18:19], s[50:51], 0, v[18:19]
	global_store_dword v[18:19], v135, off
	v_add_f32_e32 v146, v146, v180
	v_lshlrev_b64 v[18:19], 6, v[76:77]
	v_lshl_add_u64 v[18:19], s[50:51], 0, v[18:19]
	global_store_dword v[18:19], v146, off
	v_add_f32_e32 v147, v147, v181
	v_lshlrev_b64 v[18:19], 6, v[72:73]
	v_lshl_add_u64 v[18:19], s[50:51], 0, v[18:19]
	global_store_dword v[18:19], v147, off
	v_add_f32_e32 v148, v148, v182
	v_lshlrev_b64 v[18:19], 6, v[70:71]
	v_lshl_add_u64 v[18:19], s[50:51], 0, v[18:19]
	global_store_dword v[18:19], v148, off
	v_add_f32_e32 v149, v149, v183
	v_lshlrev_b64 v[18:19], 6, v[68:69]
	v_lshl_add_u64 v[18:19], s[50:51], 0, v[18:19]
	global_store_dword v[18:19], v149, off
	s_branch .LBB0_240

.Lm4bp_295:
	s_waitcnt lgkmcnt(0)
	s_mov_b32 s100, 0
	s_barrier
	v_mfma_f32_16x16x32_bf16 v[60:63], v[146:149], v[170:173], 0
	v_mfma_f32_16x16x32_bf16 v[56:59], v[162:165], v[170:173], 0
	v_mfma_f32_16x16x32_bf16 v[52:55], v[146:149], v[178:181], 0
	v_mfma_f32_16x16x32_bf16 v[48:51], v[162:165], v[178:181], 0
	v_mfma_f32_16x16x32_bf16 v[44:47], v[146:149], v[194:197], 0
	v_mfma_f32_16x16x32_bf16 v[40:43], v[162:165], v[194:197], 0
	v_mfma_f32_16x16x32_bf16 v[36:39], v[146:149], v[210:213], 0
	v_mfma_f32_16x16x32_bf16 v[32:35], v[162:165], v[210:213], 0
	v_mfma_f32_16x16x32_bf16 v[60:63], v[158:161], v[174:177], v[60:63]
	v_mfma_f32_16x16x32_bf16 v[56:59], v[166:169], v[174:177], v[56:59]
	v_mfma_f32_16x16x32_bf16 v[52:55], v[158:161], v[182:185], v[52:55]
	v_mfma_f32_16x16x32_bf16 v[48:51], v[166:169], v[182:185], v[48:51]
	v_mfma_f32_16x16x32_bf16 v[44:47], v[158:161], v[206:209], v[44:47]
	v_mfma_f32_16x16x32_bf16 v[40:43], v[166:169], v[206:209], v[40:43]
	v_mfma_f32_16x16x32_bf16 v[36:39], v[158:161], v[214:217], v[36:39]
	v_mfma_f32_16x16x32_bf16 v[32:35], v[166:169], v[214:217], v[32:35]
	v_mfma_f32_16x16x32_bf16 v[28:31], v[218:221], v[170:173], 0
	v_mfma_f32_16x16x32_bf16 v[24:27], v[226:229], v[170:173], 0
	v_mfma_f32_16x16x32_bf16 v[20:23], v[218:221], v[178:181], 0
	v_mfma_f32_16x16x32_bf16 v[16:19], v[226:229], v[178:181], 0
	v_mfma_f32_16x16x32_bf16 v[12:15], v[218:221], v[194:197], 0
	v_mfma_f32_16x16x32_bf16 v[8:11], v[226:229], v[194:197], 0
	v_mfma_f32_16x16x32_bf16 v[4:7], v[218:221], v[210:213], 0
	v_mfma_f32_16x16x32_bf16 v[0:3], v[226:229], v[210:213], 0
	v_mfma_f32_16x16x32_bf16 v[28:31], v[222:225], v[174:177], v[28:31]
	v_mfma_f32_16x16x32_bf16 v[24:27], v[230:233], v[174:177], v[24:27]
	v_mfma_f32_16x16x32_bf16 v[20:23], v[222:225], v[182:185], v[20:23]
	v_mfma_f32_16x16x32_bf16 v[16:19], v[230:233], v[182:185], v[16:19]
	v_mfma_f32_16x16x32_bf16 v[12:15], v[222:225], v[206:209], v[12:15]
	v_mfma_f32_16x16x32_bf16 v[8:11], v[230:233], v[206:209], v[8:11]
	v_mfma_f32_16x16x32_bf16 v[4:7], v[222:225], v[214:217], v[4:7]
	v_mfma_f32_16x16x32_bf16 v[0:3], v[230:233], v[214:217], v[0:3]
	s_barrier
	s_add_i32 s6, 0, 0x18000
	v_add_u32_e32 v166, s6, v154
	ds_read_b128 v[146:149], v166
	ds_read_b128 v[158:161], v166 offset:1024
	ds_read_b128 v[162:165], v166 offset:2048
	ds_read_b128 v[166:169], v166 offset:3072
	s_add_u32 s52, s52, 0x40000
	s_addc_u32 s53, s53, 0
	s_mov_b32 m0, s68
	v_lshl_add_u64 v[218:219], s[52:53], 0, v[128:129]
	ds_read_b128 v[170:173], v157 offset:32768
	ds_read_b128 v[174:177], v157 offset:33792
	ds_read_b128 v[178:181], v157 offset:34816
	ds_read_b128 v[182:185], v157 offset:35840
	ds_read_b128 v[194:197], v157 offset:36864
	ds_read_b128 v[206:209], v157 offset:37888
	ds_read_b128 v[210:213], v157 offset:38912
	ds_read_b128 v[214:217], v157 offset:39936
	global_load_lds_dwordx4 v[218:219], off
	v_lshl_add_u64 v[218:219], s[52:53], 0, v[130:131]
	s_mov_b32 m0, s69
	s_nop 0
	global_load_lds_dwordx4 v[218:219], off
	s_add_i32 s19, 0, 0x1c000
	v_add_u32_e32 v192, s19, v154
	ds_read_b128 v[218:221], v192
	ds_read_b128 v[222:225], v192 offset:1024
	ds_read_b128 v[226:229], v192 offset:2048
	ds_read_b128 v[230:233], v192 offset:3072
	s_waitcnt vmcnt(8)
	s_waitcnt lgkmcnt(0)
	s_barrier
	v_mfma_f32_16x16x32_bf16 v[124:127], v[146:149], v[170:173], v[124:127]
	v_mfma_f32_16x16x32_bf16 v[120:123], v[162:165], v[170:173], v[120:123]
	v_mfma_f32_16x16x32_bf16 v[116:119], v[146:149], v[178:181], v[116:119]
	v_mfma_f32_16x16x32_bf16 v[112:115], v[162:165], v[178:181], v[112:115]
	v_mfma_f32_16x16x32_bf16 v[108:111], v[146:149], v[194:197], v[108:111]
	v_mfma_f32_16x16x32_bf16 v[104:107], v[162:165], v[194:197], v[104:107]
	v_mfma_f32_16x16x32_bf16 v[100:103], v[146:149], v[210:213], v[100:103]
	v_mfma_f32_16x16x32_bf16 v[96:99], v[162:165], v[210:213], v[96:99]
	v_mfma_f32_16x16x32_bf16 v[124:127], v[158:161], v[174:177], v[124:127]
	v_mfma_f32_16x16x32_bf16 v[120:123], v[166:169], v[174:177], v[120:123]
	v_mfma_f32_16x16x32_bf16 v[116:119], v[158:161], v[182:185], v[116:119]
	v_mfma_f32_16x16x32_bf16 v[112:115], v[166:169], v[182:185], v[112:115]
	v_mfma_f32_16x16x32_bf16 v[108:111], v[158:161], v[206:209], v[108:111]
	v_mfma_f32_16x16x32_bf16 v[104:107], v[166:169], v[206:209], v[104:107]
	v_mfma_f32_16x16x32_bf16 v[100:103], v[158:161], v[214:217], v[100:103]
	v_mfma_f32_16x16x32_bf16 v[96:99], v[166:169], v[214:217], v[96:99]
	v_mfma_f32_16x16x32_bf16 v[92:95], v[218:221], v[170:173], v[92:95]
	v_mfma_f32_16x16x32_bf16 v[88:91], v[226:229], v[170:173], v[88:91]
	v_mfma_f32_16x16x32_bf16 v[84:87], v[218:221], v[178:181], v[84:87]
	v_mfma_f32_16x16x32_bf16 v[80:83], v[226:229], v[178:181], v[80:83]
	v_mfma_f32_16x16x32_bf16 v[76:79], v[218:221], v[194:197], v[76:79]
	v_mfma_f32_16x16x32_bf16 v[72:75], v[226:229], v[194:197], v[72:75]
	v_mfma_f32_16x16x32_bf16 v[68:71], v[218:221], v[210:213], v[68:71]
	v_mfma_f32_16x16x32_bf16 v[64:67], v[226:229], v[210:213], v[64:67]
	v_mfma_f32_16x16x32_bf16 v[92:95], v[222:225], v[174:177], v[92:95]
	v_mfma_f32_16x16x32_bf16 v[88:91], v[230:233], v[174:177], v[88:91]
	v_mfma_f32_16x16x32_bf16 v[84:87], v[222:225], v[182:185], v[84:87]
	v_mfma_f32_16x16x32_bf16 v[80:83], v[230:233], v[182:185], v[80:83]
	v_mfma_f32_16x16x32_bf16 v[76:79], v[222:225], v[206:209], v[76:79]
	v_mfma_f32_16x16x32_bf16 v[72:75], v[230:233], v[206:209], v[72:75]
	v_mfma_f32_16x16x32_bf16 v[68:71], v[222:225], v[214:217], v[68:71]
	v_mfma_f32_16x16x32_bf16 v[64:67], v[230:233], v[214:217], v[64:67]
	s_barrier
	s_add_i32 s6, s6, s57
	v_lshl_add_u64 v[234:235], v[234:235], 0, s[36:37]
	s_mov_b32 m0, s6
	s_nop 0
	global_load_lds_dwordx4 v[234:235], off
	v_lshl_add_u64 v[234:235], v[236:237], 0, s[36:37]
	s_add_i32 m0, s6, 0x2000
	s_nop 0
	global_load_lds_dwordx4 v[234:235], off
	s_mov_b32 m0, s70
	v_lshl_add_u64 v[234:235], v[238:239], 0, s[36:37]
	ds_read_b128 v[170:173], v157 offset:49152
	ds_read_b128 v[174:177], v157 offset:50176
	ds_read_b128 v[178:181], v157 offset:51200
	ds_read_b128 v[182:185], v157 offset:52224
	ds_read_b128 v[194:197], v157 offset:53248
	ds_read_b128 v[206:209], v157 offset:54272
	ds_read_b128 v[210:213], v157 offset:55296
	ds_read_b128 v[214:217], v157 offset:56320
	global_load_lds_dwordx4 v[234:235], off
	v_lshl_add_u64 v[234:235], v[240:241], 0, s[36:37]
	s_mov_b32 m0, s71
	s_nop 0
	global_load_lds_dwordx4 v[234:235], off
	s_add_u32 s50, s50, 0x40080
	s_addc_u32 s51, s51, 0
	s_add_i32 s6, s19, s57
	v_lshl_add_u64 v[250:251], s[50:51], 0, v[140:141]
	s_mov_b32 m0, s6
	s_nop 0
	global_load_lds_dwordx4 v[250:251], off
	v_lshl_add_u64 v[250:251], s[50:51], 0, v[132:133]
	s_add_i32 m0, s6, 0x2000
	s_nop 0
	global_load_lds_dwordx4 v[250:251], off
	s_add_i32 s75, s75, 2
	s_add_u32 s48, s48, 0x100
	s_addc_u32 s49, s49, 0
	s_cmp_gt_u32 s75, 13
	s_nop 0
	s_waitcnt vmcnt(8)
	s_waitcnt lgkmcnt(0)
	s_barrier
	v_mfma_f32_16x16x32_bf16 v[60:63], v[146:149], v[170:173], v[60:63]
	v_mfma_f32_16x16x32_bf16 v[56:59], v[162:165], v[170:173], v[56:59]
	v_mfma_f32_16x16x32_bf16 v[52:55], v[146:149], v[178:181], v[52:55]
	v_mfma_f32_16x16x32_bf16 v[48:51], v[162:165], v[178:181], v[48:51]
	v_mfma_f32_16x16x32_bf16 v[44:47], v[146:149], v[194:197], v[44:47]
	v_mfma_f32_16x16x32_bf16 v[40:43], v[162:165], v[194:197], v[40:43]
	v_mfma_f32_16x16x32_bf16 v[36:39], v[146:149], v[210:213], v[36:39]
	v_mfma_f32_16x16x32_bf16 v[32:35], v[162:165], v[210:213], v[32:35]
	v_mfma_f32_16x16x32_bf16 v[60:63], v[158:161], v[174:177], v[60:63]
	v_mfma_f32_16x16x32_bf16 v[56:59], v[166:169], v[174:177], v[56:59]
	v_mfma_f32_16x16x32_bf16 v[52:55], v[158:161], v[182:185], v[52:55]
	v_mfma_f32_16x16x32_bf16 v[48:51], v[166:169], v[182:185], v[48:51]
	v_mfma_f32_16x16x32_bf16 v[44:47], v[158:161], v[206:209], v[44:47]
	v_mfma_f32_16x16x32_bf16 v[40:43], v[166:169], v[206:209], v[40:43]
	v_mfma_f32_16x16x32_bf16 v[36:39], v[158:161], v[214:217], v[36:39]
	v_mfma_f32_16x16x32_bf16 v[32:35], v[166:169], v[214:217], v[32:35]
	v_mfma_f32_16x16x32_bf16 v[28:31], v[218:221], v[170:173], v[28:31]
	v_mfma_f32_16x16x32_bf16 v[24:27], v[226:229], v[170:173], v[24:27]
	v_mfma_f32_16x16x32_bf16 v[20:23], v[218:221], v[178:181], v[20:23]
	v_mfma_f32_16x16x32_bf16 v[16:19], v[226:229], v[178:181], v[16:19]
	v_mfma_f32_16x16x32_bf16 v[12:15], v[218:221], v[194:197], v[12:15]
	v_mfma_f32_16x16x32_bf16 v[8:11], v[226:229], v[194:197], v[8:11]
	v_mfma_f32_16x16x32_bf16 v[4:7], v[218:221], v[210:213], v[4:7]
	v_mfma_f32_16x16x32_bf16 v[0:3], v[226:229], v[210:213], v[0:3]
	v_mfma_f32_16x16x32_bf16 v[28:31], v[222:225], v[174:177], v[28:31]
	v_mfma_f32_16x16x32_bf16 v[24:27], v[230:233], v[174:177], v[24:27]
	v_mfma_f32_16x16x32_bf16 v[20:23], v[222:225], v[182:185], v[20:23]
	v_mfma_f32_16x16x32_bf16 v[16:19], v[230:233], v[182:185], v[16:19]
	v_mfma_f32_16x16x32_bf16 v[12:15], v[222:225], v[206:209], v[12:15]
	v_mfma_f32_16x16x32_bf16 v[8:11], v[230:233], v[206:209], v[8:11]
	v_mfma_f32_16x16x32_bf16 v[4:7], v[222:225], v[214:217], v[4:7]
	v_mfma_f32_16x16x32_bf16 v[0:3], v[230:233], v[214:217], v[0:3]
	s_barrier
	.p2align	6
.LBB0_295:
	s_add_u32 s6, s4, s48
	s_addc_u32 s19, s5, s49
	s_add_u32 s6, s6, 0x100
	s_addc_u32 s19, s19, 0
	s_add_u32 s23, s10, s48
	s_addc_u32 s50, s11, s49
	s_add_i32 s80, 0, 0x10000
	v_add_u32_e32 v166, s80, v154
	ds_read_b128 v[146:149], v166
	ds_read_b128 v[158:161], v166 offset:1024
	ds_read_b128 v[162:165], v166 offset:2048
	ds_read_b128 v[166:169], v166 offset:3072
	s_cmpk_eq_i32 s48, 0x700
	s_cselect_b32 s53, s12, s19
	s_cselect_b32 s52, s29, s6
	s_cselect_b32 s51, s31, s50
	s_cselect_b32 s50, s35, s23
	v_lshl_add_u64 v[218:219], v[150:151], 0, s[48:49]
	s_add_i32 m0, s58, 0xc000
	ds_read_b128 v[170:173], v157
	ds_read_b128 v[174:177], v157 offset:1024
	ds_read_b128 v[178:181], v157 offset:2048
	ds_read_b128 v[182:185], v157 offset:3072
	ds_read_b128 v[194:197], v157 offset:4096
	ds_read_b128 v[206:209], v157 offset:5120
	ds_read_b128 v[210:213], v157 offset:6144
	ds_read_b128 v[214:217], v157 offset:7168
	global_load_lds_dwordx4 v[218:219], off
	v_lshl_add_u64 v[218:219], v[152:153], 0, s[48:49]
	s_add_i32 m0, s58, 0xe000
	s_nop 0
	global_load_lds_dwordx4 v[218:219], off
	s_add_i32 s6, 0, 0x14000
	v_add_u32_e32 v192, s6, v154
	ds_read_b128 v[218:221], v192
	ds_read_b128 v[222:225], v192 offset:1024
	ds_read_b128 v[226:229], v192 offset:2048
	ds_read_b128 v[230:233], v192 offset:3072
	s_waitcnt vmcnt(8)
	s_waitcnt lgkmcnt(0)
	s_barrier
	v_mfma_f32_16x16x32_bf16 v[124:127], v[146:149], v[170:173], v[124:127]
	v_mfma_f32_16x16x32_bf16 v[120:123], v[162:165], v[170:173], v[120:123]
	v_mfma_f32_16x16x32_bf16 v[116:119], v[146:149], v[178:181], v[116:119]
	v_mfma_f32_16x16x32_bf16 v[112:115], v[162:165], v[178:181], v[112:115]
	v_mfma_f32_16x16x32_bf16 v[108:111], v[146:149], v[194:197], v[108:111]
	v_mfma_f32_16x16x32_bf16 v[104:107], v[162:165], v[194:197], v[104:107]
	v_mfma_f32_16x16x32_bf16 v[100:103], v[146:149], v[210:213], v[100:103]
	v_mfma_f32_16x16x32_bf16 v[96:99], v[162:165], v[210:213], v[96:99]
	v_mfma_f32_16x16x32_bf16 v[124:127], v[158:161], v[174:177], v[124:127]
	v_mfma_f32_16x16x32_bf16 v[120:123], v[166:169], v[174:177], v[120:123]
	v_mfma_f32_16x16x32_bf16 v[116:119], v[158:161], v[182:185], v[116:119]
	v_mfma_f32_16x16x32_bf16 v[112:115], v[166:169], v[182:185], v[112:115]
	v_mfma_f32_16x16x32_bf16 v[108:111], v[158:161], v[206:209], v[108:111]
	v_mfma_f32_16x16x32_bf16 v[104:107], v[166:169], v[206:209], v[104:107]
	v_mfma_f32_16x16x32_bf16 v[100:103], v[158:161], v[214:217], v[100:103]
	v_mfma_f32_16x16x32_bf16 v[96:99], v[166:169], v[214:217], v[96:99]
	v_mfma_f32_16x16x32_bf16 v[92:95], v[218:221], v[170:173], v[92:95]
	v_mfma_f32_16x16x32_bf16 v[88:91], v[226:229], v[170:173], v[88:91]
	v_mfma_f32_16x16x32_bf16 v[84:87], v[218:221], v[178:181], v[84:87]
	v_mfma_f32_16x16x32_bf16 v[80:83], v[226:229], v[178:181], v[80:83]
	v_mfma_f32_16x16x32_bf16 v[76:79], v[218:221], v[194:197], v[76:79]
	v_mfma_f32_16x16x32_bf16 v[72:75], v[226:229], v[194:197], v[72:75]
	v_mfma_f32_16x16x32_bf16 v[68:71], v[218:221], v[210:213], v[68:71]
	v_mfma_f32_16x16x32_bf16 v[64:67], v[226:229], v[210:213], v[64:67]
	v_mfma_f32_16x16x32_bf16 v[92:95], v[222:225], v[174:177], v[92:95]
	v_mfma_f32_16x16x32_bf16 v[88:91], v[230:233], v[174:177], v[88:91]
	v_mfma_f32_16x16x32_bf16 v[84:87], v[222:225], v[182:185], v[84:87]
	v_mfma_f32_16x16x32_bf16 v[80:83], v[230:233], v[182:185], v[80:83]
	v_mfma_f32_16x16x32_bf16 v[76:79], v[222:225], v[206:209], v[76:79]
	v_mfma_f32_16x16x32_bf16 v[72:75], v[230:233], v[206:209], v[72:75]
	v_mfma_f32_16x16x32_bf16 v[68:71], v[222:225], v[214:217], v[68:71]
	v_mfma_f32_16x16x32_bf16 v[64:67], v[230:233], v[214:217], v[64:67]
	s_barrier
	s_add_i32 s19, s80, s57
	v_lshl_add_u64 v[234:235], s[50:51], 0, v[140:141]
	s_mov_b32 m0, s19
	s_nop 0
	global_load_lds_dwordx4 v[234:235], off
	v_lshl_add_u64 v[236:237], s[50:51], 0, v[132:133]
	s_add_i32 m0, s19, 0x2000
	s_nop 0
	global_load_lds_dwordx4 v[236:237], off
	s_mov_b32 m0, s58
	v_lshl_add_u64 v[238:239], s[52:53], 0, v[128:129]
	ds_read_b128 v[170:173], v157 offset:16384
	ds_read_b128 v[174:177], v157 offset:17408
	ds_read_b128 v[178:181], v157 offset:18432
	ds_read_b128 v[182:185], v157 offset:19456
	ds_read_b128 v[194:197], v157 offset:20480
	ds_read_b128 v[206:209], v157 offset:21504
	ds_read_b128 v[210:213], v157 offset:22528
	ds_read_b128 v[214:217], v157 offset:23552
	global_load_lds_dwordx4 v[238:239], off
	v_lshl_add_u64 v[240:241], s[52:53], 0, v[130:131]
	s_mov_b32 m0, s59
	s_nop 0
	global_load_lds_dwordx4 v[240:241], off
	s_add_u32 s80, s50, 0x40000
	s_addc_u32 s81, s51, 0
	s_add_i32 s6, s6, s57
	v_lshl_add_u64 v[250:251], s[80:81], 0, v[140:141]
	s_mov_b32 m0, s6
	s_nop 0
	global_load_lds_dwordx4 v[250:251], off
	v_lshl_add_u64 v[250:251], s[80:81], 0, v[132:133]
	s_add_i32 m0, s6, 0x2000
	s_nop 0
	global_load_lds_dwordx4 v[250:251], off
	s_waitcnt vmcnt(8)
	s_waitcnt lgkmcnt(0)
	s_barrier
	v_mfma_f32_16x16x32_bf16 v[60:63], v[146:149], v[170:173], v[60:63]
	v_mfma_f32_16x16x32_bf16 v[56:59], v[162:165], v[170:173], v[56:59]
	v_mfma_f32_16x16x32_bf16 v[52:55], v[146:149], v[178:181], v[52:55]
	v_mfma_f32_16x16x32_bf16 v[48:51], v[162:165], v[178:181], v[48:51]
	v_mfma_f32_16x16x32_bf16 v[44:47], v[146:149], v[194:197], v[44:47]
	v_mfma_f32_16x16x32_bf16 v[40:43], v[162:165], v[194:197], v[40:43]
	v_mfma_f32_16x16x32_bf16 v[36:39], v[146:149], v[210:213], v[36:39]
	v_mfma_f32_16x16x32_bf16 v[32:35], v[162:165], v[210:213], v[32:35]
	v_mfma_f32_16x16x32_bf16 v[60:63], v[158:161], v[174:177], v[60:63]
	v_mfma_f32_16x16x32_bf16 v[56:59], v[166:169], v[174:177], v[56:59]
	v_mfma_f32_16x16x32_bf16 v[52:55], v[158:161], v[182:185], v[52:55]
	v_mfma_f32_16x16x32_bf16 v[48:51], v[166:169], v[182:185], v[48:51]
	v_mfma_f32_16x16x32_bf16 v[44:47], v[158:161], v[206:209], v[44:47]
	v_mfma_f32_16x16x32_bf16 v[40:43], v[166:169], v[206:209], v[40:43]
	v_mfma_f32_16x16x32_bf16 v[36:39], v[158:161], v[214:217], v[36:39]
	v_mfma_f32_16x16x32_bf16 v[32:35], v[166:169], v[214:217], v[32:35]
	v_mfma_f32_16x16x32_bf16 v[28:31], v[218:221], v[170:173], v[28:31]
	v_mfma_f32_16x16x32_bf16 v[24:27], v[226:229], v[170:173], v[24:27]
	v_mfma_f32_16x16x32_bf16 v[20:23], v[218:221], v[178:181], v[20:23]
	v_mfma_f32_16x16x32_bf16 v[16:19], v[226:229], v[178:181], v[16:19]
	v_mfma_f32_16x16x32_bf16 v[12:15], v[218:221], v[194:197], v[12:15]
	v_mfma_f32_16x16x32_bf16 v[8:11], v[226:229], v[194:197], v[8:11]
	v_mfma_f32_16x16x32_bf16 v[4:7], v[218:221], v[210:213], v[4:7]
	v_mfma_f32_16x16x32_bf16 v[0:3], v[226:229], v[210:213], v[0:3]
	v_mfma_f32_16x16x32_bf16 v[28:31], v[222:225], v[174:177], v[28:31]
	v_mfma_f32_16x16x32_bf16 v[24:27], v[230:233], v[174:177], v[24:27]
	v_mfma_f32_16x16x32_bf16 v[20:23], v[222:225], v[182:185], v[20:23]
	v_mfma_f32_16x16x32_bf16 v[16:19], v[230:233], v[182:185], v[16:19]
	v_mfma_f32_16x16x32_bf16 v[12:15], v[222:225], v[206:209], v[12:15]
	v_mfma_f32_16x16x32_bf16 v[8:11], v[230:233], v[206:209], v[8:11]
	v_mfma_f32_16x16x32_bf16 v[4:7], v[222:225], v[214:217], v[4:7]
	v_mfma_f32_16x16x32_bf16 v[0:3], v[230:233], v[214:217], v[0:3]
	s_barrier
	s_add_i32 s6, 0, 0x18000
	v_add_u32_e32 v166, s6, v154
	ds_read_b128 v[146:149], v166
	ds_read_b128 v[158:161], v166 offset:1024
	ds_read_b128 v[162:165], v166 offset:2048
	ds_read_b128 v[166:169], v166 offset:3072
	s_add_u32 s52, s52, 0x40000
	s_addc_u32 s53, s53, 0
	s_mov_b32 m0, s68
	v_lshl_add_u64 v[218:219], s[52:53], 0, v[128:129]
	ds_read_b128 v[170:173], v157 offset:32768
	ds_read_b128 v[174:177], v157 offset:33792
	ds_read_b128 v[178:181], v157 offset:34816
	ds_read_b128 v[182:185], v157 offset:35840
	ds_read_b128 v[194:197], v157 offset:36864
	ds_read_b128 v[206:209], v157 offset:37888
	ds_read_b128 v[210:213], v157 offset:38912
	ds_read_b128 v[214:217], v157 offset:39936
	global_load_lds_dwordx4 v[218:219], off
	v_lshl_add_u64 v[218:219], s[52:53], 0, v[130:131]
	s_mov_b32 m0, s69
	s_nop 0
	global_load_lds_dwordx4 v[218:219], off
	s_add_i32 s19, 0, 0x1c000
	v_add_u32_e32 v192, s19, v154
	ds_read_b128 v[218:221], v192
	ds_read_b128 v[222:225], v192 offset:1024
	ds_read_b128 v[226:229], v192 offset:2048
	ds_read_b128 v[230:233], v192 offset:3072
	s_waitcnt vmcnt(8)
	s_waitcnt lgkmcnt(0)
	s_barrier
	v_mfma_f32_16x16x32_bf16 v[124:127], v[146:149], v[170:173], v[124:127]
	v_mfma_f32_16x16x32_bf16 v[120:123], v[162:165], v[170:173], v[120:123]
	v_mfma_f32_16x16x32_bf16 v[116:119], v[146:149], v[178:181], v[116:119]
	v_mfma_f32_16x16x32_bf16 v[112:115], v[162:165], v[178:181], v[112:115]
	v_mfma_f32_16x16x32_bf16 v[108:111], v[146:149], v[194:197], v[108:111]
	v_mfma_f32_16x16x32_bf16 v[104:107], v[162:165], v[194:197], v[104:107]
	v_mfma_f32_16x16x32_bf16 v[100:103], v[146:149], v[210:213], v[100:103]
	v_mfma_f32_16x16x32_bf16 v[96:99], v[162:165], v[210:213], v[96:99]
	v_mfma_f32_16x16x32_bf16 v[124:127], v[158:161], v[174:177], v[124:127]
	v_mfma_f32_16x16x32_bf16 v[120:123], v[166:169], v[174:177], v[120:123]
	v_mfma_f32_16x16x32_bf16 v[116:119], v[158:161], v[182:185], v[116:119]
	v_mfma_f32_16x16x32_bf16 v[112:115], v[166:169], v[182:185], v[112:115]
	v_mfma_f32_16x16x32_bf16 v[108:111], v[158:161], v[206:209], v[108:111]
	v_mfma_f32_16x16x32_bf16 v[104:107], v[166:169], v[206:209], v[104:107]
	v_mfma_f32_16x16x32_bf16 v[100:103], v[158:161], v[214:217], v[100:103]
	v_mfma_f32_16x16x32_bf16 v[96:99], v[166:169], v[214:217], v[96:99]
	v_mfma_f32_16x16x32_bf16 v[92:95], v[218:221], v[170:173], v[92:95]
	v_mfma_f32_16x16x32_bf16 v[88:91], v[226:229], v[170:173], v[88:91]
	v_mfma_f32_16x16x32_bf16 v[84:87], v[218:221], v[178:181], v[84:87]
	v_mfma_f32_16x16x32_bf16 v[80:83], v[226:229], v[178:181], v[80:83]
	v_mfma_f32_16x16x32_bf16 v[76:79], v[218:221], v[194:197], v[76:79]
	v_mfma_f32_16x16x32_bf16 v[72:75], v[226:229], v[194:197], v[72:75]
	v_mfma_f32_16x16x32_bf16 v[68:71], v[218:221], v[210:213], v[68:71]
	v_mfma_f32_16x16x32_bf16 v[64:67], v[226:229], v[210:213], v[64:67]
	v_mfma_f32_16x16x32_bf16 v[92:95], v[222:225], v[174:177], v[92:95]
	v_mfma_f32_16x16x32_bf16 v[88:91], v[230:233], v[174:177], v[88:91]
	v_mfma_f32_16x16x32_bf16 v[84:87], v[222:225], v[182:185], v[84:87]
	v_mfma_f32_16x16x32_bf16 v[80:83], v[230:233], v[182:185], v[80:83]
	v_mfma_f32_16x16x32_bf16 v[76:79], v[222:225], v[206:209], v[76:79]
	v_mfma_f32_16x16x32_bf16 v[72:75], v[230:233], v[206:209], v[72:75]
	v_mfma_f32_16x16x32_bf16 v[68:71], v[222:225], v[214:217], v[68:71]
	v_mfma_f32_16x16x32_bf16 v[64:67], v[230:233], v[214:217], v[64:67]
	s_barrier
	s_add_i32 s6, s6, s57
	v_lshl_add_u64 v[234:235], v[234:235], 0, s[36:37]
	s_mov_b32 m0, s6
	s_nop 0
	global_load_lds_dwordx4 v[234:235], off
	v_lshl_add_u64 v[234:235], v[236:237], 0, s[36:37]
	s_add_i32 m0, s6, 0x2000
	s_nop 0
	global_load_lds_dwordx4 v[234:235], off
	s_mov_b32 m0, s70
	v_lshl_add_u64 v[234:235], v[238:239], 0, s[36:37]
	ds_read_b128 v[170:173], v157 offset:49152
	ds_read_b128 v[174:177], v157 offset:50176
	ds_read_b128 v[178:181], v157 offset:51200
	ds_read_b128 v[182:185], v157 offset:52224
	ds_read_b128 v[194:197], v157 offset:53248
	ds_read_b128 v[206:209], v157 offset:54272
	ds_read_b128 v[210:213], v157 offset:55296
	ds_read_b128 v[214:217], v157 offset:56320
	global_load_lds_dwordx4 v[234:235], off
	v_lshl_add_u64 v[234:235], v[240:241], 0, s[36:37]
	s_mov_b32 m0, s71
	s_nop 0
	global_load_lds_dwordx4 v[234:235], off
	s_add_u32 s50, s50, 0x40080
	s_addc_u32 s51, s51, 0
	s_add_i32 s6, s19, s57
	v_lshl_add_u64 v[250:251], s[50:51], 0, v[140:141]
	s_mov_b32 m0, s6
	s_nop 0
	global_load_lds_dwordx4 v[250:251], off
	v_lshl_add_u64 v[250:251], s[50:51], 0, v[132:133]
	s_add_i32 m0, s6, 0x2000
	s_nop 0
	global_load_lds_dwordx4 v[250:251], off
	s_add_i32 s75, s75, 2
	s_add_u32 s48, s48, 0x100
	s_addc_u32 s49, s49, 0
	s_cmp_gt_u32 s75, 13
	s_nop 0
	s_waitcnt vmcnt(8)
	s_waitcnt lgkmcnt(0)
	s_barrier
	v_mfma_f32_16x16x32_bf16 v[60:63], v[146:149], v[170:173], v[60:63]
	v_mfma_f32_16x16x32_bf16 v[56:59], v[162:165], v[170:173], v[56:59]
	v_mfma_f32_16x16x32_bf16 v[52:55], v[146:149], v[178:181], v[52:55]
	v_mfma_f32_16x16x32_bf16 v[48:51], v[162:165], v[178:181], v[48:51]
	v_mfma_f32_16x16x32_bf16 v[44:47], v[146:149], v[194:197], v[44:47]
	v_mfma_f32_16x16x32_bf16 v[40:43], v[162:165], v[194:197], v[40:43]
	v_mfma_f32_16x16x32_bf16 v[36:39], v[146:149], v[210:213], v[36:39]
	v_mfma_f32_16x16x32_bf16 v[32:35], v[162:165], v[210:213], v[32:35]
	v_mfma_f32_16x16x32_bf16 v[60:63], v[158:161], v[174:177], v[60:63]
	v_mfma_f32_16x16x32_bf16 v[56:59], v[166:169], v[174:177], v[56:59]
	v_mfma_f32_16x16x32_bf16 v[52:55], v[158:161], v[182:185], v[52:55]
	v_mfma_f32_16x16x32_bf16 v[48:51], v[166:169], v[182:185], v[48:51]
	v_mfma_f32_16x16x32_bf16 v[44:47], v[158:161], v[206:209], v[44:47]
	v_mfma_f32_16x16x32_bf16 v[40:43], v[166:169], v[206:209], v[40:43]
	v_mfma_f32_16x16x32_bf16 v[36:39], v[158:161], v[214:217], v[36:39]
	v_mfma_f32_16x16x32_bf16 v[32:35], v[166:169], v[214:217], v[32:35]
	v_mfma_f32_16x16x32_bf16 v[28:31], v[218:221], v[170:173], v[28:31]
	v_mfma_f32_16x16x32_bf16 v[24:27], v[226:229], v[170:173], v[24:27]
	v_mfma_f32_16x16x32_bf16 v[20:23], v[218:221], v[178:181], v[20:23]
	v_mfma_f32_16x16x32_bf16 v[16:19], v[226:229], v[178:181], v[16:19]
	v_mfma_f32_16x16x32_bf16 v[12:15], v[218:221], v[194:197], v[12:15]
	v_mfma_f32_16x16x32_bf16 v[8:11], v[226:229], v[194:197], v[8:11]
	v_mfma_f32_16x16x32_bf16 v[4:7], v[218:221], v[210:213], v[4:7]
	v_mfma_f32_16x16x32_bf16 v[0:3], v[226:229], v[210:213], v[0:3]
	v_mfma_f32_16x16x32_bf16 v[28:31], v[222:225], v[174:177], v[28:31]
	v_mfma_f32_16x16x32_bf16 v[24:27], v[230:233], v[174:177], v[24:27]
	v_mfma_f32_16x16x32_bf16 v[20:23], v[222:225], v[182:185], v[20:23]
	v_mfma_f32_16x16x32_bf16 v[16:19], v[230:233], v[182:185], v[16:19]
	v_mfma_f32_16x16x32_bf16 v[12:15], v[222:225], v[206:209], v[12:15]
	v_mfma_f32_16x16x32_bf16 v[8:11], v[230:233], v[206:209], v[8:11]
	v_mfma_f32_16x16x32_bf16 v[4:7], v[222:225], v[214:217], v[4:7]
	v_mfma_f32_16x16x32_bf16 v[0:3], v[230:233], v[214:217], v[0:3]
	s_barrier
	s_cbranch_scc0 .LBB0_295
	s_mov_b32 s100, 1
	s_add_u32 s48, s10, 0xffffff00
	v_lshl_add_u32 v166, s73, 10, v155
	s_addc_u32 s49, s11, -1
	s_ashr_i32 s29, s28, 31
	v_lshl_or_b32 v146, s72, 8, v156
	ds_read2_b32 v[158:159], v166 offset1:16
	s_lshl_b64 s[10:11], s[28:29], 8
	v_ashrrev_i32_e32 v147, 31, v146
	v_lshl_add_u64 v[148:149], s[10:11], 0, v[134:135]
	v_lshl_add_u64 v[146:147], v[146:147], 1, s[26:27]
	v_mad_u64_u32 v[150:151], s[10:11], v148, s13, v[146:147]
	v_mov_b32_e32 v146, v151
	v_mad_u64_u32 v[152:153], s[10:11], v149, s13, v[146:147]
	s_waitcnt lgkmcnt(0)
	v_pk_mul_f32 v[148:149], v[126:127], v[158:159] op_sel_hi:[1,0]
	v_pk_mul_f32 v[146:147], v[124:125], v[158:159] op_sel_hi:[1,0]
	v_pk_mul_f32 v[160:161], v[122:123], v[158:159] op_sel_hi:[1,0]
	v_pk_mul_f32 v[162:163], v[120:121], v[158:159] op_sel_hi:[1,0]
	v_mov_b32_e32 v151, v152
	v_cvt_pk_bf16_f32 v146, v146, v147
	v_cvt_pk_bf16_f32 v147, v148, v149
	v_cvt_pk_bf16_f32 v148, v162, v163
	v_cvt_pk_bf16_f32 v149, v160, v161
	global_store_dwordx4 v[150:151], v[146:149], off
	v_pk_mul_f32 v[160:161], v[90:91], v[158:159] op_sel_hi:[1,0]
	v_pk_mul_f32 v[162:163], v[88:89], v[158:159] op_sel_hi:[1,0]
	v_pk_mul_f32 v[148:149], v[94:95], v[158:159] op_sel_hi:[1,0]
	v_pk_mul_f32 v[146:147], v[92:93], v[158:159] op_sel_hi:[1,0]
	v_mov_b32_e32 v158, v159
	v_cvt_pk_bf16_f32 v146, v146, v147
	v_cvt_pk_bf16_f32 v147, v148, v149
	v_cvt_pk_bf16_f32 v148, v162, v163
	v_cvt_pk_bf16_f32 v149, v160, v161
	global_store_dwordx4 v[150:151], v[146:149], off offset:256
	v_pk_mul_f32 v[160:161], v[114:115], v[158:159] op_sel_hi:[1,0]
	s_mov_b32 s6, 0x1e000
	v_pk_mul_f32 v[148:149], v[118:119], v[158:159] op_sel_hi:[1,0]
	v_pk_mul_f32 v[146:147], v[116:117], v[158:159] op_sel_hi:[1,0]
	ds_read2_b32 v[164:165], v166 offset0:32 offset1:48
	v_pk_mul_f32 v[162:163], v[112:113], v[158:159] op_sel_hi:[1,0]
	v_cvt_pk_bf16_f32 v146, v146, v147
	v_cvt_pk_bf16_f32 v147, v148, v149
	v_cvt_pk_bf16_f32 v149, v160, v161
	v_add_co_u32_e32 v160, vcc, s6, v150
	v_cvt_pk_bf16_f32 v148, v162, v163
	s_nop 0
	v_addc_co_u32_e32 v161, vcc, 0, v152, vcc
	global_store_dwordx4 v[160:161], v[146:149], off
	v_pk_mul_f32 v[162:163], v[82:83], v[158:159] op_sel_hi:[1,0]
	s_mov_b32 s6, 0x3c000
	v_pk_mul_f32 v[148:149], v[86:87], v[158:159] op_sel_hi:[1,0]
	v_pk_mul_f32 v[146:147], v[84:85], v[158:159] op_sel_hi:[1,0]
	v_pk_mul_f32 v[158:159], v[80:81], v[158:159] op_sel_hi:[1,0]
	v_cvt_pk_bf16_f32 v146, v146, v147
	v_cvt_pk_bf16_f32 v147, v148, v149
	v_cvt_pk_bf16_f32 v148, v158, v159
	v_cvt_pk_bf16_f32 v149, v162, v163
	global_store_dwordx4 v[160:161], v[146:149], off offset:256
	s_waitcnt lgkmcnt(0)
	v_pk_mul_f32 v[158:159], v[106:107], v[164:165] op_sel_hi:[1,0]
	v_pk_mul_f32 v[160:161], v[104:105], v[164:165] op_sel_hi:[1,0]
	v_pk_mul_f32 v[148:149], v[110:111], v[164:165] op_sel_hi:[1,0]
	v_pk_mul_f32 v[146:147], v[108:109], v[164:165] op_sel_hi:[1,0]
	v_pk_mul_f32 v[162:163], v[72:73], v[164:165] op_sel_hi:[1,0]
	v_cvt_pk_bf16_f32 v146, v146, v147
	v_cvt_pk_bf16_f32 v147, v148, v149
	v_cvt_pk_bf16_f32 v149, v158, v159
	v_add_co_u32_e32 v158, vcc, s6, v150
	v_cvt_pk_bf16_f32 v148, v160, v161
	s_nop 0
	v_addc_co_u32_e32 v159, vcc, 0, v152, vcc
	global_store_dwordx4 v[158:159], v[146:149], off
	v_pk_mul_f32 v[160:161], v[74:75], v[164:165] op_sel_hi:[1,0]
	s_mov_b32 s6, 0x5a000
	v_pk_mul_f32 v[148:149], v[78:79], v[164:165] op_sel_hi:[1,0]
	v_pk_mul_f32 v[146:147], v[76:77], v[164:165] op_sel_hi:[1,0]
	s_nop 0
	v_cvt_pk_bf16_f32 v146, v146, v147
	v_cvt_pk_bf16_f32 v147, v148, v149
	v_cvt_pk_bf16_f32 v148, v162, v163
	v_cvt_pk_bf16_f32 v149, v160, v161
	global_store_dwordx4 v[158:159], v[146:149], off offset:256
	v_mov_b32_e32 v158, v165
	v_pk_mul_f32 v[160:161], v[98:99], v[158:159] op_sel_hi:[1,0]
	v_pk_mul_f32 v[148:149], v[102:103], v[158:159] op_sel_hi:[1,0]
	v_pk_mul_f32 v[146:147], v[100:101], v[158:159] op_sel_hi:[1,0]
	ds_read2_b32 v[164:165], v166 offset0:128 offset1:144
	v_pk_mul_f32 v[162:163], v[96:97], v[158:159] op_sel_hi:[1,0]
	v_cvt_pk_bf16_f32 v146, v146, v147
	v_cvt_pk_bf16_f32 v147, v148, v149
	v_cvt_pk_bf16_f32 v149, v160, v161
	v_add_co_u32_e32 v160, vcc, s6, v150
	v_cvt_pk_bf16_f32 v148, v162, v163
	s_nop 0
	v_addc_co_u32_e32 v161, vcc, 0, v152, vcc
	global_store_dwordx4 v[160:161], v[146:149], off
	v_pk_mul_f32 v[162:163], v[66:67], v[158:159] op_sel_hi:[1,0]
	s_mov_b32 s6, 0xf0000
	v_pk_mul_f32 v[148:149], v[70:71], v[158:159] op_sel_hi:[1,0]
	v_pk_mul_f32 v[146:147], v[68:69], v[158:159] op_sel_hi:[1,0]
	v_pk_mul_f32 v[158:159], v[64:65], v[158:159] op_sel_hi:[1,0]
	v_cvt_pk_bf16_f32 v146, v146, v147
	v_cvt_pk_bf16_f32 v147, v148, v149
	v_cvt_pk_bf16_f32 v148, v158, v159
	v_cvt_pk_bf16_f32 v149, v162, v163
	global_store_dwordx4 v[160:161], v[146:149], off offset:256
	s_waitcnt lgkmcnt(0)
	v_pk_mul_f32 v[158:159], v[58:59], v[164:165] op_sel_hi:[1,0]
	v_pk_mul_f32 v[160:161], v[56:57], v[164:165] op_sel_hi:[1,0]
	v_pk_mul_f32 v[148:149], v[62:63], v[164:165] op_sel_hi:[1,0]
	v_pk_mul_f32 v[146:147], v[60:61], v[164:165] op_sel_hi:[1,0]
	v_pk_mul_f32 v[162:163], v[24:25], v[164:165] op_sel_hi:[1,0]
	v_cvt_pk_bf16_f32 v146, v146, v147
	v_cvt_pk_bf16_f32 v147, v148, v149
	v_cvt_pk_bf16_f32 v149, v158, v159
	v_add_co_u32_e32 v158, vcc, s6, v150
	v_cvt_pk_bf16_f32 v148, v160, v161
	s_nop 0
	v_addc_co_u32_e32 v159, vcc, 0, v152, vcc
	global_store_dwordx4 v[158:159], v[146:149], off
	v_pk_mul_f32 v[160:161], v[26:27], v[164:165] op_sel_hi:[1,0]
	s_mov_b32 s6, 0x10e000
	v_pk_mul_f32 v[148:149], v[30:31], v[164:165] op_sel_hi:[1,0]
	v_pk_mul_f32 v[146:147], v[28:29], v[164:165] op_sel_hi:[1,0]
	s_nop 0
	v_cvt_pk_bf16_f32 v146, v146, v147
	v_cvt_pk_bf16_f32 v147, v148, v149
	v_cvt_pk_bf16_f32 v148, v162, v163
	v_cvt_pk_bf16_f32 v149, v160, v161
	global_store_dwordx4 v[158:159], v[146:149], off offset:256
	v_mov_b32_e32 v158, v165
	v_pk_mul_f32 v[160:161], v[50:51], v[158:159] op_sel_hi:[1,0]
	v_pk_mul_f32 v[148:149], v[54:55], v[158:159] op_sel_hi:[1,0]
	v_pk_mul_f32 v[146:147], v[52:53], v[158:159] op_sel_hi:[1,0]
	ds_read2_b32 v[164:165], v166 offset0:160 offset1:176
	v_pk_mul_f32 v[162:163], v[48:49], v[158:159] op_sel_hi:[1,0]
	v_cvt_pk_bf16_f32 v146, v146, v147
	v_cvt_pk_bf16_f32 v147, v148, v149
	v_cvt_pk_bf16_f32 v149, v160, v161
	v_add_co_u32_e32 v160, vcc, s6, v150
	v_cvt_pk_bf16_f32 v148, v162, v163
	s_nop 0
	v_addc_co_u32_e32 v161, vcc, 0, v152, vcc
	global_store_dwordx4 v[160:161], v[146:149], off
	v_pk_mul_f32 v[162:163], v[18:19], v[158:159] op_sel_hi:[1,0]
	s_mov_b32 s6, 0x12c000
	v_pk_mul_f32 v[148:149], v[22:23], v[158:159] op_sel_hi:[1,0]
	v_pk_mul_f32 v[146:147], v[20:21], v[158:159] op_sel_hi:[1,0]
	v_pk_mul_f32 v[158:159], v[16:17], v[158:159] op_sel_hi:[1,0]
	v_cvt_pk_bf16_f32 v146, v146, v147
	v_cvt_pk_bf16_f32 v147, v148, v149
	v_cvt_pk_bf16_f32 v148, v158, v159
	v_cvt_pk_bf16_f32 v149, v162, v163
	global_store_dwordx4 v[160:161], v[146:149], off offset:256
	s_waitcnt lgkmcnt(0)
	v_pk_mul_f32 v[158:159], v[42:43], v[164:165] op_sel_hi:[1,0]
	v_pk_mul_f32 v[160:161], v[40:41], v[164:165] op_sel_hi:[1,0]
	v_pk_mul_f32 v[148:149], v[46:47], v[164:165] op_sel_hi:[1,0]
	v_pk_mul_f32 v[146:147], v[44:45], v[164:165] op_sel_hi:[1,0]
	v_pk_mul_f32 v[162:163], v[8:9], v[164:165] op_sel_hi:[1,0]
	v_cvt_pk_bf16_f32 v146, v146, v147
	v_cvt_pk_bf16_f32 v147, v148, v149
	v_cvt_pk_bf16_f32 v149, v158, v159
	v_add_co_u32_e32 v158, vcc, s6, v150
	v_cvt_pk_bf16_f32 v148, v160, v161
	s_nop 0
	v_addc_co_u32_e32 v159, vcc, 0, v152, vcc
	global_store_dwordx4 v[158:159], v[146:149], off
	v_pk_mul_f32 v[160:161], v[10:11], v[164:165] op_sel_hi:[1,0]
	s_mov_b32 s6, 0x14a000
	v_pk_mul_f32 v[148:149], v[14:15], v[164:165] op_sel_hi:[1,0]
	v_pk_mul_f32 v[146:147], v[12:13], v[164:165] op_sel_hi:[1,0]
	v_add_co_u32_e32 v150, vcc, s6, v150
	v_cvt_pk_bf16_f32 v146, v146, v147
	v_cvt_pk_bf16_f32 v147, v148, v149
	v_cvt_pk_bf16_f32 v148, v162, v163
	v_cvt_pk_bf16_f32 v149, v160, v161
	global_store_dwordx4 v[158:159], v[146:149], off offset:256
	v_mov_b32_e32 v158, v165
	v_pk_mul_f32 v[160:161], v[34:35], v[158:159] op_sel_hi:[1,0]
	v_pk_mul_f32 v[148:149], v[38:39], v[158:159] op_sel_hi:[1,0]
	v_pk_mul_f32 v[146:147], v[36:37], v[158:159] op_sel_hi:[1,0]
	v_pk_mul_f32 v[162:163], v[32:33], v[158:159] op_sel_hi:[1,0]
	v_cvt_pk_bf16_f32 v146, v146, v147
	v_cvt_pk_bf16_f32 v147, v148, v149
	v_cvt_pk_bf16_f32 v148, v162, v163
	v_cvt_pk_bf16_f32 v149, v160, v161
	v_addc_co_u32_e32 v151, vcc, 0, v152, vcc
	global_store_dwordx4 v[150:151], v[146:149], off
	v_pk_mul_f32 v[152:153], v[2:3], v[158:159] op_sel_hi:[1,0]
	s_andn2_b64 vcc, exec, s[44:45]
	v_pk_mul_f32 v[148:149], v[6:7], v[158:159] op_sel_hi:[1,0]
	v_pk_mul_f32 v[146:147], v[4:5], v[158:159] op_sel_hi:[1,0]
	v_pk_mul_f32 v[158:159], v[0:1], v[158:159] op_sel_hi:[1,0]
	v_cvt_pk_bf16_f32 v146, v146, v147
	v_cvt_pk_bf16_f32 v147, v148, v149
	v_cvt_pk_bf16_f32 v148, v158, v159
	v_cvt_pk_bf16_f32 v149, v152, v153
	global_store_dwordx4 v[150:151], v[146:149], off offset:256
	s_cbranch_vccz .LBB0_291
	s_mov_b64 s[38:39], s[48:49]
	s_andn2_b64 vcc, exec, s[42:43]
	s_mov_b64 s[48:49], s[38:39]
	s_cbranch_vccnz .LBB0_292

.Lm4bp_315:
	s_waitcnt lgkmcnt(0)
	s_mov_b32 s100, 0
	s_barrier
	v_mfma_f32_16x16x32_bf16 v[60:63], v[146:149], v[170:173], 0
	v_mfma_f32_16x16x32_bf16 v[56:59], v[162:165], v[170:173], 0
	v_mfma_f32_16x16x32_bf16 v[52:55], v[146:149], v[178:181], 0
	v_mfma_f32_16x16x32_bf16 v[48:51], v[162:165], v[178:181], 0
	v_mfma_f32_16x16x32_bf16 v[44:47], v[146:149], v[194:197], 0
	v_mfma_f32_16x16x32_bf16 v[40:43], v[162:165], v[194:197], 0
	v_mfma_f32_16x16x32_bf16 v[36:39], v[146:149], v[210:213], 0
	v_mfma_f32_16x16x32_bf16 v[32:35], v[162:165], v[210:213], 0
	v_mfma_f32_16x16x32_bf16 v[60:63], v[158:161], v[174:177], v[60:63]
	v_mfma_f32_16x16x32_bf16 v[56:59], v[166:169], v[174:177], v[56:59]
	v_mfma_f32_16x16x32_bf16 v[52:55], v[158:161], v[182:185], v[52:55]
	v_mfma_f32_16x16x32_bf16 v[48:51], v[166:169], v[182:185], v[48:51]
	v_mfma_f32_16x16x32_bf16 v[44:47], v[158:161], v[206:209], v[44:47]
	v_mfma_f32_16x16x32_bf16 v[40:43], v[166:169], v[206:209], v[40:43]
	v_mfma_f32_16x16x32_bf16 v[36:39], v[158:161], v[214:217], v[36:39]
	v_mfma_f32_16x16x32_bf16 v[32:35], v[166:169], v[214:217], v[32:35]
	v_mfma_f32_16x16x32_bf16 v[28:31], v[218:221], v[170:173], 0
	v_mfma_f32_16x16x32_bf16 v[24:27], v[226:229], v[170:173], 0
	v_mfma_f32_16x16x32_bf16 v[20:23], v[218:221], v[178:181], 0
	v_mfma_f32_16x16x32_bf16 v[16:19], v[226:229], v[178:181], 0
	v_mfma_f32_16x16x32_bf16 v[12:15], v[218:221], v[194:197], 0
	v_mfma_f32_16x16x32_bf16 v[8:11], v[226:229], v[194:197], 0
	v_mfma_f32_16x16x32_bf16 v[4:7], v[218:221], v[210:213], 0
	v_mfma_f32_16x16x32_bf16 v[0:3], v[226:229], v[210:213], 0
	v_mfma_f32_16x16x32_bf16 v[28:31], v[222:225], v[174:177], v[28:31]
	v_mfma_f32_16x16x32_bf16 v[24:27], v[230:233], v[174:177], v[24:27]
	v_mfma_f32_16x16x32_bf16 v[20:23], v[222:225], v[182:185], v[20:23]
	v_mfma_f32_16x16x32_bf16 v[16:19], v[230:233], v[182:185], v[16:19]
	v_mfma_f32_16x16x32_bf16 v[12:15], v[222:225], v[206:209], v[12:15]
	v_mfma_f32_16x16x32_bf16 v[8:11], v[230:233], v[206:209], v[8:11]
	v_mfma_f32_16x16x32_bf16 v[4:7], v[222:225], v[214:217], v[4:7]
	v_mfma_f32_16x16x32_bf16 v[0:3], v[230:233], v[214:217], v[0:3]
	s_barrier
	s_add_i32 s6, 0, 0x18000
	v_add_u32_e32 v157, s6, v154
	ds_read_b128 v[146:149], v157
	ds_read_b128 v[158:161], v157 offset:1024
	ds_read_b128 v[162:165], v157 offset:2048
	ds_read_b128 v[166:169], v157 offset:3072
	s_add_u32 s52, s52, 0x40000
	s_addc_u32 s53, s53, 0
	s_mov_b32 m0, s68
	v_lshl_add_u64 v[218:219], s[52:53], 0, v[128:129]
	ds_read_b128 v[170:173], v156 offset:32768
	ds_read_b128 v[174:177], v156 offset:33792
	ds_read_b128 v[178:181], v156 offset:34816
	ds_read_b128 v[182:185], v156 offset:35840
	ds_read_b128 v[194:197], v156 offset:36864
	ds_read_b128 v[206:209], v156 offset:37888
	ds_read_b128 v[210:213], v156 offset:38912
	ds_read_b128 v[214:217], v156 offset:39936
	global_load_lds_dwordx4 v[218:219], off
	v_lshl_add_u64 v[218:219], s[52:53], 0, v[130:131]
	s_mov_b32 m0, s69
	s_nop 0
	global_load_lds_dwordx4 v[218:219], off
	s_add_i32 s19, 0, 0x1c000
	v_add_u32_e32 v157, s19, v154
	ds_read_b128 v[218:221], v157
	ds_read_b128 v[222:225], v157 offset:1024
	ds_read_b128 v[226:229], v157 offset:2048
	ds_read_b128 v[230:233], v157 offset:3072
	s_waitcnt vmcnt(8)
	s_waitcnt lgkmcnt(0)
	s_barrier
	v_mfma_f32_16x16x32_bf16 v[124:127], v[146:149], v[170:173], v[124:127]
	v_mfma_f32_16x16x32_bf16 v[120:123], v[162:165], v[170:173], v[120:123]
	v_mfma_f32_16x16x32_bf16 v[116:119], v[146:149], v[178:181], v[116:119]
	v_mfma_f32_16x16x32_bf16 v[112:115], v[162:165], v[178:181], v[112:115]
	v_mfma_f32_16x16x32_bf16 v[108:111], v[146:149], v[194:197], v[108:111]
	v_mfma_f32_16x16x32_bf16 v[104:107], v[162:165], v[194:197], v[104:107]
	v_mfma_f32_16x16x32_bf16 v[100:103], v[146:149], v[210:213], v[100:103]
	v_mfma_f32_16x16x32_bf16 v[96:99], v[162:165], v[210:213], v[96:99]
	v_mfma_f32_16x16x32_bf16 v[124:127], v[158:161], v[174:177], v[124:127]
	v_mfma_f32_16x16x32_bf16 v[120:123], v[166:169], v[174:177], v[120:123]
	v_mfma_f32_16x16x32_bf16 v[116:119], v[158:161], v[182:185], v[116:119]
	v_mfma_f32_16x16x32_bf16 v[112:115], v[166:169], v[182:185], v[112:115]
	v_mfma_f32_16x16x32_bf16 v[108:111], v[158:161], v[206:209], v[108:111]
	v_mfma_f32_16x16x32_bf16 v[104:107], v[166:169], v[206:209], v[104:107]
	v_mfma_f32_16x16x32_bf16 v[100:103], v[158:161], v[214:217], v[100:103]
	v_mfma_f32_16x16x32_bf16 v[96:99], v[166:169], v[214:217], v[96:99]
	v_mfma_f32_16x16x32_bf16 v[92:95], v[218:221], v[170:173], v[92:95]
	v_mfma_f32_16x16x32_bf16 v[88:91], v[226:229], v[170:173], v[88:91]
	v_mfma_f32_16x16x32_bf16 v[84:87], v[218:221], v[178:181], v[84:87]
	v_mfma_f32_16x16x32_bf16 v[80:83], v[226:229], v[178:181], v[80:83]
	v_mfma_f32_16x16x32_bf16 v[76:79], v[218:221], v[194:197], v[76:79]
	v_mfma_f32_16x16x32_bf16 v[72:75], v[226:229], v[194:197], v[72:75]
	v_mfma_f32_16x16x32_bf16 v[68:71], v[218:221], v[210:213], v[68:71]
	v_mfma_f32_16x16x32_bf16 v[64:67], v[226:229], v[210:213], v[64:67]
	v_mfma_f32_16x16x32_bf16 v[92:95], v[222:225], v[174:177], v[92:95]
	v_mfma_f32_16x16x32_bf16 v[88:91], v[230:233], v[174:177], v[88:91]
	v_mfma_f32_16x16x32_bf16 v[84:87], v[222:225], v[182:185], v[84:87]
	v_mfma_f32_16x16x32_bf16 v[80:83], v[230:233], v[182:185], v[80:83]
	v_mfma_f32_16x16x32_bf16 v[76:79], v[222:225], v[206:209], v[76:79]
	v_mfma_f32_16x16x32_bf16 v[72:75], v[230:233], v[206:209], v[72:75]
	v_mfma_f32_16x16x32_bf16 v[68:71], v[222:225], v[214:217], v[68:71]
	v_mfma_f32_16x16x32_bf16 v[64:67], v[230:233], v[214:217], v[64:67]
	s_barrier
	s_add_i32 s6, s6, s57
	v_lshl_add_u64 v[234:235], v[234:235], 0, s[36:37]
	s_mov_b32 m0, s6
	s_nop 0
	global_load_lds_dwordx4 v[234:235], off
	v_lshl_add_u64 v[234:235], v[236:237], 0, s[36:37]
	s_add_i32 m0, s6, 0x2000
	s_nop 0
	global_load_lds_dwordx4 v[234:235], off
	s_mov_b32 m0, s71
	v_lshl_add_u64 v[234:235], v[238:239], 0, s[36:37]
	ds_read_b128 v[170:173], v156 offset:49152
	ds_read_b128 v[174:177], v156 offset:50176
	ds_read_b128 v[178:181], v156 offset:51200
	ds_read_b128 v[182:185], v156 offset:52224
	ds_read_b128 v[194:197], v156 offset:53248
	ds_read_b128 v[206:209], v156 offset:54272
	ds_read_b128 v[210:213], v156 offset:55296
	ds_read_b128 v[214:217], v156 offset:56320
	global_load_lds_dwordx4 v[234:235], off
	v_lshl_add_u64 v[234:235], v[240:241], 0, s[36:37]
	s_mov_b32 m0, s72
	s_nop 0
	global_load_lds_dwordx4 v[234:235], off
	s_add_u32 s50, s50, 0x40080
	s_addc_u32 s51, s51, 0
	s_add_i32 s6, s19, s57
	v_lshl_add_u64 v[250:251], s[50:51], 0, v[140:141]
	s_mov_b32 m0, s6
	s_nop 0
	global_load_lds_dwordx4 v[250:251], off
	v_lshl_add_u64 v[250:251], s[50:51], 0, v[132:133]
	s_add_i32 m0, s6, 0x2000
	s_nop 0
	global_load_lds_dwordx4 v[250:251], off
	s_add_i32 s75, s75, 2
	s_add_u32 s48, s48, 0x100
	s_addc_u32 s49, s49, 0
	s_cmp_gt_u32 s75, 13
	s_nop 0
	s_waitcnt vmcnt(8)
	s_waitcnt lgkmcnt(0)
	s_barrier
	v_mfma_f32_16x16x32_bf16 v[60:63], v[146:149], v[170:173], v[60:63]
	v_mfma_f32_16x16x32_bf16 v[56:59], v[162:165], v[170:173], v[56:59]
	v_mfma_f32_16x16x32_bf16 v[52:55], v[146:149], v[178:181], v[52:55]
	v_mfma_f32_16x16x32_bf16 v[48:51], v[162:165], v[178:181], v[48:51]
	v_mfma_f32_16x16x32_bf16 v[44:47], v[146:149], v[194:197], v[44:47]
	v_mfma_f32_16x16x32_bf16 v[40:43], v[162:165], v[194:197], v[40:43]
	v_mfma_f32_16x16x32_bf16 v[36:39], v[146:149], v[210:213], v[36:39]
	v_mfma_f32_16x16x32_bf16 v[32:35], v[162:165], v[210:213], v[32:35]
	v_mfma_f32_16x16x32_bf16 v[60:63], v[158:161], v[174:177], v[60:63]
	v_mfma_f32_16x16x32_bf16 v[56:59], v[166:169], v[174:177], v[56:59]
	v_mfma_f32_16x16x32_bf16 v[52:55], v[158:161], v[182:185], v[52:55]
	v_mfma_f32_16x16x32_bf16 v[48:51], v[166:169], v[182:185], v[48:51]
	v_mfma_f32_16x16x32_bf16 v[44:47], v[158:161], v[206:209], v[44:47]
	v_mfma_f32_16x16x32_bf16 v[40:43], v[166:169], v[206:209], v[40:43]
	v_mfma_f32_16x16x32_bf16 v[36:39], v[158:161], v[214:217], v[36:39]
	v_mfma_f32_16x16x32_bf16 v[32:35], v[166:169], v[214:217], v[32:35]
	v_mfma_f32_16x16x32_bf16 v[28:31], v[218:221], v[170:173], v[28:31]
	v_mfma_f32_16x16x32_bf16 v[24:27], v[226:229], v[170:173], v[24:27]
	v_mfma_f32_16x16x32_bf16 v[20:23], v[218:221], v[178:181], v[20:23]
	v_mfma_f32_16x16x32_bf16 v[16:19], v[226:229], v[178:181], v[16:19]
	v_mfma_f32_16x16x32_bf16 v[12:15], v[218:221], v[194:197], v[12:15]
	v_mfma_f32_16x16x32_bf16 v[8:11], v[226:229], v[194:197], v[8:11]
	v_mfma_f32_16x16x32_bf16 v[4:7], v[218:221], v[210:213], v[4:7]
	v_mfma_f32_16x16x32_bf16 v[0:3], v[226:229], v[210:213], v[0:3]
	v_mfma_f32_16x16x32_bf16 v[28:31], v[222:225], v[174:177], v[28:31]
	v_mfma_f32_16x16x32_bf16 v[24:27], v[230:233], v[174:177], v[24:27]
	v_mfma_f32_16x16x32_bf16 v[20:23], v[222:225], v[182:185], v[20:23]
	v_mfma_f32_16x16x32_bf16 v[16:19], v[230:233], v[182:185], v[16:19]
	v_mfma_f32_16x16x32_bf16 v[12:15], v[222:225], v[206:209], v[12:15]
	v_mfma_f32_16x16x32_bf16 v[8:11], v[230:233], v[206:209], v[8:11]
	v_mfma_f32_16x16x32_bf16 v[4:7], v[222:225], v[214:217], v[4:7]
	v_mfma_f32_16x16x32_bf16 v[0:3], v[230:233], v[214:217], v[0:3]
	s_barrier
	.p2align	6
.LBB0_315:
	s_add_u32 s6, s4, s48
	s_addc_u32 s19, s5, s49
	s_add_u32 s6, s6, 0x100
	s_addc_u32 s19, s19, 0
	s_add_u32 s23, s11, s48
	s_addc_u32 s50, s12, s49
	s_add_i32 s80, 0, 0x10000
	v_add_u32_e32 v157, s80, v154
	ds_read_b128 v[146:149], v157
	ds_read_b128 v[158:161], v157 offset:1024
	ds_read_b128 v[162:165], v157 offset:2048
	ds_read_b128 v[166:169], v157 offset:3072
	s_cmpk_eq_i32 s48, 0x700
	s_cselect_b32 s53, s29, s19
	s_cselect_b32 s52, s31, s6
	s_cselect_b32 s51, s35, s50
	s_cselect_b32 s50, s74, s23
	v_lshl_add_u64 v[218:219], v[150:151], 0, s[48:49]
	s_add_i32 m0, s58, 0xc000
	ds_read_b128 v[170:173], v156
	ds_read_b128 v[174:177], v156 offset:1024
	ds_read_b128 v[178:181], v156 offset:2048
	ds_read_b128 v[182:185], v156 offset:3072
	ds_read_b128 v[194:197], v156 offset:4096
	ds_read_b128 v[206:209], v156 offset:5120
	ds_read_b128 v[210:213], v156 offset:6144
	ds_read_b128 v[214:217], v156 offset:7168
	global_load_lds_dwordx4 v[218:219], off
	v_lshl_add_u64 v[218:219], v[152:153], 0, s[48:49]
	s_add_i32 m0, s58, 0xe000
	s_nop 0
	global_load_lds_dwordx4 v[218:219], off
	s_add_i32 s6, 0, 0x14000
	v_add_u32_e32 v157, s6, v154
	ds_read_b128 v[218:221], v157
	ds_read_b128 v[222:225], v157 offset:1024
	ds_read_b128 v[226:229], v157 offset:2048
	ds_read_b128 v[230:233], v157 offset:3072
	s_waitcnt vmcnt(8)
	s_waitcnt lgkmcnt(0)
	s_barrier
	v_mfma_f32_16x16x32_bf16 v[124:127], v[146:149], v[170:173], v[124:127]
	v_mfma_f32_16x16x32_bf16 v[120:123], v[162:165], v[170:173], v[120:123]
	v_mfma_f32_16x16x32_bf16 v[116:119], v[146:149], v[178:181], v[116:119]
	v_mfma_f32_16x16x32_bf16 v[112:115], v[162:165], v[178:181], v[112:115]
	v_mfma_f32_16x16x32_bf16 v[108:111], v[146:149], v[194:197], v[108:111]
	v_mfma_f32_16x16x32_bf16 v[104:107], v[162:165], v[194:197], v[104:107]
	v_mfma_f32_16x16x32_bf16 v[100:103], v[146:149], v[210:213], v[100:103]
	v_mfma_f32_16x16x32_bf16 v[96:99], v[162:165], v[210:213], v[96:99]
	v_mfma_f32_16x16x32_bf16 v[124:127], v[158:161], v[174:177], v[124:127]
	v_mfma_f32_16x16x32_bf16 v[120:123], v[166:169], v[174:177], v[120:123]
	v_mfma_f32_16x16x32_bf16 v[116:119], v[158:161], v[182:185], v[116:119]
	v_mfma_f32_16x16x32_bf16 v[112:115], v[166:169], v[182:185], v[112:115]
	v_mfma_f32_16x16x32_bf16 v[108:111], v[158:161], v[206:209], v[108:111]
	v_mfma_f32_16x16x32_bf16 v[104:107], v[166:169], v[206:209], v[104:107]
	v_mfma_f32_16x16x32_bf16 v[100:103], v[158:161], v[214:217], v[100:103]
	v_mfma_f32_16x16x32_bf16 v[96:99], v[166:169], v[214:217], v[96:99]
	v_mfma_f32_16x16x32_bf16 v[92:95], v[218:221], v[170:173], v[92:95]
	v_mfma_f32_16x16x32_bf16 v[88:91], v[226:229], v[170:173], v[88:91]
	v_mfma_f32_16x16x32_bf16 v[84:87], v[218:221], v[178:181], v[84:87]
	v_mfma_f32_16x16x32_bf16 v[80:83], v[226:229], v[178:181], v[80:83]
	v_mfma_f32_16x16x32_bf16 v[76:79], v[218:221], v[194:197], v[76:79]
	v_mfma_f32_16x16x32_bf16 v[72:75], v[226:229], v[194:197], v[72:75]
	v_mfma_f32_16x16x32_bf16 v[68:71], v[218:221], v[210:213], v[68:71]
	v_mfma_f32_16x16x32_bf16 v[64:67], v[226:229], v[210:213], v[64:67]
	v_mfma_f32_16x16x32_bf16 v[92:95], v[222:225], v[174:177], v[92:95]
	v_mfma_f32_16x16x32_bf16 v[88:91], v[230:233], v[174:177], v[88:91]
	v_mfma_f32_16x16x32_bf16 v[84:87], v[222:225], v[182:185], v[84:87]
	v_mfma_f32_16x16x32_bf16 v[80:83], v[230:233], v[182:185], v[80:83]
	v_mfma_f32_16x16x32_bf16 v[76:79], v[222:225], v[206:209], v[76:79]
	v_mfma_f32_16x16x32_bf16 v[72:75], v[230:233], v[206:209], v[72:75]
	v_mfma_f32_16x16x32_bf16 v[68:71], v[222:225], v[214:217], v[68:71]
	v_mfma_f32_16x16x32_bf16 v[64:67], v[230:233], v[214:217], v[64:67]
	s_barrier
	s_add_i32 s19, s80, s57
	v_lshl_add_u64 v[234:235], s[50:51], 0, v[140:141]
	s_mov_b32 m0, s19
	s_nop 0
	global_load_lds_dwordx4 v[234:235], off
	v_lshl_add_u64 v[236:237], s[50:51], 0, v[132:133]
	s_add_i32 m0, s19, 0x2000
	s_nop 0
	global_load_lds_dwordx4 v[236:237], off
	s_mov_b32 m0, s58
	v_lshl_add_u64 v[238:239], s[52:53], 0, v[128:129]
	ds_read_b128 v[170:173], v156 offset:16384
	ds_read_b128 v[174:177], v156 offset:17408
	ds_read_b128 v[178:181], v156 offset:18432
	ds_read_b128 v[182:185], v156 offset:19456
	ds_read_b128 v[194:197], v156 offset:20480
	ds_read_b128 v[206:209], v156 offset:21504
	ds_read_b128 v[210:213], v156 offset:22528
	ds_read_b128 v[214:217], v156 offset:23552
	global_load_lds_dwordx4 v[238:239], off
	v_lshl_add_u64 v[240:241], s[52:53], 0, v[130:131]
	s_mov_b32 m0, s59
	s_nop 0
	global_load_lds_dwordx4 v[240:241], off
	s_add_u32 s80, s50, 0x40000
	s_addc_u32 s81, s51, 0
	s_add_i32 s6, s6, s57
	v_lshl_add_u64 v[250:251], s[80:81], 0, v[140:141]
	s_mov_b32 m0, s6
	s_nop 0
	global_load_lds_dwordx4 v[250:251], off
	v_lshl_add_u64 v[250:251], s[80:81], 0, v[132:133]
	s_add_i32 m0, s6, 0x2000
	s_nop 0
	global_load_lds_dwordx4 v[250:251], off
	s_waitcnt vmcnt(8)
	s_waitcnt lgkmcnt(0)
	s_barrier
	v_mfma_f32_16x16x32_bf16 v[60:63], v[146:149], v[170:173], v[60:63]
	v_mfma_f32_16x16x32_bf16 v[56:59], v[162:165], v[170:173], v[56:59]
	v_mfma_f32_16x16x32_bf16 v[52:55], v[146:149], v[178:181], v[52:55]
	v_mfma_f32_16x16x32_bf16 v[48:51], v[162:165], v[178:181], v[48:51]
	v_mfma_f32_16x16x32_bf16 v[44:47], v[146:149], v[194:197], v[44:47]
	v_mfma_f32_16x16x32_bf16 v[40:43], v[162:165], v[194:197], v[40:43]
	v_mfma_f32_16x16x32_bf16 v[36:39], v[146:149], v[210:213], v[36:39]
	v_mfma_f32_16x16x32_bf16 v[32:35], v[162:165], v[210:213], v[32:35]
	v_mfma_f32_16x16x32_bf16 v[60:63], v[158:161], v[174:177], v[60:63]
	v_mfma_f32_16x16x32_bf16 v[56:59], v[166:169], v[174:177], v[56:59]
	v_mfma_f32_16x16x32_bf16 v[52:55], v[158:161], v[182:185], v[52:55]
	v_mfma_f32_16x16x32_bf16 v[48:51], v[166:169], v[182:185], v[48:51]
	v_mfma_f32_16x16x32_bf16 v[44:47], v[158:161], v[206:209], v[44:47]
	v_mfma_f32_16x16x32_bf16 v[40:43], v[166:169], v[206:209], v[40:43]
	v_mfma_f32_16x16x32_bf16 v[36:39], v[158:161], v[214:217], v[36:39]
	v_mfma_f32_16x16x32_bf16 v[32:35], v[166:169], v[214:217], v[32:35]
	v_mfma_f32_16x16x32_bf16 v[28:31], v[218:221], v[170:173], v[28:31]
	v_mfma_f32_16x16x32_bf16 v[24:27], v[226:229], v[170:173], v[24:27]
	v_mfma_f32_16x16x32_bf16 v[20:23], v[218:221], v[178:181], v[20:23]
	v_mfma_f32_16x16x32_bf16 v[16:19], v[226:229], v[178:181], v[16:19]
	v_mfma_f32_16x16x32_bf16 v[12:15], v[218:221], v[194:197], v[12:15]
	v_mfma_f32_16x16x32_bf16 v[8:11], v[226:229], v[194:197], v[8:11]
	v_mfma_f32_16x16x32_bf16 v[4:7], v[218:221], v[210:213], v[4:7]
	v_mfma_f32_16x16x32_bf16 v[0:3], v[226:229], v[210:213], v[0:3]
	v_mfma_f32_16x16x32_bf16 v[28:31], v[222:225], v[174:177], v[28:31]
	v_mfma_f32_16x16x32_bf16 v[24:27], v[230:233], v[174:177], v[24:27]
	v_mfma_f32_16x16x32_bf16 v[20:23], v[222:225], v[182:185], v[20:23]
	v_mfma_f32_16x16x32_bf16 v[16:19], v[230:233], v[182:185], v[16:19]
	v_mfma_f32_16x16x32_bf16 v[12:15], v[222:225], v[206:209], v[12:15]
	v_mfma_f32_16x16x32_bf16 v[8:11], v[230:233], v[206:209], v[8:11]
	v_mfma_f32_16x16x32_bf16 v[4:7], v[222:225], v[214:217], v[4:7]
	v_mfma_f32_16x16x32_bf16 v[0:3], v[230:233], v[214:217], v[0:3]
	s_barrier
	s_add_i32 s6, 0, 0x18000
	v_add_u32_e32 v157, s6, v154
	ds_read_b128 v[146:149], v157
	ds_read_b128 v[158:161], v157 offset:1024
	ds_read_b128 v[162:165], v157 offset:2048
	ds_read_b128 v[166:169], v157 offset:3072
	s_add_u32 s52, s52, 0x40000
	s_addc_u32 s53, s53, 0
	s_mov_b32 m0, s68
	v_lshl_add_u64 v[218:219], s[52:53], 0, v[128:129]
	ds_read_b128 v[170:173], v156 offset:32768
	ds_read_b128 v[174:177], v156 offset:33792
	ds_read_b128 v[178:181], v156 offset:34816
	ds_read_b128 v[182:185], v156 offset:35840
	ds_read_b128 v[194:197], v156 offset:36864
	ds_read_b128 v[206:209], v156 offset:37888
	ds_read_b128 v[210:213], v156 offset:38912
	ds_read_b128 v[214:217], v156 offset:39936
	global_load_lds_dwordx4 v[218:219], off
	v_lshl_add_u64 v[218:219], s[52:53], 0, v[130:131]
	s_mov_b32 m0, s69
	s_nop 0
	global_load_lds_dwordx4 v[218:219], off
	s_add_i32 s19, 0, 0x1c000
	v_add_u32_e32 v157, s19, v154
	ds_read_b128 v[218:221], v157
	ds_read_b128 v[222:225], v157 offset:1024
	ds_read_b128 v[226:229], v157 offset:2048
	ds_read_b128 v[230:233], v157 offset:3072
	s_waitcnt vmcnt(8)
	s_waitcnt lgkmcnt(0)
	s_barrier
	v_mfma_f32_16x16x32_bf16 v[124:127], v[146:149], v[170:173], v[124:127]
	v_mfma_f32_16x16x32_bf16 v[120:123], v[162:165], v[170:173], v[120:123]
	v_mfma_f32_16x16x32_bf16 v[116:119], v[146:149], v[178:181], v[116:119]
	v_mfma_f32_16x16x32_bf16 v[112:115], v[162:165], v[178:181], v[112:115]
	v_mfma_f32_16x16x32_bf16 v[108:111], v[146:149], v[194:197], v[108:111]
	v_mfma_f32_16x16x32_bf16 v[104:107], v[162:165], v[194:197], v[104:107]
	v_mfma_f32_16x16x32_bf16 v[100:103], v[146:149], v[210:213], v[100:103]
	v_mfma_f32_16x16x32_bf16 v[96:99], v[162:165], v[210:213], v[96:99]
	v_mfma_f32_16x16x32_bf16 v[124:127], v[158:161], v[174:177], v[124:127]
	v_mfma_f32_16x16x32_bf16 v[120:123], v[166:169], v[174:177], v[120:123]
	v_mfma_f32_16x16x32_bf16 v[116:119], v[158:161], v[182:185], v[116:119]
	v_mfma_f32_16x16x32_bf16 v[112:115], v[166:169], v[182:185], v[112:115]
	v_mfma_f32_16x16x32_bf16 v[108:111], v[158:161], v[206:209], v[108:111]
	v_mfma_f32_16x16x32_bf16 v[104:107], v[166:169], v[206:209], v[104:107]
	v_mfma_f32_16x16x32_bf16 v[100:103], v[158:161], v[214:217], v[100:103]
	v_mfma_f32_16x16x32_bf16 v[96:99], v[166:169], v[214:217], v[96:99]
	v_mfma_f32_16x16x32_bf16 v[92:95], v[218:221], v[170:173], v[92:95]
	v_mfma_f32_16x16x32_bf16 v[88:91], v[226:229], v[170:173], v[88:91]
	v_mfma_f32_16x16x32_bf16 v[84:87], v[218:221], v[178:181], v[84:87]
	v_mfma_f32_16x16x32_bf16 v[80:83], v[226:229], v[178:181], v[80:83]
	v_mfma_f32_16x16x32_bf16 v[76:79], v[218:221], v[194:197], v[76:79]
	v_mfma_f32_16x16x32_bf16 v[72:75], v[226:229], v[194:197], v[72:75]
	v_mfma_f32_16x16x32_bf16 v[68:71], v[218:221], v[210:213], v[68:71]
	v_mfma_f32_16x16x32_bf16 v[64:67], v[226:229], v[210:213], v[64:67]
	v_mfma_f32_16x16x32_bf16 v[92:95], v[222:225], v[174:177], v[92:95]
	v_mfma_f32_16x16x32_bf16 v[88:91], v[230:233], v[174:177], v[88:91]
	v_mfma_f32_16x16x32_bf16 v[84:87], v[222:225], v[182:185], v[84:87]
	v_mfma_f32_16x16x32_bf16 v[80:83], v[230:233], v[182:185], v[80:83]
	v_mfma_f32_16x16x32_bf16 v[76:79], v[222:225], v[206:209], v[76:79]
	v_mfma_f32_16x16x32_bf16 v[72:75], v[230:233], v[206:209], v[72:75]
	v_mfma_f32_16x16x32_bf16 v[68:71], v[222:225], v[214:217], v[68:71]
	v_mfma_f32_16x16x32_bf16 v[64:67], v[230:233], v[214:217], v[64:67]
	s_barrier
	s_add_i32 s6, s6, s57
	v_lshl_add_u64 v[234:235], v[234:235], 0, s[36:37]
	s_mov_b32 m0, s6
	s_nop 0
	global_load_lds_dwordx4 v[234:235], off
	v_lshl_add_u64 v[234:235], v[236:237], 0, s[36:37]
	s_add_i32 m0, s6, 0x2000
	s_nop 0
	global_load_lds_dwordx4 v[234:235], off
	s_mov_b32 m0, s71
	v_lshl_add_u64 v[234:235], v[238:239], 0, s[36:37]
	ds_read_b128 v[170:173], v156 offset:49152
	ds_read_b128 v[174:177], v156 offset:50176
	ds_read_b128 v[178:181], v156 offset:51200
	ds_read_b128 v[182:185], v156 offset:52224
	ds_read_b128 v[194:197], v156 offset:53248
	ds_read_b128 v[206:209], v156 offset:54272
	ds_read_b128 v[210:213], v156 offset:55296
	ds_read_b128 v[214:217], v156 offset:56320
	global_load_lds_dwordx4 v[234:235], off
	v_lshl_add_u64 v[234:235], v[240:241], 0, s[36:37]
	s_mov_b32 m0, s72
	s_nop 0
	global_load_lds_dwordx4 v[234:235], off
	s_add_u32 s50, s50, 0x40080
	s_addc_u32 s51, s51, 0
	s_add_i32 s6, s19, s57
	v_lshl_add_u64 v[250:251], s[50:51], 0, v[140:141]
	s_mov_b32 m0, s6
	s_nop 0
	global_load_lds_dwordx4 v[250:251], off
	v_lshl_add_u64 v[250:251], s[50:51], 0, v[132:133]
	s_add_i32 m0, s6, 0x2000
	s_nop 0
	global_load_lds_dwordx4 v[250:251], off
	s_add_i32 s75, s75, 2
	s_add_u32 s48, s48, 0x100
	s_addc_u32 s49, s49, 0
	s_cmp_gt_u32 s75, 13
	s_nop 0
	s_waitcnt vmcnt(8)
	s_waitcnt lgkmcnt(0)
	s_barrier
	v_mfma_f32_16x16x32_bf16 v[60:63], v[146:149], v[170:173], v[60:63]
	v_mfma_f32_16x16x32_bf16 v[56:59], v[162:165], v[170:173], v[56:59]
	v_mfma_f32_16x16x32_bf16 v[52:55], v[146:149], v[178:181], v[52:55]
	v_mfma_f32_16x16x32_bf16 v[48:51], v[162:165], v[178:181], v[48:51]
	v_mfma_f32_16x16x32_bf16 v[44:47], v[146:149], v[194:197], v[44:47]
	v_mfma_f32_16x16x32_bf16 v[40:43], v[162:165], v[194:197], v[40:43]
	v_mfma_f32_16x16x32_bf16 v[36:39], v[146:149], v[210:213], v[36:39]
	v_mfma_f32_16x16x32_bf16 v[32:35], v[162:165], v[210:213], v[32:35]
	v_mfma_f32_16x16x32_bf16 v[60:63], v[158:161], v[174:177], v[60:63]
	v_mfma_f32_16x16x32_bf16 v[56:59], v[166:169], v[174:177], v[56:59]
	v_mfma_f32_16x16x32_bf16 v[52:55], v[158:161], v[182:185], v[52:55]
	v_mfma_f32_16x16x32_bf16 v[48:51], v[166:169], v[182:185], v[48:51]
	v_mfma_f32_16x16x32_bf16 v[44:47], v[158:161], v[206:209], v[44:47]
	v_mfma_f32_16x16x32_bf16 v[40:43], v[166:169], v[206:209], v[40:43]
	v_mfma_f32_16x16x32_bf16 v[36:39], v[158:161], v[214:217], v[36:39]
	v_mfma_f32_16x16x32_bf16 v[32:35], v[166:169], v[214:217], v[32:35]
	v_mfma_f32_16x16x32_bf16 v[28:31], v[218:221], v[170:173], v[28:31]
	v_mfma_f32_16x16x32_bf16 v[24:27], v[226:229], v[170:173], v[24:27]
	v_mfma_f32_16x16x32_bf16 v[20:23], v[218:221], v[178:181], v[20:23]
	v_mfma_f32_16x16x32_bf16 v[16:19], v[226:229], v[178:181], v[16:19]
	v_mfma_f32_16x16x32_bf16 v[12:15], v[218:221], v[194:197], v[12:15]
	v_mfma_f32_16x16x32_bf16 v[8:11], v[226:229], v[194:197], v[8:11]
	v_mfma_f32_16x16x32_bf16 v[4:7], v[218:221], v[210:213], v[4:7]
	v_mfma_f32_16x16x32_bf16 v[0:3], v[226:229], v[210:213], v[0:3]
	v_mfma_f32_16x16x32_bf16 v[28:31], v[222:225], v[174:177], v[28:31]
	v_mfma_f32_16x16x32_bf16 v[24:27], v[230:233], v[174:177], v[24:27]
	v_mfma_f32_16x16x32_bf16 v[20:23], v[222:225], v[182:185], v[20:23]
	v_mfma_f32_16x16x32_bf16 v[16:19], v[230:233], v[182:185], v[16:19]
	v_mfma_f32_16x16x32_bf16 v[12:15], v[222:225], v[206:209], v[12:15]
	v_mfma_f32_16x16x32_bf16 v[8:11], v[230:233], v[206:209], v[8:11]
	v_mfma_f32_16x16x32_bf16 v[4:7], v[222:225], v[214:217], v[4:7]
	v_mfma_f32_16x16x32_bf16 v[0:3], v[230:233], v[214:217], v[0:3]
	s_barrier
	s_cbranch_scc0 .LBB0_315
	s_mov_b32 s100, 1
	s_add_u32 s48, s11, 0xffffff00
	v_lshl_or_b32 v146, s70, 8, v155
	s_addc_u32 s49, s12, -1
	s_ashr_i32 s29, s28, 31
	v_ashrrev_i32_e32 v147, 31, v146
	v_lshl_add_u64 v[146:147], v[146:147], 1, s[26:27]
	s_lshl_b64 s[50:51], s[28:29], 20
	v_lshl_add_u64 v[146:147], v[146:147], 0, s[50:51]
	v_lshl_add_u64 v[150:151], v[146:147], 0, v[134:135]
	v_cvt_pk_bf16_f32 v146, v124, v125
	v_cvt_pk_bf16_f32 v147, v126, v127
	v_cvt_pk_bf16_f32 v148, v120, v121
	v_cvt_pk_bf16_f32 v149, v122, v123
	global_store_dwordx4 v[150:151], v[146:149], off
	v_add_co_u32_e32 v152, vcc, s66, v150
	s_nop 0
	v_cvt_pk_bf16_f32 v146, v92, v93
	v_cvt_pk_bf16_f32 v147, v94, v95
	v_cvt_pk_bf16_f32 v148, v88, v89
	v_cvt_pk_bf16_f32 v149, v90, v91
	global_store_dwordx4 v[150:151], v[146:149], off offset:256
	v_addc_co_u32_e32 v153, vcc, 0, v151, vcc
	s_nop 0
	v_cvt_pk_bf16_f32 v146, v116, v117
	v_cvt_pk_bf16_f32 v147, v118, v119
	v_cvt_pk_bf16_f32 v148, v112, v113
	v_cvt_pk_bf16_f32 v149, v114, v115
	global_store_dwordx4 v[152:153], v[146:149], off
	s_mov_b32 s6, 0x20000
	s_nop 0
	v_cvt_pk_bf16_f32 v146, v84, v85
	v_cvt_pk_bf16_f32 v147, v86, v87
	v_cvt_pk_bf16_f32 v148, v80, v81
	v_cvt_pk_bf16_f32 v149, v82, v83
	global_store_dwordx4 v[152:153], v[146:149], off offset:256
	v_add_co_u32_e32 v152, vcc, s6, v150
	s_nop 0
	v_cvt_pk_bf16_f32 v146, v108, v109
	v_cvt_pk_bf16_f32 v147, v110, v111
	v_cvt_pk_bf16_f32 v148, v104, v105
	v_cvt_pk_bf16_f32 v149, v106, v107
	v_addc_co_u32_e32 v153, vcc, 0, v151, vcc
	global_store_dwordx4 v[152:153], v[146:149], off
	s_mov_b32 s6, 0x30000
	s_nop 0
	v_cvt_pk_bf16_f32 v146, v76, v77
	v_cvt_pk_bf16_f32 v147, v78, v79
	v_cvt_pk_bf16_f32 v148, v72, v73
	v_cvt_pk_bf16_f32 v149, v74, v75
	global_store_dwordx4 v[152:153], v[146:149], off offset:256
	v_add_co_u32_e32 v152, vcc, s6, v150
	s_nop 0
	v_cvt_pk_bf16_f32 v146, v100, v101
	v_cvt_pk_bf16_f32 v147, v102, v103
	v_cvt_pk_bf16_f32 v148, v96, v97
	v_cvt_pk_bf16_f32 v149, v98, v99
	v_addc_co_u32_e32 v153, vcc, 0, v151, vcc
	global_store_dwordx4 v[152:153], v[146:149], off
	s_mov_b32 s6, 0x80000
	s_nop 0
	v_cvt_pk_bf16_f32 v146, v68, v69
	v_cvt_pk_bf16_f32 v147, v70, v71
	v_cvt_pk_bf16_f32 v148, v64, v65
	v_cvt_pk_bf16_f32 v149, v66, v67
	global_store_dwordx4 v[152:153], v[146:149], off offset:256
	v_add_co_u32_e32 v152, vcc, s6, v150
	s_nop 0
	v_cvt_pk_bf16_f32 v146, v60, v61
	v_cvt_pk_bf16_f32 v147, v62, v63
	v_cvt_pk_bf16_f32 v148, v56, v57
	v_cvt_pk_bf16_f32 v149, v58, v59
	v_addc_co_u32_e32 v153, vcc, 0, v151, vcc
	global_store_dwordx4 v[152:153], v[146:149], off
	s_mov_b32 s6, 0x90000
	s_nop 0
	v_cvt_pk_bf16_f32 v146, v28, v29
	v_cvt_pk_bf16_f32 v147, v30, v31
	v_cvt_pk_bf16_f32 v148, v24, v25
	v_cvt_pk_bf16_f32 v149, v26, v27
	global_store_dwordx4 v[152:153], v[146:149], off offset:256
	v_add_co_u32_e32 v152, vcc, s6, v150
	s_nop 0
	v_cvt_pk_bf16_f32 v146, v52, v53
	v_cvt_pk_bf16_f32 v147, v54, v55
	v_cvt_pk_bf16_f32 v148, v48, v49
	v_cvt_pk_bf16_f32 v149, v50, v51
	v_addc_co_u32_e32 v153, vcc, 0, v151, vcc
	global_store_dwordx4 v[152:153], v[146:149], off
	s_mov_b32 s6, 0xa0000
	s_nop 0
	v_cvt_pk_bf16_f32 v146, v20, v21
	v_cvt_pk_bf16_f32 v147, v22, v23
	v_cvt_pk_bf16_f32 v148, v16, v17
	v_cvt_pk_bf16_f32 v149, v18, v19
	global_store_dwordx4 v[152:153], v[146:149], off offset:256
	v_add_co_u32_e32 v152, vcc, s6, v150
	s_nop 0
	v_cvt_pk_bf16_f32 v146, v44, v45
	v_cvt_pk_bf16_f32 v147, v46, v47
	v_cvt_pk_bf16_f32 v148, v40, v41
	v_cvt_pk_bf16_f32 v149, v42, v43
	v_addc_co_u32_e32 v153, vcc, 0, v151, vcc
	s_mov_b32 s6, 0xb0000
	global_store_dwordx4 v[152:153], v[146:149], off
	v_add_co_u32_e32 v150, vcc, s6, v150
	s_nop 0
	v_cvt_pk_bf16_f32 v146, v12, v13
	v_cvt_pk_bf16_f32 v147, v14, v15
	v_cvt_pk_bf16_f32 v148, v8, v9
	v_cvt_pk_bf16_f32 v149, v10, v11
	global_store_dwordx4 v[152:153], v[146:149], off offset:256
	v_addc_co_u32_e32 v151, vcc, 0, v151, vcc
	s_nop 0
	v_cvt_pk_bf16_f32 v146, v36, v37
	v_cvt_pk_bf16_f32 v147, v38, v39
	v_cvt_pk_bf16_f32 v148, v32, v33
	v_cvt_pk_bf16_f32 v149, v34, v35
	global_store_dwordx4 v[150:151], v[146:149], off
	s_andn2_b64 vcc, exec, s[44:45]
	s_nop 0
	v_cvt_pk_bf16_f32 v146, v4, v5
	v_cvt_pk_bf16_f32 v147, v6, v7
	v_cvt_pk_bf16_f32 v148, v0, v1
	v_cvt_pk_bf16_f32 v149, v2, v3
	global_store_dwordx4 v[150:151], v[146:149], off offset:256
	s_cbranch_vccz .LBB0_307
	s_mov_b64 s[42:43], s[48:49]
	s_andn2_b64 vcc, exec, s[38:39]
	s_mov_b64 s[48:49], s[42:43]
	s_cbranch_vccnz .LBB0_308

.LBB0_341:
	s_add_u32 s46, s50, 0x100
	s_addc_u32 s47, s51, 0
	s_add_i32 s6, 0, 0x10000
	v_add_u32_e32 v146, s6, v206
	ds_read_b128 v[128:131], v146
	ds_read_b128 v[132:135], v146 offset:1024
	ds_read_b128 v[136:139], v146 offset:2048
	ds_read_b128 v[146:149], v146 offset:3072
	s_cmp_eq_u32 s12, 40
	s_cselect_b32 s53, s31, s47
	s_cselect_b32 s52, s30, s46
	s_cselect_b32 s49, s35, s11
	s_cselect_b32 s48, s34, s10
	v_lshl_add_u64 v[214:215], s[50:51], 0, v[158:159]
	s_add_i32 m0, s58, 0xc000
	ds_read_b128 v[162:165], v208
	ds_read_b128 v[166:169], v208 offset:1024
	ds_read_b128 v[170:173], v208 offset:2048
	ds_read_b128 v[174:177], v208 offset:3072
	ds_read_b128 v[178:181], v208 offset:4096
	ds_read_b128 v[182:185], v208 offset:5120
	ds_read_b128 v[194:197], v208 offset:6144
	ds_read_b128 v[210:213], v208 offset:7168
	global_load_lds_dwordx4 v[214:215], off
	v_lshl_add_u64 v[214:215], s[50:51], 0, v[160:161]
	s_add_i32 m0, s58, 0xe000
	s_nop 0
	global_load_lds_dwordx4 v[214:215], off
	s_add_i32 s19, 0, 0x14000
	v_add_u32_e32 v192, s19, v206
	ds_read_b128 v[214:217], v192
	ds_read_b128 v[218:221], v192 offset:1024
	ds_read_b128 v[222:225], v192 offset:2048
	ds_read_b128 v[226:229], v192 offset:3072
	s_waitcnt vmcnt(8)
	s_waitcnt lgkmcnt(0)
	s_barrier
	v_mfma_f32_16x16x32_bf16 v[124:127], v[128:131], v[162:165], v[124:127]
	v_mfma_f32_16x16x32_bf16 v[120:123], v[136:139], v[162:165], v[120:123]
	v_mfma_f32_16x16x32_bf16 v[108:111], v[128:131], v[170:173], v[108:111]
	v_mfma_f32_16x16x32_bf16 v[104:107], v[136:139], v[170:173], v[104:107]
	v_mfma_f32_16x16x32_bf16 v[96:99], v[128:131], v[178:181], v[96:99]
	v_mfma_f32_16x16x32_bf16 v[88:91], v[136:139], v[178:181], v[88:91]
	v_mfma_f32_16x16x32_bf16 v[84:87], v[128:131], v[194:197], v[84:87]
	v_mfma_f32_16x16x32_bf16 v[80:83], v[136:139], v[194:197], v[80:83]
	v_mfma_f32_16x16x32_bf16 v[124:127], v[132:135], v[166:169], v[124:127]
	v_mfma_f32_16x16x32_bf16 v[120:123], v[146:149], v[166:169], v[120:123]
	v_mfma_f32_16x16x32_bf16 v[108:111], v[132:135], v[174:177], v[108:111]
	v_mfma_f32_16x16x32_bf16 v[104:107], v[146:149], v[174:177], v[104:107]
	v_mfma_f32_16x16x32_bf16 v[96:99], v[132:135], v[182:185], v[96:99]
	v_mfma_f32_16x16x32_bf16 v[88:91], v[146:149], v[182:185], v[88:91]
	v_mfma_f32_16x16x32_bf16 v[84:87], v[132:135], v[210:213], v[84:87]
	v_mfma_f32_16x16x32_bf16 v[80:83], v[146:149], v[210:213], v[80:83]
	v_mfma_f32_16x16x32_bf16 v[116:119], v[214:217], v[162:165], v[116:119]
	v_mfma_f32_16x16x32_bf16 v[112:115], v[222:225], v[162:165], v[112:115]
	v_mfma_f32_16x16x32_bf16 v[100:103], v[214:217], v[170:173], v[100:103]
	v_mfma_f32_16x16x32_bf16 v[92:95], v[222:225], v[170:173], v[92:95]
	v_mfma_f32_16x16x32_bf16 v[76:79], v[214:217], v[178:181], v[76:79]
	v_mfma_f32_16x16x32_bf16 v[72:75], v[222:225], v[178:181], v[72:75]
	v_mfma_f32_16x16x32_bf16 v[68:71], v[214:217], v[194:197], v[68:71]
	v_mfma_f32_16x16x32_bf16 v[64:67], v[222:225], v[194:197], v[64:67]
	v_mfma_f32_16x16x32_bf16 v[116:119], v[218:221], v[166:169], v[116:119]
	v_mfma_f32_16x16x32_bf16 v[112:115], v[226:229], v[166:169], v[112:115]
	v_mfma_f32_16x16x32_bf16 v[100:103], v[218:221], v[174:177], v[100:103]
	v_mfma_f32_16x16x32_bf16 v[92:95], v[226:229], v[174:177], v[92:95]
	v_mfma_f32_16x16x32_bf16 v[76:79], v[218:221], v[182:185], v[76:79]
	v_mfma_f32_16x16x32_bf16 v[72:75], v[226:229], v[182:185], v[72:75]
	v_mfma_f32_16x16x32_bf16 v[68:71], v[218:221], v[210:213], v[68:71]
	v_mfma_f32_16x16x32_bf16 v[64:67], v[226:229], v[210:213], v[64:67]
	s_barrier
	s_add_i32 s6, s6, s57
	v_lshl_add_u64 v[230:231], s[48:49], 0, v[140:141]
	s_mov_b32 m0, s6
	s_nop 0
	global_load_lds_dwordx4 v[230:231], off
	v_lshl_add_u64 v[232:233], s[48:49], 0, v[150:151]
	s_add_i32 m0, s6, 0x2000
	s_nop 0
	global_load_lds_dwordx4 v[232:233], off
	s_mov_b32 m0, s58
	v_lshl_add_u64 v[234:235], s[52:53], 0, v[154:155]
	ds_read_b128 v[162:165], v208 offset:16384
	ds_read_b128 v[166:169], v208 offset:17408
	ds_read_b128 v[170:173], v208 offset:18432
	ds_read_b128 v[174:177], v208 offset:19456
	ds_read_b128 v[178:181], v208 offset:20480
	ds_read_b128 v[182:185], v208 offset:21504
	ds_read_b128 v[194:197], v208 offset:22528
	ds_read_b128 v[210:213], v208 offset:23552
	global_load_lds_dwordx4 v[234:235], off
	v_lshl_add_u64 v[236:237], s[52:53], 0, v[152:153]
	s_mov_b32 m0, s59
	s_nop 0
	global_load_lds_dwordx4 v[236:237], off
	s_add_u32 s50, s48, 0xb0000
	s_addc_u32 s51, s49, 0
	s_add_i32 s6, s19, s57
	v_lshl_add_u64 v[250:251], s[50:51], 0, v[140:141]
	s_mov_b32 m0, s6
	s_nop 0
	global_load_lds_dwordx4 v[250:251], off
	v_lshl_add_u64 v[250:251], s[50:51], 0, v[150:151]
	s_add_i32 m0, s6, 0x2000
	s_nop 0
	global_load_lds_dwordx4 v[250:251], off
	s_waitcnt vmcnt(8)
	s_waitcnt lgkmcnt(0)
	s_barrier
	v_mfma_f32_16x16x32_bf16 v[60:63], v[128:131], v[162:165], v[60:63]
	v_mfma_f32_16x16x32_bf16 v[56:59], v[136:139], v[162:165], v[56:59]
	v_mfma_f32_16x16x32_bf16 v[48:51], v[128:131], v[170:173], v[48:51]
	v_mfma_f32_16x16x32_bf16 v[40:43], v[136:139], v[170:173], v[40:43]
	v_mfma_f32_16x16x32_bf16 v[32:35], v[128:131], v[178:181], v[32:35]
	v_mfma_f32_16x16x32_bf16 v[24:27], v[136:139], v[178:181], v[24:27]
	v_mfma_f32_16x16x32_bf16 v[16:19], v[128:131], v[194:197], v[16:19]
	v_mfma_f32_16x16x32_bf16 v[8:11], v[136:139], v[194:197], v[8:11]
	v_mfma_f32_16x16x32_bf16 v[60:63], v[132:135], v[166:169], v[60:63]
	v_mfma_f32_16x16x32_bf16 v[56:59], v[146:149], v[166:169], v[56:59]
	v_mfma_f32_16x16x32_bf16 v[48:51], v[132:135], v[174:177], v[48:51]
	v_mfma_f32_16x16x32_bf16 v[40:43], v[146:149], v[174:177], v[40:43]
	v_mfma_f32_16x16x32_bf16 v[32:35], v[132:135], v[182:185], v[32:35]
	v_mfma_f32_16x16x32_bf16 v[24:27], v[146:149], v[182:185], v[24:27]
	v_mfma_f32_16x16x32_bf16 v[16:19], v[132:135], v[210:213], v[16:19]
	v_mfma_f32_16x16x32_bf16 v[8:11], v[146:149], v[210:213], v[8:11]
	v_mfma_f32_16x16x32_bf16 v[52:55], v[214:217], v[162:165], v[52:55]
	v_mfma_f32_16x16x32_bf16 v[44:47], v[222:225], v[162:165], v[44:47]
	v_mfma_f32_16x16x32_bf16 v[36:39], v[214:217], v[170:173], v[36:39]
	v_mfma_f32_16x16x32_bf16 v[28:31], v[222:225], v[170:173], v[28:31]
	v_mfma_f32_16x16x32_bf16 v[20:23], v[214:217], v[178:181], v[20:23]
	v_mfma_f32_16x16x32_bf16 v[12:15], v[222:225], v[178:181], v[12:15]
	v_mfma_f32_16x16x32_bf16 v[4:7], v[214:217], v[194:197], v[4:7]
	v_mfma_f32_16x16x32_bf16 v[0:3], v[222:225], v[194:197], v[0:3]
	v_mfma_f32_16x16x32_bf16 v[52:55], v[218:221], v[166:169], v[52:55]
	v_mfma_f32_16x16x32_bf16 v[44:47], v[226:229], v[166:169], v[44:47]
	v_mfma_f32_16x16x32_bf16 v[36:39], v[218:221], v[174:177], v[36:39]
	v_mfma_f32_16x16x32_bf16 v[28:31], v[226:229], v[174:177], v[28:31]
	v_mfma_f32_16x16x32_bf16 v[20:23], v[218:221], v[182:185], v[20:23]
	v_mfma_f32_16x16x32_bf16 v[12:15], v[226:229], v[182:185], v[12:15]
	v_mfma_f32_16x16x32_bf16 v[4:7], v[218:221], v[210:213], v[4:7]
	v_mfma_f32_16x16x32_bf16 v[0:3], v[226:229], v[210:213], v[0:3]
	s_barrier
	s_add_i32 s6, 0, 0x18000
	v_add_u32_e32 v146, s6, v206
	ds_read_b128 v[128:131], v146
	ds_read_b128 v[132:135], v146 offset:1024
	ds_read_b128 v[136:139], v146 offset:2048
	ds_read_b128 v[146:149], v146 offset:3072
	s_add_u32 s50, s52, 0xb0000
	s_addc_u32 s51, s53, 0
	s_mov_b32 m0, s68
	v_lshl_add_u64 v[214:215], s[50:51], 0, v[154:155]
	ds_read_b128 v[162:165], v208 offset:32768
	ds_read_b128 v[166:169], v208 offset:33792
	ds_read_b128 v[170:173], v208 offset:34816
	ds_read_b128 v[174:177], v208 offset:35840
	ds_read_b128 v[178:181], v208 offset:36864
	ds_read_b128 v[182:185], v208 offset:37888
	ds_read_b128 v[194:197], v208 offset:38912
	ds_read_b128 v[210:213], v208 offset:39936
	global_load_lds_dwordx4 v[214:215], off
	v_lshl_add_u64 v[214:215], s[50:51], 0, v[152:153]
	s_mov_b32 m0, s69
	s_nop 0
	global_load_lds_dwordx4 v[214:215], off
	s_add_i32 s19, 0, 0x1c000
	v_add_u32_e32 v192, s19, v206
	ds_read_b128 v[214:217], v192
	ds_read_b128 v[218:221], v192 offset:1024
	ds_read_b128 v[222:225], v192 offset:2048
	ds_read_b128 v[226:229], v192 offset:3072
	s_waitcnt vmcnt(8)
	s_waitcnt lgkmcnt(0)
	s_barrier
	v_mfma_f32_16x16x32_bf16 v[124:127], v[128:131], v[162:165], v[124:127]
	v_mfma_f32_16x16x32_bf16 v[120:123], v[136:139], v[162:165], v[120:123]
	v_mfma_f32_16x16x32_bf16 v[108:111], v[128:131], v[170:173], v[108:111]
	v_mfma_f32_16x16x32_bf16 v[104:107], v[136:139], v[170:173], v[104:107]
	v_mfma_f32_16x16x32_bf16 v[96:99], v[128:131], v[178:181], v[96:99]
	v_mfma_f32_16x16x32_bf16 v[88:91], v[136:139], v[178:181], v[88:91]
	v_mfma_f32_16x16x32_bf16 v[84:87], v[128:131], v[194:197], v[84:87]
	v_mfma_f32_16x16x32_bf16 v[80:83], v[136:139], v[194:197], v[80:83]
	v_mfma_f32_16x16x32_bf16 v[124:127], v[132:135], v[166:169], v[124:127]
	v_mfma_f32_16x16x32_bf16 v[120:123], v[146:149], v[166:169], v[120:123]
	v_mfma_f32_16x16x32_bf16 v[108:111], v[132:135], v[174:177], v[108:111]
	v_mfma_f32_16x16x32_bf16 v[104:107], v[146:149], v[174:177], v[104:107]
	v_mfma_f32_16x16x32_bf16 v[96:99], v[132:135], v[182:185], v[96:99]
	v_mfma_f32_16x16x32_bf16 v[88:91], v[146:149], v[182:185], v[88:91]
	v_mfma_f32_16x16x32_bf16 v[84:87], v[132:135], v[210:213], v[84:87]
	v_mfma_f32_16x16x32_bf16 v[80:83], v[146:149], v[210:213], v[80:83]
	v_mfma_f32_16x16x32_bf16 v[116:119], v[214:217], v[162:165], v[116:119]
	v_mfma_f32_16x16x32_bf16 v[112:115], v[222:225], v[162:165], v[112:115]
	v_mfma_f32_16x16x32_bf16 v[100:103], v[214:217], v[170:173], v[100:103]
	v_mfma_f32_16x16x32_bf16 v[92:95], v[222:225], v[170:173], v[92:95]
	v_mfma_f32_16x16x32_bf16 v[76:79], v[214:217], v[178:181], v[76:79]
	v_mfma_f32_16x16x32_bf16 v[72:75], v[222:225], v[178:181], v[72:75]
	v_mfma_f32_16x16x32_bf16 v[68:71], v[214:217], v[194:197], v[68:71]
	v_mfma_f32_16x16x32_bf16 v[64:67], v[222:225], v[194:197], v[64:67]
	v_mfma_f32_16x16x32_bf16 v[116:119], v[218:221], v[166:169], v[116:119]
	v_mfma_f32_16x16x32_bf16 v[112:115], v[226:229], v[166:169], v[112:115]
	v_mfma_f32_16x16x32_bf16 v[100:103], v[218:221], v[174:177], v[100:103]
	v_mfma_f32_16x16x32_bf16 v[92:95], v[226:229], v[174:177], v[92:95]
	v_mfma_f32_16x16x32_bf16 v[76:79], v[218:221], v[182:185], v[76:79]
	v_mfma_f32_16x16x32_bf16 v[72:75], v[226:229], v[182:185], v[72:75]
	v_mfma_f32_16x16x32_bf16 v[68:71], v[218:221], v[210:213], v[68:71]
	v_mfma_f32_16x16x32_bf16 v[64:67], v[226:229], v[210:213], v[64:67]
	s_barrier
	s_add_i32 s6, s6, s57
	v_lshl_add_u64 v[230:231], v[230:231], 0, s[36:37]
	s_mov_b32 m0, s6
	s_nop 0
	global_load_lds_dwordx4 v[230:231], off
	v_lshl_add_u64 v[230:231], v[232:233], 0, s[36:37]
	s_add_i32 m0, s6, 0x2000
	s_nop 0
	global_load_lds_dwordx4 v[230:231], off
	s_mov_b32 m0, s70
	v_lshl_add_u64 v[230:231], v[234:235], 0, s[36:37]
	ds_read_b128 v[162:165], v208 offset:49152
	ds_read_b128 v[166:169], v208 offset:50176
	ds_read_b128 v[170:173], v208 offset:51200
	ds_read_b128 v[174:177], v208 offset:52224
	ds_read_b128 v[178:181], v208 offset:53248
	ds_read_b128 v[182:185], v208 offset:54272
	ds_read_b128 v[194:197], v208 offset:55296
	ds_read_b128 v[210:213], v208 offset:56320
	global_load_lds_dwordx4 v[230:231], off
	v_lshl_add_u64 v[230:231], v[236:237], 0, s[36:37]
	s_mov_b32 m0, s71
	s_nop 0
	global_load_lds_dwordx4 v[230:231], off
	s_add_u32 s48, s48, 0xb0080
	s_addc_u32 s49, s49, 0
	s_add_i32 s6, s19, s57
	v_lshl_add_u64 v[250:251], s[48:49], 0, v[140:141]
	s_mov_b32 m0, s6
	s_nop 0
	global_load_lds_dwordx4 v[250:251], off
	v_lshl_add_u64 v[250:251], s[48:49], 0, v[150:151]
	s_add_i32 m0, s6, 0x2000
	s_nop 0
	global_load_lds_dwordx4 v[250:251], off
	s_add_i32 s12, s12, 2
	s_add_u32 s10, s10, 0x100
	s_addc_u32 s11, s11, 0
	s_cmp_gt_u32 s12, 41
	s_mov_b64 s[50:51], s[46:47]
	s_waitcnt vmcnt(8)
	s_waitcnt lgkmcnt(0)
	s_barrier
	v_mfma_f32_16x16x32_bf16 v[60:63], v[128:131], v[162:165], v[60:63]
	v_mfma_f32_16x16x32_bf16 v[56:59], v[136:139], v[162:165], v[56:59]
	v_mfma_f32_16x16x32_bf16 v[48:51], v[128:131], v[170:173], v[48:51]
	v_mfma_f32_16x16x32_bf16 v[40:43], v[136:139], v[170:173], v[40:43]
	v_mfma_f32_16x16x32_bf16 v[32:35], v[128:131], v[178:181], v[32:35]
	v_mfma_f32_16x16x32_bf16 v[24:27], v[136:139], v[178:181], v[24:27]
	v_mfma_f32_16x16x32_bf16 v[16:19], v[128:131], v[194:197], v[16:19]
	v_mfma_f32_16x16x32_bf16 v[8:11], v[136:139], v[194:197], v[8:11]
	v_mfma_f32_16x16x32_bf16 v[60:63], v[132:135], v[166:169], v[60:63]
	v_mfma_f32_16x16x32_bf16 v[56:59], v[146:149], v[166:169], v[56:59]
	v_mfma_f32_16x16x32_bf16 v[48:51], v[132:135], v[174:177], v[48:51]
	v_mfma_f32_16x16x32_bf16 v[40:43], v[146:149], v[174:177], v[40:43]
	v_mfma_f32_16x16x32_bf16 v[32:35], v[132:135], v[182:185], v[32:35]
	v_mfma_f32_16x16x32_bf16 v[24:27], v[146:149], v[182:185], v[24:27]
	v_mfma_f32_16x16x32_bf16 v[16:19], v[132:135], v[210:213], v[16:19]
	v_mfma_f32_16x16x32_bf16 v[8:11], v[146:149], v[210:213], v[8:11]
	v_mfma_f32_16x16x32_bf16 v[52:55], v[214:217], v[162:165], v[52:55]
	v_mfma_f32_16x16x32_bf16 v[44:47], v[222:225], v[162:165], v[44:47]
	v_mfma_f32_16x16x32_bf16 v[36:39], v[214:217], v[170:173], v[36:39]
	v_mfma_f32_16x16x32_bf16 v[28:31], v[222:225], v[170:173], v[28:31]
	v_mfma_f32_16x16x32_bf16 v[20:23], v[214:217], v[178:181], v[20:23]
	v_mfma_f32_16x16x32_bf16 v[12:15], v[222:225], v[178:181], v[12:15]
	v_mfma_f32_16x16x32_bf16 v[4:7], v[214:217], v[194:197], v[4:7]
	v_mfma_f32_16x16x32_bf16 v[0:3], v[222:225], v[194:197], v[0:3]
	v_mfma_f32_16x16x32_bf16 v[52:55], v[218:221], v[166:169], v[52:55]
	v_mfma_f32_16x16x32_bf16 v[44:47], v[226:229], v[166:169], v[44:47]
	v_mfma_f32_16x16x32_bf16 v[36:39], v[218:221], v[174:177], v[36:39]
	v_mfma_f32_16x16x32_bf16 v[28:31], v[226:229], v[174:177], v[28:31]
	v_mfma_f32_16x16x32_bf16 v[20:23], v[218:221], v[182:185], v[20:23]
	v_mfma_f32_16x16x32_bf16 v[12:15], v[226:229], v[182:185], v[12:15]
	v_mfma_f32_16x16x32_bf16 v[4:7], v[218:221], v[210:213], v[4:7]
	v_mfma_f32_16x16x32_bf16 v[0:3], v[226:229], v[210:213], v[0:3]
	s_barrier
	s_cbranch_scc0 .LBB0_341
	s_mov_b32 s100, 1
	s_ashr_i32 s39, s38, 31
	v_lshl_or_b32 v128, s81, 8, v207
	s_lshl_b64 s[10:11], s[38:39], 8
	v_ashrrev_i32_e32 v129, 31, v128
	v_lshl_add_u64 v[168:169], s[10:11], 0, v[156:157]
	v_lshlrev_b64 v[170:171], 1, v[128:129]
	v_lshl_add_u64 v[174:175], s[26:27], 0, v[170:171]
	v_lshlrev_b64 v[172:173], 11, v[168:169]
	v_lshl_add_u64 v[128:129], v[174:175], 0, v[172:173]
	global_load_dwordx4 v[182:185], v[128:129], off
	global_load_dwordx4 v[210:213], v[128:129], off offset:256
	v_or_b32_e32 v166, 16, v168
	v_mov_b32_e32 v167, v169
	v_lshlrev_b64 v[176:177], 11, v[166:167]
	v_lshl_add_u64 v[128:129], v[174:175], 0, v[176:177]
	global_load_dwordx4 v[214:217], v[128:129], off
	global_load_dwordx4 v[218:221], v[128:129], off offset:256
	v_or_b32_e32 v164, 32, v168
	v_mov_b32_e32 v165, v169
	v_or_b32_e32 v162, 48, v168
	v_mov_b32_e32 v163, v169
	v_lshlrev_b64 v[180:181], 11, v[164:165]
	v_lshlrev_b64 v[178:179], 11, v[162:163]
	v_lshl_add_u64 v[128:129], v[174:175], 0, v[180:181]
	v_lshl_add_u64 v[130:131], v[174:175], 0, v[178:179]
	global_load_dwordx4 v[222:225], v[128:129], off
	global_load_dwordx4 v[136:139], v[128:129], off offset:256
	global_load_dwordx4 v[132:135], v[130:131], off
	s_nop 0
	global_load_dwordx4 v[128:131], v[130:131], off offset:256
	s_mov_b64 s[10:11], 0x90
	v_lshl_add_u64 v[172:173], s[28:29], 0, v[172:173]
	v_lshl_add_u64 v[172:173], v[172:173], 0, v[170:171]
	s_waitcnt vmcnt(0)
	v_lshlrev_b32_e32 v146, 16, v182
	v_and_b32_e32 v147, 0xffff0000, v182
	v_lshlrev_b32_e32 v148, 16, v184
	v_and_b32_e32 v149, 0xffff0000, v184
	v_lshlrev_b32_e32 v182, 16, v183
	v_and_b32_e32 v183, 0xffff0000, v183
	v_lshlrev_b32_e32 v194, 16, v210
	v_and_b32_e32 v195, 0xffff0000, v210
	v_lshlrev_b32_e32 v196, 16, v212
	v_and_b32_e32 v197, 0xffff0000, v212
	v_lshlrev_b32_e32 v210, 16, v211
	v_and_b32_e32 v211, 0xffff0000, v211
	v_lshlrev_b32_e32 v212, 16, v213
	v_and_b32_e32 v213, 0xffff0000, v213
	v_pk_fma_f32 v[124:125], v[124:125], 0.5, v[146:147] op_sel_hi:[1,0,1]
	v_pk_fma_f32 v[120:121], v[120:121], 0.5, v[148:149] op_sel_hi:[1,0,1]
	v_pk_fma_f32 v[126:127], v[126:127], 0.5, v[182:183] op_sel_hi:[1,0,1]
	v_pk_fma_f32 v[116:117], v[116:117], 0.5, v[194:195] op_sel_hi:[1,0,1]
	v_pk_fma_f32 v[146:147], v[112:113], 0.5, v[196:197] op_sel_hi:[1,0,1]
	v_pk_fma_f32 v[118:119], v[118:119], 0.5, v[210:211] op_sel_hi:[1,0,1]
	v_pk_fma_f32 v[148:149], v[114:115], 0.5, v[212:213] op_sel_hi:[1,0,1]
	v_pk_mul_f32 v[212:213], v[124:125], v[124:125]
	v_lshlrev_b32_e32 v182, 16, v214
	v_and_b32_e32 v183, 0xffff0000, v214
	v_lshlrev_b32_e32 v194, 16, v215
	v_and_b32_e32 v195, 0xffff0000, v215
	v_pk_mul_f32 v[214:215], v[126:127], v[126:127]
	v_cvt_pk_bf16_f32 v112, v124, v125
	v_cvt_pk_bf16_f32 v113, v126, v127
	v_pk_mul_f32 v[124:125], v[116:117], v[116:117]
	v_pk_mul_f32 v[126:127], v[118:119], v[118:119]
	v_pk_mul_f32 v[228:229], v[146:147], v[146:147]
	v_cvt_pk_bf16_f32 v116, v116, v117
	v_cvt_pk_bf16_f32 v117, v118, v119
	v_cvt_pk_bf16_f32 v118, v146, v147
	v_add_f32_e32 v146, v212, v213
	v_lshlrev_b32_e32 v184, 16, v185
	v_and_b32_e32 v185, 0xffff0000, v185
	v_add_f32_e32 v146, v214, v146
	v_pk_fma_f32 v[122:123], v[122:123], 0.5, v[184:185] op_sel_hi:[1,0,1]
	v_lshlrev_b32_e32 v184, 16, v216
	v_and_b32_e32 v185, 0xffff0000, v216
	v_lshlrev_b32_e32 v196, 16, v217
	v_and_b32_e32 v197, 0xffff0000, v217
	v_pk_mul_f32 v[216:217], v[120:121], v[120:121]
	v_add_f32_e32 v146, v215, v146
	v_add_f32_e32 v146, v216, v146
	v_pk_mul_f32 v[226:227], v[122:123], v[122:123]
	v_add_f32_e32 v146, v217, v146
	v_add_f32_e32 v146, v226, v146
	v_add_f32_e32 v146, v227, v146
	v_add_f32_e32 v124, v124, v146
	v_add_f32_e32 v124, v125, v124
	v_add_f32_e32 v124, v126, v124
	v_add_f32_e32 v124, v127, v124
	v_add_f32_e32 v124, v228, v124
	v_pk_mul_f32 v[230:231], v[148:149], v[148:149]
	v_add_f32_e32 v124, v229, v124
	v_add_f32_e32 v124, v230, v124
	v_add_f32_e32 v209, v231, v124
	v_lshlrev_b32_e32 v124, 16, v220
	v_and_b32_e32 v125, 0xffff0000, v220
	v_pk_fma_f32 v[124:125], v[92:93], 0.5, v[124:125] op_sel_hi:[1,0,1]
	v_lshlrev_b32_e32 v92, 16, v219
	v_and_b32_e32 v93, 0xffff0000, v219
	v_pk_fma_f32 v[102:103], v[102:103], 0.5, v[92:93] op_sel_hi:[1,0,1]
	v_lshlrev_b32_e32 v92, 16, v221
	v_and_b32_e32 v93, 0xffff0000, v221
	v_pk_fma_f32 v[126:127], v[94:95], 0.5, v[92:93] op_sel_hi:[1,0,1]
	v_lshlrev_b32_e32 v92, 16, v222
	v_and_b32_e32 v93, 0xffff0000, v222
	v_pk_fma_f32 v[92:93], v[96:97], 0.5, v[92:93] op_sel_hi:[1,0,1]
	v_lshlrev_b32_e32 v96, 16, v225
	v_and_b32_e32 v97, 0xffff0000, v225
	v_lshlrev_b32_e32 v94, 16, v224
	v_and_b32_e32 v95, 0xffff0000, v224
	v_pk_fma_f32 v[90:91], v[90:91], 0.5, v[96:97] op_sel_hi:[1,0,1]
	v_lshlrev_b32_e32 v96, 16, v136
	v_and_b32_e32 v97, 0xffff0000, v136
	v_pk_fma_f32 v[88:89], v[88:89], 0.5, v[94:95] op_sel_hi:[1,0,1]
	v_lshlrev_b32_e32 v94, 16, v223
	v_and_b32_e32 v95, 0xffff0000, v223
	v_pk_fma_f32 v[96:97], v[76:77], 0.5, v[96:97] op_sel_hi:[1,0,1]
	v_lshl_add_u64 v[76:77], v[168:169], 0, s[36:37]
	v_cvt_pk_bf16_f32 v114, v120, v121
	v_pk_fma_f32 v[120:121], v[108:109], 0.5, v[182:183] op_sel_hi:[1,0,1]
	v_pk_fma_f32 v[94:95], v[98:99], 0.5, v[94:95] op_sel_hi:[1,0,1]
	v_lshlrev_b64 v[182:183], 11, v[76:77]
	v_lshlrev_b32_e32 v98, 16, v138
	v_and_b32_e32 v99, 0xffff0000, v138
	v_lshl_add_u64 v[146:147], v[174:175], 0, v[182:183]
	v_pk_fma_f32 v[98:99], v[72:73], 0.5, v[98:99] op_sel_hi:[1,0,1]
	v_lshlrev_b32_e32 v72, 16, v137
	v_and_b32_e32 v73, 0xffff0000, v137
	v_lshlrev_b32_e32 v210, 16, v218
	v_and_b32_e32 v211, 0xffff0000, v218
	global_load_dwordx4 v[218:221], v[146:147], off
	global_load_dwordx4 v[226:229], v[146:147], off offset:256
	v_pk_fma_f32 v[136:137], v[78:79], 0.5, v[72:73] op_sel_hi:[1,0,1]
	v_lshlrev_b32_e32 v72, 16, v139
	v_and_b32_e32 v73, 0xffff0000, v139
	v_pk_fma_f32 v[138:139], v[74:75], 0.5, v[72:73] op_sel_hi:[1,0,1]
	v_lshlrev_b32_e32 v72, 16, v132
	v_and_b32_e32 v73, 0xffff0000, v132
	v_pk_fma_f32 v[74:75], v[84:85], 0.5, v[72:73] op_sel_hi:[1,0,1]
	v_lshlrev_b32_e32 v72, 16, v134
	v_and_b32_e32 v73, 0xffff0000, v134
	v_pk_fma_f32 v[78:79], v[80:81], 0.5, v[72:73] op_sel_hi:[1,0,1]
	v_lshlrev_b32_e32 v72, 16, v133
	v_and_b32_e32 v73, 0xffff0000, v133
	v_pk_fma_f32 v[80:81], v[86:87], 0.5, v[72:73] op_sel_hi:[1,0,1]
	v_lshlrev_b32_e32 v72, 16, v135
	v_and_b32_e32 v73, 0xffff0000, v135
	v_pk_fma_f32 v[82:83], v[82:83], 0.5, v[72:73] op_sel_hi:[1,0,1]
	v_lshl_add_u64 v[72:73], v[168:169], 0, s[10:11]
	v_lshlrev_b64 v[132:133], 11, v[72:73]
	v_lshl_add_u64 v[134:135], v[174:175], 0, v[132:133]
	global_load_dwordx4 v[234:237], v[134:135], off
	global_load_dwordx4 v[242:245], v[134:135], off offset:256
	v_lshlrev_b32_e32 v84, 16, v128
	v_and_b32_e32 v85, 0xffff0000, v128
	v_pk_fma_f32 v[84:85], v[68:69], 0.5, v[84:85] op_sel_hi:[1,0,1]
	v_lshlrev_b32_e32 v68, 16, v130
	v_and_b32_e32 v69, 0xffff0000, v130
	v_pk_fma_f32 v[86:87], v[64:65], 0.5, v[68:69] op_sel_hi:[1,0,1]
	v_lshlrev_b32_e32 v64, 16, v129
	v_and_b32_e32 v65, 0xffff0000, v129
	s_mov_b64 s[10:11], 0xa0
	v_pk_fma_f32 v[128:129], v[70:71], 0.5, v[64:65] op_sel_hi:[1,0,1]
	v_lshl_add_u64 v[70:71], v[168:169], 0, s[10:11]
	v_lshlrev_b32_e32 v64, 16, v131
	v_and_b32_e32 v65, 0xffff0000, v131
	v_lshlrev_b64 v[134:135], 11, v[70:71]
	v_pk_fma_f32 v[130:131], v[66:67], 0.5, v[64:65] op_sel_hi:[1,0,1]
	v_lshl_add_u64 v[64:65], v[174:175], 0, v[134:135]
	v_cvt_pk_bf16_f32 v115, v122, v123
	v_pk_fma_f32 v[122:123], v[110:111], 0.5, v[194:195] op_sel_hi:[1,0,1]
	v_pk_fma_f32 v[110:111], v[106:107], 0.5, v[196:197] op_sel_hi:[1,0,1]
	global_load_dwordx4 v[246:249], v[64:65], off
	global_load_dwordx4 v[194:197], v[64:65], off offset:256
	s_mov_b64 s[10:11], 0xb0
	v_lshl_add_u64 v[68:69], v[168:169], 0, s[10:11]
	v_pk_fma_f32 v[108:109], v[104:105], 0.5, v[184:185] op_sel_hi:[1,0,1]
	v_lshlrev_b64 v[184:185], 11, v[68:69]
	v_lshl_add_u64 v[64:65], v[174:175], 0, v[184:185]
	v_cvt_pk_bf16_f32 v119, v148, v149
	global_load_dwordx4 v[146:149], v[64:65], off
	s_nop 0
	global_load_dwordx4 v[64:67], v[64:65], off offset:256
	global_store_dwordx4 v[172:173], v[112:115], off
	global_store_dwordx4 v[172:173], v[116:119], off offset:256
	v_cvt_pk_bf16_f32 v104, v120, v121
	v_lshl_add_u64 v[112:113], s[28:29], 0, v[176:177]
	v_cvt_pk_bf16_f32 v105, v122, v123
	v_cvt_pk_bf16_f32 v106, v108, v109
	v_cvt_pk_bf16_f32 v107, v110, v111
	v_pk_fma_f32 v[100:101], v[100:101], 0.5, v[210:211] op_sel_hi:[1,0,1]
	v_lshl_add_u64 v[112:113], v[112:113], 0, v[170:171]
	v_cvt_pk_bf16_f32 v210, v100, v101
	v_cvt_pk_bf16_f32 v211, v102, v103
	v_cvt_pk_bf16_f32 v212, v124, v125
	v_cvt_pk_bf16_f32 v213, v126, v127
	global_store_dwordx4 v[112:113], v[104:107], off
	global_store_dwordx4 v[112:113], v[210:213], off offset:256
	v_cvt_pk_bf16_f32 v214, v92, v93
	v_lshl_add_u64 v[104:105], s[28:29], 0, v[180:181]
	v_cvt_pk_bf16_f32 v215, v94, v95
	v_cvt_pk_bf16_f32 v216, v88, v89
	v_cvt_pk_bf16_f32 v217, v90, v91
	v_lshl_add_u64 v[104:105], v[104:105], 0, v[170:171]
	v_cvt_pk_bf16_f32 v222, v96, v97
	v_cvt_pk_bf16_f32 v223, v136, v137
	v_cvt_pk_bf16_f32 v224, v98, v99
	v_cvt_pk_bf16_f32 v225, v138, v139
	global_store_dwordx4 v[104:105], v[214:217], off
	global_store_dwordx4 v[104:105], v[222:225], off offset:256
	v_lshl_add_u64 v[104:105], s[28:29], 0, v[178:179]
	v_cvt_pk_bf16_f32 v230, v74, v75
	v_cvt_pk_bf16_f32 v231, v80, v81
	v_cvt_pk_bf16_f32 v232, v78, v79
	v_cvt_pk_bf16_f32 v233, v82, v83
	v_lshl_add_u64 v[104:105], v[104:105], 0, v[170:171]
	v_cvt_pk_bf16_f32 v238, v84, v85
	v_cvt_pk_bf16_f32 v239, v128, v129
	v_cvt_pk_bf16_f32 v240, v86, v87
	v_cvt_pk_bf16_f32 v241, v130, v131
	global_store_dwordx4 v[104:105], v[230:233], off
	global_store_dwordx4 v[104:105], v[238:241], off offset:256
	s_waitcnt vmcnt(8)
	v_lshlrev_b32_e32 v104, 16, v218
	v_and_b32_e32 v105, 0xffff0000, v218
	v_pk_fma_f32 v[60:61], v[60:61], 0.5, v[104:105] op_sel_hi:[1,0,1]
	v_lshlrev_b32_e32 v104, 16, v220
	v_and_b32_e32 v105, 0xffff0000, v220
	v_pk_fma_f32 v[56:57], v[56:57], 0.5, v[104:105] op_sel_hi:[1,0,1]
	v_lshlrev_b32_e32 v104, 16, v219
	v_and_b32_e32 v105, 0xffff0000, v219
	v_pk_fma_f32 v[62:63], v[62:63], 0.5, v[104:105] op_sel_hi:[1,0,1]
	v_lshlrev_b32_e32 v104, 16, v221
	v_and_b32_e32 v105, 0xffff0000, v221
	v_pk_fma_f32 v[58:59], v[58:59], 0.5, v[104:105] op_sel_hi:[1,0,1]
	v_lshlrev_b32_e32 v104, 16, v226
	v_and_b32_e32 v105, 0xffff0000, v226
	v_pk_fma_f32 v[52:53], v[52:53], 0.5, v[104:105] op_sel_hi:[1,0,1]
	v_lshlrev_b32_e32 v104, 16, v228
	v_and_b32_e32 v105, 0xffff0000, v228
	v_pk_fma_f32 v[104:105], v[44:45], 0.5, v[104:105] op_sel_hi:[1,0,1]
	v_lshlrev_b32_e32 v44, 16, v227
	v_and_b32_e32 v45, 0xffff0000, v227
	v_pk_fma_f32 v[54:55], v[54:55], 0.5, v[44:45] op_sel_hi:[1,0,1]
	v_lshlrev_b32_e32 v44, 16, v229
	v_and_b32_e32 v45, 0xffff0000, v229
	v_pk_fma_f32 v[106:107], v[46:47], 0.5, v[44:45] op_sel_hi:[1,0,1]
	v_lshlrev_b32_e32 v44, 16, v234
	v_and_b32_e32 v45, 0xffff0000, v234
	v_pk_fma_f32 v[44:45], v[48:49], 0.5, v[44:45] op_sel_hi:[1,0,1]
	v_lshlrev_b32_e32 v48, 16, v237
	v_and_b32_e32 v49, 0xffff0000, v237
	v_pk_fma_f32 v[42:43], v[42:43], 0.5, v[48:49] op_sel_hi:[1,0,1]
	v_lshlrev_b32_e32 v48, 16, v242
	v_and_b32_e32 v49, 0xffff0000, v242
	v_pk_fma_f32 v[36:37], v[36:37], 0.5, v[48:49] op_sel_hi:[1,0,1]
	v_lshlrev_b32_e32 v48, 16, v244
	v_and_b32_e32 v49, 0xffff0000, v244
	v_lshlrev_b32_e32 v46, 16, v236
	v_and_b32_e32 v47, 0xffff0000, v236
	v_pk_fma_f32 v[48:49], v[28:29], 0.5, v[48:49] op_sel_hi:[1,0,1]
	v_lshlrev_b32_e32 v28, 16, v243
	v_and_b32_e32 v29, 0xffff0000, v243
	v_pk_fma_f32 v[40:41], v[40:41], 0.5, v[46:47] op_sel_hi:[1,0,1]
	v_lshlrev_b32_e32 v46, 16, v235
	v_and_b32_e32 v47, 0xffff0000, v235
	v_pk_fma_f32 v[38:39], v[38:39], 0.5, v[28:29] op_sel_hi:[1,0,1]
	v_lshlrev_b32_e32 v28, 16, v245
	v_and_b32_e32 v29, 0xffff0000, v245
	v_pk_fma_f32 v[46:47], v[50:51], 0.5, v[46:47] op_sel_hi:[1,0,1]
	v_pk_fma_f32 v[50:51], v[30:31], 0.5, v[28:29] op_sel_hi:[1,0,1]
	v_lshlrev_b32_e32 v28, 16, v246
	v_and_b32_e32 v29, 0xffff0000, v246
	v_pk_fma_f32 v[28:29], v[32:33], 0.5, v[28:29] op_sel_hi:[1,0,1]
	v_lshlrev_b32_e32 v32, 16, v249
	v_and_b32_e32 v33, 0xffff0000, v249
	v_pk_fma_f32 v[26:27], v[26:27], 0.5, v[32:33] op_sel_hi:[1,0,1]
	v_lshlrev_b32_e32 v32, 16, v194
	v_and_b32_e32 v33, 0xffff0000, v194
	v_pk_fma_f32 v[20:21], v[20:21], 0.5, v[32:33] op_sel_hi:[1,0,1]
	v_lshlrev_b32_e32 v32, 16, v196
	v_and_b32_e32 v33, 0xffff0000, v196
	v_lshlrev_b32_e32 v30, 16, v248
	v_and_b32_e32 v31, 0xffff0000, v248
	v_pk_fma_f32 v[32:33], v[12:13], 0.5, v[32:33] op_sel_hi:[1,0,1]
	v_lshlrev_b32_e32 v12, 16, v195
	v_and_b32_e32 v13, 0xffff0000, v195
	v_pk_fma_f32 v[24:25], v[24:25], 0.5, v[30:31] op_sel_hi:[1,0,1]
	v_lshlrev_b32_e32 v30, 16, v247
	v_and_b32_e32 v31, 0xffff0000, v247
	v_pk_fma_f32 v[22:23], v[22:23], 0.5, v[12:13] op_sel_hi:[1,0,1]
	v_lshlrev_b32_e32 v12, 16, v197
	v_and_b32_e32 v13, 0xffff0000, v197
	v_pk_fma_f32 v[30:31], v[34:35], 0.5, v[30:31] op_sel_hi:[1,0,1]
	v_pk_fma_f32 v[34:35], v[14:15], 0.5, v[12:13] op_sel_hi:[1,0,1]
	v_lshlrev_b32_e32 v14, 16, v148
	v_and_b32_e32 v15, 0xffff0000, v148
	v_lshlrev_b32_e32 v12, 16, v146
	v_and_b32_e32 v13, 0xffff0000, v146
	v_pk_fma_f32 v[8:9], v[8:9], 0.5, v[14:15] op_sel_hi:[1,0,1]
	v_lshlrev_b32_e32 v14, 16, v147
	v_and_b32_e32 v15, 0xffff0000, v147
	v_lshlrev_b32_e32 v146, 16, v64
	v_and_b32_e32 v147, 0xffff0000, v64
	v_pk_fma_f32 v[4:5], v[4:5], 0.5, v[146:147] op_sel_hi:[1,0,1]
	v_lshlrev_b32_e32 v146, 16, v66
	v_and_b32_e32 v147, 0xffff0000, v66
	v_pk_fma_f32 v[0:1], v[0:1], 0.5, v[146:147] op_sel_hi:[1,0,1]
	v_lshl_add_u64 v[146:147], s[28:29], 0, v[182:183]
	v_cvt_pk_bf16_f32 v112, v60, v61
	v_cvt_pk_bf16_f32 v113, v62, v63
	v_cvt_pk_bf16_f32 v114, v56, v57
	v_cvt_pk_bf16_f32 v115, v58, v59
	v_lshl_add_u64 v[146:147], v[146:147], 0, v[170:171]
	v_cvt_pk_bf16_f32 v116, v52, v53
	v_cvt_pk_bf16_f32 v117, v54, v55
	v_cvt_pk_bf16_f32 v118, v104, v105
	v_cvt_pk_bf16_f32 v119, v106, v107
	global_store_dwordx4 v[146:147], v[112:115], off
	global_store_dwordx4 v[146:147], v[116:119], off offset:256
	v_cvt_pk_bf16_f32 v172, v44, v45
	v_lshl_add_u64 v[112:113], s[28:29], 0, v[132:133]
	v_cvt_pk_bf16_f32 v173, v46, v47
	v_cvt_pk_bf16_f32 v174, v40, v41
	v_cvt_pk_bf16_f32 v175, v42, v43
	v_lshl_add_u64 v[112:113], v[112:113], 0, v[170:171]
	v_cvt_pk_bf16_f32 v176, v36, v37
	v_cvt_pk_bf16_f32 v177, v38, v39
	v_cvt_pk_bf16_f32 v178, v48, v49
	v_cvt_pk_bf16_f32 v179, v50, v51
	global_store_dwordx4 v[112:113], v[172:175], off
	global_store_dwordx4 v[112:113], v[176:179], off offset:256
	v_lshl_add_u64 v[112:113], s[28:29], 0, v[134:135]
	v_cvt_pk_bf16_f32 v210, v28, v29
	v_cvt_pk_bf16_f32 v211, v30, v31
	v_cvt_pk_bf16_f32 v212, v24, v25
	v_cvt_pk_bf16_f32 v213, v26, v27
	v_pk_fma_f32 v[12:13], v[16:17], 0.5, v[12:13] op_sel_hi:[1,0,1]
	v_lshlrev_b32_e32 v16, 16, v149
	v_and_b32_e32 v17, 0xffff0000, v149
	v_lshlrev_b32_e32 v64, 16, v65
	v_and_b32_e32 v65, 0xffff0000, v65
	v_lshl_add_u64 v[112:113], v[112:113], 0, v[170:171]
	v_cvt_pk_bf16_f32 v194, v20, v21
	v_cvt_pk_bf16_f32 v195, v22, v23
	v_cvt_pk_bf16_f32 v196, v32, v33
	v_cvt_pk_bf16_f32 v197, v34, v35
	v_pk_fma_f32 v[14:15], v[18:19], 0.5, v[14:15] op_sel_hi:[1,0,1]
	v_pk_fma_f32 v[10:11], v[10:11], 0.5, v[16:17] op_sel_hi:[1,0,1]
	v_pk_fma_f32 v[6:7], v[6:7], 0.5, v[64:65] op_sel_hi:[1,0,1]
	v_lshlrev_b32_e32 v64, 16, v67
	v_and_b32_e32 v65, 0xffff0000, v67
	global_store_dwordx4 v[112:113], v[210:213], off
	global_store_dwordx4 v[112:113], v[194:197], off offset:256
	v_lshl_add_u64 v[112:113], s[28:29], 0, v[184:185]
	v_cvt_pk_bf16_f32 v16, v12, v13
	v_cvt_pk_bf16_f32 v17, v14, v15
	v_cvt_pk_bf16_f32 v18, v8, v9
	v_cvt_pk_bf16_f32 v19, v10, v11
	v_pk_fma_f32 v[2:3], v[2:3], 0.5, v[64:65] op_sel_hi:[1,0,1]
	v_lshl_add_u64 v[112:113], v[112:113], 0, v[170:171]
	v_cvt_pk_bf16_f32 v64, v4, v5
	v_cvt_pk_bf16_f32 v65, v6, v7
	v_cvt_pk_bf16_f32 v66, v0, v1
	v_cvt_pk_bf16_f32 v67, v2, v3
	global_store_dwordx4 v[112:113], v[16:19], off
	global_store_dwordx4 v[112:113], v[64:67], off offset:256
	s_lshl_b32 s10, s81, 2
	v_and_b32_e32 v17, 64, v188
	v_xor_b32_e32 v16, 16, v188
	v_add_u32_e32 v17, 64, v17
	v_cmp_lt_i32_e32 vcc, v16, v17
	v_xor_b32_e32 v18, 32, v188
	s_ashr_i32 s11, s10, 31
	v_cndmask_b32_e32 v16, v188, v16, vcc
	v_lshlrev_b32_e32 v16, 2, v16
	v_mov_b32_e32 v132, v209
	v_cmp_lt_i32_e32 vcc, v18, v17
	s_lshl_b64 s[10:11], s[10:11], 2
	s_add_u32 s38, s73, s10
	v_cndmask_b32_e32 v17, v188, v18, vcc
	v_lshlrev_b32_e32 v17, 2, v17
	s_addc_u32 s39, s74, s11
	v_pk_mul_f32 v[18:19], v[120:121], v[120:121]
	v_pk_mul_f32 v[64:65], v[122:123], v[122:123]
	v_add_f32_e32 v18, v18, v19
	v_add_f32_e32 v18, v64, v18
	v_pk_mul_f32 v[66:67], v[108:109], v[108:109]
	v_add_f32_e32 v18, v65, v18
	v_add_f32_e32 v18, v66, v18
	v_pk_mul_f32 v[108:109], v[110:111], v[110:111]
	v_add_f32_e32 v18, v67, v18
	v_add_f32_e32 v18, v108, v18
	v_pk_mul_f32 v[100:101], v[100:101], v[100:101]
	v_add_f32_e32 v18, v109, v18
	v_add_f32_e32 v18, v100, v18
	v_pk_mul_f32 v[102:103], v[102:103], v[102:103]
	v_add_f32_e32 v18, v101, v18
	v_add_f32_e32 v18, v102, v18
	v_pk_mul_f32 v[110:111], v[124:125], v[124:125]
	v_add_f32_e32 v18, v103, v18
	v_add_f32_e32 v18, v110, v18
	v_pk_mul_f32 v[112:113], v[126:127], v[126:127]
	v_add_f32_e32 v18, v111, v18
	v_add_f32_e32 v18, v112, v18
	v_add_f32_e32 v18, v113, v18
	v_mov_b32_e32 v133, v18
	v_pk_mul_f32 v[18:19], v[92:93], v[92:93]
	v_pk_mul_f32 v[64:65], v[94:95], v[94:95]
	v_add_f32_e32 v18, v18, v19
	v_add_f32_e32 v18, v64, v18
	v_pk_mul_f32 v[66:67], v[88:89], v[88:89]
	v_add_f32_e32 v18, v65, v18
	v_add_f32_e32 v18, v66, v18
	v_pk_mul_f32 v[88:89], v[90:91], v[90:91]
	v_add_f32_e32 v18, v67, v18
	v_add_f32_e32 v18, v88, v18
	v_pk_mul_f32 v[90:91], v[96:97], v[96:97]
	v_add_f32_e32 v18, v89, v18
	v_add_f32_e32 v18, v90, v18
	v_pk_mul_f32 v[92:93], v[136:137], v[136:137]
	v_add_f32_e32 v18, v91, v18
	v_add_f32_e32 v18, v92, v18
	v_pk_mul_f32 v[94:95], v[98:99], v[98:99]
	v_add_f32_e32 v18, v93, v18
	v_add_f32_e32 v18, v94, v18
	v_pk_mul_f32 v[96:97], v[138:139], v[138:139]
	v_add_f32_e32 v18, v95, v18
	v_add_f32_e32 v18, v96, v18
	v_add_f32_e32 v18, v97, v18
	v_mov_b32_e32 v134, v18
	v_pk_mul_f32 v[18:19], v[74:75], v[74:75]
	v_pk_mul_f32 v[180:181], v[60:61], v[60:61]
	v_pk_mul_f32 v[64:65], v[80:81], v[80:81]
	v_pk_mul_f32 v[60:61], v[62:63], v[62:63]
	v_add_f32_e32 v18, v18, v19
	v_add_f32_e32 v180, v180, v181
	v_add_f32_e32 v18, v64, v18
	v_add_f32_e32 v180, v60, v180
	v_pk_mul_f32 v[66:67], v[78:79], v[78:79]
	v_pk_mul_f32 v[56:57], v[56:57], v[56:57]
	v_add_f32_e32 v18, v65, v18
	v_add_f32_e32 v180, v61, v180
	v_add_f32_e32 v18, v66, v18
	v_add_f32_e32 v180, v56, v180
	v_pk_mul_f32 v[74:75], v[82:83], v[82:83]
	v_pk_mul_f32 v[58:59], v[58:59], v[58:59]
	v_add_f32_e32 v18, v67, v18
	v_add_f32_e32 v180, v57, v180
	v_add_f32_e32 v18, v74, v18
	v_add_f32_e32 v180, v58, v180
	v_pk_mul_f32 v[78:79], v[84:85], v[84:85]
	v_pk_mul_f32 v[52:53], v[52:53], v[52:53]
	v_add_f32_e32 v18, v75, v18
	v_add_f32_e32 v180, v59, v180
	v_add_f32_e32 v18, v78, v18
	v_add_f32_e32 v180, v52, v180
	v_pk_mul_f32 v[80:81], v[128:129], v[128:129]
	v_pk_mul_f32 v[54:55], v[54:55], v[54:55]
	v_add_f32_e32 v18, v79, v18
	v_add_f32_e32 v180, v53, v180
	v_add_f32_e32 v18, v80, v18
	v_add_f32_e32 v180, v54, v180
	v_pk_mul_f32 v[82:83], v[86:87], v[86:87]
	v_pk_mul_f32 v[62:63], v[104:105], v[104:105]
	v_add_f32_e32 v18, v81, v18
	v_add_f32_e32 v180, v55, v180
	v_add_f32_e32 v18, v82, v18
	v_add_f32_e32 v180, v62, v180
	v_pk_mul_f32 v[84:85], v[130:131], v[130:131]
	v_pk_mul_f32 v[182:183], v[106:107], v[106:107]
	v_add_f32_e32 v18, v83, v18
	v_add_f32_e32 v180, v63, v180
	v_add_f32_e32 v18, v84, v18
	v_add_f32_e32 v180, v182, v180
	v_add_f32_e32 v18, v85, v18
	v_add_f32_e32 v180, v183, v180
	v_mov_b32_e32 v135, v18
	v_mov_b32_e32 v146, v180
	v_pk_mul_f32 v[18:19], v[44:45], v[44:45]
	v_pk_mul_f32 v[180:181], v[28:29], v[28:29]
	v_pk_mul_f32 v[44:45], v[46:47], v[46:47]
	v_pk_mul_f32 v[28:29], v[30:31], v[30:31]
	v_add_f32_e32 v18, v18, v19
	v_add_f32_e32 v180, v180, v181
	v_add_f32_e32 v18, v44, v18
	v_add_f32_e32 v180, v28, v180
	v_pk_mul_f32 v[40:41], v[40:41], v[40:41]
	v_pk_mul_f32 v[24:25], v[24:25], v[24:25]
	v_add_f32_e32 v18, v45, v18
	v_add_f32_e32 v180, v29, v180
	v_add_f32_e32 v18, v40, v18
	v_add_f32_e32 v180, v24, v180
	v_pk_mul_f32 v[42:43], v[42:43], v[42:43]
	v_pk_mul_f32 v[26:27], v[26:27], v[26:27]
	v_add_f32_e32 v18, v41, v18
	v_add_f32_e32 v180, v25, v180
	v_add_f32_e32 v18, v42, v18
	v_add_f32_e32 v180, v26, v180
	v_pk_mul_f32 v[36:37], v[36:37], v[36:37]
	v_pk_mul_f32 v[20:21], v[20:21], v[20:21]
	v_add_f32_e32 v18, v43, v18
	v_add_f32_e32 v180, v27, v180
	v_add_f32_e32 v18, v36, v18
	v_add_f32_e32 v180, v20, v180
	v_pk_mul_f32 v[38:39], v[38:39], v[38:39]
	v_pk_mul_f32 v[22:23], v[22:23], v[22:23]
	v_add_f32_e32 v18, v37, v18
	v_add_f32_e32 v180, v21, v180
	v_add_f32_e32 v18, v38, v18
	v_add_f32_e32 v180, v22, v180
	v_pk_mul_f32 v[46:47], v[48:49], v[48:49]
	v_pk_mul_f32 v[30:31], v[32:33], v[32:33]
	v_add_f32_e32 v18, v39, v18
	v_add_f32_e32 v180, v23, v180
	v_add_f32_e32 v18, v46, v18
	v_add_f32_e32 v180, v30, v180
	v_pk_mul_f32 v[48:49], v[50:51], v[50:51]
	v_pk_mul_f32 v[32:33], v[34:35], v[34:35]
	v_add_f32_e32 v18, v47, v18
	v_add_f32_e32 v180, v31, v180
	v_add_f32_e32 v18, v48, v18
	v_add_f32_e32 v180, v32, v180
	v_add_f32_e32 v18, v49, v18
	v_add_f32_e32 v180, v33, v180
	v_mov_b32_e32 v147, v18
	v_mov_b32_e32 v148, v180
	v_pk_mul_f32 v[12:13], v[12:13], v[12:13]
	v_pk_mul_f32 v[14:15], v[14:15], v[14:15]
	v_add_f32_e32 v12, v12, v13
	v_add_f32_e32 v12, v14, v12
	v_pk_mul_f32 v[8:9], v[8:9], v[8:9]
	v_add_f32_e32 v12, v15, v12
	v_add_f32_e32 v8, v8, v12
	v_pk_mul_f32 v[10:11], v[10:11], v[10:11]
	v_add_f32_e32 v8, v9, v8
	v_add_f32_e32 v8, v10, v8
	v_pk_mul_f32 v[4:5], v[4:5], v[4:5]
	v_add_f32_e32 v8, v11, v8
	v_add_f32_e32 v4, v4, v8
	v_pk_mul_f32 v[6:7], v[6:7], v[6:7]
	v_add_f32_e32 v4, v5, v4
	v_add_f32_e32 v4, v6, v4
	v_pk_mul_f32 v[0:1], v[0:1], v[0:1]
	v_add_f32_e32 v4, v7, v4
	v_add_f32_e32 v0, v0, v4
	v_pk_mul_f32 v[2:3], v[2:3], v[2:3]
	v_add_f32_e32 v0, v1, v0
	v_add_f32_e32 v0, v2, v0
	v_add_f32_e32 v0, v3, v0
	v_mov_b32_e32 v149, v0
	ds_bpermute_b32 v172, v16, v132
	ds_bpermute_b32 v173, v16, v133
	ds_bpermute_b32 v174, v16, v134
	ds_bpermute_b32 v175, v16, v135
	ds_bpermute_b32 v176, v16, v146
	ds_bpermute_b32 v177, v16, v147
	ds_bpermute_b32 v178, v16, v148
	ds_bpermute_b32 v179, v16, v149
	s_waitcnt lgkmcnt(0)
	v_add_f32_e32 v132, v132, v172
	v_add_f32_e32 v133, v133, v173
	v_add_f32_e32 v134, v134, v174
	v_add_f32_e32 v135, v135, v175
	v_add_f32_e32 v146, v146, v176
	v_add_f32_e32 v147, v147, v177
	v_add_f32_e32 v148, v148, v178
	v_add_f32_e32 v149, v149, v179
	ds_bpermute_b32 v172, v17, v132
	ds_bpermute_b32 v173, v17, v133
	ds_bpermute_b32 v174, v17, v134
	ds_bpermute_b32 v175, v17, v135
	ds_bpermute_b32 v176, v17, v146
	ds_bpermute_b32 v177, v17, v147
	ds_bpermute_b32 v178, v17, v148
	ds_bpermute_b32 v179, v17, v149
	s_and_saveexec_b64 s[46:47], s[42:43]
	s_cbranch_execz .LBB0_329
	s_waitcnt lgkmcnt(0)
	v_add_f32_e32 v132, v132, v172
	v_lshlrev_b64 v[18:19], 6, v[168:169]
	v_lshl_add_u64 v[18:19], s[38:39], 0, v[18:19]
	global_store_dword v[18:19], v132, off
	v_add_f32_e32 v133, v133, v173
	v_lshlrev_b64 v[18:19], 6, v[166:167]
	v_lshl_add_u64 v[18:19], s[38:39], 0, v[18:19]
	global_store_dword v[18:19], v133, off
	v_add_f32_e32 v134, v134, v174
	v_lshlrev_b64 v[18:19], 6, v[164:165]
	v_lshl_add_u64 v[18:19], s[38:39], 0, v[18:19]
	global_store_dword v[18:19], v134, off
	v_add_f32_e32 v135, v135, v175
	v_lshlrev_b64 v[18:19], 6, v[162:163]
	v_lshl_add_u64 v[18:19], s[38:39], 0, v[18:19]
	global_store_dword v[18:19], v135, off
	v_add_f32_e32 v146, v146, v176
	v_lshlrev_b64 v[18:19], 6, v[76:77]
	v_lshl_add_u64 v[18:19], s[38:39], 0, v[18:19]
	global_store_dword v[18:19], v146, off
	v_add_f32_e32 v147, v147, v177
	v_lshlrev_b64 v[18:19], 6, v[72:73]
	v_lshl_add_u64 v[18:19], s[38:39], 0, v[18:19]
	global_store_dword v[18:19], v147, off
	v_add_f32_e32 v148, v148, v178
	v_lshlrev_b64 v[18:19], 6, v[70:71]
	v_lshl_add_u64 v[18:19], s[38:39], 0, v[18:19]
	global_store_dword v[18:19], v148, off
	v_add_f32_e32 v149, v149, v179
	v_lshlrev_b64 v[18:19], 6, v[68:69]
	v_lshl_add_u64 v[18:19], s[38:39], 0, v[18:19]
	global_store_dword v[18:19], v149, off
	s_branch .LBB0_329

.Lm4bp_386:
	s_waitcnt lgkmcnt(0)
	s_mov_b32 s100, 0
	s_barrier
	s_nop 0
	v_mfma_f32_16x16x32_bf16 v[60:63], v[158:161], v[174:177], 0
	v_mfma_f32_16x16x32_bf16 v[56:59], v[166:169], v[174:177], 0
	v_mfma_f32_16x16x32_bf16 v[52:55], v[158:161], v[182:185], 0
	v_mfma_f32_16x16x32_bf16 v[48:51], v[166:169], v[182:185], 0
	v_mfma_f32_16x16x32_bf16 v[44:47], v[158:161], v[210:213], 0
	v_mfma_f32_16x16x32_bf16 v[40:43], v[166:169], v[210:213], 0
	v_mfma_f32_16x16x32_bf16 v[36:39], v[158:161], v[218:221], 0
	v_mfma_f32_16x16x32_bf16 v[32:35], v[166:169], v[218:221], 0
	v_mfma_f32_16x16x32_bf16 v[60:63], v[162:165], v[178:181], v[60:63]
	v_mfma_f32_16x16x32_bf16 v[56:59], v[170:173], v[178:181], v[56:59]
	v_mfma_f32_16x16x32_bf16 v[52:55], v[162:165], v[206:209], v[52:55]
	v_mfma_f32_16x16x32_bf16 v[48:51], v[170:173], v[206:209], v[48:51]
	v_mfma_f32_16x16x32_bf16 v[44:47], v[162:165], v[214:217], v[44:47]
	v_mfma_f32_16x16x32_bf16 v[40:43], v[170:173], v[214:217], v[40:43]
	v_mfma_f32_16x16x32_bf16 v[36:39], v[162:165], v[222:225], v[36:39]
	v_mfma_f32_16x16x32_bf16 v[32:35], v[170:173], v[222:225], v[32:35]
	v_mfma_f32_16x16x32_bf16 v[28:31], v[226:229], v[174:177], 0
	v_mfma_f32_16x16x32_bf16 v[24:27], v[234:237], v[174:177], 0
	v_mfma_f32_16x16x32_bf16 v[20:23], v[226:229], v[182:185], 0
	v_mfma_f32_16x16x32_bf16 v[16:19], v[234:237], v[182:185], 0
	v_mfma_f32_16x16x32_bf16 v[12:15], v[226:229], v[210:213], 0
	v_mfma_f32_16x16x32_bf16 v[8:11], v[234:237], v[210:213], 0
	v_mfma_f32_16x16x32_bf16 v[4:7], v[226:229], v[218:221], 0
	v_mfma_f32_16x16x32_bf16 v[0:3], v[234:237], v[218:221], 0
	v_mfma_f32_16x16x32_bf16 v[28:31], v[230:233], v[178:181], v[28:31]
	v_mfma_f32_16x16x32_bf16 v[24:27], v[238:241], v[178:181], v[24:27]
	v_mfma_f32_16x16x32_bf16 v[20:23], v[230:233], v[206:209], v[20:23]
	v_mfma_f32_16x16x32_bf16 v[16:19], v[238:241], v[206:209], v[16:19]
	v_mfma_f32_16x16x32_bf16 v[12:15], v[230:233], v[214:217], v[12:15]
	v_mfma_f32_16x16x32_bf16 v[8:11], v[238:241], v[214:217], v[8:11]
	v_mfma_f32_16x16x32_bf16 v[4:7], v[230:233], v[222:225], v[4:7]
	v_mfma_f32_16x16x32_bf16 v[0:3], v[238:241], v[222:225], v[0:3]
	s_barrier
	s_add_i32 s6, 0, 0x18000
	v_add_u32_e32 v170, s6, v154
	ds_read_b128 v[158:161], v170
	ds_read_b128 v[162:165], v170 offset:1024
	ds_read_b128 v[166:169], v170 offset:2048
	ds_read_b128 v[170:173], v170 offset:3072
	s_add_u32 s58, s58, 0x40000
	s_addc_u32 s59, s59, 0
	s_mov_b32 m0, s70
	v_lshl_add_u64 v[226:227], s[58:59], 0, v[128:129]
	ds_read_b128 v[174:177], v157 offset:32768
	ds_read_b128 v[178:181], v157 offset:33792
	ds_read_b128 v[182:185], v157 offset:34816
	ds_read_b128 v[206:209], v157 offset:35840
	ds_read_b128 v[210:213], v157 offset:36864
	ds_read_b128 v[214:217], v157 offset:37888
	ds_read_b128 v[218:221], v157 offset:38912
	ds_read_b128 v[222:225], v157 offset:39936
	global_load_lds_dwordx4 v[226:227], off
	v_lshl_add_u64 v[226:227], s[58:59], 0, v[130:131]
	s_mov_b32 m0, s71
	s_nop 0
	global_load_lds_dwordx4 v[226:227], off
	s_add_i32 s19, 0, 0x1c000
	v_add_u32_e32 v192, s19, v154
	ds_read_b128 v[226:229], v192
	ds_read_b128 v[230:233], v192 offset:1024
	ds_read_b128 v[234:237], v192 offset:2048
	ds_read_b128 v[238:241], v192 offset:3072
	s_waitcnt vmcnt(8)
	s_waitcnt lgkmcnt(0)
	s_barrier
	v_mfma_f32_16x16x32_bf16 v[124:127], v[158:161], v[174:177], v[124:127]
	v_mfma_f32_16x16x32_bf16 v[120:123], v[166:169], v[174:177], v[120:123]
	v_mfma_f32_16x16x32_bf16 v[116:119], v[158:161], v[182:185], v[116:119]
	v_mfma_f32_16x16x32_bf16 v[112:115], v[166:169], v[182:185], v[112:115]
	v_mfma_f32_16x16x32_bf16 v[108:111], v[158:161], v[210:213], v[108:111]
	v_mfma_f32_16x16x32_bf16 v[104:107], v[166:169], v[210:213], v[104:107]
	v_mfma_f32_16x16x32_bf16 v[100:103], v[158:161], v[218:221], v[100:103]
	v_mfma_f32_16x16x32_bf16 v[96:99], v[166:169], v[218:221], v[96:99]
	v_mfma_f32_16x16x32_bf16 v[124:127], v[162:165], v[178:181], v[124:127]
	v_mfma_f32_16x16x32_bf16 v[120:123], v[170:173], v[178:181], v[120:123]
	v_mfma_f32_16x16x32_bf16 v[116:119], v[162:165], v[206:209], v[116:119]
	v_mfma_f32_16x16x32_bf16 v[112:115], v[170:173], v[206:209], v[112:115]
	v_mfma_f32_16x16x32_bf16 v[108:111], v[162:165], v[214:217], v[108:111]
	v_mfma_f32_16x16x32_bf16 v[104:107], v[170:173], v[214:217], v[104:107]
	v_mfma_f32_16x16x32_bf16 v[100:103], v[162:165], v[222:225], v[100:103]
	v_mfma_f32_16x16x32_bf16 v[96:99], v[170:173], v[222:225], v[96:99]
	v_mfma_f32_16x16x32_bf16 v[92:95], v[226:229], v[174:177], v[92:95]
	v_mfma_f32_16x16x32_bf16 v[88:91], v[234:237], v[174:177], v[88:91]
	v_mfma_f32_16x16x32_bf16 v[84:87], v[226:229], v[182:185], v[84:87]
	v_mfma_f32_16x16x32_bf16 v[80:83], v[234:237], v[182:185], v[80:83]
	v_mfma_f32_16x16x32_bf16 v[76:79], v[226:229], v[210:213], v[76:79]
	v_mfma_f32_16x16x32_bf16 v[72:75], v[234:237], v[210:213], v[72:75]
	v_mfma_f32_16x16x32_bf16 v[68:71], v[226:229], v[218:221], v[68:71]
	v_mfma_f32_16x16x32_bf16 v[64:67], v[234:237], v[218:221], v[64:67]
	v_mfma_f32_16x16x32_bf16 v[92:95], v[230:233], v[178:181], v[92:95]
	v_mfma_f32_16x16x32_bf16 v[88:91], v[238:241], v[178:181], v[88:91]
	v_mfma_f32_16x16x32_bf16 v[84:87], v[230:233], v[206:209], v[84:87]
	v_mfma_f32_16x16x32_bf16 v[80:83], v[238:241], v[206:209], v[80:83]
	v_mfma_f32_16x16x32_bf16 v[76:79], v[230:233], v[214:217], v[76:79]
	v_mfma_f32_16x16x32_bf16 v[72:75], v[238:241], v[214:217], v[72:75]
	v_mfma_f32_16x16x32_bf16 v[68:71], v[230:233], v[222:225], v[68:71]
	v_mfma_f32_16x16x32_bf16 v[64:67], v[238:241], v[222:225], v[64:67]
	s_barrier
	s_add_i32 s6, s6, s57
	v_lshl_add_u64 v[146:147], v[146:147], 0, s[36:37]
	s_mov_b32 m0, s6
	s_nop 0
	global_load_lds_dwordx4 v[146:147], off
	v_lshl_add_u64 v[146:147], v[148:149], 0, s[36:37]
	s_add_i32 m0, s6, 0x2000
	s_nop 0
	global_load_lds_dwordx4 v[146:147], off
	s_mov_b32 m0, s72
	v_lshl_add_u64 v[146:147], v[194:195], 0, s[36:37]
	ds_read_b128 v[174:177], v157 offset:49152
	ds_read_b128 v[178:181], v157 offset:50176
	ds_read_b128 v[182:185], v157 offset:51200
	ds_read_b128 v[206:209], v157 offset:52224
	ds_read_b128 v[210:213], v157 offset:53248
	ds_read_b128 v[214:217], v157 offset:54272
	ds_read_b128 v[218:221], v157 offset:55296
	ds_read_b128 v[222:225], v157 offset:56320
	global_load_lds_dwordx4 v[146:147], off
	v_lshl_add_u64 v[146:147], v[196:197], 0, s[36:37]
	s_mov_b32 m0, s73
	s_nop 0
	global_load_lds_dwordx4 v[146:147], off
	s_add_u32 s54, s54, 0x40080
	s_addc_u32 s55, s55, 0
	s_add_i32 s6, s19, s57
	v_lshl_add_u64 v[146:147], s[54:55], 0, v[140:141]
	s_mov_b32 m0, s6
	s_nop 0
	global_load_lds_dwordx4 v[146:147], off
	v_lshl_add_u64 v[146:147], s[54:55], 0, v[132:133]
	s_add_i32 m0, s6, 0x2000
	s_nop 0
	global_load_lds_dwordx4 v[146:147], off
	s_add_i32 s81, s81, 2
	s_add_u32 s52, s52, 0x100
	s_addc_u32 s53, s53, 0
	s_cmp_gt_u32 s81, 13
	s_nop 0
	s_waitcnt vmcnt(8)
	s_waitcnt lgkmcnt(0)
	s_barrier
	v_mfma_f32_16x16x32_bf16 v[60:63], v[158:161], v[174:177], v[60:63]
	v_mfma_f32_16x16x32_bf16 v[56:59], v[166:169], v[174:177], v[56:59]
	v_mfma_f32_16x16x32_bf16 v[52:55], v[158:161], v[182:185], v[52:55]
	v_mfma_f32_16x16x32_bf16 v[48:51], v[166:169], v[182:185], v[48:51]
	v_mfma_f32_16x16x32_bf16 v[44:47], v[158:161], v[210:213], v[44:47]
	v_mfma_f32_16x16x32_bf16 v[40:43], v[166:169], v[210:213], v[40:43]
	v_mfma_f32_16x16x32_bf16 v[36:39], v[158:161], v[218:221], v[36:39]
	v_mfma_f32_16x16x32_bf16 v[32:35], v[166:169], v[218:221], v[32:35]
	v_mfma_f32_16x16x32_bf16 v[60:63], v[162:165], v[178:181], v[60:63]
	v_mfma_f32_16x16x32_bf16 v[56:59], v[170:173], v[178:181], v[56:59]
	v_mfma_f32_16x16x32_bf16 v[52:55], v[162:165], v[206:209], v[52:55]
	v_mfma_f32_16x16x32_bf16 v[48:51], v[170:173], v[206:209], v[48:51]
	v_mfma_f32_16x16x32_bf16 v[44:47], v[162:165], v[214:217], v[44:47]
	v_mfma_f32_16x16x32_bf16 v[40:43], v[170:173], v[214:217], v[40:43]
	v_mfma_f32_16x16x32_bf16 v[36:39], v[162:165], v[222:225], v[36:39]
	v_mfma_f32_16x16x32_bf16 v[32:35], v[170:173], v[222:225], v[32:35]
	v_mfma_f32_16x16x32_bf16 v[28:31], v[226:229], v[174:177], v[28:31]
	v_mfma_f32_16x16x32_bf16 v[24:27], v[234:237], v[174:177], v[24:27]
	v_mfma_f32_16x16x32_bf16 v[20:23], v[226:229], v[182:185], v[20:23]
	v_mfma_f32_16x16x32_bf16 v[16:19], v[234:237], v[182:185], v[16:19]
	v_mfma_f32_16x16x32_bf16 v[12:15], v[226:229], v[210:213], v[12:15]
	v_mfma_f32_16x16x32_bf16 v[8:11], v[234:237], v[210:213], v[8:11]
	v_mfma_f32_16x16x32_bf16 v[4:7], v[226:229], v[218:221], v[4:7]
	v_mfma_f32_16x16x32_bf16 v[0:3], v[234:237], v[218:221], v[0:3]
	v_mfma_f32_16x16x32_bf16 v[28:31], v[230:233], v[178:181], v[28:31]
	v_mfma_f32_16x16x32_bf16 v[24:27], v[238:241], v[178:181], v[24:27]
	v_mfma_f32_16x16x32_bf16 v[20:23], v[230:233], v[206:209], v[20:23]
	v_mfma_f32_16x16x32_bf16 v[16:19], v[238:241], v[206:209], v[16:19]
	v_mfma_f32_16x16x32_bf16 v[12:15], v[230:233], v[214:217], v[12:15]
	v_mfma_f32_16x16x32_bf16 v[8:11], v[238:241], v[214:217], v[8:11]
	v_mfma_f32_16x16x32_bf16 v[4:7], v[230:233], v[222:225], v[4:7]
	v_mfma_f32_16x16x32_bf16 v[0:3], v[238:241], v[222:225], v[0:3]
	s_barrier
	.p2align	6
.LBB0_386:
	s_add_u32 s6, s28, s52
	s_addc_u32 s19, s29, s53
	s_add_u32 s6, s6, 0x100
	s_addc_u32 s19, s19, 0
	s_add_u32 s23, s10, s52
	s_addc_u32 s54, s11, s53
	s_add_i32 s82, 0, 0x10000
	v_add_u32_e32 v146, s82, v154
	ds_read_b128 v[158:161], v146
	ds_read_b128 v[162:165], v146 offset:1024
	ds_read_b128 v[166:169], v146 offset:2048
	ds_read_b128 v[170:173], v146 offset:3072
	s_cmpk_eq_i32 s52, 0x700
	s_cselect_b32 s59, s12, s19
	s_cselect_b32 s58, s35, s6
	s_cselect_b32 s55, s39, s54
	s_cselect_b32 s54, s47, s23
	v_lshl_add_u64 v[146:147], v[150:151], 0, s[52:53]
	s_add_i32 m0, s68, 0xc000
	ds_read_b128 v[174:177], v157
	ds_read_b128 v[178:181], v157 offset:1024
	ds_read_b128 v[182:185], v157 offset:2048
	ds_read_b128 v[206:209], v157 offset:3072
	ds_read_b128 v[210:213], v157 offset:4096
	ds_read_b128 v[214:217], v157 offset:5120
	ds_read_b128 v[218:221], v157 offset:6144
	ds_read_b128 v[222:225], v157 offset:7168
	global_load_lds_dwordx4 v[146:147], off
	v_lshl_add_u64 v[146:147], v[152:153], 0, s[52:53]
	s_add_i32 m0, s68, 0xe000
	s_nop 0
	global_load_lds_dwordx4 v[146:147], off
	s_add_i32 s6, 0, 0x14000
	v_add_u32_e32 v146, s6, v154
	ds_read_b128 v[226:229], v146
	ds_read_b128 v[230:233], v146 offset:1024
	ds_read_b128 v[234:237], v146 offset:2048
	ds_read_b128 v[238:241], v146 offset:3072
	s_waitcnt vmcnt(8)
	s_waitcnt lgkmcnt(0)
	s_barrier
	v_mfma_f32_16x16x32_bf16 v[124:127], v[158:161], v[174:177], v[124:127]
	v_mfma_f32_16x16x32_bf16 v[120:123], v[166:169], v[174:177], v[120:123]
	v_mfma_f32_16x16x32_bf16 v[116:119], v[158:161], v[182:185], v[116:119]
	v_mfma_f32_16x16x32_bf16 v[112:115], v[166:169], v[182:185], v[112:115]
	v_mfma_f32_16x16x32_bf16 v[108:111], v[158:161], v[210:213], v[108:111]
	v_mfma_f32_16x16x32_bf16 v[104:107], v[166:169], v[210:213], v[104:107]
	v_mfma_f32_16x16x32_bf16 v[100:103], v[158:161], v[218:221], v[100:103]
	v_mfma_f32_16x16x32_bf16 v[96:99], v[166:169], v[218:221], v[96:99]
	v_mfma_f32_16x16x32_bf16 v[124:127], v[162:165], v[178:181], v[124:127]
	v_mfma_f32_16x16x32_bf16 v[120:123], v[170:173], v[178:181], v[120:123]
	v_mfma_f32_16x16x32_bf16 v[116:119], v[162:165], v[206:209], v[116:119]
	v_mfma_f32_16x16x32_bf16 v[112:115], v[170:173], v[206:209], v[112:115]
	v_mfma_f32_16x16x32_bf16 v[108:111], v[162:165], v[214:217], v[108:111]
	v_mfma_f32_16x16x32_bf16 v[104:107], v[170:173], v[214:217], v[104:107]
	v_mfma_f32_16x16x32_bf16 v[100:103], v[162:165], v[222:225], v[100:103]
	v_mfma_f32_16x16x32_bf16 v[96:99], v[170:173], v[222:225], v[96:99]
	v_mfma_f32_16x16x32_bf16 v[92:95], v[226:229], v[174:177], v[92:95]
	v_mfma_f32_16x16x32_bf16 v[88:91], v[234:237], v[174:177], v[88:91]
	v_mfma_f32_16x16x32_bf16 v[84:87], v[226:229], v[182:185], v[84:87]
	v_mfma_f32_16x16x32_bf16 v[80:83], v[234:237], v[182:185], v[80:83]
	v_mfma_f32_16x16x32_bf16 v[76:79], v[226:229], v[210:213], v[76:79]
	v_mfma_f32_16x16x32_bf16 v[72:75], v[234:237], v[210:213], v[72:75]
	v_mfma_f32_16x16x32_bf16 v[68:71], v[226:229], v[218:221], v[68:71]
	v_mfma_f32_16x16x32_bf16 v[64:67], v[234:237], v[218:221], v[64:67]
	v_mfma_f32_16x16x32_bf16 v[92:95], v[230:233], v[178:181], v[92:95]
	v_mfma_f32_16x16x32_bf16 v[88:91], v[238:241], v[178:181], v[88:91]
	v_mfma_f32_16x16x32_bf16 v[84:87], v[230:233], v[206:209], v[84:87]
	v_mfma_f32_16x16x32_bf16 v[80:83], v[238:241], v[206:209], v[80:83]
	v_mfma_f32_16x16x32_bf16 v[76:79], v[230:233], v[214:217], v[76:79]
	v_mfma_f32_16x16x32_bf16 v[72:75], v[238:241], v[214:217], v[72:75]
	v_mfma_f32_16x16x32_bf16 v[68:71], v[230:233], v[222:225], v[68:71]
	v_mfma_f32_16x16x32_bf16 v[64:67], v[238:241], v[222:225], v[64:67]
	s_barrier
	s_add_i32 s19, s82, s57
	v_lshl_add_u64 v[146:147], s[54:55], 0, v[140:141]
	s_mov_b32 m0, s19
	v_lshl_add_u64 v[148:149], s[54:55], 0, v[132:133]
	global_load_lds_dwordx4 v[146:147], off
	s_add_i32 m0, s19, 0x2000
	s_nop 0
	global_load_lds_dwordx4 v[148:149], off
	s_mov_b32 m0, s68
	v_lshl_add_u64 v[194:195], s[58:59], 0, v[128:129]
	ds_read_b128 v[174:177], v157 offset:16384
	ds_read_b128 v[178:181], v157 offset:17408
	ds_read_b128 v[182:185], v157 offset:18432
	ds_read_b128 v[206:209], v157 offset:19456
	ds_read_b128 v[210:213], v157 offset:20480
	ds_read_b128 v[214:217], v157 offset:21504
	ds_read_b128 v[218:221], v157 offset:22528
	ds_read_b128 v[222:225], v157 offset:23552
	global_load_lds_dwordx4 v[194:195], off
	v_lshl_add_u64 v[196:197], s[58:59], 0, v[130:131]
	s_mov_b32 m0, s69
	s_nop 0
	global_load_lds_dwordx4 v[196:197], off
	s_add_u32 s82, s54, 0x40000
	s_addc_u32 s83, s55, 0
	s_add_i32 s6, s6, s57
	v_lshl_add_u64 v[250:251], s[82:83], 0, v[140:141]
	s_mov_b32 m0, s6
	s_nop 0
	global_load_lds_dwordx4 v[250:251], off
	v_lshl_add_u64 v[250:251], s[82:83], 0, v[132:133]
	s_add_i32 m0, s6, 0x2000
	s_nop 0
	global_load_lds_dwordx4 v[250:251], off
	s_nop 0
	s_waitcnt vmcnt(8)
	s_waitcnt lgkmcnt(0)
	s_barrier
	v_mfma_f32_16x16x32_bf16 v[60:63], v[158:161], v[174:177], v[60:63]
	v_mfma_f32_16x16x32_bf16 v[56:59], v[166:169], v[174:177], v[56:59]
	v_mfma_f32_16x16x32_bf16 v[52:55], v[158:161], v[182:185], v[52:55]
	v_mfma_f32_16x16x32_bf16 v[48:51], v[166:169], v[182:185], v[48:51]
	v_mfma_f32_16x16x32_bf16 v[44:47], v[158:161], v[210:213], v[44:47]
	v_mfma_f32_16x16x32_bf16 v[40:43], v[166:169], v[210:213], v[40:43]
	v_mfma_f32_16x16x32_bf16 v[36:39], v[158:161], v[218:221], v[36:39]
	v_mfma_f32_16x16x32_bf16 v[32:35], v[166:169], v[218:221], v[32:35]
	v_mfma_f32_16x16x32_bf16 v[60:63], v[162:165], v[178:181], v[60:63]
	v_mfma_f32_16x16x32_bf16 v[56:59], v[170:173], v[178:181], v[56:59]
	v_mfma_f32_16x16x32_bf16 v[52:55], v[162:165], v[206:209], v[52:55]
	v_mfma_f32_16x16x32_bf16 v[48:51], v[170:173], v[206:209], v[48:51]
	v_mfma_f32_16x16x32_bf16 v[44:47], v[162:165], v[214:217], v[44:47]
	v_mfma_f32_16x16x32_bf16 v[40:43], v[170:173], v[214:217], v[40:43]
	v_mfma_f32_16x16x32_bf16 v[36:39], v[162:165], v[222:225], v[36:39]
	v_mfma_f32_16x16x32_bf16 v[32:35], v[170:173], v[222:225], v[32:35]
	v_mfma_f32_16x16x32_bf16 v[28:31], v[226:229], v[174:177], v[28:31]
	v_mfma_f32_16x16x32_bf16 v[24:27], v[234:237], v[174:177], v[24:27]
	v_mfma_f32_16x16x32_bf16 v[20:23], v[226:229], v[182:185], v[20:23]
	v_mfma_f32_16x16x32_bf16 v[16:19], v[234:237], v[182:185], v[16:19]
	v_mfma_f32_16x16x32_bf16 v[12:15], v[226:229], v[210:213], v[12:15]
	v_mfma_f32_16x16x32_bf16 v[8:11], v[234:237], v[210:213], v[8:11]
	v_mfma_f32_16x16x32_bf16 v[4:7], v[226:229], v[218:221], v[4:7]
	v_mfma_f32_16x16x32_bf16 v[0:3], v[234:237], v[218:221], v[0:3]
	v_mfma_f32_16x16x32_bf16 v[28:31], v[230:233], v[178:181], v[28:31]
	v_mfma_f32_16x16x32_bf16 v[24:27], v[238:241], v[178:181], v[24:27]
	v_mfma_f32_16x16x32_bf16 v[20:23], v[230:233], v[206:209], v[20:23]
	v_mfma_f32_16x16x32_bf16 v[16:19], v[238:241], v[206:209], v[16:19]
	v_mfma_f32_16x16x32_bf16 v[12:15], v[230:233], v[214:217], v[12:15]
	v_mfma_f32_16x16x32_bf16 v[8:11], v[238:241], v[214:217], v[8:11]
	v_mfma_f32_16x16x32_bf16 v[4:7], v[230:233], v[222:225], v[4:7]
	v_mfma_f32_16x16x32_bf16 v[0:3], v[238:241], v[222:225], v[0:3]
	s_barrier
	s_add_i32 s6, 0, 0x18000
	v_add_u32_e32 v170, s6, v154
	ds_read_b128 v[158:161], v170
	ds_read_b128 v[162:165], v170 offset:1024
	ds_read_b128 v[166:169], v170 offset:2048
	ds_read_b128 v[170:173], v170 offset:3072
	s_add_u32 s58, s58, 0x40000
	s_addc_u32 s59, s59, 0
	s_mov_b32 m0, s70
	v_lshl_add_u64 v[226:227], s[58:59], 0, v[128:129]
	ds_read_b128 v[174:177], v157 offset:32768
	ds_read_b128 v[178:181], v157 offset:33792
	ds_read_b128 v[182:185], v157 offset:34816
	ds_read_b128 v[206:209], v157 offset:35840
	ds_read_b128 v[210:213], v157 offset:36864
	ds_read_b128 v[214:217], v157 offset:37888
	ds_read_b128 v[218:221], v157 offset:38912
	ds_read_b128 v[222:225], v157 offset:39936
	global_load_lds_dwordx4 v[226:227], off
	v_lshl_add_u64 v[226:227], s[58:59], 0, v[130:131]
	s_mov_b32 m0, s71
	s_nop 0
	global_load_lds_dwordx4 v[226:227], off
	s_add_i32 s19, 0, 0x1c000
	v_add_u32_e32 v192, s19, v154
	ds_read_b128 v[226:229], v192
	ds_read_b128 v[230:233], v192 offset:1024
	ds_read_b128 v[234:237], v192 offset:2048
	ds_read_b128 v[238:241], v192 offset:3072
	s_waitcnt vmcnt(8)
	s_waitcnt lgkmcnt(0)
	s_barrier
	v_mfma_f32_16x16x32_bf16 v[124:127], v[158:161], v[174:177], v[124:127]
	v_mfma_f32_16x16x32_bf16 v[120:123], v[166:169], v[174:177], v[120:123]
	v_mfma_f32_16x16x32_bf16 v[116:119], v[158:161], v[182:185], v[116:119]
	v_mfma_f32_16x16x32_bf16 v[112:115], v[166:169], v[182:185], v[112:115]
	v_mfma_f32_16x16x32_bf16 v[108:111], v[158:161], v[210:213], v[108:111]
	v_mfma_f32_16x16x32_bf16 v[104:107], v[166:169], v[210:213], v[104:107]
	v_mfma_f32_16x16x32_bf16 v[100:103], v[158:161], v[218:221], v[100:103]
	v_mfma_f32_16x16x32_bf16 v[96:99], v[166:169], v[218:221], v[96:99]
	v_mfma_f32_16x16x32_bf16 v[124:127], v[162:165], v[178:181], v[124:127]
	v_mfma_f32_16x16x32_bf16 v[120:123], v[170:173], v[178:181], v[120:123]
	v_mfma_f32_16x16x32_bf16 v[116:119], v[162:165], v[206:209], v[116:119]
	v_mfma_f32_16x16x32_bf16 v[112:115], v[170:173], v[206:209], v[112:115]
	v_mfma_f32_16x16x32_bf16 v[108:111], v[162:165], v[214:217], v[108:111]
	v_mfma_f32_16x16x32_bf16 v[104:107], v[170:173], v[214:217], v[104:107]
	v_mfma_f32_16x16x32_bf16 v[100:103], v[162:165], v[222:225], v[100:103]
	v_mfma_f32_16x16x32_bf16 v[96:99], v[170:173], v[222:225], v[96:99]
	v_mfma_f32_16x16x32_bf16 v[92:95], v[226:229], v[174:177], v[92:95]
	v_mfma_f32_16x16x32_bf16 v[88:91], v[234:237], v[174:177], v[88:91]
	v_mfma_f32_16x16x32_bf16 v[84:87], v[226:229], v[182:185], v[84:87]
	v_mfma_f32_16x16x32_bf16 v[80:83], v[234:237], v[182:185], v[80:83]
	v_mfma_f32_16x16x32_bf16 v[76:79], v[226:229], v[210:213], v[76:79]
	v_mfma_f32_16x16x32_bf16 v[72:75], v[234:237], v[210:213], v[72:75]
	v_mfma_f32_16x16x32_bf16 v[68:71], v[226:229], v[218:221], v[68:71]
	v_mfma_f32_16x16x32_bf16 v[64:67], v[234:237], v[218:221], v[64:67]
	v_mfma_f32_16x16x32_bf16 v[92:95], v[230:233], v[178:181], v[92:95]
	v_mfma_f32_16x16x32_bf16 v[88:91], v[238:241], v[178:181], v[88:91]
	v_mfma_f32_16x16x32_bf16 v[84:87], v[230:233], v[206:209], v[84:87]
	v_mfma_f32_16x16x32_bf16 v[80:83], v[238:241], v[206:209], v[80:83]
	v_mfma_f32_16x16x32_bf16 v[76:79], v[230:233], v[214:217], v[76:79]
	v_mfma_f32_16x16x32_bf16 v[72:75], v[238:241], v[214:217], v[72:75]
	v_mfma_f32_16x16x32_bf16 v[68:71], v[230:233], v[222:225], v[68:71]
	v_mfma_f32_16x16x32_bf16 v[64:67], v[238:241], v[222:225], v[64:67]
	s_barrier
	s_add_i32 s6, s6, s57
	v_lshl_add_u64 v[146:147], v[146:147], 0, s[36:37]
	s_mov_b32 m0, s6
	s_nop 0
	global_load_lds_dwordx4 v[146:147], off
	v_lshl_add_u64 v[146:147], v[148:149], 0, s[36:37]
	s_add_i32 m0, s6, 0x2000
	s_nop 0
	global_load_lds_dwordx4 v[146:147], off
	s_mov_b32 m0, s72
	v_lshl_add_u64 v[146:147], v[194:195], 0, s[36:37]
	ds_read_b128 v[174:177], v157 offset:49152
	ds_read_b128 v[178:181], v157 offset:50176
	ds_read_b128 v[182:185], v157 offset:51200
	ds_read_b128 v[206:209], v157 offset:52224
	ds_read_b128 v[210:213], v157 offset:53248
	ds_read_b128 v[214:217], v157 offset:54272
	ds_read_b128 v[218:221], v157 offset:55296
	ds_read_b128 v[222:225], v157 offset:56320
	global_load_lds_dwordx4 v[146:147], off
	v_lshl_add_u64 v[146:147], v[196:197], 0, s[36:37]
	s_mov_b32 m0, s73
	s_nop 0
	global_load_lds_dwordx4 v[146:147], off
	s_add_u32 s54, s54, 0x40080
	s_addc_u32 s55, s55, 0
	s_add_i32 s6, s19, s57
	v_lshl_add_u64 v[146:147], s[54:55], 0, v[140:141]
	s_mov_b32 m0, s6
	s_nop 0
	global_load_lds_dwordx4 v[146:147], off
	v_lshl_add_u64 v[146:147], s[54:55], 0, v[132:133]
	s_add_i32 m0, s6, 0x2000
	s_nop 0
	global_load_lds_dwordx4 v[146:147], off
	s_add_i32 s81, s81, 2
	s_add_u32 s52, s52, 0x100
	s_addc_u32 s53, s53, 0
	s_cmp_gt_u32 s81, 13
	s_nop 0
	s_waitcnt vmcnt(8)
	s_waitcnt lgkmcnt(0)
	s_barrier
	v_mfma_f32_16x16x32_bf16 v[60:63], v[158:161], v[174:177], v[60:63]
	v_mfma_f32_16x16x32_bf16 v[56:59], v[166:169], v[174:177], v[56:59]
	v_mfma_f32_16x16x32_bf16 v[52:55], v[158:161], v[182:185], v[52:55]
	v_mfma_f32_16x16x32_bf16 v[48:51], v[166:169], v[182:185], v[48:51]
	v_mfma_f32_16x16x32_bf16 v[44:47], v[158:161], v[210:213], v[44:47]
	v_mfma_f32_16x16x32_bf16 v[40:43], v[166:169], v[210:213], v[40:43]
	v_mfma_f32_16x16x32_bf16 v[36:39], v[158:161], v[218:221], v[36:39]
	v_mfma_f32_16x16x32_bf16 v[32:35], v[166:169], v[218:221], v[32:35]
	v_mfma_f32_16x16x32_bf16 v[60:63], v[162:165], v[178:181], v[60:63]
	v_mfma_f32_16x16x32_bf16 v[56:59], v[170:173], v[178:181], v[56:59]
	v_mfma_f32_16x16x32_bf16 v[52:55], v[162:165], v[206:209], v[52:55]
	v_mfma_f32_16x16x32_bf16 v[48:51], v[170:173], v[206:209], v[48:51]
	v_mfma_f32_16x16x32_bf16 v[44:47], v[162:165], v[214:217], v[44:47]
	v_mfma_f32_16x16x32_bf16 v[40:43], v[170:173], v[214:217], v[40:43]
	v_mfma_f32_16x16x32_bf16 v[36:39], v[162:165], v[222:225], v[36:39]
	v_mfma_f32_16x16x32_bf16 v[32:35], v[170:173], v[222:225], v[32:35]
	v_mfma_f32_16x16x32_bf16 v[28:31], v[226:229], v[174:177], v[28:31]
	v_mfma_f32_16x16x32_bf16 v[24:27], v[234:237], v[174:177], v[24:27]
	v_mfma_f32_16x16x32_bf16 v[20:23], v[226:229], v[182:185], v[20:23]
	v_mfma_f32_16x16x32_bf16 v[16:19], v[234:237], v[182:185], v[16:19]
	v_mfma_f32_16x16x32_bf16 v[12:15], v[226:229], v[210:213], v[12:15]
	v_mfma_f32_16x16x32_bf16 v[8:11], v[234:237], v[210:213], v[8:11]
	v_mfma_f32_16x16x32_bf16 v[4:7], v[226:229], v[218:221], v[4:7]
	v_mfma_f32_16x16x32_bf16 v[0:3], v[234:237], v[218:221], v[0:3]
	v_mfma_f32_16x16x32_bf16 v[28:31], v[230:233], v[178:181], v[28:31]
	v_mfma_f32_16x16x32_bf16 v[24:27], v[238:241], v[178:181], v[24:27]
	v_mfma_f32_16x16x32_bf16 v[20:23], v[230:233], v[206:209], v[20:23]
	v_mfma_f32_16x16x32_bf16 v[16:19], v[238:241], v[206:209], v[16:19]
	v_mfma_f32_16x16x32_bf16 v[12:15], v[230:233], v[214:217], v[12:15]
	v_mfma_f32_16x16x32_bf16 v[8:11], v[238:241], v[214:217], v[8:11]
	v_mfma_f32_16x16x32_bf16 v[4:7], v[230:233], v[222:225], v[4:7]
	v_mfma_f32_16x16x32_bf16 v[0:3], v[238:241], v[222:225], v[0:3]
	s_barrier
	s_cbranch_scc0 .LBB0_386
	s_mov_b32 s100, 1
	v_lshl_add_u32 v158, s75, 10, v155
	ds_read2_b32 v[146:147], v158 offset1:16
	ds_read2_b32 v[208:209], v158 offset0:32 offset1:48
	ds_read2_b32 v[210:211], v158 offset0:128 offset1:144
	ds_read2_b32 v[212:213], v158 offset0:160 offset1:176
	s_add_u32 s52, s10, 0xffffff00
	s_addc_u32 s53, s11, -1
	s_ashr_i32 s35, s34, 31
	s_lshl_b64 s[10:11], s[34:35], 8
	s_waitcnt lgkmcnt(0)
	v_mul_f32_e32 v184, 0xbfb8aa3b, v146
	v_mul_f32_e32 v206, v146, v146
	v_pk_mul_f32 v[168:169], v[124:125], v[184:185] op_sel_hi:[1,0]
	v_pk_mul_f32 v[170:171], v[126:127], v[184:185] op_sel_hi:[1,0]
	v_pk_mul_f32 v[172:173], v[120:121], v[184:185] op_sel_hi:[1,0]
	v_pk_mul_f32 v[174:175], v[122:123], v[184:185] op_sel_hi:[1,0]
	v_exp_f32_e32 v168, v168
	v_exp_f32_e32 v169, v169
	v_exp_f32_e32 v170, v170
	v_exp_f32_e32 v171, v171
	v_exp_f32_e32 v172, v172
	v_exp_f32_e32 v173, v173
	v_exp_f32_e32 v174, v174
	v_exp_f32_e32 v175, v175
	v_pk_mul_f32 v[176:177], v[124:125], v[92:93]
	v_pk_mul_f32 v[178:179], v[126:127], v[94:95]
	v_pk_mul_f32 v[180:181], v[120:121], v[88:89]
	v_pk_mul_f32 v[182:183], v[122:123], v[90:91]
	v_pk_add_f32 v[168:169], v[168:169], 1.0 op_sel_hi:[1,0]
	v_pk_add_f32 v[170:171], v[170:171], 1.0 op_sel_hi:[1,0]
	v_pk_add_f32 v[172:173], v[172:173], 1.0 op_sel_hi:[1,0]
	v_pk_add_f32 v[174:175], v[174:175], 1.0 op_sel_hi:[1,0]
	v_rcp_f32_e32 v168, v168
	v_rcp_f32_e32 v169, v169
	v_rcp_f32_e32 v170, v170
	v_rcp_f32_e32 v171, v171
	v_rcp_f32_e32 v172, v172
	v_rcp_f32_e32 v173, v173
	v_rcp_f32_e32 v174, v174
	v_rcp_f32_e32 v175, v175
	v_pk_mul_f32 v[176:177], v[176:177], v[206:207] op_sel_hi:[1,0]
	v_pk_mul_f32 v[178:179], v[178:179], v[206:207] op_sel_hi:[1,0]
	v_pk_mul_f32 v[180:181], v[180:181], v[206:207] op_sel_hi:[1,0]
	v_pk_mul_f32 v[182:183], v[182:183], v[206:207] op_sel_hi:[1,0]
	v_pk_mul_f32 v[176:177], v[176:177], v[168:169]
	v_pk_mul_f32 v[178:179], v[178:179], v[170:171]
	v_pk_mul_f32 v[180:181], v[180:181], v[172:173]
	v_pk_mul_f32 v[182:183], v[182:183], v[174:175]
	v_cvt_pk_bf16_f32 v160, v176, v177
	v_cvt_pk_bf16_f32 v161, v178, v179
	v_cvt_pk_bf16_f32 v162, v180, v181
	v_cvt_pk_bf16_f32 v163, v182, v183
	v_lshl_add_u64 v[152:153], v[134:135], 0, s[10:11]
	s_movk_i32 s6, 0x1600
	v_lshl_or_b32 v150, s74, 7, v156
	v_ashrrev_i32_e32 v151, 31, v150
	s_nop 1
	v_mov_b64_e32 v[148:149], s[30:31]
	v_mad_u64_u32 v[148:149], s[10:11], v152, s6, v[148:149]
	v_mov_b32_e32 v146, v149
	v_mad_u64_u32 v[152:153], s[10:11], v153, s6, v[146:147]
	v_mov_b32_e32 v149, v152
	v_mov_b32_e32 v146, v147
	v_lshl_add_u64 v[150:151], v[150:151], 1, v[148:149]
	global_store_dwordx4 v[150:151], v[160:163], off
	v_mul_f32_e32 v184, 0xbfb8aa3b, v146
	v_mul_f32_e32 v206, v146, v146
	v_pk_mul_f32 v[168:169], v[116:117], v[184:185] op_sel_hi:[1,0]
	v_pk_mul_f32 v[170:171], v[118:119], v[184:185] op_sel_hi:[1,0]
	v_pk_mul_f32 v[172:173], v[112:113], v[184:185] op_sel_hi:[1,0]
	v_pk_mul_f32 v[174:175], v[114:115], v[184:185] op_sel_hi:[1,0]
	v_exp_f32_e32 v168, v168
	v_exp_f32_e32 v169, v169
	v_exp_f32_e32 v170, v170
	v_exp_f32_e32 v171, v171
	v_exp_f32_e32 v172, v172
	v_exp_f32_e32 v173, v173
	v_exp_f32_e32 v174, v174
	v_exp_f32_e32 v175, v175
	v_pk_mul_f32 v[176:177], v[116:117], v[84:85]
	v_pk_mul_f32 v[178:179], v[118:119], v[86:87]
	v_pk_mul_f32 v[180:181], v[112:113], v[80:81]
	v_pk_mul_f32 v[182:183], v[114:115], v[82:83]
	v_pk_add_f32 v[168:169], v[168:169], 1.0 op_sel_hi:[1,0]
	v_pk_add_f32 v[170:171], v[170:171], 1.0 op_sel_hi:[1,0]
	v_pk_add_f32 v[172:173], v[172:173], 1.0 op_sel_hi:[1,0]
	v_pk_add_f32 v[174:175], v[174:175], 1.0 op_sel_hi:[1,0]
	v_rcp_f32_e32 v168, v168
	v_rcp_f32_e32 v169, v169
	v_rcp_f32_e32 v170, v170
	v_rcp_f32_e32 v171, v171
	v_rcp_f32_e32 v172, v172
	v_rcp_f32_e32 v173, v173
	v_rcp_f32_e32 v174, v174
	v_rcp_f32_e32 v175, v175
	v_pk_mul_f32 v[176:177], v[176:177], v[206:207] op_sel_hi:[1,0]
	v_pk_mul_f32 v[178:179], v[178:179], v[206:207] op_sel_hi:[1,0]
	v_pk_mul_f32 v[180:181], v[180:181], v[206:207] op_sel_hi:[1,0]
	v_pk_mul_f32 v[182:183], v[182:183], v[206:207] op_sel_hi:[1,0]
	v_pk_mul_f32 v[176:177], v[176:177], v[168:169]
	v_pk_mul_f32 v[178:179], v[178:179], v[170:171]
	v_pk_mul_f32 v[180:181], v[180:181], v[172:173]
	v_pk_mul_f32 v[182:183], v[182:183], v[174:175]
	v_cvt_pk_bf16_f32 v160, v176, v177
	v_cvt_pk_bf16_f32 v161, v178, v179
	v_cvt_pk_bf16_f32 v162, v180, v181
	v_cvt_pk_bf16_f32 v163, v182, v183
	s_mov_b32 s6, 0x16000
	s_nop 1
	v_add_co_u32_e32 v146, vcc, s6, v150
	s_nop 0
	v_addc_co_u32_e32 v147, vcc, 0, v151, vcc
	global_store_dwordx4 v[146:147], v[160:163], off
	v_mov_b32_e32 v146, v208
	v_mov_b32_e32 v147, v209
	s_mov_b32 s6, 0x2c000
	s_waitcnt lgkmcnt(0)
	v_mul_f32_e32 v184, 0xbfb8aa3b, v146
	v_mul_f32_e32 v206, v146, v146
	v_pk_mul_f32 v[168:169], v[108:109], v[184:185] op_sel_hi:[1,0]
	v_pk_mul_f32 v[170:171], v[110:111], v[184:185] op_sel_hi:[1,0]
	v_pk_mul_f32 v[172:173], v[104:105], v[184:185] op_sel_hi:[1,0]
	v_pk_mul_f32 v[174:175], v[106:107], v[184:185] op_sel_hi:[1,0]
	v_exp_f32_e32 v168, v168
	v_exp_f32_e32 v169, v169
	v_exp_f32_e32 v170, v170
	v_exp_f32_e32 v171, v171
	v_exp_f32_e32 v172, v172
	v_exp_f32_e32 v173, v173
	v_exp_f32_e32 v174, v174
	v_exp_f32_e32 v175, v175
	v_pk_mul_f32 v[176:177], v[108:109], v[76:77]
	v_pk_mul_f32 v[178:179], v[110:111], v[78:79]
	v_pk_mul_f32 v[180:181], v[104:105], v[72:73]
	v_pk_mul_f32 v[182:183], v[106:107], v[74:75]
	v_pk_add_f32 v[168:169], v[168:169], 1.0 op_sel_hi:[1,0]
	v_pk_add_f32 v[170:171], v[170:171], 1.0 op_sel_hi:[1,0]
	v_pk_add_f32 v[172:173], v[172:173], 1.0 op_sel_hi:[1,0]
	v_pk_add_f32 v[174:175], v[174:175], 1.0 op_sel_hi:[1,0]
	v_rcp_f32_e32 v168, v168
	v_rcp_f32_e32 v169, v169
	v_rcp_f32_e32 v170, v170
	v_rcp_f32_e32 v171, v171
	v_rcp_f32_e32 v172, v172
	v_rcp_f32_e32 v173, v173
	v_rcp_f32_e32 v174, v174
	v_rcp_f32_e32 v175, v175
	v_pk_mul_f32 v[176:177], v[176:177], v[206:207] op_sel_hi:[1,0]
	v_pk_mul_f32 v[178:179], v[178:179], v[206:207] op_sel_hi:[1,0]
	v_pk_mul_f32 v[180:181], v[180:181], v[206:207] op_sel_hi:[1,0]
	v_pk_mul_f32 v[182:183], v[182:183], v[206:207] op_sel_hi:[1,0]
	v_pk_mul_f32 v[176:177], v[176:177], v[168:169]
	v_pk_mul_f32 v[178:179], v[178:179], v[170:171]
	v_pk_mul_f32 v[180:181], v[180:181], v[172:173]
	v_pk_mul_f32 v[182:183], v[182:183], v[174:175]
	v_cvt_pk_bf16_f32 v160, v176, v177
	v_cvt_pk_bf16_f32 v161, v178, v179
	v_cvt_pk_bf16_f32 v162, v180, v181
	v_cvt_pk_bf16_f32 v163, v182, v183
	s_nop 1
	v_mov_b32_e32 v146, v147
	v_add_co_u32_e32 v148, vcc, s6, v150
	v_addc_co_u32_e32 v149, vcc, 0, v151, vcc
	global_store_dwordx4 v[148:149], v[160:163], off
	v_mul_f32_e32 v184, 0xbfb8aa3b, v146
	v_mul_f32_e32 v206, v146, v146
	v_pk_mul_f32 v[168:169], v[100:101], v[184:185] op_sel_hi:[1,0]
	v_pk_mul_f32 v[170:171], v[102:103], v[184:185] op_sel_hi:[1,0]
	v_pk_mul_f32 v[172:173], v[96:97], v[184:185] op_sel_hi:[1,0]
	v_pk_mul_f32 v[174:175], v[98:99], v[184:185] op_sel_hi:[1,0]
	v_exp_f32_e32 v168, v168
	v_exp_f32_e32 v169, v169
	v_exp_f32_e32 v170, v170
	v_exp_f32_e32 v171, v171
	v_exp_f32_e32 v172, v172
	v_exp_f32_e32 v173, v173
	v_exp_f32_e32 v174, v174
	v_exp_f32_e32 v175, v175
	v_pk_mul_f32 v[176:177], v[100:101], v[68:69]
	v_pk_mul_f32 v[178:179], v[102:103], v[70:71]
	v_pk_mul_f32 v[180:181], v[96:97], v[64:65]
	v_pk_mul_f32 v[182:183], v[98:99], v[66:67]
	v_pk_add_f32 v[168:169], v[168:169], 1.0 op_sel_hi:[1,0]
	v_pk_add_f32 v[170:171], v[170:171], 1.0 op_sel_hi:[1,0]
	v_pk_add_f32 v[172:173], v[172:173], 1.0 op_sel_hi:[1,0]
	v_pk_add_f32 v[174:175], v[174:175], 1.0 op_sel_hi:[1,0]
	v_rcp_f32_e32 v168, v168
	v_rcp_f32_e32 v169, v169
	v_rcp_f32_e32 v170, v170
	v_rcp_f32_e32 v171, v171
	v_rcp_f32_e32 v172, v172
	v_rcp_f32_e32 v173, v173
	v_rcp_f32_e32 v174, v174
	v_rcp_f32_e32 v175, v175
	v_pk_mul_f32 v[176:177], v[176:177], v[206:207] op_sel_hi:[1,0]
	v_pk_mul_f32 v[178:179], v[178:179], v[206:207] op_sel_hi:[1,0]
	v_pk_mul_f32 v[180:181], v[180:181], v[206:207] op_sel_hi:[1,0]
	v_pk_mul_f32 v[182:183], v[182:183], v[206:207] op_sel_hi:[1,0]
	v_pk_mul_f32 v[176:177], v[176:177], v[168:169]
	v_pk_mul_f32 v[178:179], v[178:179], v[170:171]
	v_pk_mul_f32 v[180:181], v[180:181], v[172:173]
	v_pk_mul_f32 v[182:183], v[182:183], v[174:175]
	v_cvt_pk_bf16_f32 v160, v176, v177
	v_cvt_pk_bf16_f32 v161, v178, v179
	v_cvt_pk_bf16_f32 v162, v180, v181
	v_cvt_pk_bf16_f32 v163, v182, v183
	s_mov_b32 s6, 0x42000
	s_nop 1
	v_add_co_u32_e32 v146, vcc, s6, v150
	s_nop 0
	v_addc_co_u32_e32 v147, vcc, 0, v151, vcc
	global_store_dwordx4 v[146:147], v[160:163], off
	v_mov_b32_e32 v146, v210
	v_mov_b32_e32 v147, v211
	s_mov_b32 s6, 0xb0000
	s_waitcnt lgkmcnt(0)
	v_mul_f32_e32 v184, 0xbfb8aa3b, v146
	v_mul_f32_e32 v206, v146, v146
	v_pk_mul_f32 v[168:169], v[60:61], v[184:185] op_sel_hi:[1,0]
	v_pk_mul_f32 v[170:171], v[62:63], v[184:185] op_sel_hi:[1,0]
	v_pk_mul_f32 v[172:173], v[56:57], v[184:185] op_sel_hi:[1,0]
	v_pk_mul_f32 v[174:175], v[58:59], v[184:185] op_sel_hi:[1,0]
	v_exp_f32_e32 v168, v168
	v_exp_f32_e32 v169, v169
	v_exp_f32_e32 v170, v170
	v_exp_f32_e32 v171, v171
	v_exp_f32_e32 v172, v172
	v_exp_f32_e32 v173, v173
	v_exp_f32_e32 v174, v174
	v_exp_f32_e32 v175, v175
	v_pk_mul_f32 v[176:177], v[60:61], v[28:29]
	v_pk_mul_f32 v[178:179], v[62:63], v[30:31]
	v_pk_mul_f32 v[180:181], v[56:57], v[24:25]
	v_pk_mul_f32 v[182:183], v[58:59], v[26:27]
	v_pk_add_f32 v[168:169], v[168:169], 1.0 op_sel_hi:[1,0]
	v_pk_add_f32 v[170:171], v[170:171], 1.0 op_sel_hi:[1,0]
	v_pk_add_f32 v[172:173], v[172:173], 1.0 op_sel_hi:[1,0]
	v_pk_add_f32 v[174:175], v[174:175], 1.0 op_sel_hi:[1,0]
	v_rcp_f32_e32 v168, v168
	v_rcp_f32_e32 v169, v169
	v_rcp_f32_e32 v170, v170
	v_rcp_f32_e32 v171, v171
	v_rcp_f32_e32 v172, v172
	v_rcp_f32_e32 v173, v173
	v_rcp_f32_e32 v174, v174
	v_rcp_f32_e32 v175, v175
	v_pk_mul_f32 v[176:177], v[176:177], v[206:207] op_sel_hi:[1,0]
	v_pk_mul_f32 v[178:179], v[178:179], v[206:207] op_sel_hi:[1,0]
	v_pk_mul_f32 v[180:181], v[180:181], v[206:207] op_sel_hi:[1,0]
	v_pk_mul_f32 v[182:183], v[182:183], v[206:207] op_sel_hi:[1,0]
	v_pk_mul_f32 v[176:177], v[176:177], v[168:169]
	v_pk_mul_f32 v[178:179], v[178:179], v[170:171]
	v_pk_mul_f32 v[180:181], v[180:181], v[172:173]
	v_pk_mul_f32 v[182:183], v[182:183], v[174:175]
	v_cvt_pk_bf16_f32 v160, v176, v177
	v_cvt_pk_bf16_f32 v161, v178, v179
	v_cvt_pk_bf16_f32 v162, v180, v181
	v_cvt_pk_bf16_f32 v163, v182, v183
	s_nop 1
	v_mov_b32_e32 v146, v147
	v_add_co_u32_e32 v148, vcc, s6, v150
	v_addc_co_u32_e32 v149, vcc, 0, v151, vcc
	global_store_dwordx4 v[148:149], v[160:163], off
	v_mul_f32_e32 v184, 0xbfb8aa3b, v146
	v_mul_f32_e32 v206, v146, v146
	v_pk_mul_f32 v[168:169], v[52:53], v[184:185] op_sel_hi:[1,0]
	v_pk_mul_f32 v[170:171], v[54:55], v[184:185] op_sel_hi:[1,0]
	v_pk_mul_f32 v[172:173], v[48:49], v[184:185] op_sel_hi:[1,0]
	v_pk_mul_f32 v[174:175], v[50:51], v[184:185] op_sel_hi:[1,0]
	v_exp_f32_e32 v168, v168
	v_exp_f32_e32 v169, v169
	v_exp_f32_e32 v170, v170
	v_exp_f32_e32 v171, v171
	v_exp_f32_e32 v172, v172
	v_exp_f32_e32 v173, v173
	v_exp_f32_e32 v174, v174
	v_exp_f32_e32 v175, v175
	v_pk_mul_f32 v[176:177], v[52:53], v[20:21]
	v_pk_mul_f32 v[178:179], v[54:55], v[22:23]
	v_pk_mul_f32 v[180:181], v[48:49], v[16:17]
	v_pk_mul_f32 v[182:183], v[50:51], v[18:19]
	v_pk_add_f32 v[168:169], v[168:169], 1.0 op_sel_hi:[1,0]
	v_pk_add_f32 v[170:171], v[170:171], 1.0 op_sel_hi:[1,0]
	v_pk_add_f32 v[172:173], v[172:173], 1.0 op_sel_hi:[1,0]
	v_pk_add_f32 v[174:175], v[174:175], 1.0 op_sel_hi:[1,0]
	v_rcp_f32_e32 v168, v168
	v_rcp_f32_e32 v169, v169
	v_rcp_f32_e32 v170, v170
	v_rcp_f32_e32 v171, v171
	v_rcp_f32_e32 v172, v172
	v_rcp_f32_e32 v173, v173
	v_rcp_f32_e32 v174, v174
	v_rcp_f32_e32 v175, v175
	v_pk_mul_f32 v[176:177], v[176:177], v[206:207] op_sel_hi:[1,0]
	v_pk_mul_f32 v[178:179], v[178:179], v[206:207] op_sel_hi:[1,0]
	v_pk_mul_f32 v[180:181], v[180:181], v[206:207] op_sel_hi:[1,0]
	v_pk_mul_f32 v[182:183], v[182:183], v[206:207] op_sel_hi:[1,0]
	v_pk_mul_f32 v[176:177], v[176:177], v[168:169]
	v_pk_mul_f32 v[178:179], v[178:179], v[170:171]
	v_pk_mul_f32 v[180:181], v[180:181], v[172:173]
	v_pk_mul_f32 v[182:183], v[182:183], v[174:175]
	v_cvt_pk_bf16_f32 v160, v176, v177
	v_cvt_pk_bf16_f32 v161, v178, v179
	v_cvt_pk_bf16_f32 v162, v180, v181
	v_cvt_pk_bf16_f32 v163, v182, v183
	s_mov_b32 s6, 0xc6000
	s_nop 1
	v_add_co_u32_e32 v146, vcc, s6, v150
	s_nop 0
	v_addc_co_u32_e32 v147, vcc, 0, v151, vcc
	global_store_dwordx4 v[146:147], v[160:163], off
	v_mov_b32_e32 v146, v212
	v_mov_b32_e32 v147, v213
	s_mov_b32 s6, 0xdc000
	s_waitcnt lgkmcnt(0)
	v_mul_f32_e32 v184, 0xbfb8aa3b, v146
	v_mul_f32_e32 v206, v146, v146
	v_pk_mul_f32 v[168:169], v[44:45], v[184:185] op_sel_hi:[1,0]
	v_pk_mul_f32 v[170:171], v[46:47], v[184:185] op_sel_hi:[1,0]
	v_pk_mul_f32 v[172:173], v[40:41], v[184:185] op_sel_hi:[1,0]
	v_pk_mul_f32 v[174:175], v[42:43], v[184:185] op_sel_hi:[1,0]
	v_exp_f32_e32 v168, v168
	v_exp_f32_e32 v169, v169
	v_exp_f32_e32 v170, v170
	v_exp_f32_e32 v171, v171
	v_exp_f32_e32 v172, v172
	v_exp_f32_e32 v173, v173
	v_exp_f32_e32 v174, v174
	v_exp_f32_e32 v175, v175
	v_pk_mul_f32 v[176:177], v[44:45], v[12:13]
	v_pk_mul_f32 v[178:179], v[46:47], v[14:15]
	v_pk_mul_f32 v[180:181], v[40:41], v[8:9]
	v_pk_mul_f32 v[182:183], v[42:43], v[10:11]
	v_pk_add_f32 v[168:169], v[168:169], 1.0 op_sel_hi:[1,0]
	v_pk_add_f32 v[170:171], v[170:171], 1.0 op_sel_hi:[1,0]
	v_pk_add_f32 v[172:173], v[172:173], 1.0 op_sel_hi:[1,0]
	v_pk_add_f32 v[174:175], v[174:175], 1.0 op_sel_hi:[1,0]
	v_rcp_f32_e32 v168, v168
	v_rcp_f32_e32 v169, v169
	v_rcp_f32_e32 v170, v170
	v_rcp_f32_e32 v171, v171
	v_rcp_f32_e32 v172, v172
	v_rcp_f32_e32 v173, v173
	v_rcp_f32_e32 v174, v174
	v_rcp_f32_e32 v175, v175
	v_pk_mul_f32 v[176:177], v[176:177], v[206:207] op_sel_hi:[1,0]
	v_pk_mul_f32 v[178:179], v[178:179], v[206:207] op_sel_hi:[1,0]
	v_pk_mul_f32 v[180:181], v[180:181], v[206:207] op_sel_hi:[1,0]
	v_pk_mul_f32 v[182:183], v[182:183], v[206:207] op_sel_hi:[1,0]
	v_pk_mul_f32 v[176:177], v[176:177], v[168:169]
	v_pk_mul_f32 v[178:179], v[178:179], v[170:171]
	v_pk_mul_f32 v[180:181], v[180:181], v[172:173]
	v_pk_mul_f32 v[182:183], v[182:183], v[174:175]
	v_cvt_pk_bf16_f32 v158, v176, v177
	v_cvt_pk_bf16_f32 v159, v178, v179
	v_cvt_pk_bf16_f32 v160, v180, v181
	v_cvt_pk_bf16_f32 v161, v182, v183
	s_nop 1
	v_mov_b32_e32 v146, v147
	v_add_co_u32_e32 v148, vcc, s6, v150
	v_addc_co_u32_e32 v149, vcc, 0, v151, vcc
	global_store_dwordx4 v[148:149], v[158:161], off
	v_mul_f32_e32 v184, 0xbfb8aa3b, v146
	v_mul_f32_e32 v206, v146, v146
	v_pk_mul_f32 v[168:169], v[36:37], v[184:185] op_sel_hi:[1,0]
	v_pk_mul_f32 v[170:171], v[38:39], v[184:185] op_sel_hi:[1,0]
	v_pk_mul_f32 v[172:173], v[32:33], v[184:185] op_sel_hi:[1,0]
	v_pk_mul_f32 v[174:175], v[34:35], v[184:185] op_sel_hi:[1,0]
	v_exp_f32_e32 v168, v168
	v_exp_f32_e32 v169, v169
	v_exp_f32_e32 v170, v170
	v_exp_f32_e32 v171, v171
	v_exp_f32_e32 v172, v172
	v_exp_f32_e32 v173, v173
	v_exp_f32_e32 v174, v174
	v_exp_f32_e32 v175, v175
	v_pk_mul_f32 v[176:177], v[36:37], v[4:5]
	v_pk_mul_f32 v[178:179], v[38:39], v[6:7]
	v_pk_mul_f32 v[180:181], v[32:33], v[0:1]
	v_pk_mul_f32 v[182:183], v[34:35], v[2:3]
	v_pk_add_f32 v[168:169], v[168:169], 1.0 op_sel_hi:[1,0]
	v_pk_add_f32 v[170:171], v[170:171], 1.0 op_sel_hi:[1,0]
	v_pk_add_f32 v[172:173], v[172:173], 1.0 op_sel_hi:[1,0]
	v_pk_add_f32 v[174:175], v[174:175], 1.0 op_sel_hi:[1,0]
	v_rcp_f32_e32 v168, v168
	v_rcp_f32_e32 v169, v169
	v_rcp_f32_e32 v170, v170
	v_rcp_f32_e32 v171, v171
	v_rcp_f32_e32 v172, v172
	v_rcp_f32_e32 v173, v173
	v_rcp_f32_e32 v174, v174
	v_rcp_f32_e32 v175, v175
	v_pk_mul_f32 v[176:177], v[176:177], v[206:207] op_sel_hi:[1,0]
	v_pk_mul_f32 v[178:179], v[178:179], v[206:207] op_sel_hi:[1,0]
	v_pk_mul_f32 v[180:181], v[180:181], v[206:207] op_sel_hi:[1,0]
	v_pk_mul_f32 v[182:183], v[182:183], v[206:207] op_sel_hi:[1,0]
	v_pk_mul_f32 v[176:177], v[176:177], v[168:169]
	v_pk_mul_f32 v[178:179], v[178:179], v[170:171]
	v_pk_mul_f32 v[180:181], v[180:181], v[172:173]
	v_pk_mul_f32 v[182:183], v[182:183], v[174:175]
	v_cvt_pk_bf16_f32 v158, v176, v177
	v_cvt_pk_bf16_f32 v159, v178, v179
	v_cvt_pk_bf16_f32 v160, v180, v181
	v_cvt_pk_bf16_f32 v161, v182, v183
	s_nop 1
	v_add_co_u32_e32 v146, vcc, 0xf2000, v150
	s_nop 0
	v_addc_co_u32_e32 v147, vcc, 0, v151, vcc
	s_andn2_b64 vcc, exec, s[44:45]
	global_store_dwordx4 v[146:147], v[158:161], off
	s_cbranch_vccz .LBB0_382
	s_mov_b64 s[48:49], s[52:53]
	s_andn2_b64 vcc, exec, s[42:43]
	s_mov_b64 s[52:53], s[48:49]
	s_cbranch_vccnz .LBB0_383
